# GEMM: per-segment s_setprio flips deleted, one static s_setprio 1 for waves 4-7 (set at their stagger barrier), reset to 0 at phase end
# speedup vs baseline: 1.0181x; 1.0080x over previous
.LBB0_27:
	s_add_u32 s49, s6, 0x10a00000
	s_addc_u32 s50, s7, 0
	s_add_u32 s51, s6, 0xf400000
	s_addc_u32 s52, s7, 0
	s_add_i32 s6, s40, s8
	v_ashrrev_i32_e32 v3, 31, v0
	s_ashr_i32 s7, s6, 31
	v_lshrrev_b32_e32 v3, 26, v3
	s_lshr_b32 s7, s7, 27
	v_lshlrev_b32_e32 v2, 4, v0
	v_add_u32_e32 v3, v0, v3
	v_bfe_i32 v0, v0, 27, 1
	s_add_i32 s7, s6, s7
	v_lshrrev_b32_e32 v0, 22, v0
	s_ashr_i32 s8, s7, 5
	s_and_b32 s7, s7, 0xffe0
	v_add_u32_e32 v0, v2, v0
	s_sub_i32 s6, s6, s7
	v_and_b32_e32 v0, 0xfffffc00, v0
	s_bfe_i32 s7, s6, 0x80000
	v_sub_u32_e32 v0, v2, v0
	s_bfe_u32 s7, s7, 0x2000d
	v_lshrrev_b32_e32 v2, 4, v0
	s_add_i32 s7, s6, s7
	v_bitop3_b32 v0, v2, v0, 32 bitop3:0x6c
	s_bfe_i32 s9, s7, 0x80000
	s_and_b32 s7, s7, 0xfc
	v_ashrrev_i32_e32 v6, 6, v3
	v_ashrrev_i32_e32 v3, 31, v0
	s_sub_i32 s6, s6, s7
	v_lshrrev_b32_e32 v3, 26, v3
	s_lshl_b32 s8, s8, 2
	s_sext_i32_i8 s6, s6
	s_ashr_i32 s10, s48, 6
	v_add_u32_e32 v3, v0, v3
	s_sext_i32_i16 s9, s9
	s_add_i32 s85, s8, s6
	s_ashr_i32 s11, s48, 8
	v_lshlrev_b32_e32 v2, 3, v6
	v_ashrrev_i32_e32 v7, 6, v3
	v_and_b32_e32 v3, 0xc0, v3
	s_lshl_b32 s53, s10, 10
	s_lshr_b32 s40, s9, 2
	s_mul_i32 s6, s85, 0x2c0000
	v_and_b32_e32 v2, 0x7ffff0, v2
	v_sub_u32_e32 v0, v0, v3
	v_mov_b32_e32 v3, 1
	s_mul_hi_i32 s7, s85, 0x2c0000
	s_add_u32 s6, s49, s6
	v_add_u32_e32 v2, v7, v2
	v_lshlrev_b32_e32 v4, 5, v6
	v_ashrrev_i16_sdwa v0, v3, sext(v0) dst_sel:DWORD dst_unused:UNUSED_PAD src0_sel:DWORD src1_sel:BYTE_0
	s_movk_i32 s0, 0x1600
	s_addc_u32 s7, s50, s7
	s_ashr_i32 s8, s9, 2
	v_and_b32_e32 v8, 32, v4
	v_bfe_i32 v9, v0, 0, 16
	v_mul_lo_u32 v0, v2, s0
	s_mul_hi_i32 s9, s8, 0x2c0000
	s_mul_i32 s8, s8, 0x2c0000
	v_or_b32_e32 v0, v0, v8
	s_add_u32 s8, s51, s8
	v_add_lshl_u32 v0, v0, v9, 1
	s_addc_u32 s9, s52, s9
	s_add_i32 s54, s53, 0
	v_lshl_add_u64 v[2:3], s[8:9], 0, v[0:1]
	s_add_i32 m0, s54, 0x10000
	v_lshl_add_u64 v[4:5], v[2:3], 0, s[26:27]
	global_load_lds_dwordx4 v0, s[8:9]
	s_add_i32 m0, s54, 0x12000
	s_add_i32 s55, s54, 0x2000
	global_load_lds_dwordx4 v[4:5], off
	v_lshl_add_u64 v[4:5], s[6:7], 0, v[0:1]
	s_mov_b32 m0, s54
	v_lshl_add_u64 v[12:13], v[4:5], 0, s[26:27]
	global_load_lds_dwordx4 v0, s[6:7]
	s_mov_b32 m0, s55
	s_add_i32 s56, s54, 0x4000
	global_load_lds_dwordx4 v[12:13], off
	v_lshl_add_u64 v[12:13], v[2:3], 0, s[28:29]
	s_add_i32 m0, s54, 0x14000
	s_add_i32 s57, s54, 0x6000
	global_load_lds_dwordx4 v[12:13], off
	v_lshl_add_u64 v[12:13], v[2:3], 0, s[30:31]
	s_add_i32 m0, s54, 0x16000
	s_mov_b64 s[90:91], s[58:59]
	global_load_lds_dwordx4 v[12:13], off
	v_lshl_add_u64 v[12:13], v[4:5], 0, s[28:29]
	s_mov_b32 m0, s56
	s_cmp_lg_u32 s11, 1
	global_load_lds_dwordx4 v[12:13], off
	v_lshl_add_u64 v[12:13], v[4:5], 0, s[30:31]
	s_mov_b32 m0, s57
	s_nop 0
	global_load_lds_dwordx4 v[12:13], off
	s_cbranch_scc1 .LBB0_29
	s_setprio 1
	s_barrier

.LBB0_37:
	s_barrier
	v_mfma_f32_16x16x32_bf16 v[50:53], v[188:191], v[156:159], v[50:53]
	v_mfma_f32_16x16x32_bf16 v[42:45], v[196:199], v[156:159], v[42:45]
	v_mfma_f32_16x16x32_bf16 v[34:37], v[188:191], v[164:167], v[34:37]
	v_mfma_f32_16x16x32_bf16 v[26:29], v[196:199], v[164:167], v[26:29]
	v_mfma_f32_16x16x32_bf16 v[18:21], v[188:191], v[172:175], v[18:21]
	v_mfma_f32_16x16x32_bf16 v[10:13], v[196:199], v[172:175], v[10:13]
	v_mfma_f32_16x16x32_bf16 v[6:9], v[188:191], v[180:183], v[6:9]
	v_mfma_f32_16x16x32_bf16 v[2:5], v[196:199], v[180:183], v[2:5]
	v_mfma_f32_16x16x32_bf16 v[50:53], v[192:195], v[160:163], v[50:53]
	v_mfma_f32_16x16x32_bf16 v[42:45], v[200:203], v[160:163], v[42:45]
	v_mfma_f32_16x16x32_bf16 v[34:37], v[192:195], v[168:171], v[34:37]
	v_mfma_f32_16x16x32_bf16 v[26:29], v[200:203], v[168:171], v[26:29]
	v_mfma_f32_16x16x32_bf16 v[18:21], v[192:195], v[176:179], v[18:21]
	v_mfma_f32_16x16x32_bf16 v[10:13], v[200:203], v[176:179], v[10:13]
	v_mfma_f32_16x16x32_bf16 v[6:9], v[192:195], v[184:187], v[6:9]
	v_mfma_f32_16x16x32_bf16 v[2:5], v[200:203], v[184:187], v[2:5]
	s_barrier
.Lrot_enter_10:
	s_add_u32 s7, s46, 0xffea0080
	s_addc_u32 s78, s47, -1
	s_add_i32 s87, 0, 0x10000
	v_add_u32_e32 v132, s87, v135
	ds_read_b128 v[138:141], v132
	ds_read_b128 v[142:145], v132 offset:1024
	ds_read_b128 v[148:151], v132 offset:2048
	ds_read_b128 v[152:155], v132 offset:3072
	s_cmpk_eq_i32 s6, 0x54
	s_cselect_b32 s79, s43, s78
	s_cselect_b32 s78, s42, s7
	s_cselect_b32 s89, s45, s9
	s_cselect_b32 s88, s44, s8
	v_lshl_add_u64 v[132:133], s[46:47], 0, v[130:131]
	s_add_i32 m0, s54, 0xc000
	ds_read_b128 v[156:159], v136
	ds_read_b128 v[160:163], v136 offset:1024
	ds_read_b128 v[164:167], v136 offset:2048
	ds_read_b128 v[168:171], v136 offset:3072
	ds_read_b128 v[172:175], v136 offset:4096
	ds_read_b128 v[176:179], v136 offset:5120
	ds_read_b128 v[180:183], v136 offset:6144
	ds_read_b128 v[184:187], v136 offset:7168
	global_load_lds_dwordx4 v[132:133], off
	v_lshl_add_u64 v[132:133], v[132:133], 0, s[26:27]
	s_add_i32 m0, s54, 0xe000
	s_nop 0
	global_load_lds_dwordx4 v[132:133], off
	s_waitcnt lgkmcnt(8)
	s_barrier
	s_waitcnt lgkmcnt(0)
	v_mfma_f32_16x16x32_bf16 v[126:129], v[138:141], v[156:159], v[126:129]
	v_mfma_f32_16x16x32_bf16 v[122:125], v[148:151], v[156:159], v[122:125]
	v_mfma_f32_16x16x32_bf16 v[118:121], v[138:141], v[164:167], v[118:121]
	v_mfma_f32_16x16x32_bf16 v[110:113], v[148:151], v[164:167], v[110:113]
	v_mfma_f32_16x16x32_bf16 v[102:105], v[138:141], v[172:175], v[102:105]
	v_mfma_f32_16x16x32_bf16 v[94:97], v[148:151], v[172:175], v[94:97]
	v_mfma_f32_16x16x32_bf16 v[86:89], v[138:141], v[180:183], v[86:89]
	v_mfma_f32_16x16x32_bf16 v[78:81], v[148:151], v[180:183], v[78:81]
	v_mfma_f32_16x16x32_bf16 v[126:129], v[142:145], v[160:163], v[126:129]
	v_mfma_f32_16x16x32_bf16 v[122:125], v[152:155], v[160:163], v[122:125]
	v_mfma_f32_16x16x32_bf16 v[118:121], v[142:145], v[168:171], v[118:121]
	v_mfma_f32_16x16x32_bf16 v[110:113], v[152:155], v[168:171], v[110:113]
	v_mfma_f32_16x16x32_bf16 v[102:105], v[142:145], v[176:179], v[102:105]
	v_mfma_f32_16x16x32_bf16 v[94:97], v[152:155], v[176:179], v[94:97]
	v_mfma_f32_16x16x32_bf16 v[86:89], v[142:145], v[184:187], v[86:89]
	v_mfma_f32_16x16x32_bf16 v[78:81], v[152:155], v[184:187], v[78:81]
	s_barrier
	s_add_i32 s7, 0, 0x14000
	v_add_u32_e32 v132, s7, v135
	s_add_i32 s87, s87, s53
	ds_read_b128 v[188:191], v132
	ds_read_b128 v[192:195], v132 offset:1024
	ds_read_b128 v[196:199], v132 offset:2048
	ds_read_b128 v[200:203], v132 offset:3072
	v_lshl_add_u64 v[132:133], s[88:89], 0, v[0:1]
	s_mov_b32 m0, s87
	v_lshl_add_u64 v[204:205], v[132:133], 0, s[26:27]
	global_load_lds_dwordx4 v[132:133], off
	s_add_i32 m0, s87, 0x2000
	s_nop 0
	global_load_lds_dwordx4 v[204:205], off
	s_barrier
	s_waitcnt lgkmcnt(0)
	v_mfma_f32_16x16x32_bf16 v[114:117], v[188:191], v[156:159], v[114:117]
	v_mfma_f32_16x16x32_bf16 v[106:109], v[196:199], v[156:159], v[106:109]
	v_mfma_f32_16x16x32_bf16 v[98:101], v[188:191], v[164:167], v[98:101]
	v_mfma_f32_16x16x32_bf16 v[90:93], v[196:199], v[164:167], v[90:93]
	v_mfma_f32_16x16x32_bf16 v[82:85], v[188:191], v[172:175], v[82:85]
	v_mfma_f32_16x16x32_bf16 v[74:77], v[196:199], v[172:175], v[74:77]
	v_mfma_f32_16x16x32_bf16 v[70:73], v[188:191], v[180:183], v[70:73]
	v_mfma_f32_16x16x32_bf16 v[66:69], v[196:199], v[180:183], v[66:69]
	v_mfma_f32_16x16x32_bf16 v[114:117], v[192:195], v[160:163], v[114:117]
	v_mfma_f32_16x16x32_bf16 v[106:109], v[200:203], v[160:163], v[106:109]
	v_mfma_f32_16x16x32_bf16 v[98:101], v[192:195], v[168:171], v[98:101]
	v_mfma_f32_16x16x32_bf16 v[90:93], v[200:203], v[168:171], v[90:93]
	v_mfma_f32_16x16x32_bf16 v[82:85], v[192:195], v[176:179], v[82:85]
	v_mfma_f32_16x16x32_bf16 v[74:77], v[200:203], v[176:179], v[74:77]
	v_mfma_f32_16x16x32_bf16 v[70:73], v[192:195], v[184:187], v[70:73]
	v_mfma_f32_16x16x32_bf16 v[66:69], v[200:203], v[184:187], v[66:69]
	s_barrier
	s_mov_b32 m0, s54
	v_lshl_add_u64 v[204:205], s[78:79], 0, v[0:1]
	ds_read_b128 v[156:159], v136 offset:16384
	ds_read_b128 v[160:163], v136 offset:17408
	ds_read_b128 v[164:167], v136 offset:18432
	ds_read_b128 v[168:171], v136 offset:19456
	ds_read_b128 v[172:175], v136 offset:20480
	ds_read_b128 v[176:179], v136 offset:21504
	ds_read_b128 v[180:183], v136 offset:22528
	ds_read_b128 v[184:187], v136 offset:23552
	global_load_lds_dwordx4 v[204:205], off
	v_lshl_add_u64 v[206:207], v[204:205], 0, s[26:27]
	s_mov_b32 m0, s55
	s_nop 0
	global_load_lds_dwordx4 v[206:207], off
	s_barrier
	s_waitcnt lgkmcnt(0)
	v_mfma_f32_16x16x32_bf16 v[62:65], v[138:141], v[156:159], v[62:65]
	v_mfma_f32_16x16x32_bf16 v[58:61], v[148:151], v[156:159], v[58:61]
	v_mfma_f32_16x16x32_bf16 v[54:57], v[138:141], v[164:167], v[54:57]
	v_mfma_f32_16x16x32_bf16 v[46:49], v[148:151], v[164:167], v[46:49]
	v_mfma_f32_16x16x32_bf16 v[38:41], v[138:141], v[172:175], v[38:41]
	v_mfma_f32_16x16x32_bf16 v[30:33], v[148:151], v[172:175], v[30:33]
	v_mfma_f32_16x16x32_bf16 v[22:25], v[138:141], v[180:183], v[22:25]
	v_mfma_f32_16x16x32_bf16 v[14:17], v[148:151], v[180:183], v[14:17]
	v_mfma_f32_16x16x32_bf16 v[62:65], v[142:145], v[160:163], v[62:65]
	v_mfma_f32_16x16x32_bf16 v[58:61], v[152:155], v[160:163], v[58:61]
	v_mfma_f32_16x16x32_bf16 v[54:57], v[142:145], v[168:171], v[54:57]
	v_mfma_f32_16x16x32_bf16 v[46:49], v[152:155], v[168:171], v[46:49]
	v_mfma_f32_16x16x32_bf16 v[38:41], v[142:145], v[176:179], v[38:41]
	v_mfma_f32_16x16x32_bf16 v[30:33], v[152:155], v[176:179], v[30:33]
	v_mfma_f32_16x16x32_bf16 v[22:25], v[142:145], v[184:187], v[22:25]
	v_mfma_f32_16x16x32_bf16 v[14:17], v[152:155], v[184:187], v[14:17]
	s_barrier
	s_add_i32 s7, s7, s53
	v_lshl_add_u64 v[138:139], v[132:133], 0, s[28:29]
	s_mov_b32 m0, s7
	s_nop 0
	global_load_lds_dwordx4 v[138:139], off
	v_lshl_add_u64 v[138:139], v[132:133], 0, s[30:31]
	s_add_i32 m0, s7, 0x2000
	s_nop 0
	global_load_lds_dwordx4 v[138:139], off
	v_lshl_add_u64 v[230:231], v[204:205], 0, s[28:29]
	s_mov_b32 m0, s56
	s_nop 0
	global_load_lds_dwordx4 v[230:231], off
	v_lshl_add_u64 v[230:231], v[204:205], 0, s[30:31]
	s_mov_b32 m0, s57
	s_nop 0
	global_load_lds_dwordx4 v[230:231], off
	s_waitcnt vmcnt(8)
	s_barrier
	v_mfma_f32_16x16x32_bf16 v[50:53], v[188:191], v[156:159], v[50:53]
	v_mfma_f32_16x16x32_bf16 v[42:45], v[196:199], v[156:159], v[42:45]
	v_mfma_f32_16x16x32_bf16 v[34:37], v[188:191], v[164:167], v[34:37]
	v_mfma_f32_16x16x32_bf16 v[26:29], v[196:199], v[164:167], v[26:29]
	v_mfma_f32_16x16x32_bf16 v[18:21], v[188:191], v[172:175], v[18:21]
	v_mfma_f32_16x16x32_bf16 v[10:13], v[196:199], v[172:175], v[10:13]
	v_mfma_f32_16x16x32_bf16 v[6:9], v[188:191], v[180:183], v[6:9]
	v_mfma_f32_16x16x32_bf16 v[2:5], v[196:199], v[180:183], v[2:5]
	v_mfma_f32_16x16x32_bf16 v[50:53], v[192:195], v[160:163], v[50:53]
	v_mfma_f32_16x16x32_bf16 v[42:45], v[200:203], v[160:163], v[42:45]
	v_mfma_f32_16x16x32_bf16 v[34:37], v[192:195], v[168:171], v[34:37]
	v_mfma_f32_16x16x32_bf16 v[26:29], v[200:203], v[168:171], v[26:29]
	v_mfma_f32_16x16x32_bf16 v[18:21], v[192:195], v[176:179], v[18:21]
	v_mfma_f32_16x16x32_bf16 v[10:13], v[200:203], v[176:179], v[10:13]
	v_mfma_f32_16x16x32_bf16 v[6:9], v[192:195], v[184:187], v[6:9]
	v_mfma_f32_16x16x32_bf16 v[2:5], v[200:203], v[184:187], v[2:5]
	s_barrier
	s_add_i32 s7, 0, 0x18000
	v_add_u32_e32 v137, s7, v135
	ds_read_b128 v[138:141], v137
	ds_read_b128 v[142:145], v137 offset:1024
	ds_read_b128 v[148:151], v137 offset:2048
	ds_read_b128 v[152:155], v137 offset:3072
	ds_read_b128 v[156:159], v136 offset:32768
	ds_read_b128 v[160:163], v136 offset:33792
	ds_read_b128 v[164:167], v136 offset:34816
	ds_read_b128 v[168:171], v136 offset:35840
	ds_read_b128 v[172:175], v136 offset:36864
	ds_read_b128 v[176:179], v136 offset:37888
	ds_read_b128 v[180:183], v136 offset:38912
	ds_read_b128 v[184:187], v136 offset:39936
	s_waitcnt lgkmcnt(8)
	s_barrier
	s_waitcnt lgkmcnt(0)
	v_mfma_f32_16x16x32_bf16 v[126:129], v[138:141], v[156:159], v[126:129]
	v_mfma_f32_16x16x32_bf16 v[122:125], v[148:151], v[156:159], v[122:125]
	v_mfma_f32_16x16x32_bf16 v[118:121], v[138:141], v[164:167], v[118:121]
	v_mfma_f32_16x16x32_bf16 v[110:113], v[148:151], v[164:167], v[110:113]
	v_mfma_f32_16x16x32_bf16 v[102:105], v[138:141], v[172:175], v[102:105]
	v_mfma_f32_16x16x32_bf16 v[94:97], v[148:151], v[172:175], v[94:97]
	v_mfma_f32_16x16x32_bf16 v[86:89], v[138:141], v[180:183], v[86:89]
	v_mfma_f32_16x16x32_bf16 v[78:81], v[148:151], v[180:183], v[78:81]
	v_mfma_f32_16x16x32_bf16 v[126:129], v[142:145], v[160:163], v[126:129]
	v_mfma_f32_16x16x32_bf16 v[122:125], v[152:155], v[160:163], v[122:125]
	v_mfma_f32_16x16x32_bf16 v[118:121], v[142:145], v[168:171], v[118:121]
	v_mfma_f32_16x16x32_bf16 v[110:113], v[152:155], v[168:171], v[110:113]
	v_mfma_f32_16x16x32_bf16 v[102:105], v[142:145], v[176:179], v[102:105]
	v_mfma_f32_16x16x32_bf16 v[94:97], v[152:155], v[176:179], v[94:97]
	v_mfma_f32_16x16x32_bf16 v[86:89], v[142:145], v[184:187], v[86:89]
	v_mfma_f32_16x16x32_bf16 v[78:81], v[152:155], v[184:187], v[78:81]
	s_barrier
	s_add_i32 s78, 0, 0x1c000
	s_add_i32 s7, s7, s53
	v_add_u32_e32 v137, s78, v135
	v_lshl_add_u64 v[206:207], v[132:133], 0, s[34:35]
	s_mov_b32 m0, s7
	ds_read_b128 v[188:191], v137
	ds_read_b128 v[192:195], v137 offset:1024
	ds_read_b128 v[196:199], v137 offset:2048
	ds_read_b128 v[200:203], v137 offset:3072
	global_load_lds_dwordx4 v[206:207], off
	v_lshl_add_u64 v[206:207], v[132:133], 0, s[36:37]
	s_add_i32 m0, s7, 0x2000
	s_nop 0
	global_load_lds_dwordx4 v[206:207], off
	s_barrier
	s_waitcnt lgkmcnt(0)
	v_mfma_f32_16x16x32_bf16 v[114:117], v[188:191], v[156:159], v[114:117]
	v_mfma_f32_16x16x32_bf16 v[106:109], v[196:199], v[156:159], v[106:109]
	v_mfma_f32_16x16x32_bf16 v[98:101], v[188:191], v[164:167], v[98:101]
	v_mfma_f32_16x16x32_bf16 v[90:93], v[196:199], v[164:167], v[90:93]
	v_mfma_f32_16x16x32_bf16 v[82:85], v[188:191], v[172:175], v[82:85]
	v_mfma_f32_16x16x32_bf16 v[74:77], v[196:199], v[172:175], v[74:77]
	v_mfma_f32_16x16x32_bf16 v[70:73], v[188:191], v[180:183], v[70:73]
	v_mfma_f32_16x16x32_bf16 v[66:69], v[196:199], v[180:183], v[66:69]
	v_mfma_f32_16x16x32_bf16 v[114:117], v[192:195], v[160:163], v[114:117]
	v_mfma_f32_16x16x32_bf16 v[106:109], v[200:203], v[160:163], v[106:109]
	v_mfma_f32_16x16x32_bf16 v[98:101], v[192:195], v[168:171], v[98:101]
	v_mfma_f32_16x16x32_bf16 v[90:93], v[200:203], v[168:171], v[90:93]
	v_mfma_f32_16x16x32_bf16 v[82:85], v[192:195], v[176:179], v[82:85]
	v_mfma_f32_16x16x32_bf16 v[74:77], v[200:203], v[176:179], v[74:77]
	v_mfma_f32_16x16x32_bf16 v[70:73], v[192:195], v[184:187], v[70:73]
	v_mfma_f32_16x16x32_bf16 v[66:69], v[200:203], v[184:187], v[66:69]
	s_barrier
	s_mov_b32 m0, s62
	v_lshl_add_u64 v[206:207], v[204:205], 0, s[34:35]
	ds_read_b128 v[156:159], v136 offset:49152
	ds_read_b128 v[160:163], v136 offset:50176
	ds_read_b128 v[164:167], v136 offset:51200
	ds_read_b128 v[168:171], v136 offset:52224
	ds_read_b128 v[172:175], v136 offset:53248
	ds_read_b128 v[176:179], v136 offset:54272
	ds_read_b128 v[180:183], v136 offset:55296
	ds_read_b128 v[184:187], v136 offset:56320
	global_load_lds_dwordx4 v[206:207], off
	v_lshl_add_u64 v[204:205], v[204:205], 0, s[36:37]
	s_mov_b32 m0, s63
	s_nop 0
	global_load_lds_dwordx4 v[204:205], off
	s_barrier
	s_waitcnt lgkmcnt(0)
	v_mfma_f32_16x16x32_bf16 v[62:65], v[138:141], v[156:159], v[62:65]
	v_mfma_f32_16x16x32_bf16 v[58:61], v[148:151], v[156:159], v[58:61]
	v_mfma_f32_16x16x32_bf16 v[54:57], v[138:141], v[164:167], v[54:57]
	v_mfma_f32_16x16x32_bf16 v[46:49], v[148:151], v[164:167], v[46:49]
	v_mfma_f32_16x16x32_bf16 v[38:41], v[138:141], v[172:175], v[38:41]
	v_mfma_f32_16x16x32_bf16 v[30:33], v[148:151], v[172:175], v[30:33]
	v_mfma_f32_16x16x32_bf16 v[22:25], v[138:141], v[180:183], v[22:25]
	v_mfma_f32_16x16x32_bf16 v[14:17], v[148:151], v[180:183], v[14:17]
	v_mfma_f32_16x16x32_bf16 v[62:65], v[142:145], v[160:163], v[62:65]
	v_mfma_f32_16x16x32_bf16 v[58:61], v[152:155], v[160:163], v[58:61]
	v_mfma_f32_16x16x32_bf16 v[54:57], v[142:145], v[168:171], v[54:57]
	v_mfma_f32_16x16x32_bf16 v[46:49], v[152:155], v[168:171], v[46:49]
	v_mfma_f32_16x16x32_bf16 v[38:41], v[142:145], v[176:179], v[38:41]
	v_mfma_f32_16x16x32_bf16 v[30:33], v[152:155], v[176:179], v[30:33]
	v_mfma_f32_16x16x32_bf16 v[22:25], v[142:145], v[184:187], v[22:25]
	v_mfma_f32_16x16x32_bf16 v[14:17], v[152:155], v[184:187], v[14:17]
	s_barrier
	s_add_i32 s7, s78, s53
	v_lshl_add_u64 v[138:139], v[132:133], 0, s[18:19]
	s_mov_b32 m0, s7
	v_lshl_add_u64 v[132:133], v[132:133], 0, s[14:15]
	global_load_lds_dwordx4 v[138:139], off
	s_add_i32 m0, s7, 0x2000
	s_nop 0
	global_load_lds_dwordx4 v[132:133], off
	s_waitcnt vmcnt(6)
	s_add_i32 s6, s6, 2
	s_add_u32 s8, s8, 0x100
	s_addc_u32 s9, s9, 0
	s_add_u32 s46, s46, 0x100
	s_addc_u32 s47, s47, 0
	s_cmpk_gt_u32 s6, 0x55
	s_cbranch_scc0 .LBB0_37
	s_barrier
	v_mfma_f32_16x16x32_bf16 v[50:53], v[188:191], v[156:159], v[50:53]
	v_mfma_f32_16x16x32_bf16 v[42:45], v[196:199], v[156:159], v[42:45]
	v_mfma_f32_16x16x32_bf16 v[34:37], v[188:191], v[164:167], v[34:37]
	v_mfma_f32_16x16x32_bf16 v[26:29], v[196:199], v[164:167], v[26:29]
	v_mfma_f32_16x16x32_bf16 v[18:21], v[188:191], v[172:175], v[18:21]
	v_mfma_f32_16x16x32_bf16 v[10:13], v[196:199], v[172:175], v[10:13]
	v_mfma_f32_16x16x32_bf16 v[6:9], v[188:191], v[180:183], v[6:9]
	v_mfma_f32_16x16x32_bf16 v[2:5], v[196:199], v[180:183], v[2:5]
	v_mfma_f32_16x16x32_bf16 v[50:53], v[192:195], v[160:163], v[50:53]
	v_mfma_f32_16x16x32_bf16 v[42:45], v[200:203], v[160:163], v[42:45]
	v_mfma_f32_16x16x32_bf16 v[34:37], v[192:195], v[168:171], v[34:37]
	v_mfma_f32_16x16x32_bf16 v[26:29], v[200:203], v[168:171], v[26:29]
	v_mfma_f32_16x16x32_bf16 v[18:21], v[192:195], v[176:179], v[18:21]
	v_mfma_f32_16x16x32_bf16 v[10:13], v[200:203], v[176:179], v[10:13]
	v_mfma_f32_16x16x32_bf16 v[6:9], v[192:195], v[184:187], v[6:9]
	v_mfma_f32_16x16x32_bf16 v[2:5], v[200:203], v[184:187], v[2:5]
	s_barrier
	v_mov_b32_e32 v137, v134
	s_lshl_b32 s6, s86, 8
	v_ashrrev_i32_e32 v132, 2, v137
	s_or_b32 s6, s6, s59
	v_and_b32_e32 v132, -4, v132
	v_add_u32_e32 v132, s6, v132
	s_lshl_b32 s6, s85, 8
	s_add_i32 s6, s6, s58
	v_and_or_b32 v188, v137, 15, s6
	v_ashrrev_i32_e32 v189, 31, v188
	v_ashrrev_i32_e32 v133, 31, v132
	v_lshlrev_b64 v[206:207], 13, v[188:189]
	v_or_b32_e32 v156, 16, v188
	v_or_b32_e32 v172, 32, v188
	v_or_b32_e32 v188, 48, v188
	v_lshlrev_b64 v[132:133], 2, v[132:133]
	v_ashrrev_i32_e32 v157, 31, v156
	v_ashrrev_i32_e32 v173, 31, v172
	v_ashrrev_i32_e32 v189, 31, v188
	v_lshl_add_u64 v[204:205], s[4:5], 0, v[132:133]
	v_lshlrev_b64 v[208:209], 13, v[156:157]
	v_lshlrev_b64 v[210:211], 13, v[172:173]
	v_lshlrev_b64 v[212:213], 13, v[188:189]
	v_lshl_add_u64 v[152:153], v[204:205], 0, v[206:207]
	v_lshl_add_u64 v[168:169], v[204:205], 0, v[208:209]
	v_lshl_add_u64 v[184:185], v[204:205], 0, v[210:211]
	v_lshl_add_u64 v[200:201], v[204:205], 0, v[212:213]
	global_load_dwordx4 v[138:141], v[152:153], off
	global_load_dwordx4 v[142:145], v[152:153], off offset:64
	global_load_dwordx4 v[148:151], v[152:153], off offset:512
	s_nop 0
	global_load_dwordx4 v[152:155], v[152:153], off offset:576
	s_nop 0
	global_load_dwordx4 v[156:159], v[168:169], off
	global_load_dwordx4 v[160:163], v[168:169], off offset:64
	global_load_dwordx4 v[164:167], v[168:169], off offset:512
	s_nop 0
	global_load_dwordx4 v[168:171], v[168:169], off offset:576
	s_nop 0
	global_load_dwordx4 v[172:175], v[184:185], off
	global_load_dwordx4 v[176:179], v[184:185], off offset:64
	global_load_dwordx4 v[180:183], v[184:185], off offset:512
	s_nop 0
	global_load_dwordx4 v[184:187], v[184:185], off offset:576
	s_nop 0
	global_load_dwordx4 v[188:191], v[200:201], off
	global_load_dwordx4 v[192:195], v[200:201], off offset:64
	global_load_dwordx4 v[196:199], v[200:201], off offset:512
	s_nop 0
	global_load_dwordx4 v[200:203], v[200:201], off offset:576
	s_waitcnt vmcnt(0) lgkmcnt(0)
	v_pk_fma_f32 v[126:127], v[126:127], 0.5, v[138:139] op_sel_hi:[1,0,1]
	v_lshl_add_u64 v[138:139], s[4:5], 0, v[206:207]
	v_lshl_add_u64 v[138:139], v[138:139], 0, v[132:133]
	v_pk_fma_f32 v[116:117], v[116:117], 0.5, v[150:151] op_sel_hi:[1,0,1]
	v_pk_fma_f32 v[114:115], v[114:115], 0.5, v[148:149] op_sel_hi:[1,0,1]
	global_store_dwordx4 v[138:139], v[114:117], off offset:512
	v_pk_fma_f32 v[100:101], v[100:101], 0.5, v[166:167] op_sel_hi:[1,0,1]
	v_pk_fma_f32 v[98:99], v[98:99], 0.5, v[164:165] op_sel_hi:[1,0,1]
	v_lshl_add_u64 v[114:115], s[4:5], 0, v[208:209]
	v_lshl_add_u64 v[114:115], v[114:115], 0, v[132:133]
	global_store_dwordx4 v[114:115], v[98:101], off offset:512
	v_pk_fma_f32 v[84:85], v[84:85], 0.5, v[182:183] op_sel_hi:[1,0,1]
	v_pk_fma_f32 v[82:83], v[82:83], 0.5, v[180:181] op_sel_hi:[1,0,1]
	v_lshl_add_u64 v[98:99], s[4:5], 0, v[210:211]
	v_lshl_add_u64 v[98:99], v[98:99], 0, v[132:133]
	v_pk_fma_f32 v[108:109], v[108:109], 0.5, v[154:155] op_sel_hi:[1,0,1]
	v_pk_fma_f32 v[106:107], v[106:107], 0.5, v[152:153] op_sel_hi:[1,0,1]
	v_pk_fma_f32 v[92:93], v[92:93], 0.5, v[170:171] op_sel_hi:[1,0,1]
	v_pk_fma_f32 v[90:91], v[90:91], 0.5, v[168:169] op_sel_hi:[1,0,1]
	global_store_dwordx4 v[98:99], v[82:85], off offset:512
	v_pk_fma_f32 v[76:77], v[76:77], 0.5, v[186:187] op_sel_hi:[1,0,1]
	v_pk_fma_f32 v[74:75], v[74:75], 0.5, v[184:185] op_sel_hi:[1,0,1]
	v_lshl_add_u64 v[82:83], s[4:5], 0, v[212:213]
	global_store_dwordx4 v[138:139], v[106:109], off offset:576
	global_store_dwordx4 v[114:115], v[90:93], off offset:576
	global_store_dwordx4 v[98:99], v[74:77], off offset:576
	v_pk_fma_f32 v[108:109], v[120:121], 0.5, v[158:159] op_sel_hi:[1,0,1]
	v_pk_fma_f32 v[106:107], v[118:119], 0.5, v[156:157] op_sel_hi:[1,0,1]
	v_pk_fma_f32 v[92:93], v[104:105], 0.5, v[174:175] op_sel_hi:[1,0,1]
	v_pk_fma_f32 v[90:91], v[102:103], 0.5, v[172:173] op_sel_hi:[1,0,1]
	v_pk_fma_f32 v[76:77], v[88:89], 0.5, v[190:191] op_sel_hi:[1,0,1]
	v_pk_fma_f32 v[74:75], v[86:87], 0.5, v[188:189] op_sel_hi:[1,0,1]
	v_lshl_add_u64 v[82:83], v[82:83], 0, v[132:133]
	v_pk_fma_f32 v[128:129], v[128:129], 0.5, v[140:141] op_sel_hi:[1,0,1]
	v_pk_fma_f32 v[124:125], v[124:125], 0.5, v[144:145] op_sel_hi:[1,0,1]
	v_pk_fma_f32 v[122:123], v[122:123], 0.5, v[142:143] op_sel_hi:[1,0,1]
	global_store_dwordx4 v[114:115], v[106:109], off
	global_store_dwordx4 v[98:99], v[90:93], off
	global_store_dwordx4 v[82:83], v[74:77], off
	v_pk_fma_f32 v[108:109], v[112:113], 0.5, v[162:163] op_sel_hi:[1,0,1]
	v_pk_fma_f32 v[106:107], v[110:111], 0.5, v[160:161] op_sel_hi:[1,0,1]
	v_pk_fma_f32 v[92:93], v[96:97], 0.5, v[178:179] op_sel_hi:[1,0,1]
	v_pk_fma_f32 v[90:91], v[94:95], 0.5, v[176:177] op_sel_hi:[1,0,1]
	v_pk_fma_f32 v[76:77], v[80:81], 0.5, v[194:195] op_sel_hi:[1,0,1]
	v_pk_fma_f32 v[74:75], v[78:79], 0.5, v[192:193] op_sel_hi:[1,0,1]
	v_pk_fma_f32 v[72:73], v[72:73], 0.5, v[198:199] op_sel_hi:[1,0,1]
	v_pk_fma_f32 v[70:71], v[70:71], 0.5, v[196:197] op_sel_hi:[1,0,1]
	v_pk_fma_f32 v[68:69], v[68:69], 0.5, v[202:203] op_sel_hi:[1,0,1]
	v_pk_fma_f32 v[66:67], v[66:67], 0.5, v[200:201] op_sel_hi:[1,0,1]
	global_store_dwordx4 v[138:139], v[126:129], off
	global_store_dwordx4 v[138:139], v[122:125], off offset:64
	global_store_dwordx4 v[114:115], v[106:109], off offset:64
	global_store_dwordx4 v[98:99], v[90:93], off offset:64
	global_store_dwordx4 v[82:83], v[74:77], off offset:64
	global_store_dwordx4 v[82:83], v[70:73], off offset:512
	global_store_dwordx4 v[82:83], v[66:69], off offset:576
	s_mov_b64 s[6:7], 0x120000
	v_lshl_add_u64 v[140:141], v[206:207], 0, s[6:7]
	s_mov_b64 s[6:7], 0x140000
	v_lshl_add_u64 v[138:139], v[206:207], 0, s[0:1]
	v_lshl_add_u64 v[142:143], v[206:207], 0, s[6:7]
	v_lshl_add_u64 v[144:145], v[206:207], 0, s[28:29]
	v_lshl_add_u64 v[78:79], v[204:205], 0, v[138:139]
	v_lshl_add_u64 v[94:95], v[204:205], 0, v[140:141]
	v_lshl_add_u64 v[110:111], v[204:205], 0, v[142:143]
	v_lshl_add_u64 v[126:127], v[204:205], 0, v[144:145]
	global_load_dwordx4 v[66:69], v[78:79], off
	global_load_dwordx4 v[70:73], v[78:79], off offset:64
	global_load_dwordx4 v[74:77], v[78:79], off offset:512
	s_nop 0
	global_load_dwordx4 v[78:81], v[78:79], off offset:576
	s_nop 0
	global_load_dwordx4 v[82:85], v[94:95], off
	global_load_dwordx4 v[86:89], v[94:95], off offset:64
	global_load_dwordx4 v[90:93], v[94:95], off offset:512
	s_nop 0
	global_load_dwordx4 v[94:97], v[94:95], off offset:576
	s_nop 0
	global_load_dwordx4 v[98:101], v[110:111], off
	global_load_dwordx4 v[102:105], v[110:111], off offset:64
	global_load_dwordx4 v[106:109], v[110:111], off offset:512
	s_nop 0
	global_load_dwordx4 v[110:113], v[110:111], off offset:576
	s_nop 0
	global_load_dwordx4 v[114:117], v[126:127], off
	global_load_dwordx4 v[118:121], v[126:127], off offset:64
	global_load_dwordx4 v[122:125], v[126:127], off offset:512
	s_nop 0
	global_load_dwordx4 v[126:129], v[126:127], off offset:576
	s_waitcnt vmcnt(0) lgkmcnt(0)
	v_pk_fma_f32 v[62:63], v[62:63], 0.5, v[66:67] op_sel_hi:[1,0,1]
	v_lshl_add_u64 v[66:67], s[4:5], 0, v[138:139]
	v_lshl_add_u64 v[66:67], v[66:67], 0, v[132:133]
	v_pk_fma_f32 v[52:53], v[52:53], 0.5, v[76:77] op_sel_hi:[1,0,1]
	v_pk_fma_f32 v[50:51], v[50:51], 0.5, v[74:75] op_sel_hi:[1,0,1]
	global_store_dwordx4 v[66:67], v[50:53], off offset:512
	v_pk_fma_f32 v[36:37], v[36:37], 0.5, v[92:93] op_sel_hi:[1,0,1]
	v_pk_fma_f32 v[34:35], v[34:35], 0.5, v[90:91] op_sel_hi:[1,0,1]
	v_lshl_add_u64 v[50:51], s[4:5], 0, v[140:141]
	v_lshl_add_u64 v[50:51], v[50:51], 0, v[132:133]
	global_store_dwordx4 v[50:51], v[34:37], off offset:512
	v_pk_fma_f32 v[20:21], v[20:21], 0.5, v[108:109] op_sel_hi:[1,0,1]
	v_pk_fma_f32 v[18:19], v[18:19], 0.5, v[106:107] op_sel_hi:[1,0,1]
	v_lshl_add_u64 v[34:35], s[4:5], 0, v[142:143]
	v_lshl_add_u64 v[34:35], v[34:35], 0, v[132:133]
	v_pk_fma_f32 v[44:45], v[44:45], 0.5, v[80:81] op_sel_hi:[1,0,1]
	v_pk_fma_f32 v[42:43], v[42:43], 0.5, v[78:79] op_sel_hi:[1,0,1]
	v_pk_fma_f32 v[28:29], v[28:29], 0.5, v[96:97] op_sel_hi:[1,0,1]
	v_pk_fma_f32 v[26:27], v[26:27], 0.5, v[94:95] op_sel_hi:[1,0,1]
	global_store_dwordx4 v[34:35], v[18:21], off offset:512
	v_pk_fma_f32 v[12:13], v[12:13], 0.5, v[112:113] op_sel_hi:[1,0,1]
	v_pk_fma_f32 v[10:11], v[10:11], 0.5, v[110:111] op_sel_hi:[1,0,1]
	v_lshl_add_u64 v[18:19], s[4:5], 0, v[144:145]
	global_store_dwordx4 v[66:67], v[42:45], off offset:576
	global_store_dwordx4 v[50:51], v[26:29], off offset:576
	global_store_dwordx4 v[34:35], v[10:13], off offset:576
	v_pk_fma_f32 v[44:45], v[56:57], 0.5, v[84:85] op_sel_hi:[1,0,1]
	v_pk_fma_f32 v[42:43], v[54:55], 0.5, v[82:83] op_sel_hi:[1,0,1]
	v_pk_fma_f32 v[28:29], v[40:41], 0.5, v[100:101] op_sel_hi:[1,0,1]
	v_pk_fma_f32 v[26:27], v[38:39], 0.5, v[98:99] op_sel_hi:[1,0,1]
	v_pk_fma_f32 v[12:13], v[24:25], 0.5, v[116:117] op_sel_hi:[1,0,1]
	v_pk_fma_f32 v[10:11], v[22:23], 0.5, v[114:115] op_sel_hi:[1,0,1]
	v_lshl_add_u64 v[18:19], v[18:19], 0, v[132:133]
	v_pk_fma_f32 v[64:65], v[64:65], 0.5, v[68:69] op_sel_hi:[1,0,1]
	v_pk_fma_f32 v[60:61], v[60:61], 0.5, v[72:73] op_sel_hi:[1,0,1]
	v_pk_fma_f32 v[58:59], v[58:59], 0.5, v[70:71] op_sel_hi:[1,0,1]
	global_store_dwordx4 v[50:51], v[42:45], off
	global_store_dwordx4 v[34:35], v[26:29], off
	global_store_dwordx4 v[18:19], v[10:13], off
	v_pk_fma_f32 v[44:45], v[48:49], 0.5, v[88:89] op_sel_hi:[1,0,1]
	v_pk_fma_f32 v[42:43], v[46:47], 0.5, v[86:87] op_sel_hi:[1,0,1]
	v_pk_fma_f32 v[28:29], v[32:33], 0.5, v[104:105] op_sel_hi:[1,0,1]
	v_pk_fma_f32 v[26:27], v[30:31], 0.5, v[102:103] op_sel_hi:[1,0,1]
	v_pk_fma_f32 v[12:13], v[16:17], 0.5, v[120:121] op_sel_hi:[1,0,1]
	v_pk_fma_f32 v[10:11], v[14:15], 0.5, v[118:119] op_sel_hi:[1,0,1]
	v_pk_fma_f32 v[8:9], v[8:9], 0.5, v[124:125] op_sel_hi:[1,0,1]
	v_pk_fma_f32 v[6:7], v[6:7], 0.5, v[122:123] op_sel_hi:[1,0,1]
	v_pk_fma_f32 v[4:5], v[4:5], 0.5, v[128:129] op_sel_hi:[1,0,1]
	v_pk_fma_f32 v[2:3], v[2:3], 0.5, v[126:127] op_sel_hi:[1,0,1]
	global_store_dwordx4 v[66:67], v[62:65], off
	global_store_dwordx4 v[66:67], v[58:61], off offset:64
	global_store_dwordx4 v[50:51], v[42:45], off offset:64
	global_store_dwordx4 v[34:35], v[26:29], off offset:64
	global_store_dwordx4 v[18:19], v[10:13], off offset:64
	global_store_dwordx4 v[18:19], v[6:9], off offset:512
	global_store_dwordx4 v[18:19], v[2:5], off offset:576
	s_and_b64 vcc, exec, s[40:41]
	s_mov_b32 s85, s10
	s_mov_b32 s86, s11
	s_mov_b64 s[8:9], s[44:45]
	s_mov_b64 s[6:7], s[42:43]
	s_movk_i32 s89, 0x37ff
	s_mov_b32 s88, 0x16000
	s_cbranch_vccz .LBB0_30
	s_waitcnt vmcnt(0)
	s_cmpk_gt_u32 s48, 0xff
	s_cbranch_scc1 .LBB0_41
	s_barrier
.LBB0_41:
	s_setprio 0
	v_readlane_b32 s0, v255, 8
	v_readlane_b32 s62, v255, 10
	v_readlane_b32 s84, v255, 12
	v_readlane_b32 s86, v255, 14
	v_readlane_b32 s56, v255, 16
	v_readlane_b32 s52, v255, 18
	v_readlane_b32 s54, v255, 22
	v_readlane_b32 s44, v255, 26
	v_readlane_b32 s50, v255, 28
	v_readlane_b32 s72, v255, 7
	v_readlane_b32 s1, v255, 9
	s_mov_b64 s[58:59], s[90:91]
	v_readlane_b32 s63, v255, 11
	v_readlane_b32 s85, v255, 13
	v_readlane_b32 s87, v255, 15
	v_readlane_b32 s57, v255, 17
	v_readlane_b32 s53, v255, 19
	v_readlane_b32 s55, v255, 23
	v_readlane_b32 s45, v255, 27
	v_readlane_b32 s51, v255, 29
	s_movk_i32 s91, 0x60
	s_mov_b32 s78, 0x2a000000
	s_mov_b32 s79, 0x3fffe
	s_mov_b32 s90, 0xc0000
	s_barrier

.LBB0_43:
	s_andn2_b64 vcc, exec, s[4:5]
	s_cbranch_vccnz .LBB0_56
	s_mov_b32 s4, -1
	v_readlane_b32 s40, v255, 3
	v_mbcnt_lo_u32_b32 v0, s4, 0
	v_mbcnt_hi_u32_b32 v9, s4, v0
	v_readlane_b32 s4, v254, 4
	s_mov_b32 s11, s72
	v_readlane_b32 s41, v255, 4
	v_add_u32_e32 v0, s4, v9
	v_readlane_b32 s42, v255, 5
	v_readlane_b32 s43, v255, 6
	s_mov_b64 s[4:5], s[42:43]
	s_mov_b64 s[6:7], s[40:41]
	s_cmpk_gt_i32 s11, 0xaff
	v_readfirstlane_b32 s22, v0
	s_cbranch_scc1 .LBB0_56
	v_bfe_i32 v3, v0, 27, 1
	v_lshlrev_b32_e32 v2, 4, v0
	v_lshrrev_b32_e32 v3, 22, v3
	v_add_u32_e32 v3, v2, v3
	v_and_b32_e32 v3, 0xfffffc00, v3
	s_add_u32 s50, s4, 0x4600000
	v_sub_u32_e32 v2, v2, v3
	s_addc_u32 s51, s5, 0
	v_lshrrev_b32_e32 v3, 4, v2
	v_ashrrev_i32_e32 v4, 31, v0
	s_add_u32 s52, s4, 0xc800000
	v_bitop3_b32 v2, v3, v2, 32 bitop3:0x6c
	v_lshrrev_b32_e32 v4, 26, v4
	s_addc_u32 s53, s5, 0
	v_ashrrev_i32_e32 v3, 31, v2
	v_add_u32_e32 v0, v0, v4
	s_ashr_i32 s6, s11, 31
	v_lshrrev_b32_e32 v3, 26, v3
	v_ashrrev_i32_e32 v7, 6, v0
	s_lshr_b32 s6, s6, 29
	v_add_u32_e32 v3, v2, v3
	v_lshlrev_b32_e32 v0, 3, v7
	s_add_i32 s6, s11, s6
	s_ashr_i32 s40, s22, 6
	v_ashrrev_i32_e32 v6, 6, v3
	v_and_b32_e32 v0, -16, v0
	s_ashr_i32 s7, s6, 3
	s_and_b32 s6, s6, -8
	s_ashr_i32 s41, s22, 8
	s_lshl_b32 s54, s40, 10
	v_add_u32_e32 v4, v6, v0
	v_and_b32_e32 v0, 3, v6
	s_mov_b32 s0, 0xfffe0
	s_sub_i32 s6, s11, s6
	v_and_or_b32 v0, v4, s0, v0
	s_cmp_lt_i32 s6, 0
	s_movk_i32 s0, 0x161
	s_cselect_b32 s8, s0, 0x160
	s_mul_i32 s6, s8, s6
	s_add_i32 s6, s6, s7
	s_mul_hi_i32 s7, s6, 0x2e8ba2e9
	s_lshr_b32 s8, s7, 31
	s_ashr_i32 s7, s7, 6
	s_add_i32 s7, s7, s8
	s_lshl_b32 s8, s7, 3
	s_mulk_i32 s7, 0x160
	s_sub_i32 s6, s6, s7
	s_bfe_u32 s7, s6, 0x3001c
	s_add_i32 s7, s6, s7
	s_sext_i32_i16 s9, s7
	s_and_b32 s7, s7, 0xfff8
	s_sub_i32 s6, s6, s7
	s_sext_i32_i16 s6, s6
	s_add_i32 s48, s8, s6
	s_ashr_i32 s49, s48, 31
	v_lshrrev_b32_e32 v5, 2, v4
	v_lshlrev_b32_e32 v8, 1, v4
	v_and_b32_e32 v3, 0xc0, v3
	s_lshr_b32 s10, s9, 3
	s_lshl_b64 s[6:7], s[48:49], 20
	v_and_b32_e32 v5, 4, v5
	v_and_b32_e32 v8, 24, v8
	v_sub_u32_e32 v2, v2, v3
	v_mov_b32_e32 v3, 1
	s_add_u32 s6, s50, s6
	v_or3_b32 v0, v0, v5, v8
	v_lshlrev_b32_e32 v5, 5, v7
	v_ashrrev_i16_sdwa v2, v3, sext(v2) dst_sel:DWORD dst_unused:UNUSED_PAD src0_sel:DWORD src1_sel:BYTE_0
	s_addc_u32 s7, s51, s7
	s_bfe_i64 s[8:9], s[10:11], 0x100000
	v_and_b32_e32 v5, 32, v5
	v_bfe_i32 v8, v2, 0, 16
	s_lshl_b64 s[8:9], s[8:9], 20
	v_add_lshl_u32 v2, v5, v8, 1
	s_add_u32 s8, s52, s8
	v_lshl_add_u32 v0, v0, 12, v2
	s_addc_u32 s9, s53, s9
	s_add_i32 s49, s54, 0
	v_lshl_add_u32 v130, v4, 12, v2
	v_lshl_add_u64 v[2:3], s[8:9], 0, v[0:1]
	s_add_i32 m0, s49, 0x10000
	v_lshl_add_u64 v[4:5], v[2:3], 0, s[60:61]
	global_load_lds_dwordx4 v0, s[8:9]
	s_add_i32 m0, s49, 0x12000
	v_mov_b32_e32 v131, v1
	global_load_lds_dwordx4 v[4:5], off
	v_lshl_add_u64 v[4:5], s[6:7], 0, v[130:131]
	s_mov_b32 m0, s49
	s_add_i32 s55, s49, 0x2000
	global_load_lds_dwordx4 v130, s[6:7]
	v_lshl_add_u64 v[10:11], v[4:5], 0, s[60:61]
	s_mov_b32 m0, s55
	s_add_i32 s56, s49, 0x4000
	global_load_lds_dwordx4 v[10:11], off
	v_lshl_add_u64 v[10:11], v[2:3], 0, s[20:21]
	s_add_i32 m0, s49, 0x14000
	s_add_i32 s57, s49, 0x6000
	global_load_lds_dwordx4 v[10:11], off
	v_lshl_add_u64 v[10:11], v[2:3], 0, s[64:65]
	s_add_i32 m0, s49, 0x16000
	s_mov_b64 s[92:93], s[58:59]
	global_load_lds_dwordx4 v[10:11], off
	v_lshl_add_u64 v[10:11], v[4:5], 0, s[20:21]
	s_mov_b32 m0, s56
	s_cmp_lg_u32 s41, 1
	global_load_lds_dwordx4 v[10:11], off
	v_lshl_add_u64 v[10:11], v[4:5], 0, s[64:65]
	s_mov_b32 m0, s57
	s_nop 0
	global_load_lds_dwordx4 v[10:11], off
	s_cbranch_scc1 .LBB0_47
	s_setprio 1
	s_barrier

.LBB0_51:
	s_barrier
	v_mfma_f32_16x16x32_bf16 v[58:61], v[192:195], v[160:163], v[58:61]
	v_mfma_f32_16x16x32_bf16 v[50:53], v[200:203], v[160:163], v[50:53]
	v_mfma_f32_16x16x32_bf16 v[42:45], v[192:195], v[168:171], v[42:45]
	v_mfma_f32_16x16x32_bf16 v[34:37], v[200:203], v[168:171], v[34:37]
	v_mfma_f32_16x16x32_bf16 v[26:29], v[192:195], v[176:179], v[26:29]
	v_mfma_f32_16x16x32_bf16 v[18:21], v[200:203], v[176:179], v[18:21]
	v_mfma_f32_16x16x32_bf16 v[10:13], v[192:195], v[184:187], v[10:13]
	v_mfma_f32_16x16x32_bf16 v[2:5], v[200:203], v[184:187], v[2:5]
	v_mfma_f32_16x16x32_bf16 v[58:61], v[196:199], v[164:167], v[58:61]
	v_mfma_f32_16x16x32_bf16 v[50:53], v[204:207], v[164:167], v[50:53]
	v_mfma_f32_16x16x32_bf16 v[42:45], v[196:199], v[172:175], v[42:45]
	v_mfma_f32_16x16x32_bf16 v[34:37], v[204:207], v[172:175], v[34:37]
	v_mfma_f32_16x16x32_bf16 v[26:29], v[196:199], v[180:183], v[26:29]
	v_mfma_f32_16x16x32_bf16 v[18:21], v[204:207], v[180:183], v[18:21]
	v_mfma_f32_16x16x32_bf16 v[10:13], v[196:199], v[188:191], v[10:13]
	v_mfma_f32_16x16x32_bf16 v[2:5], v[204:207], v[188:191], v[2:5]
	s_barrier
.Lrot_enter_9:
	s_add_u32 s8, s6, 0x100
	s_addc_u32 s9, s7, 0
	s_add_i32 s90, 0, 0x10000
	v_add_u32_e32 v134, s90, v137
	ds_read_b128 v[140:143], v134
	ds_read_b128 v[148:151], v134 offset:1024
	ds_read_b128 v[152:155], v134 offset:2048
	ds_read_b128 v[156:159], v134 offset:3072
	s_cmp_eq_u32 s87, 28
	s_cselect_b32 s79, s43, s9
	s_cselect_b32 s78, s42, s8
	s_cselect_b32 s89, s47, s86
	s_cselect_b32 s88, s46, s41
	v_lshl_add_u64 v[134:135], s[6:7], 0, v[132:133]
	v_lshl_add_u64 v[144:145], v[134:135], 0, s[16:17]
	s_add_i32 m0, s49, 0xc000
	ds_read_b128 v[160:163], v138
	ds_read_b128 v[164:167], v138 offset:1024
	ds_read_b128 v[168:171], v138 offset:2048
	ds_read_b128 v[172:175], v138 offset:3072
	ds_read_b128 v[176:179], v138 offset:4096
	ds_read_b128 v[180:183], v138 offset:5120
	ds_read_b128 v[184:187], v138 offset:6144
	ds_read_b128 v[188:191], v138 offset:7168
	global_load_lds_dwordx4 v[144:145], off
	v_lshl_add_u64 v[134:135], v[134:135], 0, s[80:81]
	s_add_i32 m0, s49, 0xe000
	s_nop 0
	global_load_lds_dwordx4 v[134:135], off
	s_waitcnt lgkmcnt(8)
	s_barrier
	s_waitcnt lgkmcnt(0)
	v_mfma_f32_16x16x32_bf16 v[126:129], v[140:143], v[160:163], v[126:129]
	v_mfma_f32_16x16x32_bf16 v[118:121], v[152:155], v[160:163], v[118:121]
	v_mfma_f32_16x16x32_bf16 v[110:113], v[140:143], v[168:171], v[110:113]
	v_mfma_f32_16x16x32_bf16 v[102:105], v[152:155], v[168:171], v[102:105]
	v_mfma_f32_16x16x32_bf16 v[94:97], v[140:143], v[176:179], v[94:97]
	v_mfma_f32_16x16x32_bf16 v[86:89], v[152:155], v[176:179], v[86:89]
	v_mfma_f32_16x16x32_bf16 v[78:81], v[140:143], v[184:187], v[78:81]
	v_mfma_f32_16x16x32_bf16 v[70:73], v[152:155], v[184:187], v[70:73]
	v_mfma_f32_16x16x32_bf16 v[126:129], v[148:151], v[164:167], v[126:129]
	v_mfma_f32_16x16x32_bf16 v[118:121], v[156:159], v[164:167], v[118:121]
	v_mfma_f32_16x16x32_bf16 v[110:113], v[148:151], v[172:175], v[110:113]
	v_mfma_f32_16x16x32_bf16 v[102:105], v[156:159], v[172:175], v[102:105]
	v_mfma_f32_16x16x32_bf16 v[94:97], v[148:151], v[180:183], v[94:97]
	v_mfma_f32_16x16x32_bf16 v[86:89], v[156:159], v[180:183], v[86:89]
	v_mfma_f32_16x16x32_bf16 v[78:81], v[148:151], v[188:191], v[78:81]
	v_mfma_f32_16x16x32_bf16 v[70:73], v[156:159], v[188:191], v[70:73]
	s_barrier
	s_add_i32 s6, 0, 0x14000
	v_add_u32_e32 v134, s6, v137
	s_add_i32 s7, s90, s54
	ds_read_b128 v[192:195], v134
	ds_read_b128 v[196:199], v134 offset:1024
	ds_read_b128 v[200:203], v134 offset:2048
	ds_read_b128 v[204:207], v134 offset:3072
	v_lshl_add_u64 v[134:135], s[88:89], 0, v[0:1]
	s_mov_b32 m0, s7
	v_lshl_add_u64 v[144:145], v[134:135], 0, s[60:61]
	global_load_lds_dwordx4 v[134:135], off
	s_add_i32 m0, s7, 0x2000
	s_nop 0
	global_load_lds_dwordx4 v[144:145], off
	s_barrier
	s_waitcnt lgkmcnt(0)
	v_mfma_f32_16x16x32_bf16 v[122:125], v[192:195], v[160:163], v[122:125]
	v_mfma_f32_16x16x32_bf16 v[114:117], v[200:203], v[160:163], v[114:117]
	v_mfma_f32_16x16x32_bf16 v[106:109], v[192:195], v[168:171], v[106:109]
	v_mfma_f32_16x16x32_bf16 v[98:101], v[200:203], v[168:171], v[98:101]
	v_mfma_f32_16x16x32_bf16 v[90:93], v[192:195], v[176:179], v[90:93]
	v_mfma_f32_16x16x32_bf16 v[82:85], v[200:203], v[176:179], v[82:85]
	v_mfma_f32_16x16x32_bf16 v[74:77], v[192:195], v[184:187], v[74:77]
	v_mfma_f32_16x16x32_bf16 v[66:69], v[200:203], v[184:187], v[66:69]
	v_mfma_f32_16x16x32_bf16 v[122:125], v[196:199], v[164:167], v[122:125]
	v_mfma_f32_16x16x32_bf16 v[114:117], v[204:207], v[164:167], v[114:117]
	v_mfma_f32_16x16x32_bf16 v[106:109], v[196:199], v[172:175], v[106:109]
	v_mfma_f32_16x16x32_bf16 v[98:101], v[204:207], v[172:175], v[98:101]
	v_mfma_f32_16x16x32_bf16 v[90:93], v[196:199], v[180:183], v[90:93]
	v_mfma_f32_16x16x32_bf16 v[82:85], v[204:207], v[180:183], v[82:85]
	v_mfma_f32_16x16x32_bf16 v[74:77], v[196:199], v[188:191], v[74:77]
	v_mfma_f32_16x16x32_bf16 v[66:69], v[204:207], v[188:191], v[66:69]
	s_barrier
	s_mov_b32 m0, s49
	v_lshl_add_u64 v[144:145], s[78:79], 0, v[130:131]
	ds_read_b128 v[160:163], v138 offset:16384
	ds_read_b128 v[164:167], v138 offset:17408
	ds_read_b128 v[168:171], v138 offset:18432
	ds_read_b128 v[172:175], v138 offset:19456
	ds_read_b128 v[176:179], v138 offset:20480
	ds_read_b128 v[180:183], v138 offset:21504
	ds_read_b128 v[184:187], v138 offset:22528
	ds_read_b128 v[188:191], v138 offset:23552
	global_load_lds_dwordx4 v[144:145], off
	v_lshl_add_u64 v[208:209], v[144:145], 0, s[60:61]
	s_mov_b32 m0, s55
	s_nop 0
	global_load_lds_dwordx4 v[208:209], off
	s_barrier
	s_waitcnt lgkmcnt(0)
	v_mfma_f32_16x16x32_bf16 v[62:65], v[140:143], v[160:163], v[62:65]
	v_mfma_f32_16x16x32_bf16 v[54:57], v[152:155], v[160:163], v[54:57]
	v_mfma_f32_16x16x32_bf16 v[46:49], v[140:143], v[168:171], v[46:49]
	v_mfma_f32_16x16x32_bf16 v[38:41], v[152:155], v[168:171], v[38:41]
	v_mfma_f32_16x16x32_bf16 v[30:33], v[140:143], v[176:179], v[30:33]
	v_mfma_f32_16x16x32_bf16 v[22:25], v[152:155], v[176:179], v[22:25]
	v_mfma_f32_16x16x32_bf16 v[14:17], v[140:143], v[184:187], v[14:17]
	v_mfma_f32_16x16x32_bf16 v[6:9], v[152:155], v[184:187], v[6:9]
	v_mfma_f32_16x16x32_bf16 v[62:65], v[148:151], v[164:167], v[62:65]
	v_mfma_f32_16x16x32_bf16 v[54:57], v[156:159], v[164:167], v[54:57]
	v_mfma_f32_16x16x32_bf16 v[46:49], v[148:151], v[172:175], v[46:49]
	v_mfma_f32_16x16x32_bf16 v[38:41], v[156:159], v[172:175], v[38:41]
	v_mfma_f32_16x16x32_bf16 v[30:33], v[148:151], v[180:183], v[30:33]
	v_mfma_f32_16x16x32_bf16 v[22:25], v[156:159], v[180:183], v[22:25]
	v_mfma_f32_16x16x32_bf16 v[14:17], v[148:151], v[188:191], v[14:17]
	v_mfma_f32_16x16x32_bf16 v[6:9], v[156:159], v[188:191], v[6:9]
	s_barrier
	s_add_i32 s6, s6, s54
	v_lshl_add_u64 v[140:141], v[134:135], 0, s[20:21]
	s_mov_b32 m0, s6
	s_nop 0
	global_load_lds_dwordx4 v[140:141], off
	v_lshl_add_u64 v[140:141], v[134:135], 0, s[64:65]
	s_add_i32 m0, s6, 0x2000
	s_nop 0
	global_load_lds_dwordx4 v[140:141], off
	v_lshl_add_u64 v[230:231], v[144:145], 0, s[20:21]
	s_mov_b32 m0, s56
	s_nop 0
	global_load_lds_dwordx4 v[230:231], off
	v_lshl_add_u64 v[230:231], v[144:145], 0, s[64:65]
	s_mov_b32 m0, s57
	s_nop 0
	global_load_lds_dwordx4 v[230:231], off
	s_waitcnt vmcnt(8)
	s_barrier
	v_mfma_f32_16x16x32_bf16 v[58:61], v[192:195], v[160:163], v[58:61]
	v_mfma_f32_16x16x32_bf16 v[50:53], v[200:203], v[160:163], v[50:53]
	v_mfma_f32_16x16x32_bf16 v[42:45], v[192:195], v[168:171], v[42:45]
	v_mfma_f32_16x16x32_bf16 v[34:37], v[200:203], v[168:171], v[34:37]
	v_mfma_f32_16x16x32_bf16 v[26:29], v[192:195], v[176:179], v[26:29]
	v_mfma_f32_16x16x32_bf16 v[18:21], v[200:203], v[176:179], v[18:21]
	v_mfma_f32_16x16x32_bf16 v[10:13], v[192:195], v[184:187], v[10:13]
	v_mfma_f32_16x16x32_bf16 v[2:5], v[200:203], v[184:187], v[2:5]
	v_mfma_f32_16x16x32_bf16 v[58:61], v[196:199], v[164:167], v[58:61]
	v_mfma_f32_16x16x32_bf16 v[50:53], v[204:207], v[164:167], v[50:53]
	v_mfma_f32_16x16x32_bf16 v[42:45], v[196:199], v[172:175], v[42:45]
	v_mfma_f32_16x16x32_bf16 v[34:37], v[204:207], v[172:175], v[34:37]
	v_mfma_f32_16x16x32_bf16 v[26:29], v[196:199], v[180:183], v[26:29]
	v_mfma_f32_16x16x32_bf16 v[18:21], v[204:207], v[180:183], v[18:21]
	v_mfma_f32_16x16x32_bf16 v[10:13], v[196:199], v[188:191], v[10:13]
	v_mfma_f32_16x16x32_bf16 v[2:5], v[204:207], v[188:191], v[2:5]
	s_barrier
	s_add_i32 s6, 0, 0x18000
	v_add_u32_e32 v139, s6, v137
	ds_read_b128 v[140:143], v139
	ds_read_b128 v[148:151], v139 offset:1024
	ds_read_b128 v[152:155], v139 offset:2048
	ds_read_b128 v[156:159], v139 offset:3072
	ds_read_b128 v[160:163], v138 offset:32768
	ds_read_b128 v[164:167], v138 offset:33792
	ds_read_b128 v[168:171], v138 offset:34816
	ds_read_b128 v[172:175], v138 offset:35840
	ds_read_b128 v[176:179], v138 offset:36864
	ds_read_b128 v[180:183], v138 offset:37888
	ds_read_b128 v[184:187], v138 offset:38912
	ds_read_b128 v[188:191], v138 offset:39936
	s_waitcnt lgkmcnt(8)
	s_barrier
	s_waitcnt lgkmcnt(0)
	v_mfma_f32_16x16x32_bf16 v[126:129], v[140:143], v[160:163], v[126:129]
	v_mfma_f32_16x16x32_bf16 v[118:121], v[152:155], v[160:163], v[118:121]
	v_mfma_f32_16x16x32_bf16 v[110:113], v[140:143], v[168:171], v[110:113]
	v_mfma_f32_16x16x32_bf16 v[102:105], v[152:155], v[168:171], v[102:105]
	v_mfma_f32_16x16x32_bf16 v[94:97], v[140:143], v[176:179], v[94:97]
	v_mfma_f32_16x16x32_bf16 v[86:89], v[152:155], v[176:179], v[86:89]
	v_mfma_f32_16x16x32_bf16 v[78:81], v[140:143], v[184:187], v[78:81]
	v_mfma_f32_16x16x32_bf16 v[70:73], v[152:155], v[184:187], v[70:73]
	v_mfma_f32_16x16x32_bf16 v[126:129], v[148:151], v[164:167], v[126:129]
	v_mfma_f32_16x16x32_bf16 v[118:121], v[156:159], v[164:167], v[118:121]
	v_mfma_f32_16x16x32_bf16 v[110:113], v[148:151], v[172:175], v[110:113]
	v_mfma_f32_16x16x32_bf16 v[102:105], v[156:159], v[172:175], v[102:105]
	v_mfma_f32_16x16x32_bf16 v[94:97], v[148:151], v[180:183], v[94:97]
	v_mfma_f32_16x16x32_bf16 v[86:89], v[156:159], v[180:183], v[86:89]
	v_mfma_f32_16x16x32_bf16 v[78:81], v[148:151], v[188:191], v[78:81]
	v_mfma_f32_16x16x32_bf16 v[70:73], v[156:159], v[188:191], v[70:73]
	s_barrier
	s_add_i32 s7, 0, 0x1c000
	s_add_i32 s6, s6, s54
	v_add_u32_e32 v139, s7, v137
	v_lshl_add_u64 v[208:209], v[134:135], 0, s[34:35]
	s_mov_b32 m0, s6
	ds_read_b128 v[192:195], v139
	ds_read_b128 v[196:199], v139 offset:1024
	ds_read_b128 v[200:203], v139 offset:2048
	ds_read_b128 v[204:207], v139 offset:3072
	global_load_lds_dwordx4 v[208:209], off
	v_lshl_add_u64 v[208:209], v[134:135], 0, s[66:67]
	s_add_i32 m0, s6, 0x2000
	s_nop 0
	global_load_lds_dwordx4 v[208:209], off
	s_barrier
	s_waitcnt lgkmcnt(0)
	v_mfma_f32_16x16x32_bf16 v[122:125], v[192:195], v[160:163], v[122:125]
	v_mfma_f32_16x16x32_bf16 v[114:117], v[200:203], v[160:163], v[114:117]
	v_mfma_f32_16x16x32_bf16 v[106:109], v[192:195], v[168:171], v[106:109]
	v_mfma_f32_16x16x32_bf16 v[98:101], v[200:203], v[168:171], v[98:101]
	v_mfma_f32_16x16x32_bf16 v[90:93], v[192:195], v[176:179], v[90:93]
	v_mfma_f32_16x16x32_bf16 v[82:85], v[200:203], v[176:179], v[82:85]
	v_mfma_f32_16x16x32_bf16 v[74:77], v[192:195], v[184:187], v[74:77]
	v_mfma_f32_16x16x32_bf16 v[66:69], v[200:203], v[184:187], v[66:69]
	v_mfma_f32_16x16x32_bf16 v[122:125], v[196:199], v[164:167], v[122:125]
	v_mfma_f32_16x16x32_bf16 v[114:117], v[204:207], v[164:167], v[114:117]
	v_mfma_f32_16x16x32_bf16 v[106:109], v[196:199], v[172:175], v[106:109]
	v_mfma_f32_16x16x32_bf16 v[98:101], v[204:207], v[172:175], v[98:101]
	v_mfma_f32_16x16x32_bf16 v[90:93], v[196:199], v[180:183], v[90:93]
	v_mfma_f32_16x16x32_bf16 v[82:85], v[204:207], v[180:183], v[82:85]
	v_mfma_f32_16x16x32_bf16 v[74:77], v[196:199], v[188:191], v[74:77]
	v_mfma_f32_16x16x32_bf16 v[66:69], v[204:207], v[188:191], v[66:69]
	s_barrier
	s_mov_b32 m0, s59
	v_lshl_add_u64 v[208:209], v[144:145], 0, s[34:35]
	ds_read_b128 v[160:163], v138 offset:49152
	ds_read_b128 v[164:167], v138 offset:50176
	ds_read_b128 v[168:171], v138 offset:51200
	ds_read_b128 v[172:175], v138 offset:52224
	ds_read_b128 v[176:179], v138 offset:53248
	ds_read_b128 v[180:183], v138 offset:54272
	ds_read_b128 v[184:187], v138 offset:55296
	ds_read_b128 v[188:191], v138 offset:56320
	global_load_lds_dwordx4 v[208:209], off
	v_lshl_add_u64 v[144:145], v[144:145], 0, s[66:67]
	s_mov_b32 m0, s62
	s_nop 0
	global_load_lds_dwordx4 v[144:145], off
	s_barrier
	s_waitcnt lgkmcnt(0)
	v_mfma_f32_16x16x32_bf16 v[62:65], v[140:143], v[160:163], v[62:65]
	v_mfma_f32_16x16x32_bf16 v[54:57], v[152:155], v[160:163], v[54:57]
	v_mfma_f32_16x16x32_bf16 v[46:49], v[140:143], v[168:171], v[46:49]
	v_mfma_f32_16x16x32_bf16 v[38:41], v[152:155], v[168:171], v[38:41]
	v_mfma_f32_16x16x32_bf16 v[30:33], v[140:143], v[176:179], v[30:33]
	v_mfma_f32_16x16x32_bf16 v[22:25], v[152:155], v[176:179], v[22:25]
	v_mfma_f32_16x16x32_bf16 v[14:17], v[140:143], v[184:187], v[14:17]
	v_mfma_f32_16x16x32_bf16 v[6:9], v[152:155], v[184:187], v[6:9]
	v_mfma_f32_16x16x32_bf16 v[62:65], v[148:151], v[164:167], v[62:65]
	v_mfma_f32_16x16x32_bf16 v[54:57], v[156:159], v[164:167], v[54:57]
	v_mfma_f32_16x16x32_bf16 v[46:49], v[148:151], v[172:175], v[46:49]
	v_mfma_f32_16x16x32_bf16 v[38:41], v[156:159], v[172:175], v[38:41]
	v_mfma_f32_16x16x32_bf16 v[30:33], v[148:151], v[180:183], v[30:33]
	v_mfma_f32_16x16x32_bf16 v[22:25], v[156:159], v[180:183], v[22:25]
	v_mfma_f32_16x16x32_bf16 v[14:17], v[148:151], v[188:191], v[14:17]
	v_mfma_f32_16x16x32_bf16 v[6:9], v[156:159], v[188:191], v[6:9]
	s_barrier
	s_add_i32 s6, s7, s54
	v_lshl_add_u64 v[140:141], v[134:135], 0, s[16:17]
	s_mov_b32 m0, s6
	v_lshl_add_u64 v[134:135], v[134:135], 0, s[80:81]
	global_load_lds_dwordx4 v[140:141], off
	s_add_i32 m0, s6, 0x2000
	s_nop 0
	global_load_lds_dwordx4 v[134:135], off
	s_waitcnt vmcnt(6)
	s_add_i32 s87, s87, 2
	s_add_u32 s41, s41, 0x100
	s_addc_u32 s86, s86, 0
	s_cmp_gt_u32 s87, 29
	s_mov_b64 s[6:7], s[8:9]
	s_cbranch_scc0 .LBB0_51
	s_barrier
	v_mfma_f32_16x16x32_bf16 v[58:61], v[192:195], v[160:163], v[58:61]
	v_mfma_f32_16x16x32_bf16 v[50:53], v[200:203], v[160:163], v[50:53]
	v_mfma_f32_16x16x32_bf16 v[42:45], v[192:195], v[168:171], v[42:45]
	v_mfma_f32_16x16x32_bf16 v[34:37], v[200:203], v[168:171], v[34:37]
	v_mfma_f32_16x16x32_bf16 v[26:29], v[192:195], v[176:179], v[26:29]
	v_mfma_f32_16x16x32_bf16 v[18:21], v[200:203], v[176:179], v[18:21]
	v_mfma_f32_16x16x32_bf16 v[10:13], v[192:195], v[184:187], v[10:13]
	v_mfma_f32_16x16x32_bf16 v[2:5], v[200:203], v[184:187], v[2:5]
	v_mfma_f32_16x16x32_bf16 v[58:61], v[196:199], v[164:167], v[58:61]
	v_mfma_f32_16x16x32_bf16 v[50:53], v[204:207], v[164:167], v[50:53]
	v_mfma_f32_16x16x32_bf16 v[42:45], v[196:199], v[172:175], v[42:45]
	v_mfma_f32_16x16x32_bf16 v[34:37], v[204:207], v[172:175], v[34:37]
	v_mfma_f32_16x16x32_bf16 v[26:29], v[196:199], v[180:183], v[26:29]
	v_mfma_f32_16x16x32_bf16 v[18:21], v[204:207], v[180:183], v[18:21]
	v_mfma_f32_16x16x32_bf16 v[10:13], v[196:199], v[188:191], v[10:13]
	v_mfma_f32_16x16x32_bf16 v[2:5], v[204:207], v[188:191], v[2:5]
	s_barrier
	v_mul_f32_e32 v144, 0xbfb8aa3b, v126
	v_exp_f32_e32 v144, v144
	v_mov_b32_e32 v134, v136
	s_lshl_b32 s6, s48, 8
	v_add_f32_e32 v144, 1.0, v144
	v_rcp_f32_e32 v144, v144
	s_add_i32 s6, s6, s10
	v_and_or_b32 v139, v134, 15, s6
	s_lshl_b32 s6, s85, 7
	v_mul_f32_e32 v126, v126, v144
	v_mul_f32_e32 v122, v126, v122
	v_mul_f32_e32 v126, 0xbfb8aa3b, v127
	v_exp_f32_e32 v126, v126
	v_ashrrev_i32_e32 v134, 1, v134
	s_or_b32 s6, s6, s58
	v_and_b32_e32 v134, -8, v134
	v_add_f32_e32 v126, 1.0, v126
	v_rcp_f32_e32 v126, v126
	v_add_u32_e32 v140, s6, v134
	v_ashrrev_i32_e32 v141, 31, v140
	v_mov_b64_e32 v[134:135], s[4:5]
	v_mul_f32_e32 v126, v127, v126
	v_mul_f32_e32 v123, v126, v123
	v_mul_f32_e32 v126, 0xbfb8aa3b, v128
	v_exp_f32_e32 v126, v126
	v_mad_i64_i32 v[142:143], s[6:7], v139, s74, v[134:135]
	s_and_b64 vcc, exec, s[44:45]
	v_add_f32_e32 v126, 1.0, v126
	v_rcp_f32_e32 v126, v126
	s_mov_b32 s48, s40
	s_mov_b32 s85, s84
	s_mov_b64 s[8:9], s[46:47]
	v_mul_f32_e32 v126, v128, v126
	v_mul_f32_e32 v124, v126, v124
	v_mul_f32_e32 v126, 0xbfb8aa3b, v129
	v_exp_f32_e32 v126, v126
	s_nop 0
	v_add_f32_e32 v126, 1.0, v126
	v_rcp_f32_e32 v126, v126
	s_nop 0
	v_mul_f32_e32 v126, v129, v126
	v_mul_f32_e32 v125, v126, v125
	v_mul_f32_e32 v126, 0xbfb8aa3b, v118
	v_exp_f32_e32 v126, v126
	s_nop 0
	v_add_f32_e32 v126, 1.0, v126
	v_rcp_f32_e32 v126, v126
	s_nop 0
	v_mul_f32_e32 v118, v118, v126
	v_mul_f32_e32 v118, v118, v114
	v_mul_f32_e32 v114, 0xbfb8aa3b, v119
	v_exp_f32_e32 v114, v114
	s_nop 0
	v_add_f32_e32 v114, 1.0, v114
	v_rcp_f32_e32 v114, v114
	s_nop 0
	v_mul_f32_e32 v114, v119, v114
	v_mul_f32_e32 v119, v114, v115
	v_mul_f32_e32 v114, 0xbfb8aa3b, v120
	v_exp_f32_e32 v114, v114
	s_nop 0
	v_add_f32_e32 v114, 1.0, v114
	v_rcp_f32_e32 v114, v114
	s_nop 0
	v_mul_f32_e32 v114, v120, v114
	v_mul_f32_e32 v126, v114, v116
	v_mul_f32_e32 v114, 0xbfb8aa3b, v121
	v_exp_f32_e32 v114, v114
	v_cvt_pk_bf16_f32 v116, v122, v123
	s_nop 0
	v_add_f32_e32 v114, 1.0, v114
	v_rcp_f32_e32 v114, v114
	s_nop 0
	v_mul_f32_e32 v114, v121, v114
	v_mul_f32_e32 v127, v114, v117
	v_lshlrev_b64 v[114:115], 1, v[140:141]
	v_lshl_add_u64 v[120:121], v[142:143], 0, v[114:115]
	v_cvt_pk_bf16_f32 v117, v124, v125
	v_cvt_pk_bf16_f32 v118, v118, v119
	v_cvt_pk_bf16_f32 v119, v126, v127
	global_store_dwordx4 v[120:121], v[116:119], off
	s_nop 1
	v_mul_f32_e32 v118, 0xbfb8aa3b, v110
	v_exp_f32_e32 v118, v118
	v_or_b32_e32 v116, 16, v139
	v_mad_i64_i32 v[116:117], s[6:7], v116, s74, v[134:135]
	v_add_f32_e32 v118, 1.0, v118
	v_rcp_f32_e32 v118, v118
	s_nop 0
	v_mul_f32_e32 v110, v110, v118
	v_mul_f32_e32 v106, v110, v106
	v_mul_f32_e32 v110, 0xbfb8aa3b, v111
	v_exp_f32_e32 v110, v110
	s_nop 0
	v_add_f32_e32 v110, 1.0, v110
	v_rcp_f32_e32 v110, v110
	s_nop 0
	v_mul_f32_e32 v110, v111, v110
	v_mul_f32_e32 v107, v110, v107
	v_mul_f32_e32 v110, 0xbfb8aa3b, v112
	v_exp_f32_e32 v110, v110
	s_nop 0
	v_add_f32_e32 v110, 1.0, v110
	v_rcp_f32_e32 v110, v110
	s_nop 0
	v_mul_f32_e32 v110, v112, v110
	v_mul_f32_e32 v108, v110, v108
	v_mul_f32_e32 v110, 0xbfb8aa3b, v113
	v_exp_f32_e32 v110, v110
	s_nop 0
	v_add_f32_e32 v110, 1.0, v110
	v_rcp_f32_e32 v110, v110
	s_nop 0
	v_mul_f32_e32 v110, v113, v110
	v_mul_f32_e32 v109, v110, v109
	v_mul_f32_e32 v110, 0xbfb8aa3b, v102
	v_exp_f32_e32 v110, v110
	s_nop 0
	v_add_f32_e32 v110, 1.0, v110
	v_rcp_f32_e32 v110, v110
	s_nop 0
	v_mul_f32_e32 v102, v102, v110
	v_mul_f32_e32 v110, v102, v98
	v_mul_f32_e32 v98, 0xbfb8aa3b, v103
	v_exp_f32_e32 v98, v98
	s_nop 0
	v_add_f32_e32 v98, 1.0, v98
	v_rcp_f32_e32 v98, v98
	s_nop 0
	v_mul_f32_e32 v98, v103, v98
	v_mul_f32_e32 v111, v98, v99
	v_mul_f32_e32 v98, 0xbfb8aa3b, v104
	v_exp_f32_e32 v98, v98
	v_lshl_add_u64 v[102:103], v[116:117], 0, v[114:115]
	v_add_f32_e32 v98, 1.0, v98
	v_rcp_f32_e32 v98, v98
	s_nop 0
	v_mul_f32_e32 v98, v104, v98
	v_mul_f32_e32 v104, v98, v100
	v_mul_f32_e32 v98, 0xbfb8aa3b, v105
	v_exp_f32_e32 v98, v98
	s_nop 0
	v_add_f32_e32 v98, 1.0, v98
	v_rcp_f32_e32 v98, v98
	s_nop 0
	v_mul_f32_e32 v98, v105, v98
	v_mul_f32_e32 v101, v98, v101
	v_cvt_pk_bf16_f32 v98, v106, v107
	v_cvt_pk_bf16_f32 v99, v108, v109
	v_cvt_pk_bf16_f32 v100, v110, v111
	v_cvt_pk_bf16_f32 v101, v104, v101
	global_store_dwordx4 v[102:103], v[98:101], off
	s_nop 1
	v_mul_f32_e32 v100, 0xbfb8aa3b, v94
	v_exp_f32_e32 v100, v100
	v_or_b32_e32 v98, 32, v139
	v_mad_i64_i32 v[98:99], s[6:7], v98, s74, v[134:135]
	v_add_f32_e32 v100, 1.0, v100
	v_rcp_f32_e32 v100, v100
	s_nop 0
	v_mul_f32_e32 v94, v94, v100
	v_mul_f32_e32 v90, v94, v90
	v_mul_f32_e32 v94, 0xbfb8aa3b, v95
	v_exp_f32_e32 v94, v94
	s_nop 0
	v_add_f32_e32 v94, 1.0, v94
	v_rcp_f32_e32 v94, v94
	s_nop 0
	v_mul_f32_e32 v94, v95, v94
	v_mul_f32_e32 v91, v94, v91
	v_mul_f32_e32 v94, 0xbfb8aa3b, v96
	v_exp_f32_e32 v94, v94
	s_nop 0
	v_add_f32_e32 v94, 1.0, v94
	v_rcp_f32_e32 v94, v94
	s_nop 0
	v_mul_f32_e32 v94, v96, v94
	v_mul_f32_e32 v92, v94, v92
	v_mul_f32_e32 v94, 0xbfb8aa3b, v97
	v_exp_f32_e32 v94, v94
	s_nop 0
	v_add_f32_e32 v94, 1.0, v94
	v_rcp_f32_e32 v94, v94
	s_nop 0
	v_mul_f32_e32 v94, v97, v94
	v_mul_f32_e32 v93, v94, v93
	v_mul_f32_e32 v94, 0xbfb8aa3b, v86
	v_exp_f32_e32 v94, v94
	s_nop 0
	v_add_f32_e32 v94, 1.0, v94
	v_rcp_f32_e32 v94, v94
	s_nop 0
	v_mul_f32_e32 v86, v86, v94
	v_mul_f32_e32 v94, v86, v82
	v_mul_f32_e32 v82, 0xbfb8aa3b, v87
	v_exp_f32_e32 v82, v82
	s_nop 0
	v_add_f32_e32 v82, 1.0, v82
	v_rcp_f32_e32 v82, v82
	s_nop 0
	v_mul_f32_e32 v82, v87, v82
	v_mul_f32_e32 v95, v82, v83
	v_mul_f32_e32 v82, 0xbfb8aa3b, v88
	v_exp_f32_e32 v82, v82
	v_lshl_add_u64 v[86:87], v[98:99], 0, v[114:115]
	v_add_f32_e32 v82, 1.0, v82
	v_rcp_f32_e32 v82, v82
	s_nop 0
	v_mul_f32_e32 v82, v88, v82
	v_mul_f32_e32 v88, v82, v84
	v_mul_f32_e32 v82, 0xbfb8aa3b, v89
	v_exp_f32_e32 v82, v82
	s_nop 0
	v_add_f32_e32 v82, 1.0, v82
	v_rcp_f32_e32 v82, v82
	s_nop 0
	v_mul_f32_e32 v82, v89, v82
	v_mul_f32_e32 v85, v82, v85
	v_cvt_pk_bf16_f32 v82, v90, v91
	v_cvt_pk_bf16_f32 v83, v92, v93
	v_cvt_pk_bf16_f32 v84, v94, v95
	v_cvt_pk_bf16_f32 v85, v88, v85
	global_store_dwordx4 v[86:87], v[82:85], off
	s_nop 1
	v_mul_f32_e32 v84, 0xbfb8aa3b, v78
	v_exp_f32_e32 v84, v84
	v_or_b32_e32 v82, 48, v139
	v_mad_i64_i32 v[82:83], s[6:7], v82, s74, v[134:135]
	v_add_f32_e32 v84, 1.0, v84
	v_rcp_f32_e32 v84, v84
	s_nop 0
	v_mul_f32_e32 v78, v78, v84
	v_mul_f32_e32 v74, v78, v74
	v_mul_f32_e32 v78, 0xbfb8aa3b, v79
	v_exp_f32_e32 v78, v78
	s_nop 0
	v_add_f32_e32 v78, 1.0, v78
	v_rcp_f32_e32 v78, v78
	s_nop 0
	v_mul_f32_e32 v78, v79, v78
	v_mul_f32_e32 v75, v78, v75
	v_mul_f32_e32 v78, 0xbfb8aa3b, v80
	v_exp_f32_e32 v78, v78
	s_nop 0
	v_add_f32_e32 v78, 1.0, v78
	v_rcp_f32_e32 v78, v78
	s_nop 0
	v_mul_f32_e32 v78, v80, v78
	v_mul_f32_e32 v76, v78, v76
	v_mul_f32_e32 v78, 0xbfb8aa3b, v81
	v_exp_f32_e32 v78, v78
	s_nop 0
	v_add_f32_e32 v78, 1.0, v78
	v_rcp_f32_e32 v78, v78
	s_nop 0
	v_mul_f32_e32 v78, v81, v78
	v_mul_f32_e32 v77, v78, v77
	v_mul_f32_e32 v78, 0xbfb8aa3b, v70
	v_exp_f32_e32 v78, v78
	s_nop 0
	v_add_f32_e32 v78, 1.0, v78
	v_rcp_f32_e32 v78, v78
	s_nop 0
	v_mul_f32_e32 v70, v70, v78
	v_mul_f32_e32 v78, v70, v66
	v_mul_f32_e32 v66, 0xbfb8aa3b, v71
	v_exp_f32_e32 v66, v66
	s_nop 0
	v_add_f32_e32 v66, 1.0, v66
	v_rcp_f32_e32 v66, v66
	s_nop 0
	v_mul_f32_e32 v66, v71, v66
	v_mul_f32_e32 v79, v66, v67
	v_mul_f32_e32 v66, 0xbfb8aa3b, v72
	v_exp_f32_e32 v66, v66
	v_lshl_add_u64 v[70:71], v[82:83], 0, v[114:115]
	v_add_f32_e32 v66, 1.0, v66
	v_rcp_f32_e32 v66, v66
	s_nop 0
	v_mul_f32_e32 v66, v72, v66
	v_mul_f32_e32 v72, v66, v68
	v_mul_f32_e32 v66, 0xbfb8aa3b, v73
	v_exp_f32_e32 v66, v66
	s_nop 0
	v_add_f32_e32 v66, 1.0, v66
	v_rcp_f32_e32 v66, v66
	s_nop 0
	v_mul_f32_e32 v66, v73, v66
	v_mul_f32_e32 v69, v66, v69
	v_cvt_pk_bf16_f32 v66, v74, v75
	v_cvt_pk_bf16_f32 v67, v76, v77
	v_cvt_pk_bf16_f32 v68, v78, v79
	v_cvt_pk_bf16_f32 v69, v72, v69
	global_store_dwordx4 v[70:71], v[66:69], off
	s_nop 1
	v_mul_f32_e32 v68, 0xbfb8aa3b, v62
	v_exp_f32_e32 v68, v68
	v_add_u32_e32 v66, 0x80, v139
	v_mad_i64_i32 v[66:67], s[6:7], v66, s74, v[134:135]
	v_add_f32_e32 v68, 1.0, v68
	v_rcp_f32_e32 v68, v68
	s_nop 0
	v_mul_f32_e32 v62, v62, v68
	v_mul_f32_e32 v58, v62, v58
	v_mul_f32_e32 v62, 0xbfb8aa3b, v63
	v_exp_f32_e32 v62, v62
	s_nop 0
	v_add_f32_e32 v62, 1.0, v62
	v_rcp_f32_e32 v62, v62
	s_nop 0
	v_mul_f32_e32 v62, v63, v62
	v_mul_f32_e32 v59, v62, v59
	v_mul_f32_e32 v62, 0xbfb8aa3b, v64
	v_exp_f32_e32 v62, v62
	s_nop 0
	v_add_f32_e32 v62, 1.0, v62
	v_rcp_f32_e32 v62, v62
	s_nop 0
	v_mul_f32_e32 v62, v64, v62
	v_mul_f32_e32 v60, v62, v60
	v_mul_f32_e32 v62, 0xbfb8aa3b, v65
	v_exp_f32_e32 v62, v62
	s_nop 0
	v_add_f32_e32 v62, 1.0, v62
	v_rcp_f32_e32 v62, v62
	s_nop 0
	v_mul_f32_e32 v62, v65, v62
	v_mul_f32_e32 v61, v62, v61
	v_mul_f32_e32 v62, 0xbfb8aa3b, v54
	v_exp_f32_e32 v62, v62
	s_nop 0
	v_add_f32_e32 v62, 1.0, v62
	v_rcp_f32_e32 v62, v62
	s_nop 0
	v_mul_f32_e32 v54, v54, v62
	v_mul_f32_e32 v62, v54, v50
	v_mul_f32_e32 v50, 0xbfb8aa3b, v55
	v_exp_f32_e32 v50, v50
	s_nop 0
	v_add_f32_e32 v50, 1.0, v50
	v_rcp_f32_e32 v50, v50
	s_nop 0
	v_mul_f32_e32 v50, v55, v50
	v_mul_f32_e32 v63, v50, v51
	v_mul_f32_e32 v50, 0xbfb8aa3b, v56
	v_exp_f32_e32 v50, v50
	v_lshl_add_u64 v[54:55], v[66:67], 0, v[114:115]
	v_add_f32_e32 v50, 1.0, v50
	v_rcp_f32_e32 v50, v50
	s_nop 0
	v_mul_f32_e32 v50, v56, v50
	v_mul_f32_e32 v56, v50, v52
	v_mul_f32_e32 v50, 0xbfb8aa3b, v57
	v_exp_f32_e32 v50, v50
	s_nop 0
	v_add_f32_e32 v50, 1.0, v50
	v_rcp_f32_e32 v50, v50
	s_nop 0
	v_mul_f32_e32 v50, v57, v50
	v_mul_f32_e32 v53, v50, v53
	v_cvt_pk_bf16_f32 v50, v58, v59
	v_cvt_pk_bf16_f32 v51, v60, v61
	v_cvt_pk_bf16_f32 v52, v62, v63
	v_cvt_pk_bf16_f32 v53, v56, v53
	global_store_dwordx4 v[54:55], v[50:53], off
	s_nop 1
	v_mul_f32_e32 v52, 0xbfb8aa3b, v46
	v_exp_f32_e32 v52, v52
	v_add_u32_e32 v50, 0x90, v139
	v_mad_i64_i32 v[50:51], s[6:7], v50, s74, v[134:135]
	v_add_f32_e32 v52, 1.0, v52
	v_rcp_f32_e32 v52, v52
	s_nop 0
	v_mul_f32_e32 v46, v46, v52
	v_mul_f32_e32 v42, v46, v42
	v_mul_f32_e32 v46, 0xbfb8aa3b, v47
	v_exp_f32_e32 v46, v46
	s_nop 0
	v_add_f32_e32 v46, 1.0, v46
	v_rcp_f32_e32 v46, v46
	s_nop 0
	v_mul_f32_e32 v46, v47, v46
	v_mul_f32_e32 v43, v46, v43
	v_mul_f32_e32 v46, 0xbfb8aa3b, v48
	v_exp_f32_e32 v46, v46
	s_nop 0
	v_add_f32_e32 v46, 1.0, v46
	v_rcp_f32_e32 v46, v46
	s_nop 0
	v_mul_f32_e32 v46, v48, v46
	v_mul_f32_e32 v44, v46, v44
	v_mul_f32_e32 v46, 0xbfb8aa3b, v49
	v_exp_f32_e32 v46, v46
	s_nop 0
	v_add_f32_e32 v46, 1.0, v46
	v_rcp_f32_e32 v46, v46
	s_nop 0
	v_mul_f32_e32 v46, v49, v46
	v_mul_f32_e32 v45, v46, v45
	v_mul_f32_e32 v46, 0xbfb8aa3b, v38
	v_exp_f32_e32 v46, v46
	s_nop 0
	v_add_f32_e32 v46, 1.0, v46
	v_rcp_f32_e32 v46, v46
	s_nop 0
	v_mul_f32_e32 v38, v38, v46
	v_mul_f32_e32 v46, v38, v34
	v_mul_f32_e32 v34, 0xbfb8aa3b, v39
	v_exp_f32_e32 v34, v34
	s_nop 0
	v_add_f32_e32 v34, 1.0, v34
	v_rcp_f32_e32 v34, v34
	s_nop 0
	v_mul_f32_e32 v34, v39, v34
	v_mul_f32_e32 v47, v34, v35
	v_mul_f32_e32 v34, 0xbfb8aa3b, v40
	v_exp_f32_e32 v34, v34
	v_lshl_add_u64 v[38:39], v[50:51], 0, v[114:115]
	v_add_f32_e32 v34, 1.0, v34
	v_rcp_f32_e32 v34, v34
	s_nop 0
	v_mul_f32_e32 v34, v40, v34
	v_mul_f32_e32 v40, v34, v36
	v_mul_f32_e32 v34, 0xbfb8aa3b, v41
	v_exp_f32_e32 v34, v34
	s_nop 0
	v_add_f32_e32 v34, 1.0, v34
	v_rcp_f32_e32 v34, v34
	s_nop 0
	v_mul_f32_e32 v34, v41, v34
	v_mul_f32_e32 v37, v34, v37
	v_cvt_pk_bf16_f32 v34, v42, v43
	v_cvt_pk_bf16_f32 v35, v44, v45
	v_cvt_pk_bf16_f32 v36, v46, v47
	v_cvt_pk_bf16_f32 v37, v40, v37
	global_store_dwordx4 v[38:39], v[34:37], off
	s_nop 1
	v_mul_f32_e32 v36, 0xbfb8aa3b, v30
	v_exp_f32_e32 v36, v36
	v_add_u32_e32 v34, 0xa0, v139
	v_mad_i64_i32 v[34:35], s[6:7], v34, s74, v[134:135]
	v_add_f32_e32 v36, 1.0, v36
	v_rcp_f32_e32 v36, v36
	s_nop 0
	v_mul_f32_e32 v30, v30, v36
	v_mul_f32_e32 v26, v30, v26
	v_mul_f32_e32 v30, 0xbfb8aa3b, v31
	v_exp_f32_e32 v30, v30
	s_nop 0
	v_add_f32_e32 v30, 1.0, v30
	v_rcp_f32_e32 v30, v30
	s_nop 0
	v_mul_f32_e32 v30, v31, v30
	v_mul_f32_e32 v27, v30, v27
	v_mul_f32_e32 v30, 0xbfb8aa3b, v32
	v_exp_f32_e32 v30, v30
	s_nop 0
	v_add_f32_e32 v30, 1.0, v30
	v_rcp_f32_e32 v30, v30
	s_nop 0
	v_mul_f32_e32 v30, v32, v30
	v_mul_f32_e32 v28, v30, v28
	v_mul_f32_e32 v30, 0xbfb8aa3b, v33
	v_exp_f32_e32 v30, v30
	s_nop 0
	v_add_f32_e32 v30, 1.0, v30
	v_rcp_f32_e32 v30, v30
	s_nop 0
	v_mul_f32_e32 v30, v33, v30
	v_mul_f32_e32 v29, v30, v29
	v_mul_f32_e32 v30, 0xbfb8aa3b, v22
	v_exp_f32_e32 v30, v30
	s_nop 0
	v_add_f32_e32 v30, 1.0, v30
	v_rcp_f32_e32 v30, v30
	s_nop 0
	v_mul_f32_e32 v22, v22, v30
	v_mul_f32_e32 v30, v22, v18
	v_mul_f32_e32 v18, 0xbfb8aa3b, v23
	v_exp_f32_e32 v18, v18
	s_nop 0
	v_add_f32_e32 v18, 1.0, v18
	v_rcp_f32_e32 v18, v18
	s_nop 0
	v_mul_f32_e32 v18, v23, v18
	v_mul_f32_e32 v31, v18, v19
	v_mul_f32_e32 v18, 0xbfb8aa3b, v24
	v_exp_f32_e32 v18, v18
	v_lshl_add_u64 v[22:23], v[34:35], 0, v[114:115]
	v_add_f32_e32 v18, 1.0, v18
	v_rcp_f32_e32 v18, v18
	s_nop 0
	v_mul_f32_e32 v18, v24, v18
	v_mul_f32_e32 v24, v18, v20
	v_mul_f32_e32 v18, 0xbfb8aa3b, v25
	v_exp_f32_e32 v18, v18
	s_nop 0
	v_add_f32_e32 v18, 1.0, v18
	v_rcp_f32_e32 v18, v18
	s_nop 0
	v_mul_f32_e32 v18, v25, v18
	v_mul_f32_e32 v21, v18, v21
	v_cvt_pk_bf16_f32 v18, v26, v27
	v_cvt_pk_bf16_f32 v19, v28, v29
	v_cvt_pk_bf16_f32 v20, v30, v31
	v_cvt_pk_bf16_f32 v21, v24, v21
	global_store_dwordx4 v[22:23], v[18:21], off
	s_nop 1
	v_mul_f32_e32 v20, 0xbfb8aa3b, v14
	v_exp_f32_e32 v20, v20
	v_add_u32_e32 v18, 0xb0, v139
	v_mad_i64_i32 v[18:19], s[6:7], v18, s74, v[134:135]
	v_add_f32_e32 v20, 1.0, v20
	v_rcp_f32_e32 v20, v20
	s_mov_b64 s[6:7], s[42:43]
	v_mul_f32_e32 v14, v14, v20
	v_mul_f32_e32 v10, v14, v10
	v_mul_f32_e32 v14, 0xbfb8aa3b, v15
	v_exp_f32_e32 v14, v14
	s_nop 0
	v_add_f32_e32 v14, 1.0, v14
	v_rcp_f32_e32 v14, v14
	s_nop 0
	v_mul_f32_e32 v14, v15, v14
	v_mul_f32_e32 v11, v14, v11
	v_mul_f32_e32 v14, 0xbfb8aa3b, v16
	v_exp_f32_e32 v14, v14
	s_nop 0
	v_add_f32_e32 v14, 1.0, v14
	v_rcp_f32_e32 v14, v14
	s_nop 0
	v_mul_f32_e32 v14, v16, v14
	v_mul_f32_e32 v12, v14, v12
	v_mul_f32_e32 v14, 0xbfb8aa3b, v17
	v_exp_f32_e32 v14, v14
	s_nop 0
	v_add_f32_e32 v14, 1.0, v14
	v_rcp_f32_e32 v14, v14
	s_nop 0
	v_mul_f32_e32 v14, v17, v14
	v_mul_f32_e32 v13, v14, v13
	v_mul_f32_e32 v14, 0xbfb8aa3b, v6
	v_exp_f32_e32 v14, v14
	s_nop 0
	v_add_f32_e32 v14, 1.0, v14
	v_rcp_f32_e32 v14, v14
	s_nop 0
	v_mul_f32_e32 v6, v6, v14
	v_mul_f32_e32 v14, v6, v2
	v_mul_f32_e32 v2, 0xbfb8aa3b, v7
	v_exp_f32_e32 v2, v2
	s_nop 0
	v_add_f32_e32 v2, 1.0, v2
	v_rcp_f32_e32 v2, v2
	s_nop 0
	v_mul_f32_e32 v2, v7, v2
	v_mul_f32_e32 v15, v2, v3
	v_mul_f32_e32 v2, 0xbfb8aa3b, v8
	v_exp_f32_e32 v2, v2
	v_lshl_add_u64 v[6:7], v[18:19], 0, v[114:115]
	v_add_f32_e32 v2, 1.0, v2
	v_rcp_f32_e32 v2, v2
	s_nop 0
	v_mul_f32_e32 v2, v8, v2
	v_mul_f32_e32 v8, v2, v4
	v_mul_f32_e32 v2, 0xbfb8aa3b, v9
	v_exp_f32_e32 v2, v2
	s_nop 0
	v_add_f32_e32 v2, 1.0, v2
	v_rcp_f32_e32 v2, v2
	s_nop 0
	v_mul_f32_e32 v2, v9, v2
	v_mul_f32_e32 v5, v2, v5
	v_cvt_pk_bf16_f32 v2, v10, v11
	v_cvt_pk_bf16_f32 v3, v12, v13
	v_cvt_pk_bf16_f32 v4, v14, v15
	v_cvt_pk_bf16_f32 v5, v8, v5
	global_store_dwordx4 v[6:7], v[2:5], off
	s_cbranch_vccz .LBB0_48
	s_waitcnt vmcnt(0)
	v_readlane_b32 s0, v255, 8
	v_readlane_b32 s62, v255, 10
	v_readlane_b32 s84, v255, 12
	s_cmpk_gt_u32 s22, 0xff
	v_readlane_b32 s1, v255, 9
	s_mov_b64 s[58:59], s[92:93]
	v_readlane_b32 s63, v255, 11
	v_readlane_b32 s85, v255, 13
	s_cbranch_scc1 .LBB0_55
	s_barrier
.LBB0_55:
	s_setprio 0
	v_readlane_b32 s86, v255, 14
	v_readlane_b32 s56, v255, 16
	v_readlane_b32 s52, v255, 18
	v_readlane_b32 s54, v255, 22
	v_readlane_b32 s44, v255, 26
	v_readlane_b32 s50, v255, 28
	v_readlane_b32 s72, v255, 7
	v_readlane_b32 s87, v255, 15
	v_readlane_b32 s57, v255, 17
	v_readlane_b32 s53, v255, 19
	v_readlane_b32 s55, v255, 23
	v_readlane_b32 s45, v255, 27
	v_readlane_b32 s51, v255, 29
	s_movk_i32 s92, 0x4000
	s_movk_i32 s93, 0xf800
	s_movk_i32 s89, 0x37ff
	s_mov_b32 s88, 0x16000
	s_mov_b32 s78, 0x2a000000
	s_mov_b32 s79, 0x3fffe
	s_mov_b32 s90, 0xc0000
	s_barrier

.LBB0_87:
	s_add_u32 s53, s6, 0x18600000
	s_addc_u32 s54, s7, 0
	s_add_u32 s55, s6, 0x1800000
	s_addc_u32 s56, s7, 0
	s_add_i32 s6, s10, s8
	s_ashr_i32 s7, s6, 31
	v_ashrrev_i32_e32 v3, 31, v0
	s_lshr_b32 s7, s7, 27
	v_lshrrev_b32_e32 v3, 26, v3
	s_add_i32 s7, s6, s7
	v_lshlrev_b32_e32 v2, 4, v0
	v_add_u32_e32 v3, v0, v3
	v_bfe_i32 v0, v0, 27, 1
	s_ashr_i32 s8, s7, 5
	s_and_b32 s7, s7, 0xffe0
	v_lshrrev_b32_e32 v0, 22, v0
	s_sub_i32 s6, s6, s7
	v_add_u32_e32 v0, v2, v0
	s_bfe_i32 s7, s6, 0x80000
	v_and_b32_e32 v0, 0xfffffc00, v0
	s_bfe_u32 s7, s7, 0x2000d
	v_sub_u32_e32 v0, v2, v0
	s_add_i32 s7, s6, s7
	v_lshrrev_b32_e32 v2, 4, v0
	s_bfe_i32 s9, s7, 0x80000
	s_and_b32 s7, s7, 0xfc
	v_bitop3_b32 v0, v2, v0, 32 bitop3:0x6c
	s_sub_i32 s6, s6, s7
	v_ashrrev_i32_e32 v6, 6, v3
	v_ashrrev_i32_e32 v3, 31, v0
	s_lshl_b32 s8, s8, 2
	s_sext_i32_i8 s6, s6
	v_lshrrev_b32_e32 v3, 26, v3
	s_add_i32 s48, s8, s6
	s_ashr_i32 s11, s52, 6
	v_add_u32_e32 v3, v0, v3
	s_sext_i32_i16 s9, s9
	s_ashr_i32 s49, s48, 31
	s_ashr_i32 s40, s52, 8
	v_ashrrev_i32_e32 v7, 6, v3
	v_and_b32_e32 v3, 0xc0, v3
	s_lshl_b32 s57, s11, 10
	s_lshr_b32 s10, s9, 2
	s_lshl_b64 s[6:7], s[48:49], 20
	v_sub_u32_e32 v0, v0, v3
	v_mov_b32_e32 v3, 1
	s_add_u32 s6, s53, s6
	v_lshlrev_b32_e32 v2, 3, v6
	v_lshlrev_b32_e32 v4, 5, v6
	v_ashrrev_i16_sdwa v0, v3, sext(v0) dst_sel:DWORD dst_unused:UNUSED_PAD src0_sel:DWORD src1_sel:BYTE_0
	s_addc_u32 s7, s54, s7
	s_bfe_i64 s[8:9], s[10:11], 0x100000
	v_and_b32_e32 v2, 0xffff0, v2
	v_and_b32_e32 v4, 32, v4
	v_bfe_i32 v8, v0, 0, 16
	s_lshl_b64 s[8:9], s[8:9], 20
	v_add_u32_e32 v0, v4, v8
	v_add_lshl_u32 v2, v7, v2, 12
	s_add_u32 s8, s55, s8
	v_lshl_add_u32 v0, v0, 1, v2
	s_addc_u32 s9, s56, s9
	s_add_i32 s49, s57, 0
	v_lshl_add_u64 v[2:3], s[8:9], 0, v[0:1]
	s_add_i32 m0, s49, 0x10000
	v_lshl_add_u64 v[4:5], v[2:3], 0, s[60:61]
	global_load_lds_dwordx4 v0, s[8:9]
	s_add_i32 m0, s49, 0x12000
	s_add_i32 s58, s49, 0x2000
	global_load_lds_dwordx4 v[4:5], off
	v_lshl_add_u64 v[4:5], s[6:7], 0, v[0:1]
	s_mov_b32 m0, s49
	v_lshl_add_u64 v[10:11], v[4:5], 0, s[60:61]
	global_load_lds_dwordx4 v0, s[6:7]
	s_mov_b32 m0, s58
	s_add_i32 s59, s49, 0x4000
	global_load_lds_dwordx4 v[10:11], off
	v_lshl_add_u64 v[10:11], v[2:3], 0, s[20:21]
	s_add_i32 m0, s49, 0x14000
	s_add_i32 s62, s49, 0x6000
	global_load_lds_dwordx4 v[10:11], off
	v_lshl_add_u64 v[10:11], v[2:3], 0, s[64:65]
	s_add_i32 m0, s49, 0x16000
	s_cmp_lg_u32 s40, 1
	global_load_lds_dwordx4 v[10:11], off
	v_lshl_add_u64 v[10:11], v[4:5], 0, s[20:21]
	s_mov_b32 m0, s59
	s_nop 0
	global_load_lds_dwordx4 v[10:11], off
	v_lshl_add_u64 v[10:11], v[4:5], 0, s[64:65]
	s_mov_b32 m0, s62
	s_nop 0
	global_load_lds_dwordx4 v[10:11], off
	s_cbranch_scc1 .LBB0_89
	s_setprio 1
	s_barrier

.Lrot_enter_8:
	s_add_u32 s7, s50, 0xfff80080
	s_addc_u32 s11, s51, -1
	s_add_i32 s43, 0, 0x10000
	v_add_u32_e32 v132, s43, v135
	ds_read_b128 v[138:141], v132
	ds_read_b128 v[142:145], v132 offset:1024
	ds_read_b128 v[148:151], v132 offset:2048
	ds_read_b128 v[152:155], v132 offset:3072
	s_cmp_eq_u32 s6, 28
	s_cselect_b32 s79, s45, s11
	s_cselect_b32 s78, s44, s7
	s_cselect_b32 s91, s47, s9
	s_cselect_b32 s90, s46, s8
	v_lshl_add_u64 v[132:133], s[50:51], 0, v[130:131]
	s_add_i32 m0, s49, 0xc000
	ds_read_b128 v[156:159], v136
	ds_read_b128 v[160:163], v136 offset:1024
	ds_read_b128 v[164:167], v136 offset:2048
	ds_read_b128 v[168:171], v136 offset:3072
	ds_read_b128 v[172:175], v136 offset:4096
	ds_read_b128 v[176:179], v136 offset:5120
	ds_read_b128 v[180:183], v136 offset:6144
	ds_read_b128 v[184:187], v136 offset:7168
	global_load_lds_dwordx4 v[132:133], off
	v_lshl_add_u64 v[132:133], v[132:133], 0, s[60:61]
	s_add_i32 m0, s49, 0xe000
	s_nop 0
	global_load_lds_dwordx4 v[132:133], off
	s_waitcnt lgkmcnt(8)
	s_barrier
	s_waitcnt lgkmcnt(0)
	v_mfma_f32_16x16x32_bf16 v[126:129], v[138:141], v[156:159], v[126:129]
	v_mfma_f32_16x16x32_bf16 v[122:125], v[148:151], v[156:159], v[122:125]
	v_mfma_f32_16x16x32_bf16 v[118:121], v[138:141], v[164:167], v[118:121]
	v_mfma_f32_16x16x32_bf16 v[110:113], v[148:151], v[164:167], v[110:113]
	v_mfma_f32_16x16x32_bf16 v[102:105], v[138:141], v[172:175], v[102:105]
	v_mfma_f32_16x16x32_bf16 v[94:97], v[148:151], v[172:175], v[94:97]
	v_mfma_f32_16x16x32_bf16 v[86:89], v[138:141], v[180:183], v[86:89]
	v_mfma_f32_16x16x32_bf16 v[78:81], v[148:151], v[180:183], v[78:81]
	v_mfma_f32_16x16x32_bf16 v[126:129], v[142:145], v[160:163], v[126:129]
	v_mfma_f32_16x16x32_bf16 v[122:125], v[152:155], v[160:163], v[122:125]
	v_mfma_f32_16x16x32_bf16 v[118:121], v[142:145], v[168:171], v[118:121]
	v_mfma_f32_16x16x32_bf16 v[110:113], v[152:155], v[168:171], v[110:113]
	v_mfma_f32_16x16x32_bf16 v[102:105], v[142:145], v[176:179], v[102:105]
	v_mfma_f32_16x16x32_bf16 v[94:97], v[152:155], v[176:179], v[94:97]
	v_mfma_f32_16x16x32_bf16 v[86:89], v[142:145], v[184:187], v[86:89]
	v_mfma_f32_16x16x32_bf16 v[78:81], v[152:155], v[184:187], v[78:81]
	s_barrier
	s_add_i32 s7, 0, 0x14000
	v_add_u32_e32 v132, s7, v135
	s_add_i32 s11, s43, s57
	ds_read_b128 v[188:191], v132
	ds_read_b128 v[192:195], v132 offset:1024
	ds_read_b128 v[196:199], v132 offset:2048
	ds_read_b128 v[200:203], v132 offset:3072
	v_lshl_add_u64 v[132:133], s[90:91], 0, v[0:1]
	s_mov_b32 m0, s11
	v_lshl_add_u64 v[204:205], v[132:133], 0, s[60:61]
	global_load_lds_dwordx4 v[132:133], off
	s_add_i32 m0, s11, 0x2000
	s_nop 0
	global_load_lds_dwordx4 v[204:205], off
	s_barrier
	s_waitcnt lgkmcnt(0)
	v_mfma_f32_16x16x32_bf16 v[114:117], v[188:191], v[156:159], v[114:117]
	v_mfma_f32_16x16x32_bf16 v[106:109], v[196:199], v[156:159], v[106:109]
	v_mfma_f32_16x16x32_bf16 v[98:101], v[188:191], v[164:167], v[98:101]
	v_mfma_f32_16x16x32_bf16 v[90:93], v[196:199], v[164:167], v[90:93]
	v_mfma_f32_16x16x32_bf16 v[82:85], v[188:191], v[172:175], v[82:85]
	v_mfma_f32_16x16x32_bf16 v[74:77], v[196:199], v[172:175], v[74:77]
	v_mfma_f32_16x16x32_bf16 v[70:73], v[188:191], v[180:183], v[70:73]
	v_mfma_f32_16x16x32_bf16 v[66:69], v[196:199], v[180:183], v[66:69]
	v_mfma_f32_16x16x32_bf16 v[114:117], v[192:195], v[160:163], v[114:117]
	v_mfma_f32_16x16x32_bf16 v[106:109], v[200:203], v[160:163], v[106:109]
	v_mfma_f32_16x16x32_bf16 v[98:101], v[192:195], v[168:171], v[98:101]
	v_mfma_f32_16x16x32_bf16 v[90:93], v[200:203], v[168:171], v[90:93]
	v_mfma_f32_16x16x32_bf16 v[82:85], v[192:195], v[176:179], v[82:85]
	v_mfma_f32_16x16x32_bf16 v[74:77], v[200:203], v[176:179], v[74:77]
	v_mfma_f32_16x16x32_bf16 v[70:73], v[192:195], v[184:187], v[70:73]
	v_mfma_f32_16x16x32_bf16 v[66:69], v[200:203], v[184:187], v[66:69]
	s_barrier
	s_mov_b32 m0, s49
	v_lshl_add_u64 v[204:205], s[78:79], 0, v[0:1]
	ds_read_b128 v[156:159], v136 offset:16384
	ds_read_b128 v[160:163], v136 offset:17408
	ds_read_b128 v[164:167], v136 offset:18432
	ds_read_b128 v[168:171], v136 offset:19456
	ds_read_b128 v[172:175], v136 offset:20480
	ds_read_b128 v[176:179], v136 offset:21504
	ds_read_b128 v[180:183], v136 offset:22528
	ds_read_b128 v[184:187], v136 offset:23552
	global_load_lds_dwordx4 v[204:205], off
	v_lshl_add_u64 v[206:207], v[204:205], 0, s[60:61]
	s_mov_b32 m0, s58
	s_nop 0
	global_load_lds_dwordx4 v[206:207], off
	s_barrier
	s_waitcnt lgkmcnt(0)
	v_mfma_f32_16x16x32_bf16 v[62:65], v[138:141], v[156:159], v[62:65]
	v_mfma_f32_16x16x32_bf16 v[58:61], v[148:151], v[156:159], v[58:61]
	v_mfma_f32_16x16x32_bf16 v[54:57], v[138:141], v[164:167], v[54:57]
	v_mfma_f32_16x16x32_bf16 v[46:49], v[148:151], v[164:167], v[46:49]
	v_mfma_f32_16x16x32_bf16 v[38:41], v[138:141], v[172:175], v[38:41]
	v_mfma_f32_16x16x32_bf16 v[30:33], v[148:151], v[172:175], v[30:33]
	v_mfma_f32_16x16x32_bf16 v[22:25], v[138:141], v[180:183], v[22:25]
	v_mfma_f32_16x16x32_bf16 v[14:17], v[148:151], v[180:183], v[14:17]
	v_mfma_f32_16x16x32_bf16 v[62:65], v[142:145], v[160:163], v[62:65]
	v_mfma_f32_16x16x32_bf16 v[58:61], v[152:155], v[160:163], v[58:61]
	v_mfma_f32_16x16x32_bf16 v[54:57], v[142:145], v[168:171], v[54:57]
	v_mfma_f32_16x16x32_bf16 v[46:49], v[152:155], v[168:171], v[46:49]
	v_mfma_f32_16x16x32_bf16 v[38:41], v[142:145], v[176:179], v[38:41]
	v_mfma_f32_16x16x32_bf16 v[30:33], v[152:155], v[176:179], v[30:33]
	v_mfma_f32_16x16x32_bf16 v[22:25], v[142:145], v[184:187], v[22:25]
	v_mfma_f32_16x16x32_bf16 v[14:17], v[152:155], v[184:187], v[14:17]
	s_barrier
	s_add_i32 s7, s7, s57
	v_lshl_add_u64 v[138:139], v[132:133], 0, s[20:21]
	s_mov_b32 m0, s7
	s_nop 0
	global_load_lds_dwordx4 v[138:139], off
	v_lshl_add_u64 v[138:139], v[132:133], 0, s[64:65]
	s_add_i32 m0, s7, 0x2000
	s_nop 0
	global_load_lds_dwordx4 v[138:139], off
	v_lshl_add_u64 v[230:231], v[204:205], 0, s[20:21]
	s_mov_b32 m0, s59
	s_nop 0
	global_load_lds_dwordx4 v[230:231], off
	v_lshl_add_u64 v[230:231], v[204:205], 0, s[64:65]
	s_mov_b32 m0, s62
	s_nop 0
	global_load_lds_dwordx4 v[230:231], off
	s_waitcnt vmcnt(8)
	s_barrier
	v_mfma_f32_16x16x32_bf16 v[50:53], v[188:191], v[156:159], v[50:53]
	v_mfma_f32_16x16x32_bf16 v[42:45], v[196:199], v[156:159], v[42:45]
	v_mfma_f32_16x16x32_bf16 v[34:37], v[188:191], v[164:167], v[34:37]
	v_mfma_f32_16x16x32_bf16 v[26:29], v[196:199], v[164:167], v[26:29]
	v_mfma_f32_16x16x32_bf16 v[18:21], v[188:191], v[172:175], v[18:21]
	v_mfma_f32_16x16x32_bf16 v[10:13], v[196:199], v[172:175], v[10:13]
	v_mfma_f32_16x16x32_bf16 v[6:9], v[188:191], v[180:183], v[6:9]
	v_mfma_f32_16x16x32_bf16 v[2:5], v[196:199], v[180:183], v[2:5]
	v_mfma_f32_16x16x32_bf16 v[50:53], v[192:195], v[160:163], v[50:53]
	v_mfma_f32_16x16x32_bf16 v[42:45], v[200:203], v[160:163], v[42:45]
	v_mfma_f32_16x16x32_bf16 v[34:37], v[192:195], v[168:171], v[34:37]
	v_mfma_f32_16x16x32_bf16 v[26:29], v[200:203], v[168:171], v[26:29]
	v_mfma_f32_16x16x32_bf16 v[18:21], v[192:195], v[176:179], v[18:21]
	v_mfma_f32_16x16x32_bf16 v[10:13], v[200:203], v[176:179], v[10:13]
	v_mfma_f32_16x16x32_bf16 v[6:9], v[192:195], v[184:187], v[6:9]
	v_mfma_f32_16x16x32_bf16 v[2:5], v[200:203], v[184:187], v[2:5]
	s_barrier
	s_add_i32 s7, 0, 0x18000
	v_add_u32_e32 v137, s7, v135
	ds_read_b128 v[138:141], v137
	ds_read_b128 v[142:145], v137 offset:1024
	ds_read_b128 v[148:151], v137 offset:2048
	ds_read_b128 v[152:155], v137 offset:3072
	ds_read_b128 v[156:159], v136 offset:32768
	ds_read_b128 v[160:163], v136 offset:33792
	ds_read_b128 v[164:167], v136 offset:34816
	ds_read_b128 v[168:171], v136 offset:35840
	ds_read_b128 v[172:175], v136 offset:36864
	ds_read_b128 v[176:179], v136 offset:37888
	ds_read_b128 v[180:183], v136 offset:38912
	ds_read_b128 v[184:187], v136 offset:39936
	s_waitcnt lgkmcnt(8)
	s_barrier
	s_waitcnt lgkmcnt(0)
	v_mfma_f32_16x16x32_bf16 v[126:129], v[138:141], v[156:159], v[126:129]
	v_mfma_f32_16x16x32_bf16 v[122:125], v[148:151], v[156:159], v[122:125]
	v_mfma_f32_16x16x32_bf16 v[118:121], v[138:141], v[164:167], v[118:121]
	v_mfma_f32_16x16x32_bf16 v[110:113], v[148:151], v[164:167], v[110:113]
	v_mfma_f32_16x16x32_bf16 v[102:105], v[138:141], v[172:175], v[102:105]
	v_mfma_f32_16x16x32_bf16 v[94:97], v[148:151], v[172:175], v[94:97]
	v_mfma_f32_16x16x32_bf16 v[86:89], v[138:141], v[180:183], v[86:89]
	v_mfma_f32_16x16x32_bf16 v[78:81], v[148:151], v[180:183], v[78:81]
	v_mfma_f32_16x16x32_bf16 v[126:129], v[142:145], v[160:163], v[126:129]
	v_mfma_f32_16x16x32_bf16 v[122:125], v[152:155], v[160:163], v[122:125]
	v_mfma_f32_16x16x32_bf16 v[118:121], v[142:145], v[168:171], v[118:121]
	v_mfma_f32_16x16x32_bf16 v[110:113], v[152:155], v[168:171], v[110:113]
	v_mfma_f32_16x16x32_bf16 v[102:105], v[142:145], v[176:179], v[102:105]
	v_mfma_f32_16x16x32_bf16 v[94:97], v[152:155], v[176:179], v[94:97]
	v_mfma_f32_16x16x32_bf16 v[86:89], v[142:145], v[184:187], v[86:89]
	v_mfma_f32_16x16x32_bf16 v[78:81], v[152:155], v[184:187], v[78:81]
	s_barrier
	s_add_i32 s11, 0, 0x1c000
	s_add_i32 s7, s7, s57
	v_add_u32_e32 v137, s11, v135
	v_lshl_add_u64 v[206:207], v[132:133], 0, s[34:35]
	s_mov_b32 m0, s7
	ds_read_b128 v[188:191], v137
	ds_read_b128 v[192:195], v137 offset:1024
	ds_read_b128 v[196:199], v137 offset:2048
	ds_read_b128 v[200:203], v137 offset:3072
	global_load_lds_dwordx4 v[206:207], off
	v_lshl_add_u64 v[206:207], v[132:133], 0, s[66:67]
	s_add_i32 m0, s7, 0x2000
	s_nop 0
	global_load_lds_dwordx4 v[206:207], off
	s_barrier
	s_waitcnt lgkmcnt(0)
	v_mfma_f32_16x16x32_bf16 v[114:117], v[188:191], v[156:159], v[114:117]
	v_mfma_f32_16x16x32_bf16 v[106:109], v[196:199], v[156:159], v[106:109]
	v_mfma_f32_16x16x32_bf16 v[98:101], v[188:191], v[164:167], v[98:101]
	v_mfma_f32_16x16x32_bf16 v[90:93], v[196:199], v[164:167], v[90:93]
	v_mfma_f32_16x16x32_bf16 v[82:85], v[188:191], v[172:175], v[82:85]
	v_mfma_f32_16x16x32_bf16 v[74:77], v[196:199], v[172:175], v[74:77]
	v_mfma_f32_16x16x32_bf16 v[70:73], v[188:191], v[180:183], v[70:73]
	v_mfma_f32_16x16x32_bf16 v[66:69], v[196:199], v[180:183], v[66:69]
	v_mfma_f32_16x16x32_bf16 v[114:117], v[192:195], v[160:163], v[114:117]
	v_mfma_f32_16x16x32_bf16 v[106:109], v[200:203], v[160:163], v[106:109]
	v_mfma_f32_16x16x32_bf16 v[98:101], v[192:195], v[168:171], v[98:101]
	v_mfma_f32_16x16x32_bf16 v[90:93], v[200:203], v[168:171], v[90:93]
	v_mfma_f32_16x16x32_bf16 v[82:85], v[192:195], v[176:179], v[82:85]
	v_mfma_f32_16x16x32_bf16 v[74:77], v[200:203], v[176:179], v[74:77]
	v_mfma_f32_16x16x32_bf16 v[70:73], v[192:195], v[184:187], v[70:73]
	v_mfma_f32_16x16x32_bf16 v[66:69], v[200:203], v[184:187], v[66:69]
	s_barrier
	s_mov_b32 m0, s85
	v_lshl_add_u64 v[206:207], v[204:205], 0, s[34:35]
	ds_read_b128 v[156:159], v136 offset:49152
	ds_read_b128 v[160:163], v136 offset:50176
	ds_read_b128 v[164:167], v136 offset:51200
	ds_read_b128 v[168:171], v136 offset:52224
	ds_read_b128 v[172:175], v136 offset:53248
	ds_read_b128 v[176:179], v136 offset:54272
	ds_read_b128 v[180:183], v136 offset:55296
	ds_read_b128 v[184:187], v136 offset:56320
	global_load_lds_dwordx4 v[206:207], off
	v_lshl_add_u64 v[204:205], v[204:205], 0, s[66:67]
	s_mov_b32 m0, s86
	s_nop 0
	global_load_lds_dwordx4 v[204:205], off
	s_barrier
	s_waitcnt lgkmcnt(0)
	v_mfma_f32_16x16x32_bf16 v[62:65], v[138:141], v[156:159], v[62:65]
	v_mfma_f32_16x16x32_bf16 v[58:61], v[148:151], v[156:159], v[58:61]
	v_mfma_f32_16x16x32_bf16 v[54:57], v[138:141], v[164:167], v[54:57]
	v_mfma_f32_16x16x32_bf16 v[46:49], v[148:151], v[164:167], v[46:49]
	v_mfma_f32_16x16x32_bf16 v[38:41], v[138:141], v[172:175], v[38:41]
	v_mfma_f32_16x16x32_bf16 v[30:33], v[148:151], v[172:175], v[30:33]
	v_mfma_f32_16x16x32_bf16 v[22:25], v[138:141], v[180:183], v[22:25]
	v_mfma_f32_16x16x32_bf16 v[14:17], v[148:151], v[180:183], v[14:17]
	v_mfma_f32_16x16x32_bf16 v[62:65], v[142:145], v[160:163], v[62:65]
	v_mfma_f32_16x16x32_bf16 v[58:61], v[152:155], v[160:163], v[58:61]
	v_mfma_f32_16x16x32_bf16 v[54:57], v[142:145], v[168:171], v[54:57]
	v_mfma_f32_16x16x32_bf16 v[46:49], v[152:155], v[168:171], v[46:49]
	v_mfma_f32_16x16x32_bf16 v[38:41], v[142:145], v[176:179], v[38:41]
	v_mfma_f32_16x16x32_bf16 v[30:33], v[152:155], v[176:179], v[30:33]
	v_mfma_f32_16x16x32_bf16 v[22:25], v[142:145], v[184:187], v[22:25]
	v_mfma_f32_16x16x32_bf16 v[14:17], v[152:155], v[184:187], v[14:17]
	s_barrier
	s_add_i32 s7, s11, s57
	v_lshl_add_u64 v[138:139], v[132:133], 0, s[16:17]
	s_mov_b32 m0, s7
	v_lshl_add_u64 v[132:133], v[132:133], 0, s[80:81]
	global_load_lds_dwordx4 v[138:139], off
	s_add_i32 m0, s7, 0x2000
	s_nop 0
	global_load_lds_dwordx4 v[132:133], off
	s_waitcnt vmcnt(6)
	s_add_i32 s6, s6, 2
	s_add_u32 s8, s8, 0x100
	s_addc_u32 s9, s9, 0
	s_add_u32 s50, s50, 0x100
	s_addc_u32 s51, s51, 0
	s_cmp_gt_u32 s6, 29
	s_cbranch_scc0 .LBB0_97
	s_barrier
	v_mfma_f32_16x16x32_bf16 v[50:53], v[188:191], v[156:159], v[50:53]
	v_mfma_f32_16x16x32_bf16 v[42:45], v[196:199], v[156:159], v[42:45]
	v_mfma_f32_16x16x32_bf16 v[34:37], v[188:191], v[164:167], v[34:37]
	v_mfma_f32_16x16x32_bf16 v[26:29], v[196:199], v[164:167], v[26:29]
	v_mfma_f32_16x16x32_bf16 v[18:21], v[188:191], v[172:175], v[18:21]
	v_mfma_f32_16x16x32_bf16 v[10:13], v[196:199], v[172:175], v[10:13]
	v_mfma_f32_16x16x32_bf16 v[6:9], v[188:191], v[180:183], v[6:9]
	v_mfma_f32_16x16x32_bf16 v[2:5], v[196:199], v[180:183], v[2:5]
	v_mfma_f32_16x16x32_bf16 v[50:53], v[192:195], v[160:163], v[50:53]
	v_mfma_f32_16x16x32_bf16 v[42:45], v[200:203], v[160:163], v[42:45]
	v_mfma_f32_16x16x32_bf16 v[34:37], v[192:195], v[168:171], v[34:37]
	v_mfma_f32_16x16x32_bf16 v[26:29], v[200:203], v[168:171], v[26:29]
	v_mfma_f32_16x16x32_bf16 v[18:21], v[192:195], v[176:179], v[18:21]
	v_mfma_f32_16x16x32_bf16 v[10:13], v[200:203], v[176:179], v[10:13]
	v_mfma_f32_16x16x32_bf16 v[6:9], v[192:195], v[184:187], v[6:9]
	v_mfma_f32_16x16x32_bf16 v[2:5], v[200:203], v[184:187], v[2:5]
	s_barrier
	v_mov_b32_e32 v137, v134
	s_lshl_b32 s6, s88, 8
	v_ashrrev_i32_e32 v132, 2, v137
	s_or_b32 s6, s6, s84
	v_and_b32_e32 v132, -4, v132
	v_add_u32_e32 v132, s6, v132
	s_lshl_b32 s6, s48, 8
	s_add_i32 s6, s6, s63
	v_and_or_b32 v188, v137, 15, s6
	v_ashrrev_i32_e32 v189, 31, v188
	v_ashrrev_i32_e32 v133, 31, v132
	v_lshlrev_b64 v[206:207], 13, v[188:189]
	v_or_b32_e32 v156, 16, v188
	v_or_b32_e32 v172, 32, v188
	v_or_b32_e32 v188, 48, v188
	v_lshlrev_b64 v[132:133], 2, v[132:133]
	v_ashrrev_i32_e32 v157, 31, v156
	v_ashrrev_i32_e32 v173, 31, v172
	v_ashrrev_i32_e32 v189, 31, v188
	v_lshl_add_u64 v[204:205], s[4:5], 0, v[132:133]
	v_lshlrev_b64 v[208:209], 13, v[156:157]
	v_lshlrev_b64 v[210:211], 13, v[172:173]
	v_lshlrev_b64 v[212:213], 13, v[188:189]
	v_lshl_add_u64 v[152:153], v[204:205], 0, v[206:207]
	v_lshl_add_u64 v[168:169], v[204:205], 0, v[208:209]
	v_lshl_add_u64 v[184:185], v[204:205], 0, v[210:211]
	v_lshl_add_u64 v[200:201], v[204:205], 0, v[212:213]
	global_load_dwordx4 v[138:141], v[152:153], off
	global_load_dwordx4 v[142:145], v[152:153], off offset:64
	global_load_dwordx4 v[148:151], v[152:153], off offset:512
	s_nop 0
	global_load_dwordx4 v[152:155], v[152:153], off offset:576
	s_nop 0
	global_load_dwordx4 v[156:159], v[168:169], off
	global_load_dwordx4 v[160:163], v[168:169], off offset:64
	global_load_dwordx4 v[164:167], v[168:169], off offset:512
	s_nop 0
	global_load_dwordx4 v[168:171], v[168:169], off offset:576
	s_nop 0
	global_load_dwordx4 v[172:175], v[184:185], off
	global_load_dwordx4 v[176:179], v[184:185], off offset:64
	global_load_dwordx4 v[180:183], v[184:185], off offset:512
	s_nop 0
	global_load_dwordx4 v[184:187], v[184:185], off offset:576
	s_nop 0
	global_load_dwordx4 v[188:191], v[200:201], off
	global_load_dwordx4 v[192:195], v[200:201], off offset:64
	global_load_dwordx4 v[196:199], v[200:201], off offset:512
	s_nop 0
	global_load_dwordx4 v[200:203], v[200:201], off offset:576
	s_waitcnt vmcnt(0) lgkmcnt(0)
	v_pk_add_f32 v[126:127], v[126:127], v[138:139]
	v_lshl_add_u64 v[138:139], s[4:5], 0, v[206:207]
	v_lshl_add_u64 v[138:139], v[138:139], 0, v[132:133]
	v_pk_add_f32 v[116:117], v[116:117], v[150:151]
	v_pk_add_f32 v[114:115], v[114:115], v[148:149]
	global_store_dwordx4 v[138:139], v[114:117], off offset:512
	v_pk_add_f32 v[100:101], v[100:101], v[166:167]
	v_pk_add_f32 v[98:99], v[98:99], v[164:165]
	v_lshl_add_u64 v[114:115], s[4:5], 0, v[208:209]
	v_lshl_add_u64 v[114:115], v[114:115], 0, v[132:133]
	global_store_dwordx4 v[114:115], v[98:101], off offset:512
	v_pk_add_f32 v[84:85], v[84:85], v[182:183]
	v_pk_add_f32 v[82:83], v[82:83], v[180:181]
	v_lshl_add_u64 v[98:99], s[4:5], 0, v[210:211]
	v_lshl_add_u64 v[98:99], v[98:99], 0, v[132:133]
	v_pk_add_f32 v[108:109], v[108:109], v[154:155]
	v_pk_add_f32 v[106:107], v[106:107], v[152:153]
	v_pk_add_f32 v[92:93], v[92:93], v[170:171]
	v_pk_add_f32 v[90:91], v[90:91], v[168:169]
	global_store_dwordx4 v[98:99], v[82:85], off offset:512
	v_pk_add_f32 v[76:77], v[76:77], v[186:187]
	v_pk_add_f32 v[74:75], v[74:75], v[184:185]
	v_lshl_add_u64 v[82:83], s[4:5], 0, v[212:213]
	global_store_dwordx4 v[138:139], v[106:109], off offset:576
	global_store_dwordx4 v[114:115], v[90:93], off offset:576
	global_store_dwordx4 v[98:99], v[74:77], off offset:576
	v_pk_add_f32 v[108:109], v[120:121], v[158:159]
	v_pk_add_f32 v[106:107], v[118:119], v[156:157]
	v_pk_add_f32 v[92:93], v[104:105], v[174:175]
	v_pk_add_f32 v[90:91], v[102:103], v[172:173]
	v_pk_add_f32 v[76:77], v[88:89], v[190:191]
	v_pk_add_f32 v[74:75], v[86:87], v[188:189]
	v_lshl_add_u64 v[82:83], v[82:83], 0, v[132:133]
	v_pk_add_f32 v[128:129], v[128:129], v[140:141]
	v_pk_add_f32 v[124:125], v[124:125], v[144:145]
	v_pk_add_f32 v[122:123], v[122:123], v[142:143]
	global_store_dwordx4 v[114:115], v[106:109], off
	global_store_dwordx4 v[98:99], v[90:93], off
	global_store_dwordx4 v[82:83], v[74:77], off
	v_pk_add_f32 v[108:109], v[112:113], v[162:163]
	v_pk_add_f32 v[106:107], v[110:111], v[160:161]
	v_pk_add_f32 v[92:93], v[96:97], v[178:179]
	v_pk_add_f32 v[90:91], v[94:95], v[176:177]
	v_pk_add_f32 v[76:77], v[80:81], v[194:195]
	v_pk_add_f32 v[74:75], v[78:79], v[192:193]
	v_pk_add_f32 v[72:73], v[72:73], v[198:199]
	v_pk_add_f32 v[70:71], v[70:71], v[196:197]
	v_pk_add_f32 v[68:69], v[68:69], v[202:203]
	v_pk_add_f32 v[66:67], v[66:67], v[200:201]
	global_store_dwordx4 v[138:139], v[126:129], off
	global_store_dwordx4 v[138:139], v[122:125], off offset:64
	global_store_dwordx4 v[114:115], v[106:109], off offset:64
	global_store_dwordx4 v[98:99], v[90:93], off offset:64
	global_store_dwordx4 v[82:83], v[74:77], off offset:64
	global_store_dwordx4 v[82:83], v[70:73], off offset:512
	global_store_dwordx4 v[82:83], v[66:69], off offset:576
	s_mov_b64 s[6:7], 0x120000
	v_lshl_add_u64 v[140:141], v[206:207], 0, s[6:7]
	s_mov_b64 s[6:7], 0x140000
	v_lshl_add_u64 v[138:139], v[206:207], 0, s[0:1]
	v_lshl_add_u64 v[142:143], v[206:207], 0, s[6:7]
	v_lshl_add_u64 v[144:145], v[206:207], 0, s[28:29]
	v_lshl_add_u64 v[78:79], v[204:205], 0, v[138:139]
	v_lshl_add_u64 v[94:95], v[204:205], 0, v[140:141]
	v_lshl_add_u64 v[110:111], v[204:205], 0, v[142:143]
	v_lshl_add_u64 v[126:127], v[204:205], 0, v[144:145]
	global_load_dwordx4 v[66:69], v[78:79], off
	global_load_dwordx4 v[70:73], v[78:79], off offset:64
	global_load_dwordx4 v[74:77], v[78:79], off offset:512
	s_nop 0
	global_load_dwordx4 v[78:81], v[78:79], off offset:576
	s_nop 0
	global_load_dwordx4 v[82:85], v[94:95], off
	global_load_dwordx4 v[86:89], v[94:95], off offset:64
	global_load_dwordx4 v[90:93], v[94:95], off offset:512
	s_nop 0
	global_load_dwordx4 v[94:97], v[94:95], off offset:576
	s_nop 0
	global_load_dwordx4 v[98:101], v[110:111], off
	global_load_dwordx4 v[102:105], v[110:111], off offset:64
	global_load_dwordx4 v[106:109], v[110:111], off offset:512
	s_nop 0
	global_load_dwordx4 v[110:113], v[110:111], off offset:576
	s_nop 0
	global_load_dwordx4 v[114:117], v[126:127], off
	global_load_dwordx4 v[118:121], v[126:127], off offset:64
	global_load_dwordx4 v[122:125], v[126:127], off offset:512
	s_nop 0
	global_load_dwordx4 v[126:129], v[126:127], off offset:576
	s_waitcnt vmcnt(0) lgkmcnt(0)
	v_pk_add_f32 v[62:63], v[62:63], v[66:67]
	v_lshl_add_u64 v[66:67], s[4:5], 0, v[138:139]
	v_lshl_add_u64 v[66:67], v[66:67], 0, v[132:133]
	v_pk_add_f32 v[52:53], v[52:53], v[76:77]
	v_pk_add_f32 v[50:51], v[50:51], v[74:75]
	global_store_dwordx4 v[66:67], v[50:53], off offset:512
	v_pk_add_f32 v[36:37], v[36:37], v[92:93]
	v_pk_add_f32 v[34:35], v[34:35], v[90:91]
	v_lshl_add_u64 v[50:51], s[4:5], 0, v[140:141]
	v_lshl_add_u64 v[50:51], v[50:51], 0, v[132:133]
	global_store_dwordx4 v[50:51], v[34:37], off offset:512
	v_pk_add_f32 v[20:21], v[20:21], v[108:109]
	v_pk_add_f32 v[18:19], v[18:19], v[106:107]
	v_lshl_add_u64 v[34:35], s[4:5], 0, v[142:143]
	v_lshl_add_u64 v[34:35], v[34:35], 0, v[132:133]
	v_pk_add_f32 v[44:45], v[44:45], v[80:81]
	v_pk_add_f32 v[42:43], v[42:43], v[78:79]
	v_pk_add_f32 v[28:29], v[28:29], v[96:97]
	v_pk_add_f32 v[26:27], v[26:27], v[94:95]
	global_store_dwordx4 v[34:35], v[18:21], off offset:512
	v_pk_add_f32 v[12:13], v[12:13], v[112:113]
	v_pk_add_f32 v[10:11], v[10:11], v[110:111]
	v_lshl_add_u64 v[18:19], s[4:5], 0, v[144:145]
	global_store_dwordx4 v[66:67], v[42:45], off offset:576
	global_store_dwordx4 v[50:51], v[26:29], off offset:576
	global_store_dwordx4 v[34:35], v[10:13], off offset:576
	v_pk_add_f32 v[44:45], v[56:57], v[84:85]
	v_pk_add_f32 v[42:43], v[54:55], v[82:83]
	v_pk_add_f32 v[28:29], v[40:41], v[100:101]
	v_pk_add_f32 v[26:27], v[38:39], v[98:99]
	v_pk_add_f32 v[12:13], v[24:25], v[116:117]
	v_pk_add_f32 v[10:11], v[22:23], v[114:115]
	v_lshl_add_u64 v[18:19], v[18:19], 0, v[132:133]
	v_pk_add_f32 v[64:65], v[64:65], v[68:69]
	v_pk_add_f32 v[60:61], v[60:61], v[72:73]
	v_pk_add_f32 v[58:59], v[58:59], v[70:71]
	global_store_dwordx4 v[50:51], v[42:45], off
	global_store_dwordx4 v[34:35], v[26:29], off
	global_store_dwordx4 v[18:19], v[10:13], off
	v_pk_add_f32 v[44:45], v[48:49], v[88:89]
	v_pk_add_f32 v[42:43], v[46:47], v[86:87]
	v_pk_add_f32 v[28:29], v[32:33], v[104:105]
	v_pk_add_f32 v[26:27], v[30:31], v[102:103]
	v_pk_add_f32 v[12:13], v[16:17], v[120:121]
	v_pk_add_f32 v[10:11], v[14:15], v[118:119]
	v_pk_add_f32 v[8:9], v[8:9], v[124:125]
	v_pk_add_f32 v[6:7], v[6:7], v[122:123]
	v_pk_add_f32 v[4:5], v[4:5], v[128:129]
	v_pk_add_f32 v[2:3], v[2:3], v[126:127]
	global_store_dwordx4 v[66:67], v[62:65], off
	global_store_dwordx4 v[66:67], v[58:61], off offset:64
	global_store_dwordx4 v[50:51], v[42:45], off offset:64
	global_store_dwordx4 v[34:35], v[26:29], off offset:64
	global_store_dwordx4 v[18:19], v[10:13], off offset:64
	global_store_dwordx4 v[18:19], v[6:9], off offset:512
	global_store_dwordx4 v[18:19], v[2:5], off offset:576
	v_readlane_b32 s50, v255, 28
	s_and_b64 vcc, exec, s[40:41]
	s_mov_b32 s48, s42
	s_mov_b32 s88, s10
	s_mov_b64 s[8:9], s[46:47]
	s_mov_b64 s[6:7], s[44:45]
	v_readlane_b32 s51, v255, 29
	s_movk_i32 s91, 0x60
	s_mov_b32 s78, 0x2a000000
	s_mov_b32 s79, 0x3fffe
	s_mov_b32 s90, 0xc0000
	s_cbranch_vccz .LBB0_90
	s_waitcnt vmcnt(0)
	s_cmpk_gt_u32 s52, 0xff
	s_cbranch_scc1 .LBB0_101
	s_barrier
.LBB0_101:
	s_setprio 0
	v_readlane_b32 s0, v255, 8
	v_readlane_b32 s62, v255, 10
	v_readlane_b32 s84, v255, 12
	v_readlane_b32 s86, v255, 14
	v_readlane_b32 s56, v255, 16
	v_readlane_b32 s54, v255, 22
	v_readlane_b32 s44, v255, 26
	v_readlane_b32 s72, v255, 7
	v_readlane_b32 s1, v255, 9
	s_mov_b64 s[58:59], s[92:93]
	v_readlane_b32 s63, v255, 11
	v_readlane_b32 s85, v255, 13
	v_readlane_b32 s87, v255, 15
	v_readlane_b32 s57, v255, 17
	v_readlane_b32 s55, v255, 23
	v_readlane_b32 s45, v255, 27
	s_movk_i32 s92, 0x4000
	s_movk_i32 s93, 0xf800
	s_mov_b32 s88, 0x16000
	s_barrier

.LBB0_213:
	s_load_dwordx2 s[42:43], s[10:11], 0x0
	s_nop 0
	s_load_dwordx2 s[44:45], s[44:45], 0x0
	s_andn2_b64 vcc, exec, s[40:41]
	s_cbranch_vccnz .LBB0_272
	v_ashrrev_i32_e32 v3, 31, v0
	v_lshrrev_b32_e32 v3, 26, v3
	v_lshlrev_b32_e32 v2, 4, v0
	v_add_u32_e32 v3, v0, v3
	v_bfe_i32 v0, v0, 27, 1
	v_lshrrev_b32_e32 v0, 22, v0
	v_add_u32_e32 v0, v2, v0
	v_and_b32_e32 v0, 0xfffffc00, v0
	v_sub_u32_e32 v0, v2, v0
	v_lshrrev_b32_e32 v2, 4, v0
	v_bitop3_b32 v0, v2, v0, 32 bitop3:0x6c
	v_ashrrev_i32_e32 v4, 31, v0
	v_ashrrev_i32_e32 v3, 6, v3
	v_lshrrev_b32_e32 v4, 26, v4
	v_lshlrev_b32_e32 v2, 3, v3
	v_add_u32_e32 v4, v0, v4
	v_and_b32_e32 v2, -16, v2
	v_ashrrev_i32_e32 v5, 6, v4
	v_and_b32_e32 v4, 0xc0, v4
	v_add_u32_e32 v2, v5, v2
	v_sub_u32_e32 v0, v0, v4
	v_mov_b32_e32 v4, 1
	v_lshlrev_b32_e32 v3, 5, v3
	v_ashrrev_i16_sdwa v0, v4, sext(v0) dst_sel:DWORD dst_unused:UNUSED_PAD src0_sel:DWORD src1_sel:BYTE_0
	v_lshlrev_b32_e32 v4, 1, v2
	v_lshrrev_b32_e32 v7, 2, v2
	v_and_b32_e32 v5, 3, v5
	s_mov_b32 s11, 0x7fffe0
	s_ashr_i32 s10, s55, 6
	v_and_b32_e32 v3, 32, v3
	v_bfe_i32 v0, v0, 0, 16
	v_and_b32_e32 v4, 24, v4
	v_and_b32_e32 v7, 4, v7
	v_and_or_b32 v5, v2, s11, v5
	v_or3_b32 v4, v5, v7, v4
	v_add_lshl_u32 v0, v3, v0, 1
	s_lshl_b32 s56, s10, 10
	v_lshl_add_u32 v138, v2, 9, v0
	v_lshl_add_u32 v0, v4, 9, v0
	s_add_i32 s57, s56, 0
	v_lshl_add_u64 v[2:3], s[6:7], 0, v[0:1]
	s_add_i32 m0, s57, 0x10000
	v_writelane_b32 v255, s58, 30
	global_load_lds_dwordx4 v0, s[6:7]
	v_lshl_add_u64 v[4:5], v[2:3], 0, s[68:69]
	s_add_i32 m0, s57, 0x12000
	v_mov_b32_e32 v139, v1
	v_writelane_b32 v255, s59, 31
	global_load_lds_dwordx4 v[4:5], off
	v_lshl_add_u64 v[4:5], s[8:9], 0, v[138:139]
	s_mov_b32 m0, s57
	s_add_i32 s58, s57, 0x2000
	global_load_lds_dwordx4 v138, s[8:9]
	v_lshl_add_u64 v[8:9], v[4:5], 0, s[68:69]
	s_mov_b32 m0, s58
	s_mov_b64 s[0:1], 0x18000
	global_load_lds_dwordx4 v[8:9], off
	v_lshl_add_u64 v[8:9], v[2:3], 0, s[38:39]
	s_add_i32 m0, s57, 0x14000
	s_add_i32 s59, s57, 0x4000
	global_load_lds_dwordx4 v[8:9], off
	v_lshl_add_u64 v[8:9], v[2:3], 0, s[0:1]
	s_add_i32 m0, s57, 0x16000
	s_add_i32 s62, s57, 0x6000
	global_load_lds_dwordx4 v[8:9], off
	v_lshl_add_u64 v[8:9], v[4:5], 0, s[38:39]
	s_mov_b32 m0, s59
	s_ashr_i32 s11, s55, 8
	global_load_lds_dwordx4 v[8:9], off
	v_lshl_add_u64 v[8:9], v[4:5], 0, s[0:1]
	s_mov_b32 m0, s62
	s_cmp_lg_u32 s11, 1
	global_load_lds_dwordx4 v[8:9], off
	s_mov_b32 s2, 0x2600000
	s_mov_b32 s95, 0x28e00000
	s_cbranch_scc1 .LBB0_216
	s_setprio 1
	s_barrier

.LBB0_229:
	s_add_i32 s11, 0, 0x10000
	v_add_u32_e32 v206, s11, v148
	ds_read_b128 v[4:7], v206
	ds_read_b128 v[8:11], v206 offset:1024
	ds_read_b128 v[12:15], v206 offset:2048
	ds_read_b128 v[16:19], v206 offset:3072
	v_lshl_add_u64 v[2:3], s[8:9], 0, v[138:139]
	s_add_i32 s10, s57, 0xc000
	v_lshl_add_u64 v[52:53], v[2:3], 0, s[72:73]
	s_mov_b32 m0, s10
	s_mov_b64 vcc, 0x18080
	s_add_i32 s8, s57, 0xe000
	ds_read_b128 v[20:23], v149
	ds_read_b128 v[24:27], v149 offset:1024
	ds_read_b128 v[28:31], v149 offset:2048
	ds_read_b128 v[32:35], v149 offset:3072
	ds_read_b128 v[36:39], v149 offset:4096
	ds_read_b128 v[40:43], v149 offset:5120
	ds_read_b128 v[44:47], v149 offset:6144
	ds_read_b128 v[48:51], v149 offset:7168
	global_load_lds_dwordx4 v[52:53], off
	v_lshl_add_u64 v[52:53], v[2:3], 0, vcc
	s_mov_b32 m0, s8
	s_nop 0
	global_load_lds_dwordx4 v[52:53], off
	s_waitcnt lgkmcnt(8)
	s_barrier
	s_waitcnt lgkmcnt(0)
	v_mfma_f32_16x16x32_bf16 v[52:55], v[4:7], v[20:23], 0
	v_mfma_f32_16x16x32_bf16 v[56:59], v[12:15], v[20:23], 0
	v_mfma_f32_16x16x32_bf16 v[60:63], v[4:7], v[28:31], 0
	v_mfma_f32_16x16x32_bf16 v[64:67], v[12:15], v[28:31], 0
	v_mfma_f32_16x16x32_bf16 v[68:71], v[4:7], v[36:39], 0
	v_mfma_f32_16x16x32_bf16 v[72:75], v[12:15], v[36:39], 0
	v_mfma_f32_16x16x32_bf16 v[80:83], v[12:15], v[44:47], 0
	v_mfma_f32_16x16x32_bf16 v[52:55], v[8:11], v[24:27], v[52:55]
	v_mfma_f32_16x16x32_bf16 v[56:59], v[16:19], v[24:27], v[56:59]
	v_mfma_f32_16x16x32_bf16 v[60:63], v[8:11], v[32:35], v[60:63]
	v_mfma_f32_16x16x32_bf16 v[64:67], v[16:19], v[32:35], v[64:67]
	v_mfma_f32_16x16x32_bf16 v[68:71], v[8:11], v[40:43], v[68:71]
	v_mfma_f32_16x16x32_bf16 v[72:75], v[16:19], v[40:43], v[72:75]
	v_mfma_f32_16x16x32_bf16 v[76:79], v[4:7], v[44:47], 0
	v_mfma_f32_16x16x32_bf16 v[80:83], v[16:19], v[48:51], v[80:83]
	v_mfma_f32_16x16x32_bf16 v[76:79], v[8:11], v[48:51], v[76:79]
	s_barrier
	s_add_i32 s9, 0, 0x14000
	v_lshl_add_u64 v[136:137], s[6:7], 0, v[0:1]
	s_mov_b64 s[40:41], 0x100
	s_add_i32 s11, s11, s56
	v_add_u32_e32 v207, s9, v148
	v_lshl_add_u64 v[100:101], v[136:137], 0, s[40:41]
	s_mov_b32 m0, s11
	s_mov_b64 s[78:79], 0x8100
	s_add_i32 s6, s11, 0x2000
	ds_read_b128 v[84:87], v207
	ds_read_b128 v[88:91], v207 offset:1024
	ds_read_b128 v[92:95], v207 offset:2048
	ds_read_b128 v[96:99], v207 offset:3072
	global_load_lds_dwordx4 v[100:101], off
	v_lshl_add_u64 v[100:101], v[136:137], 0, s[78:79]
	s_mov_b32 m0, s6
	s_nop 0
	global_load_lds_dwordx4 v[100:101], off
	s_barrier
	s_waitcnt lgkmcnt(0)
	v_mfma_f32_16x16x32_bf16 v[100:103], v[84:87], v[20:23], 0
	v_mfma_f32_16x16x32_bf16 v[20:23], v[92:95], v[20:23], 0
	v_mfma_f32_16x16x32_bf16 v[100:103], v[88:91], v[24:27], v[100:103]
	v_mfma_f32_16x16x32_bf16 v[20:23], v[96:99], v[24:27], v[20:23]
	v_mfma_f32_16x16x32_bf16 v[24:27], v[84:87], v[28:31], 0
	v_mfma_f32_16x16x32_bf16 v[28:31], v[92:95], v[28:31], 0
	v_mfma_f32_16x16x32_bf16 v[24:27], v[88:91], v[32:35], v[24:27]
	v_mfma_f32_16x16x32_bf16 v[28:31], v[96:99], v[32:35], v[28:31]
	v_mfma_f32_16x16x32_bf16 v[32:35], v[84:87], v[36:39], 0
	v_mfma_f32_16x16x32_bf16 v[36:39], v[92:95], v[36:39], 0
	v_mfma_f32_16x16x32_bf16 v[32:35], v[88:91], v[40:43], v[32:35]
	v_mfma_f32_16x16x32_bf16 v[36:39], v[96:99], v[40:43], v[36:39]
	v_mfma_f32_16x16x32_bf16 v[40:43], v[84:87], v[44:47], 0
	v_mfma_f32_16x16x32_bf16 v[44:47], v[92:95], v[44:47], 0
	v_mfma_f32_16x16x32_bf16 v[40:43], v[88:91], v[48:51], v[40:43]
	v_mfma_f32_16x16x32_bf16 v[44:47], v[96:99], v[48:51], v[44:47]
	s_barrier
	s_mov_b32 m0, s57
	v_lshl_add_u64 v[132:133], v[2:3], 0, s[40:41]
	ds_read_b128 v[48:51], v149 offset:16384
	ds_read_b128 v[104:107], v149 offset:17408
	ds_read_b128 v[108:111], v149 offset:18432
	ds_read_b128 v[112:115], v149 offset:19456
	ds_read_b128 v[116:119], v149 offset:20480
	ds_read_b128 v[120:123], v149 offset:21504
	ds_read_b128 v[124:127], v149 offset:22528
	ds_read_b128 v[128:131], v149 offset:23552
	global_load_lds_dwordx4 v[132:133], off
	v_lshl_add_u64 v[132:133], v[2:3], 0, s[78:79]
	s_mov_b32 m0, s58
	s_nop 0
	global_load_lds_dwordx4 v[132:133], off
	s_barrier
	s_waitcnt lgkmcnt(0)
	v_mfma_f32_16x16x32_bf16 v[132:135], v[4:7], v[48:51], 0
	v_mfma_f32_16x16x32_bf16 v[150:153], v[4:7], v[108:111], 0
	v_mfma_f32_16x16x32_bf16 v[158:161], v[4:7], v[116:119], 0
	v_mfma_f32_16x16x32_bf16 v[4:7], v[4:7], v[124:127], 0
	v_mfma_f32_16x16x32_bf16 v[132:135], v[8:11], v[104:107], v[132:135]
	v_mfma_f32_16x16x32_bf16 v[150:153], v[8:11], v[112:115], v[150:153]
	v_mfma_f32_16x16x32_bf16 v[158:161], v[8:11], v[120:123], v[158:161]
	v_mfma_f32_16x16x32_bf16 v[4:7], v[8:11], v[128:131], v[4:7]
	v_mfma_f32_16x16x32_bf16 v[8:11], v[12:15], v[124:127], 0
	v_mfma_f32_16x16x32_bf16 v[140:143], v[12:15], v[48:51], 0
	v_mfma_f32_16x16x32_bf16 v[154:157], v[12:15], v[108:111], 0
	v_mfma_f32_16x16x32_bf16 v[162:165], v[12:15], v[116:119], 0
	v_mfma_f32_16x16x32_bf16 v[8:11], v[16:19], v[128:131], v[8:11]
	v_mfma_f32_16x16x32_bf16 v[140:143], v[16:19], v[104:107], v[140:143]
	v_mfma_f32_16x16x32_bf16 v[154:157], v[16:19], v[112:115], v[154:157]
	v_mfma_f32_16x16x32_bf16 v[162:165], v[16:19], v[120:123], v[162:165]
	s_barrier
	s_mov_b64 s[40:41], 0x10100
	s_add_i32 s9, s9, s56
	v_lshl_add_u64 v[12:13], v[136:137], 0, s[40:41]
	s_mov_b32 m0, s9
	s_mov_b64 s[78:79], 0x18100
	s_add_i32 s7, s9, 0x2000
	global_load_lds_dwordx4 v[12:13], off
	v_lshl_add_u64 v[12:13], v[136:137], 0, s[78:79]
	s_mov_b32 m0, s7
	s_nop 0
	global_load_lds_dwordx4 v[12:13], off
	s_waitcnt vmcnt(6)
	s_barrier
	v_mfma_f32_16x16x32_bf16 v[12:15], v[84:87], v[48:51], 0
	v_mfma_f32_16x16x32_bf16 v[16:19], v[92:95], v[48:51], 0
	v_mfma_f32_16x16x32_bf16 v[12:15], v[88:91], v[104:107], v[12:15]
	v_mfma_f32_16x16x32_bf16 v[16:19], v[96:99], v[104:107], v[16:19]
	v_mfma_f32_16x16x32_bf16 v[48:51], v[84:87], v[108:111], 0
	v_mfma_f32_16x16x32_bf16 v[104:107], v[92:95], v[108:111], 0
	v_mfma_f32_16x16x32_bf16 v[108:111], v[84:87], v[116:119], 0
	v_mfma_f32_16x16x32_bf16 v[84:87], v[84:87], v[124:127], 0
	v_mfma_f32_16x16x32_bf16 v[48:51], v[88:91], v[112:115], v[48:51]
	v_mfma_f32_16x16x32_bf16 v[104:107], v[96:99], v[112:115], v[104:107]
	v_mfma_f32_16x16x32_bf16 v[108:111], v[88:91], v[120:123], v[108:111]
	v_mfma_f32_16x16x32_bf16 v[112:115], v[92:95], v[116:119], 0
	v_mfma_f32_16x16x32_bf16 v[84:87], v[88:91], v[128:131], v[84:87]
	v_mfma_f32_16x16x32_bf16 v[88:91], v[92:95], v[124:127], 0
	v_mfma_f32_16x16x32_bf16 v[112:115], v[96:99], v[120:123], v[112:115]
	v_mfma_f32_16x16x32_bf16 v[88:91], v[96:99], v[128:131], v[88:91]
	s_barrier
	s_add_i32 s53, 0, 0x18000
	v_add_u32_e32 v222, s53, v148
	ds_read_b128 v[92:95], v222
	ds_read_b128 v[96:99], v222 offset:1024
	ds_read_b128 v[116:119], v222 offset:2048
	ds_read_b128 v[120:123], v222 offset:3072
	s_mov_b32 m0, s59
	v_lshl_add_u64 v[144:145], v[2:3], 0, s[40:41]
	ds_read_b128 v[124:127], v149 offset:32768
	ds_read_b128 v[128:131], v149 offset:33792
	ds_read_b128 v[166:169], v149 offset:34816
	ds_read_b128 v[170:173], v149 offset:35840
	ds_read_b128 v[174:177], v149 offset:36864
	ds_read_b128 v[178:181], v149 offset:37888
	ds_read_b128 v[182:185], v149 offset:38912
	ds_read_b128 v[186:189], v149 offset:39936
	global_load_lds_dwordx4 v[144:145], off
	v_lshl_add_u64 v[144:145], v[2:3], 0, s[78:79]
	s_mov_b32 m0, s62
	s_nop 0
	global_load_lds_dwordx4 v[144:145], off
	s_waitcnt lgkmcnt(8)
	s_barrier
	s_waitcnt lgkmcnt(0)
	v_mfma_f32_16x16x32_bf16 v[52:55], v[92:95], v[124:127], v[52:55]
	v_mfma_f32_16x16x32_bf16 v[56:59], v[116:119], v[124:127], v[56:59]
	v_mfma_f32_16x16x32_bf16 v[60:63], v[92:95], v[166:169], v[60:63]
	v_mfma_f32_16x16x32_bf16 v[64:67], v[116:119], v[166:169], v[64:67]
	v_mfma_f32_16x16x32_bf16 v[68:71], v[92:95], v[174:177], v[68:71]
	v_mfma_f32_16x16x32_bf16 v[72:75], v[116:119], v[174:177], v[72:75]
	v_mfma_f32_16x16x32_bf16 v[80:83], v[116:119], v[182:185], v[80:83]
	v_mfma_f32_16x16x32_bf16 v[52:55], v[96:99], v[128:131], v[52:55]
	v_mfma_f32_16x16x32_bf16 v[56:59], v[120:123], v[128:131], v[56:59]
	v_mfma_f32_16x16x32_bf16 v[60:63], v[96:99], v[170:173], v[60:63]
	v_mfma_f32_16x16x32_bf16 v[64:67], v[120:123], v[170:173], v[64:67]
	v_mfma_f32_16x16x32_bf16 v[68:71], v[96:99], v[178:181], v[68:71]
	v_mfma_f32_16x16x32_bf16 v[72:75], v[120:123], v[178:181], v[72:75]
	v_mfma_f32_16x16x32_bf16 v[76:79], v[92:95], v[182:185], v[76:79]
	v_mfma_f32_16x16x32_bf16 v[80:83], v[120:123], v[186:189], v[80:83]
	v_mfma_f32_16x16x32_bf16 v[76:79], v[96:99], v[186:189], v[76:79]
	s_barrier
	s_add_i32 s41, 0, 0x1c000
	s_mov_b64 s[78:79], 0x180
	s_add_i32 s53, s53, s56
	v_add_u32_e32 v226, s41, v148
	v_lshl_add_u64 v[144:145], v[136:137], 0, s[78:79]
	s_mov_b32 m0, s53
	s_mov_b64 s[0:1], 0x8180
	s_add_i32 s22, s53, 0x2000
	ds_read_b128 v[190:193], v226
	ds_read_b128 v[194:197], v226 offset:1024
	ds_read_b128 v[198:201], v226 offset:2048
	ds_read_b128 v[202:205], v226 offset:3072
	global_load_lds_dwordx4 v[144:145], off
	v_lshl_add_u64 v[144:145], v[136:137], 0, s[0:1]
	s_mov_b32 m0, s22
	s_nop 0
	global_load_lds_dwordx4 v[144:145], off
	s_barrier
	s_waitcnt lgkmcnt(0)
	v_mfma_f32_16x16x32_bf16 v[100:103], v[190:193], v[124:127], v[100:103]
	v_mfma_f32_16x16x32_bf16 v[20:23], v[198:201], v[124:127], v[20:23]
	v_mfma_f32_16x16x32_bf16 v[24:27], v[190:193], v[166:169], v[24:27]
	v_mfma_f32_16x16x32_bf16 v[28:31], v[198:201], v[166:169], v[28:31]
	v_mfma_f32_16x16x32_bf16 v[32:35], v[190:193], v[174:177], v[32:35]
	v_mfma_f32_16x16x32_bf16 v[36:39], v[198:201], v[174:177], v[36:39]
	v_mfma_f32_16x16x32_bf16 v[40:43], v[190:193], v[182:185], v[40:43]
	v_mfma_f32_16x16x32_bf16 v[44:47], v[198:201], v[182:185], v[44:47]
	v_mfma_f32_16x16x32_bf16 v[100:103], v[194:197], v[128:131], v[100:103]
	v_mfma_f32_16x16x32_bf16 v[20:23], v[202:205], v[128:131], v[20:23]
	v_mfma_f32_16x16x32_bf16 v[24:27], v[194:197], v[170:173], v[24:27]
	v_mfma_f32_16x16x32_bf16 v[28:31], v[202:205], v[170:173], v[28:31]
	v_mfma_f32_16x16x32_bf16 v[32:35], v[194:197], v[178:181], v[32:35]
	v_mfma_f32_16x16x32_bf16 v[36:39], v[202:205], v[178:181], v[36:39]
	v_mfma_f32_16x16x32_bf16 v[40:43], v[194:197], v[186:189], v[40:43]
	v_mfma_f32_16x16x32_bf16 v[44:47], v[202:205], v[186:189], v[44:47]
	s_barrier
	s_mov_b32 m0, s85
	v_lshl_add_u64 v[144:145], v[2:3], 0, s[78:79]
	ds_read_b128 v[124:127], v149 offset:49152
	ds_read_b128 v[128:131], v149 offset:50176
	ds_read_b128 v[166:169], v149 offset:51200
	ds_read_b128 v[170:173], v149 offset:52224
	ds_read_b128 v[174:177], v149 offset:53248
	ds_read_b128 v[178:181], v149 offset:54272
	ds_read_b128 v[182:185], v149 offset:55296
	ds_read_b128 v[186:189], v149 offset:56320
	global_load_lds_dwordx4 v[144:145], off
	v_lshl_add_u64 v[144:145], v[2:3], 0, s[0:1]
	s_mov_b32 m0, s86
	s_nop 0
	global_load_lds_dwordx4 v[144:145], off
	s_barrier
	s_waitcnt lgkmcnt(0)
	v_mfma_f32_16x16x32_bf16 v[132:135], v[92:95], v[124:127], v[132:135]
	v_mfma_f32_16x16x32_bf16 v[150:153], v[92:95], v[166:169], v[150:153]
	v_mfma_f32_16x16x32_bf16 v[4:7], v[92:95], v[182:185], v[4:7]
	v_mfma_f32_16x16x32_bf16 v[8:11], v[116:119], v[182:185], v[8:11]
	v_mfma_f32_16x16x32_bf16 v[132:135], v[96:99], v[128:131], v[132:135]
	v_mfma_f32_16x16x32_bf16 v[140:143], v[116:119], v[124:127], v[140:143]
	v_mfma_f32_16x16x32_bf16 v[150:153], v[96:99], v[170:173], v[150:153]
	v_mfma_f32_16x16x32_bf16 v[154:157], v[116:119], v[166:169], v[154:157]
	v_mfma_f32_16x16x32_bf16 v[158:161], v[92:95], v[174:177], v[158:161]
	v_mfma_f32_16x16x32_bf16 v[162:165], v[116:119], v[174:177], v[162:165]
	v_mfma_f32_16x16x32_bf16 v[4:7], v[96:99], v[186:189], v[4:7]
	v_mfma_f32_16x16x32_bf16 v[8:11], v[120:123], v[186:189], v[8:11]
	v_mfma_f32_16x16x32_bf16 v[140:143], v[120:123], v[128:131], v[140:143]
	v_mfma_f32_16x16x32_bf16 v[154:157], v[120:123], v[170:173], v[154:157]
	v_mfma_f32_16x16x32_bf16 v[158:161], v[96:99], v[178:181], v[158:161]
	v_mfma_f32_16x16x32_bf16 v[162:165], v[120:123], v[178:181], v[162:165]
	s_barrier
	s_mov_b64 s[0:1], 0x10180
	s_add_i32 s41, s41, s56
	v_lshl_add_u64 v[92:93], v[136:137], 0, s[0:1]
	s_mov_b32 m0, s41
	s_mov_b64 s[78:79], 0x18180
	s_add_i32 s40, s41, 0x2000
	global_load_lds_dwordx4 v[92:93], off
	v_lshl_add_u64 v[92:93], v[136:137], 0, s[78:79]
	s_mov_b32 m0, s40
	s_nop 0
	global_load_lds_dwordx4 v[92:93], off
	s_waitcnt vmcnt(6)
	s_barrier
	v_mfma_f32_16x16x32_bf16 v[12:15], v[190:193], v[124:127], v[12:15]
	v_mfma_f32_16x16x32_bf16 v[16:19], v[198:201], v[124:127], v[16:19]
	v_mfma_f32_16x16x32_bf16 v[48:51], v[190:193], v[166:169], v[48:51]
	v_mfma_f32_16x16x32_bf16 v[92:95], v[198:201], v[166:169], v[104:107]
	v_mfma_f32_16x16x32_bf16 v[96:99], v[190:193], v[174:177], v[108:111]
	v_mfma_f32_16x16x32_bf16 v[104:107], v[198:201], v[174:177], v[112:115]
	v_mfma_f32_16x16x32_bf16 v[84:87], v[190:193], v[182:185], v[84:87]
	v_mfma_f32_16x16x32_bf16 v[88:91], v[198:201], v[182:185], v[88:91]
	v_mfma_f32_16x16x32_bf16 v[12:15], v[194:197], v[128:131], v[12:15]
	v_mfma_f32_16x16x32_bf16 v[16:19], v[202:205], v[128:131], v[16:19]
	v_mfma_f32_16x16x32_bf16 v[48:51], v[194:197], v[170:173], v[48:51]
	v_mfma_f32_16x16x32_bf16 v[92:95], v[202:205], v[170:173], v[92:95]
	v_mfma_f32_16x16x32_bf16 v[96:99], v[194:197], v[178:181], v[96:99]
	v_mfma_f32_16x16x32_bf16 v[104:107], v[202:205], v[178:181], v[104:107]
	v_mfma_f32_16x16x32_bf16 v[84:87], v[194:197], v[186:189], v[84:87]
	v_mfma_f32_16x16x32_bf16 v[88:91], v[202:205], v[186:189], v[88:91]
	s_barrier
	ds_read_b128 v[108:111], v206
	ds_read_b128 v[112:115], v206 offset:1024
	ds_read_b128 v[116:119], v206 offset:2048
	ds_read_b128 v[120:123], v206 offset:3072
	s_mov_b32 m0, s10
	v_lshl_add_u64 v[136:137], v[2:3], 0, s[0:1]
	ds_read_b128 v[124:127], v149
	ds_read_b128 v[128:131], v149 offset:1024
	ds_read_b128 v[166:169], v149 offset:2048
	ds_read_b128 v[170:173], v149 offset:3072
	ds_read_b128 v[174:177], v149 offset:4096
	ds_read_b128 v[178:181], v149 offset:5120
	ds_read_b128 v[182:185], v149 offset:6144
	ds_read_b128 v[186:189], v149 offset:7168
	global_load_lds_dwordx4 v[136:137], off
	v_lshl_add_u64 v[2:3], v[2:3], 0, s[78:79]
	s_mov_b32 m0, s8
	s_nop 0
	global_load_lds_dwordx4 v[2:3], off
	s_waitcnt lgkmcnt(8)
	s_barrier
	s_waitcnt lgkmcnt(0)
	v_mfma_f32_16x16x32_bf16 v[52:55], v[108:111], v[124:127], v[52:55]
	v_mfma_f32_16x16x32_bf16 v[56:59], v[116:119], v[124:127], v[56:59]
	v_mfma_f32_16x16x32_bf16 v[60:63], v[108:111], v[166:169], v[60:63]
	v_mfma_f32_16x16x32_bf16 v[64:67], v[116:119], v[166:169], v[64:67]
	v_mfma_f32_16x16x32_bf16 v[68:71], v[108:111], v[174:177], v[68:71]
	v_mfma_f32_16x16x32_bf16 v[72:75], v[116:119], v[174:177], v[72:75]
	v_mfma_f32_16x16x32_bf16 v[80:83], v[116:119], v[182:185], v[80:83]
	v_mfma_f32_16x16x32_bf16 v[52:55], v[112:115], v[128:131], v[52:55]
	v_mfma_f32_16x16x32_bf16 v[56:59], v[120:123], v[128:131], v[56:59]
	v_mfma_f32_16x16x32_bf16 v[60:63], v[112:115], v[170:173], v[60:63]
	v_mfma_f32_16x16x32_bf16 v[64:67], v[120:123], v[170:173], v[64:67]
	v_mfma_f32_16x16x32_bf16 v[68:71], v[112:115], v[178:181], v[68:71]
	v_mfma_f32_16x16x32_bf16 v[72:75], v[120:123], v[178:181], v[72:75]
	v_mfma_f32_16x16x32_bf16 v[76:79], v[108:111], v[182:185], v[76:79]
	v_mfma_f32_16x16x32_bf16 v[80:83], v[120:123], v[186:189], v[80:83]
	v_mfma_f32_16x16x32_bf16 v[76:79], v[112:115], v[186:189], v[76:79]
	s_barrier
	s_mov_b32 m0, s11
	v_lshl_add_u64 v[144:145], s[50:51], 0, v[0:1]
	ds_read_b128 v[190:193], v207
	ds_read_b128 v[194:197], v207 offset:1024
	ds_read_b128 v[198:201], v207 offset:2048
	ds_read_b128 v[202:205], v207 offset:3072
	global_load_lds_dwordx4 v[144:145], off
	v_lshl_add_u64 v[2:3], v[144:145], 0, s[68:69]
	s_mov_b32 m0, s6
	s_nop 0
	global_load_lds_dwordx4 v[2:3], off
	s_barrier
	s_waitcnt lgkmcnt(0)
	v_mfma_f32_16x16x32_bf16 v[100:103], v[190:193], v[124:127], v[100:103]
	v_mfma_f32_16x16x32_bf16 v[20:23], v[198:201], v[124:127], v[20:23]
	v_mfma_f32_16x16x32_bf16 v[24:27], v[190:193], v[166:169], v[24:27]
	v_mfma_f32_16x16x32_bf16 v[28:31], v[198:201], v[166:169], v[28:31]
	v_mfma_f32_16x16x32_bf16 v[32:35], v[190:193], v[174:177], v[32:35]
	v_mfma_f32_16x16x32_bf16 v[36:39], v[198:201], v[174:177], v[36:39]
	v_mfma_f32_16x16x32_bf16 v[40:43], v[190:193], v[182:185], v[40:43]
	v_mfma_f32_16x16x32_bf16 v[100:103], v[194:197], v[128:131], v[100:103]
	v_mfma_f32_16x16x32_bf16 v[20:23], v[202:205], v[128:131], v[20:23]
	v_mfma_f32_16x16x32_bf16 v[24:27], v[194:197], v[170:173], v[24:27]
	v_mfma_f32_16x16x32_bf16 v[28:31], v[202:205], v[170:173], v[28:31]
	v_mfma_f32_16x16x32_bf16 v[32:35], v[194:197], v[178:181], v[32:35]
	v_mfma_f32_16x16x32_bf16 v[36:39], v[202:205], v[178:181], v[36:39]
	v_mfma_f32_16x16x32_bf16 v[166:169], v[194:197], v[186:189], v[40:43]
	v_mfma_f32_16x16x32_bf16 v[40:43], v[198:201], v[182:185], v[44:47]
	v_mfma_f32_16x16x32_bf16 v[170:173], v[202:205], v[186:189], v[40:43]
	s_barrier
	s_mov_b32 m0, s57
	v_lshl_add_u64 v[234:235], s[48:49], 0, v[138:139]
	s_nop 2
	ds_read_b128 v[40:43], v149 offset:16384
	ds_read_b128 v[44:47], v149 offset:17408
	ds_read_b128 v[124:127], v149 offset:18432
	ds_read_b128 v[128:131], v149 offset:19456
	ds_read_b128 v[174:177], v149 offset:20480
	ds_read_b128 v[178:181], v149 offset:21504
	ds_read_b128 v[182:185], v149 offset:22528
	ds_read_b128 v[186:189], v149 offset:23552
	global_load_lds_dwordx4 v[234:235], off
	v_lshl_add_u64 v[2:3], v[234:235], 0, s[68:69]
	s_mov_b32 m0, s58
	s_nop 0
	global_load_lds_dwordx4 v[2:3], off
	s_barrier
	s_waitcnt lgkmcnt(0)
	v_mfma_f32_16x16x32_bf16 v[132:135], v[108:111], v[40:43], v[132:135]
	v_mfma_f32_16x16x32_bf16 v[206:209], v[112:115], v[44:47], v[132:135]
	v_mfma_f32_16x16x32_bf16 v[132:135], v[116:119], v[40:43], v[140:143]
	v_mfma_f32_16x16x32_bf16 v[140:143], v[120:123], v[44:47], v[132:135]
	v_mfma_f32_16x16x32_bf16 v[132:135], v[108:111], v[124:127], v[150:153]
	v_mfma_f32_16x16x32_bf16 v[150:153], v[112:115], v[128:131], v[132:135]
	v_mfma_f32_16x16x32_bf16 v[132:135], v[116:119], v[124:127], v[154:157]
	v_mfma_f32_16x16x32_bf16 v[154:157], v[120:123], v[128:131], v[132:135]
	v_mfma_f32_16x16x32_bf16 v[132:135], v[108:111], v[174:177], v[158:161]
	v_mfma_f32_16x16x32_bf16 v[2:5], v[108:111], v[182:185], v[4:7]
	v_mfma_f32_16x16x32_bf16 v[6:9], v[116:119], v[182:185], v[8:11]
	v_mfma_f32_16x16x32_bf16 v[158:161], v[112:115], v[178:181], v[132:135]
	v_mfma_f32_16x16x32_bf16 v[132:135], v[116:119], v[174:177], v[162:165]
	v_mfma_f32_16x16x32_bf16 v[2:5], v[112:115], v[186:189], v[2:5]
	v_mfma_f32_16x16x32_bf16 v[6:9], v[120:123], v[186:189], v[6:9]
	v_mfma_f32_16x16x32_bf16 v[162:165], v[120:123], v[178:181], v[132:135]
	s_barrier
	s_mov_b32 m0, s9
	v_lshl_add_u64 v[10:11], v[144:145], 0, s[38:39]
	s_mov_b64 s[8:9], 0x18000
	global_load_lds_dwordx4 v[10:11], off
	v_lshl_add_u64 v[10:11], v[144:145], 0, s[8:9]
	s_mov_b32 m0, s7
	s_nop 0
	global_load_lds_dwordx4 v[10:11], off
	s_waitcnt vmcnt(6)
	s_barrier
	v_mfma_f32_16x16x32_bf16 v[10:13], v[190:193], v[40:43], v[12:15]
	v_mfma_f32_16x16x32_bf16 v[14:17], v[198:201], v[40:43], v[16:19]
	v_mfma_f32_16x16x32_bf16 v[40:43], v[190:193], v[124:127], v[48:51]
	v_mfma_f32_16x16x32_bf16 v[210:213], v[194:197], v[128:131], v[40:43]
	v_mfma_f32_16x16x32_bf16 v[40:43], v[198:201], v[124:127], v[92:95]
	v_mfma_f32_16x16x32_bf16 v[214:217], v[202:205], v[128:131], v[40:43]
	v_mfma_f32_16x16x32_bf16 v[40:43], v[190:193], v[174:177], v[96:99]
	v_mfma_f32_16x16x32_bf16 v[218:221], v[194:197], v[178:181], v[40:43]
	v_mfma_f32_16x16x32_bf16 v[40:43], v[198:201], v[174:177], v[104:107]
	v_mfma_f32_16x16x32_bf16 v[174:177], v[202:205], v[178:181], v[40:43]
	v_mfma_f32_16x16x32_bf16 v[40:43], v[190:193], v[182:185], v[84:87]
	v_mfma_f32_16x16x32_bf16 v[10:13], v[194:197], v[44:47], v[10:13]
	v_mfma_f32_16x16x32_bf16 v[14:17], v[202:205], v[44:47], v[14:17]
	v_mfma_f32_16x16x32_bf16 v[178:181], v[194:197], v[186:189], v[40:43]
	v_mfma_f32_16x16x32_bf16 v[40:43], v[198:201], v[182:185], v[88:91]
	v_mfma_f32_16x16x32_bf16 v[182:185], v[202:205], v[186:189], v[40:43]
	s_barrier
	ds_read_b128 v[186:189], v222
	ds_read_b128 v[190:193], v222 offset:1024
	ds_read_b128 v[194:197], v222 offset:2048
	ds_read_b128 v[198:201], v222 offset:3072
	s_mov_b32 m0, s59
	v_lshl_add_u64 v[18:19], v[234:235], 0, s[38:39]
	ds_read_b128 v[40:43], v149 offset:32768
	ds_read_b128 v[44:47], v149 offset:33792
	ds_read_b128 v[48:51], v149 offset:34816
	ds_read_b128 v[84:87], v149 offset:35840
	ds_read_b128 v[88:91], v149 offset:36864
	ds_read_b128 v[92:95], v149 offset:37888
	ds_read_b128 v[96:99], v149 offset:38912
	ds_read_b128 v[202:205], v149 offset:39936
	global_load_lds_dwordx4 v[18:19], off
	v_lshl_add_u64 v[18:19], v[234:235], 0, s[8:9]
	s_mov_b32 m0, s62
	s_nop 0
	global_load_lds_dwordx4 v[18:19], off
	s_waitcnt lgkmcnt(8)
	s_barrier
	s_waitcnt lgkmcnt(0)
	v_mfma_f32_16x16x32_bf16 v[52:55], v[186:189], v[40:43], v[52:55]
	v_mfma_f32_16x16x32_bf16 v[134:137], v[190:193], v[44:47], v[52:55]
	v_mfma_f32_16x16x32_bf16 v[52:55], v[194:197], v[40:43], v[56:59]
	v_mfma_f32_16x16x32_bf16 v[130:133], v[198:201], v[44:47], v[52:55]
	v_mfma_f32_16x16x32_bf16 v[52:55], v[186:189], v[48:51], v[60:63]
	v_mfma_f32_16x16x32_bf16 v[126:129], v[190:193], v[84:87], v[52:55]
	v_mfma_f32_16x16x32_bf16 v[52:55], v[194:197], v[48:51], v[64:67]
	v_mfma_f32_16x16x32_bf16 v[122:125], v[198:201], v[84:87], v[52:55]
	v_mfma_f32_16x16x32_bf16 v[52:55], v[186:189], v[88:91], v[68:71]
	v_mfma_f32_16x16x32_bf16 v[118:121], v[190:193], v[92:95], v[52:55]
	v_mfma_f32_16x16x32_bf16 v[52:55], v[194:197], v[88:91], v[72:75]
	v_mfma_f32_16x16x32_bf16 v[114:117], v[198:201], v[92:95], v[52:55]
	v_mfma_f32_16x16x32_bf16 v[52:55], v[186:189], v[96:99], v[76:79]
	v_mfma_f32_16x16x32_bf16 v[110:113], v[190:193], v[202:205], v[52:55]
	v_mfma_f32_16x16x32_bf16 v[52:55], v[194:197], v[96:99], v[80:83]
	v_mfma_f32_16x16x32_bf16 v[106:109], v[198:201], v[202:205], v[52:55]
	s_barrier
	s_mov_b32 m0, s53
	v_lshl_add_u64 v[18:19], v[144:145], 0, s[34:35]
	s_mov_b64 s[6:7], 0x8080
	ds_read_b128 v[74:77], v226
	ds_read_b128 v[78:81], v226 offset:1024
	ds_read_b128 v[222:225], v226 offset:2048
	ds_read_b128 v[226:229], v226 offset:3072
	global_load_lds_dwordx4 v[18:19], off
	v_lshl_add_u64 v[18:19], v[144:145], 0, s[6:7]
	s_mov_b32 m0, s22
	s_nop 0
	global_load_lds_dwordx4 v[18:19], off
	s_barrier
	s_waitcnt lgkmcnt(0)
	v_mfma_f32_16x16x32_bf16 v[18:21], v[222:225], v[40:43], v[20:23]
	v_mfma_f32_16x16x32_bf16 v[52:55], v[74:77], v[40:43], v[100:103]
	v_mfma_f32_16x16x32_bf16 v[58:61], v[226:229], v[44:47], v[18:21]
	v_mfma_f32_16x16x32_bf16 v[18:21], v[74:77], v[48:51], v[24:27]
	v_mfma_f32_16x16x32_bf16 v[62:65], v[78:81], v[44:47], v[52:55]
	v_mfma_f32_16x16x32_bf16 v[54:57], v[78:81], v[84:87], v[18:21]
	v_mfma_f32_16x16x32_bf16 v[18:21], v[222:225], v[48:51], v[28:31]
	v_mfma_f32_16x16x32_bf16 v[50:53], v[226:229], v[84:87], v[18:21]
	v_mfma_f32_16x16x32_bf16 v[18:21], v[74:77], v[88:91], v[32:35]
	v_mfma_f32_16x16x32_bf16 v[46:49], v[78:81], v[92:95], v[18:21]
	v_mfma_f32_16x16x32_bf16 v[18:21], v[222:225], v[88:91], v[36:39]
	v_mfma_f32_16x16x32_bf16 v[42:45], v[226:229], v[92:95], v[18:21]
	v_mfma_f32_16x16x32_bf16 v[18:21], v[74:77], v[96:99], v[166:169]
	v_mfma_f32_16x16x32_bf16 v[38:41], v[78:81], v[202:205], v[18:21]
	v_mfma_f32_16x16x32_bf16 v[18:21], v[222:225], v[96:99], v[170:173]
	v_mfma_f32_16x16x32_bf16 v[34:37], v[226:229], v[202:205], v[18:21]
	s_barrier
	s_mov_b32 m0, s85
	v_lshl_add_u64 v[26:27], v[234:235], 0, s[34:35]
	s_nop 2
	ds_read_b128 v[18:21], v149 offset:49152
	ds_read_b128 v[22:25], v149 offset:50176
	ds_read_b128 v[166:169], v149 offset:51200
	ds_read_b128 v[170:173], v149 offset:52224
	ds_read_b128 v[202:205], v149 offset:53248
	ds_read_b128 v[230:233], v149 offset:54272
	ds_read_b128 v[248:251], v149 offset:55296
	ds_read_b128 v[244:247], v149 offset:56320
	global_load_lds_dwordx4 v[26:27], off
	v_lshl_add_u64 v[26:27], v[234:235], 0, s[6:7]
	s_mov_b32 m0, s86
	s_nop 0
	global_load_lds_dwordx4 v[26:27], off
	s_barrier
	s_waitcnt lgkmcnt(0)
	v_mfma_f32_16x16x32_bf16 v[26:29], v[186:189], v[18:21], v[206:209]
	v_mfma_f32_16x16x32_bf16 v[102:105], v[190:193], v[22:25], v[26:29]
	v_mfma_f32_16x16x32_bf16 v[26:29], v[194:197], v[18:21], v[140:143]
	v_mfma_f32_16x16x32_bf16 v[98:101], v[198:201], v[22:25], v[26:29]
	v_mfma_f32_16x16x32_bf16 v[26:29], v[186:189], v[166:169], v[150:153]
	v_mfma_f32_16x16x32_bf16 v[94:97], v[190:193], v[170:173], v[26:29]
	v_mfma_f32_16x16x32_bf16 v[26:29], v[194:197], v[166:169], v[154:157]
	v_mfma_f32_16x16x32_bf16 v[90:93], v[198:201], v[170:173], v[26:29]
	v_mfma_f32_16x16x32_bf16 v[26:29], v[186:189], v[202:205], v[158:161]
	v_mfma_f32_16x16x32_bf16 v[2:5], v[186:189], v[248:251], v[2:5]
	v_mfma_f32_16x16x32_bf16 v[86:89], v[190:193], v[230:233], v[26:29]
	v_mfma_f32_16x16x32_bf16 v[26:29], v[194:197], v[202:205], v[162:165]
	v_mfma_f32_16x16x32_bf16 v[70:73], v[190:193], v[244:247], v[2:5]
	v_mfma_f32_16x16x32_bf16 v[2:5], v[194:197], v[248:251], v[6:9]
	v_mfma_f32_16x16x32_bf16 v[82:85], v[198:201], v[230:233], v[26:29]
	v_mfma_f32_16x16x32_bf16 v[66:69], v[198:201], v[244:247], v[2:5]
	s_barrier
	s_mov_b32 m0, s41
	s_nop 2
	v_lshl_add_u64 v[2:3], v[144:145], 0, s[72:73]
	global_load_lds_dwordx4 v[2:3], off
	v_lshl_add_u64 v[2:3], v[144:145], 0, vcc
	s_mov_b32 m0, s40
	s_nop 0
	global_load_lds_dwordx4 v[2:3], off
	s_waitcnt vmcnt(6)
	s_barrier
	v_mfma_f32_16x16x32_bf16 v[2:5], v[74:77], v[18:21], v[10:13]
	v_mfma_f32_16x16x32_bf16 v[30:33], v[78:81], v[22:25], v[2:5]
	v_mfma_f32_16x16x32_bf16 v[2:5], v[222:225], v[18:21], v[14:17]
	v_mfma_f32_16x16x32_bf16 v[26:29], v[226:229], v[22:25], v[2:5]
	v_mfma_f32_16x16x32_bf16 v[2:5], v[74:77], v[166:169], v[210:213]
	v_mfma_f32_16x16x32_bf16 v[22:25], v[78:81], v[170:173], v[2:5]
	v_mfma_f32_16x16x32_bf16 v[2:5], v[222:225], v[166:169], v[214:217]
	v_mfma_f32_16x16x32_bf16 v[18:21], v[226:229], v[170:173], v[2:5]
	v_mfma_f32_16x16x32_bf16 v[2:5], v[74:77], v[202:205], v[218:221]
	v_mfma_f32_16x16x32_bf16 v[14:17], v[78:81], v[230:233], v[2:5]
	v_mfma_f32_16x16x32_bf16 v[2:5], v[222:225], v[202:205], v[174:177]
	v_mfma_f32_16x16x32_bf16 v[10:13], v[226:229], v[230:233], v[2:5]
	v_mfma_f32_16x16x32_bf16 v[2:5], v[74:77], v[248:251], v[178:181]
	v_mfma_f32_16x16x32_bf16 v[6:9], v[78:81], v[244:247], v[2:5]
	v_mfma_f32_16x16x32_bf16 v[2:5], v[222:225], v[248:251], v[182:185]
	v_mfma_f32_16x16x32_bf16 v[2:5], v[226:229], v[244:247], v[2:5]
	s_barrier
	v_mov_b32_e32 v150, v146
	s_cmp_gt_i32 s52, 1
	s_mov_b64 s[8:9], -1
	s_cbranch_scc0 .LBB0_231
	s_lshl_b32 s6, s52, 13
	s_and_b32 s6, s6, 0x2000
	s_add_u32 s6, s44, s6
	s_addc_u32 s7, s45, 0
	s_mov_b64 s[8:9], 0

.LBB0_271:
	s_setprio 0
	v_readlane_b32 s0, v255, 8
	v_readlane_b32 s58, v255, 30
	v_readlane_b32 s62, v255, 10
	v_readlane_b32 s56, v255, 16
	v_readlane_b32 s72, v255, 7
	v_readlane_b32 s1, v255, 9
	v_readlane_b32 s59, v255, 31
	v_readlane_b32 s63, v255, 11
	v_readlane_b32 s57, v255, 17
	s_barrier

.LBB0_280:
	s_andn2_b64 vcc, exec, s[8:9]
	s_cbranch_vccnz .LBB0_456
	v_ashrrev_i32_e32 v3, 31, v0
	v_lshrrev_b32_e32 v3, 26, v3
	v_lshlrev_b32_e32 v2, 4, v0
	v_add_u32_e32 v3, v0, v3
	v_bfe_i32 v0, v0, 27, 1
	v_lshrrev_b32_e32 v0, 22, v0
	v_add_u32_e32 v0, v2, v0
	v_and_b32_e32 v0, 0xfffffc00, v0
	v_sub_u32_e32 v0, v2, v0
	v_lshrrev_b32_e32 v2, 4, v0
	v_bitop3_b32 v0, v2, v0, 32 bitop3:0x6c
	v_ashrrev_i32_e32 v7, 6, v3
	v_ashrrev_i32_e32 v3, 31, v0
	v_lshrrev_b32_e32 v3, 26, v3
	v_add_u32_e32 v3, v0, v3
	v_lshlrev_b32_e32 v2, 3, v7
	v_ashrrev_i32_e32 v8, 6, v3
	v_and_b32_e32 v3, 0xc0, v3
	v_and_b32_e32 v2, -16, v2
	v_sub_u32_e32 v0, v0, v3
	v_mov_b32_e32 v3, 1
	v_add_u32_e32 v2, v8, v2
	v_ashrrev_i16_sdwa v0, v3, sext(v0) dst_sel:DWORD dst_unused:UNUSED_PAD src0_sel:DWORD src1_sel:BYTE_0
	v_lshlrev_b32_e32 v4, 5, v7
	v_bfe_i32 v9, v0, 0, 16
	v_lshlrev_b32_e32 v0, 1, v2
	v_lshrrev_b32_e32 v3, 2, v2
	v_and_b32_e32 v5, 3, v8
	s_mov_b32 s0, 0xfffe0
	s_ashr_i32 s8, s51, 6
	v_and_b32_e32 v4, 32, v4
	v_and_b32_e32 v0, 24, v0
	v_and_b32_e32 v3, 4, v3
	v_and_or_b32 v5, v2, s0, v5
	v_or3_b32 v0, v5, v3, v0
	v_add_lshl_u32 v3, v4, v9, 1
	s_lshl_b32 s53, s8, 10
	v_lshl_add_u32 v0, v0, 12, v3
	s_add_i32 s54, s53, 0
	v_lshl_add_u32 v134, v2, 12, v3
	v_lshl_add_u64 v[2:3], s[6:7], 0, v[0:1]
	s_add_i32 m0, s54, 0x10000
	v_lshl_add_u64 v[4:5], v[2:3], 0, s[60:61]
	global_load_lds_dwordx4 v0, s[6:7]
	s_add_i32 m0, s54, 0x12000
	v_mov_b32_e32 v135, v1
	global_load_lds_dwordx4 v[4:5], off
	v_lshl_add_u64 v[4:5], s[4:5], 0, v[134:135]
	s_mov_b32 m0, s54
	s_add_i32 s55, s54, 0x2000
	global_load_lds_dwordx4 v134, s[4:5]
	v_lshl_add_u64 v[10:11], v[4:5], 0, s[60:61]
	s_mov_b32 m0, s55
	s_add_i32 s56, s54, 0x4000
	global_load_lds_dwordx4 v[10:11], off
	v_lshl_add_u64 v[10:11], v[2:3], 0, s[20:21]
	s_add_i32 m0, s54, 0x14000
	s_add_i32 s57, s54, 0x6000
	global_load_lds_dwordx4 v[10:11], off
	v_lshl_add_u64 v[10:11], v[2:3], 0, s[64:65]
	s_add_i32 m0, s54, 0x16000
	s_ashr_i32 s9, s51, 8
	global_load_lds_dwordx4 v[10:11], off
	v_lshl_add_u64 v[10:11], v[4:5], 0, s[20:21]
	s_mov_b32 m0, s56
	s_mov_b64 s[78:79], s[58:59]
	global_load_lds_dwordx4 v[10:11], off
	v_lshl_add_u64 v[10:11], v[4:5], 0, s[64:65]
	s_mov_b32 m0, s57
	s_cmp_lg_u32 s9, 1
	global_load_lds_dwordx4 v[10:11], off
	s_mov_b32 s2, 0x1000000
	s_cbranch_scc1 .LBB0_283
	s_setprio 1
	s_barrier

.LBB0_292:
	s_barrier
	v_mfma_f32_16x16x32_bf16 v[54:57], v[192:195], v[160:163], v[54:57]
	v_mfma_f32_16x16x32_bf16 v[50:53], v[200:203], v[160:163], v[50:53]
	v_mfma_f32_16x16x32_bf16 v[38:41], v[192:195], v[168:171], v[38:41]
	v_mfma_f32_16x16x32_bf16 v[34:37], v[200:203], v[168:171], v[34:37]
	v_mfma_f32_16x16x32_bf16 v[22:25], v[192:195], v[176:179], v[22:25]
	v_mfma_f32_16x16x32_bf16 v[18:21], v[200:203], v[176:179], v[18:21]
	v_mfma_f32_16x16x32_bf16 v[6:9], v[192:195], v[184:187], v[6:9]
	v_mfma_f32_16x16x32_bf16 v[2:5], v[200:203], v[184:187], v[2:5]
	v_mfma_f32_16x16x32_bf16 v[54:57], v[196:199], v[164:167], v[54:57]
	v_mfma_f32_16x16x32_bf16 v[50:53], v[204:207], v[164:167], v[50:53]
	v_mfma_f32_16x16x32_bf16 v[38:41], v[196:199], v[172:175], v[38:41]
	v_mfma_f32_16x16x32_bf16 v[34:37], v[204:207], v[172:175], v[34:37]
	v_mfma_f32_16x16x32_bf16 v[22:25], v[196:199], v[180:183], v[22:25]
	v_mfma_f32_16x16x32_bf16 v[18:21], v[204:207], v[180:183], v[18:21]
	v_mfma_f32_16x16x32_bf16 v[6:9], v[196:199], v[188:191], v[6:9]
	v_mfma_f32_16x16x32_bf16 v[2:5], v[204:207], v[188:191], v[2:5]
	s_barrier
.Lrot_enter_7:
	s_add_u32 s6, s4, 0x100
	s_addc_u32 s7, s5, 0
	s_add_i32 s11, 0, 0x10000
	v_add_u32_e32 v138, s11, v141
	ds_read_b128 v[130:133], v138
	ds_read_b128 v[148:151], v138 offset:1024
	ds_read_b128 v[152:155], v138 offset:2048
	ds_read_b128 v[156:159], v138 offset:3072
	s_cmp_eq_u32 s10, 28
	s_cselect_b32 s41, s47, s7
	s_cselect_b32 s40, s46, s6
	s_cselect_b32 s93, s49, s9
	s_cselect_b32 s92, s48, s8
	v_lshl_add_u64 v[144:145], s[4:5], 0, v[136:137]
	v_lshl_add_u64 v[192:193], v[144:145], 0, s[16:17]
	s_add_i32 m0, s54, 0xc000
	ds_read_b128 v[160:163], v142
	ds_read_b128 v[164:167], v142 offset:1024
	ds_read_b128 v[168:171], v142 offset:2048
	ds_read_b128 v[172:175], v142 offset:3072
	ds_read_b128 v[176:179], v142 offset:4096
	ds_read_b128 v[180:183], v142 offset:5120
	ds_read_b128 v[184:187], v142 offset:6144
	ds_read_b128 v[188:191], v142 offset:7168
	global_load_lds_dwordx4 v[192:193], off
	v_lshl_add_u64 v[144:145], v[144:145], 0, s[80:81]
	s_add_i32 m0, s54, 0xe000
	s_nop 0
	global_load_lds_dwordx4 v[144:145], off
	s_waitcnt lgkmcnt(8)
	s_barrier
	s_waitcnt lgkmcnt(0)
	v_mfma_f32_16x16x32_bf16 v[126:129], v[130:133], v[160:163], v[126:129]
	v_mfma_f32_16x16x32_bf16 v[122:125], v[152:155], v[160:163], v[122:125]
	v_mfma_f32_16x16x32_bf16 v[110:113], v[130:133], v[168:171], v[110:113]
	v_mfma_f32_16x16x32_bf16 v[106:109], v[152:155], v[168:171], v[106:109]
	v_mfma_f32_16x16x32_bf16 v[94:97], v[130:133], v[176:179], v[94:97]
	v_mfma_f32_16x16x32_bf16 v[90:93], v[152:155], v[176:179], v[90:93]
	v_mfma_f32_16x16x32_bf16 v[78:81], v[130:133], v[184:187], v[78:81]
	v_mfma_f32_16x16x32_bf16 v[74:77], v[152:155], v[184:187], v[74:77]
	v_mfma_f32_16x16x32_bf16 v[126:129], v[148:151], v[164:167], v[126:129]
	v_mfma_f32_16x16x32_bf16 v[122:125], v[156:159], v[164:167], v[122:125]
	v_mfma_f32_16x16x32_bf16 v[110:113], v[148:151], v[172:175], v[110:113]
	v_mfma_f32_16x16x32_bf16 v[106:109], v[156:159], v[172:175], v[106:109]
	v_mfma_f32_16x16x32_bf16 v[94:97], v[148:151], v[180:183], v[94:97]
	v_mfma_f32_16x16x32_bf16 v[90:93], v[156:159], v[180:183], v[90:93]
	v_mfma_f32_16x16x32_bf16 v[78:81], v[148:151], v[188:191], v[78:81]
	v_mfma_f32_16x16x32_bf16 v[74:77], v[156:159], v[188:191], v[74:77]
	s_barrier
	s_add_i32 s4, 0, 0x14000
	s_add_i32 s5, s11, s53
	v_add_u32_e32 v138, s4, v141
	v_lshl_add_u64 v[144:145], s[92:93], 0, v[0:1]
	s_mov_b32 m0, s5
	ds_read_b128 v[192:195], v138
	ds_read_b128 v[196:199], v138 offset:1024
	ds_read_b128 v[200:203], v138 offset:2048
	ds_read_b128 v[204:207], v138 offset:3072
	global_load_lds_dwordx4 v[144:145], off
	v_lshl_add_u64 v[208:209], v[144:145], 0, s[60:61]
	s_add_i32 m0, s5, 0x2000
	s_nop 0
	global_load_lds_dwordx4 v[208:209], off
	s_barrier
	s_waitcnt lgkmcnt(0)
	v_mfma_f32_16x16x32_bf16 v[118:121], v[192:195], v[160:163], v[118:121]
	v_mfma_f32_16x16x32_bf16 v[114:117], v[200:203], v[160:163], v[114:117]
	v_mfma_f32_16x16x32_bf16 v[102:105], v[192:195], v[168:171], v[102:105]
	v_mfma_f32_16x16x32_bf16 v[98:101], v[200:203], v[168:171], v[98:101]
	v_mfma_f32_16x16x32_bf16 v[86:89], v[192:195], v[176:179], v[86:89]
	v_mfma_f32_16x16x32_bf16 v[82:85], v[200:203], v[176:179], v[82:85]
	v_mfma_f32_16x16x32_bf16 v[70:73], v[192:195], v[184:187], v[70:73]
	v_mfma_f32_16x16x32_bf16 v[66:69], v[200:203], v[184:187], v[66:69]
	v_mfma_f32_16x16x32_bf16 v[118:121], v[196:199], v[164:167], v[118:121]
	v_mfma_f32_16x16x32_bf16 v[114:117], v[204:207], v[164:167], v[114:117]
	v_mfma_f32_16x16x32_bf16 v[102:105], v[196:199], v[172:175], v[102:105]
	v_mfma_f32_16x16x32_bf16 v[98:101], v[204:207], v[172:175], v[98:101]
	v_mfma_f32_16x16x32_bf16 v[86:89], v[196:199], v[180:183], v[86:89]
	v_mfma_f32_16x16x32_bf16 v[82:85], v[204:207], v[180:183], v[82:85]
	v_mfma_f32_16x16x32_bf16 v[70:73], v[196:199], v[188:191], v[70:73]
	v_mfma_f32_16x16x32_bf16 v[66:69], v[204:207], v[188:191], v[66:69]
	s_barrier
	s_mov_b32 m0, s54
	v_lshl_add_u64 v[208:209], s[40:41], 0, v[134:135]
	ds_read_b128 v[160:163], v142 offset:16384
	ds_read_b128 v[164:167], v142 offset:17408
	ds_read_b128 v[168:171], v142 offset:18432
	ds_read_b128 v[172:175], v142 offset:19456
	ds_read_b128 v[176:179], v142 offset:20480
	ds_read_b128 v[180:183], v142 offset:21504
	ds_read_b128 v[184:187], v142 offset:22528
	ds_read_b128 v[188:191], v142 offset:23552
	global_load_lds_dwordx4 v[208:209], off
	v_lshl_add_u64 v[210:211], v[208:209], 0, s[60:61]
	s_mov_b32 m0, s55
	s_nop 0
	global_load_lds_dwordx4 v[210:211], off
	s_barrier
	s_waitcnt lgkmcnt(0)
	v_mfma_f32_16x16x32_bf16 v[62:65], v[130:133], v[160:163], v[62:65]
	v_mfma_f32_16x16x32_bf16 v[58:61], v[152:155], v[160:163], v[58:61]
	v_mfma_f32_16x16x32_bf16 v[46:49], v[130:133], v[168:171], v[46:49]
	v_mfma_f32_16x16x32_bf16 v[42:45], v[152:155], v[168:171], v[42:45]
	v_mfma_f32_16x16x32_bf16 v[30:33], v[130:133], v[176:179], v[30:33]
	v_mfma_f32_16x16x32_bf16 v[26:29], v[152:155], v[176:179], v[26:29]
	v_mfma_f32_16x16x32_bf16 v[14:17], v[130:133], v[184:187], v[14:17]
	v_mfma_f32_16x16x32_bf16 v[10:13], v[152:155], v[184:187], v[10:13]
	v_mfma_f32_16x16x32_bf16 v[62:65], v[148:151], v[164:167], v[62:65]
	v_mfma_f32_16x16x32_bf16 v[58:61], v[156:159], v[164:167], v[58:61]
	v_mfma_f32_16x16x32_bf16 v[46:49], v[148:151], v[172:175], v[46:49]
	v_mfma_f32_16x16x32_bf16 v[42:45], v[156:159], v[172:175], v[42:45]
	v_mfma_f32_16x16x32_bf16 v[30:33], v[148:151], v[180:183], v[30:33]
	v_mfma_f32_16x16x32_bf16 v[26:29], v[156:159], v[180:183], v[26:29]
	v_mfma_f32_16x16x32_bf16 v[14:17], v[148:151], v[188:191], v[14:17]
	v_mfma_f32_16x16x32_bf16 v[10:13], v[156:159], v[188:191], v[10:13]
	s_barrier
	s_add_i32 s4, s4, s53
	v_lshl_add_u64 v[130:131], v[144:145], 0, s[20:21]
	s_mov_b32 m0, s4
	s_nop 0
	global_load_lds_dwordx4 v[130:131], off
	v_lshl_add_u64 v[130:131], v[144:145], 0, s[64:65]
	s_add_i32 m0, s4, 0x2000
	s_nop 0
	global_load_lds_dwordx4 v[130:131], off
	v_lshl_add_u64 v[230:231], v[208:209], 0, s[20:21]
	s_mov_b32 m0, s56
	s_nop 0
	global_load_lds_dwordx4 v[230:231], off
	v_lshl_add_u64 v[230:231], v[208:209], 0, s[64:65]
	s_mov_b32 m0, s57
	s_nop 0
	global_load_lds_dwordx4 v[230:231], off
	s_waitcnt vmcnt(8)
	s_barrier
	v_mfma_f32_16x16x32_bf16 v[54:57], v[192:195], v[160:163], v[54:57]
	v_mfma_f32_16x16x32_bf16 v[50:53], v[200:203], v[160:163], v[50:53]
	v_mfma_f32_16x16x32_bf16 v[38:41], v[192:195], v[168:171], v[38:41]
	v_mfma_f32_16x16x32_bf16 v[34:37], v[200:203], v[168:171], v[34:37]
	v_mfma_f32_16x16x32_bf16 v[22:25], v[192:195], v[176:179], v[22:25]
	v_mfma_f32_16x16x32_bf16 v[18:21], v[200:203], v[176:179], v[18:21]
	v_mfma_f32_16x16x32_bf16 v[6:9], v[192:195], v[184:187], v[6:9]
	v_mfma_f32_16x16x32_bf16 v[2:5], v[200:203], v[184:187], v[2:5]
	v_mfma_f32_16x16x32_bf16 v[54:57], v[196:199], v[164:167], v[54:57]
	v_mfma_f32_16x16x32_bf16 v[50:53], v[204:207], v[164:167], v[50:53]
	v_mfma_f32_16x16x32_bf16 v[38:41], v[196:199], v[172:175], v[38:41]
	v_mfma_f32_16x16x32_bf16 v[34:37], v[204:207], v[172:175], v[34:37]
	v_mfma_f32_16x16x32_bf16 v[22:25], v[196:199], v[180:183], v[22:25]
	v_mfma_f32_16x16x32_bf16 v[18:21], v[204:207], v[180:183], v[18:21]
	v_mfma_f32_16x16x32_bf16 v[6:9], v[196:199], v[188:191], v[6:9]
	v_mfma_f32_16x16x32_bf16 v[2:5], v[204:207], v[188:191], v[2:5]
	s_barrier
	s_add_i32 s4, 0, 0x18000
	v_add_u32_e32 v138, s4, v141
	ds_read_b128 v[130:133], v138
	ds_read_b128 v[148:151], v138 offset:1024
	ds_read_b128 v[152:155], v138 offset:2048
	ds_read_b128 v[156:159], v138 offset:3072
	ds_read_b128 v[160:163], v142 offset:32768
	ds_read_b128 v[164:167], v142 offset:33792
	ds_read_b128 v[168:171], v142 offset:34816
	ds_read_b128 v[172:175], v142 offset:35840
	ds_read_b128 v[176:179], v142 offset:36864
	ds_read_b128 v[180:183], v142 offset:37888
	ds_read_b128 v[184:187], v142 offset:38912
	ds_read_b128 v[188:191], v142 offset:39936
	s_waitcnt lgkmcnt(8)
	s_barrier
	s_waitcnt lgkmcnt(0)
	v_mfma_f32_16x16x32_bf16 v[126:129], v[130:133], v[160:163], v[126:129]
	v_mfma_f32_16x16x32_bf16 v[122:125], v[152:155], v[160:163], v[122:125]
	v_mfma_f32_16x16x32_bf16 v[110:113], v[130:133], v[168:171], v[110:113]
	v_mfma_f32_16x16x32_bf16 v[106:109], v[152:155], v[168:171], v[106:109]
	v_mfma_f32_16x16x32_bf16 v[94:97], v[130:133], v[176:179], v[94:97]
	v_mfma_f32_16x16x32_bf16 v[90:93], v[152:155], v[176:179], v[90:93]
	v_mfma_f32_16x16x32_bf16 v[78:81], v[130:133], v[184:187], v[78:81]
	v_mfma_f32_16x16x32_bf16 v[74:77], v[152:155], v[184:187], v[74:77]
	v_mfma_f32_16x16x32_bf16 v[126:129], v[148:151], v[164:167], v[126:129]
	v_mfma_f32_16x16x32_bf16 v[122:125], v[156:159], v[164:167], v[122:125]
	v_mfma_f32_16x16x32_bf16 v[110:113], v[148:151], v[172:175], v[110:113]
	v_mfma_f32_16x16x32_bf16 v[106:109], v[156:159], v[172:175], v[106:109]
	v_mfma_f32_16x16x32_bf16 v[94:97], v[148:151], v[180:183], v[94:97]
	v_mfma_f32_16x16x32_bf16 v[90:93], v[156:159], v[180:183], v[90:93]
	v_mfma_f32_16x16x32_bf16 v[78:81], v[148:151], v[188:191], v[78:81]
	v_mfma_f32_16x16x32_bf16 v[74:77], v[156:159], v[188:191], v[74:77]
	s_barrier
	s_add_i32 s5, 0, 0x1c000
	s_add_i32 s4, s4, s53
	v_add_u32_e32 v138, s5, v141
	v_lshl_add_u64 v[210:211], v[144:145], 0, s[34:35]
	s_mov_b32 m0, s4
	ds_read_b128 v[192:195], v138
	ds_read_b128 v[196:199], v138 offset:1024
	ds_read_b128 v[200:203], v138 offset:2048
	ds_read_b128 v[204:207], v138 offset:3072
	global_load_lds_dwordx4 v[210:211], off
	v_lshl_add_u64 v[210:211], v[144:145], 0, s[66:67]
	s_add_i32 m0, s4, 0x2000
	s_nop 0
	global_load_lds_dwordx4 v[210:211], off
	s_barrier
	s_waitcnt lgkmcnt(0)
	v_mfma_f32_16x16x32_bf16 v[118:121], v[192:195], v[160:163], v[118:121]
	v_mfma_f32_16x16x32_bf16 v[114:117], v[200:203], v[160:163], v[114:117]
	v_mfma_f32_16x16x32_bf16 v[102:105], v[192:195], v[168:171], v[102:105]
	v_mfma_f32_16x16x32_bf16 v[98:101], v[200:203], v[168:171], v[98:101]
	v_mfma_f32_16x16x32_bf16 v[86:89], v[192:195], v[176:179], v[86:89]
	v_mfma_f32_16x16x32_bf16 v[82:85], v[200:203], v[176:179], v[82:85]
	v_mfma_f32_16x16x32_bf16 v[70:73], v[192:195], v[184:187], v[70:73]
	v_mfma_f32_16x16x32_bf16 v[66:69], v[200:203], v[184:187], v[66:69]
	v_mfma_f32_16x16x32_bf16 v[118:121], v[196:199], v[164:167], v[118:121]
	v_mfma_f32_16x16x32_bf16 v[114:117], v[204:207], v[164:167], v[114:117]
	v_mfma_f32_16x16x32_bf16 v[102:105], v[196:199], v[172:175], v[102:105]
	v_mfma_f32_16x16x32_bf16 v[98:101], v[204:207], v[172:175], v[98:101]
	v_mfma_f32_16x16x32_bf16 v[86:89], v[196:199], v[180:183], v[86:89]
	v_mfma_f32_16x16x32_bf16 v[82:85], v[204:207], v[180:183], v[82:85]
	v_mfma_f32_16x16x32_bf16 v[70:73], v[196:199], v[188:191], v[70:73]
	v_mfma_f32_16x16x32_bf16 v[66:69], v[204:207], v[188:191], v[66:69]
	s_barrier
	s_mov_b32 m0, s62
	v_lshl_add_u64 v[210:211], v[208:209], 0, s[34:35]
	ds_read_b128 v[160:163], v142 offset:49152
	ds_read_b128 v[164:167], v142 offset:50176
	ds_read_b128 v[168:171], v142 offset:51200
	ds_read_b128 v[172:175], v142 offset:52224
	ds_read_b128 v[176:179], v142 offset:53248
	ds_read_b128 v[180:183], v142 offset:54272
	ds_read_b128 v[184:187], v142 offset:55296
	ds_read_b128 v[188:191], v142 offset:56320
	global_load_lds_dwordx4 v[210:211], off
	v_lshl_add_u64 v[208:209], v[208:209], 0, s[66:67]
	s_mov_b32 m0, s63
	s_nop 0
	global_load_lds_dwordx4 v[208:209], off
	s_barrier
	s_waitcnt lgkmcnt(0)
	v_mfma_f32_16x16x32_bf16 v[62:65], v[130:133], v[160:163], v[62:65]
	v_mfma_f32_16x16x32_bf16 v[58:61], v[152:155], v[160:163], v[58:61]
	v_mfma_f32_16x16x32_bf16 v[46:49], v[130:133], v[168:171], v[46:49]
	v_mfma_f32_16x16x32_bf16 v[42:45], v[152:155], v[168:171], v[42:45]
	v_mfma_f32_16x16x32_bf16 v[30:33], v[130:133], v[176:179], v[30:33]
	v_mfma_f32_16x16x32_bf16 v[26:29], v[152:155], v[176:179], v[26:29]
	v_mfma_f32_16x16x32_bf16 v[14:17], v[130:133], v[184:187], v[14:17]
	v_mfma_f32_16x16x32_bf16 v[10:13], v[152:155], v[184:187], v[10:13]
	v_mfma_f32_16x16x32_bf16 v[62:65], v[148:151], v[164:167], v[62:65]
	v_mfma_f32_16x16x32_bf16 v[58:61], v[156:159], v[164:167], v[58:61]
	v_mfma_f32_16x16x32_bf16 v[46:49], v[148:151], v[172:175], v[46:49]
	v_mfma_f32_16x16x32_bf16 v[42:45], v[156:159], v[172:175], v[42:45]
	v_mfma_f32_16x16x32_bf16 v[30:33], v[148:151], v[180:183], v[30:33]
	v_mfma_f32_16x16x32_bf16 v[26:29], v[156:159], v[180:183], v[26:29]
	v_mfma_f32_16x16x32_bf16 v[14:17], v[148:151], v[188:191], v[14:17]
	v_mfma_f32_16x16x32_bf16 v[10:13], v[156:159], v[188:191], v[10:13]
	s_barrier
	s_add_i32 s4, s5, s53
	v_lshl_add_u64 v[130:131], v[144:145], 0, s[16:17]
	s_mov_b32 m0, s4
	s_nop 0
	global_load_lds_dwordx4 v[130:131], off
	v_lshl_add_u64 v[130:131], v[144:145], 0, s[80:81]
	s_add_i32 m0, s4, 0x2000
	s_nop 0
	global_load_lds_dwordx4 v[130:131], off
	s_waitcnt vmcnt(6)
	s_add_i32 s10, s10, 2
	s_add_u32 s8, s8, 0x100
	s_addc_u32 s9, s9, 0
	s_cmp_gt_u32 s10, 29
	s_mov_b64 s[4:5], s[6:7]
	s_cbranch_scc0 .LBB0_292
	s_barrier
	v_mfma_f32_16x16x32_bf16 v[54:57], v[192:195], v[160:163], v[54:57]
	v_mfma_f32_16x16x32_bf16 v[50:53], v[200:203], v[160:163], v[50:53]
	v_mfma_f32_16x16x32_bf16 v[38:41], v[192:195], v[168:171], v[38:41]
	v_mfma_f32_16x16x32_bf16 v[34:37], v[200:203], v[168:171], v[34:37]
	v_mfma_f32_16x16x32_bf16 v[22:25], v[192:195], v[176:179], v[22:25]
	v_mfma_f32_16x16x32_bf16 v[18:21], v[200:203], v[176:179], v[18:21]
	v_mfma_f32_16x16x32_bf16 v[6:9], v[192:195], v[184:187], v[6:9]
	v_mfma_f32_16x16x32_bf16 v[2:5], v[200:203], v[184:187], v[2:5]
	v_mfma_f32_16x16x32_bf16 v[54:57], v[196:199], v[164:167], v[54:57]
	v_mfma_f32_16x16x32_bf16 v[50:53], v[204:207], v[164:167], v[50:53]
	v_mfma_f32_16x16x32_bf16 v[38:41], v[196:199], v[172:175], v[38:41]
	v_mfma_f32_16x16x32_bf16 v[34:37], v[204:207], v[172:175], v[34:37]
	v_mfma_f32_16x16x32_bf16 v[22:25], v[196:199], v[180:183], v[22:25]
	v_mfma_f32_16x16x32_bf16 v[18:21], v[204:207], v[180:183], v[18:21]
	v_mfma_f32_16x16x32_bf16 v[6:9], v[196:199], v[188:191], v[6:9]
	v_mfma_f32_16x16x32_bf16 v[2:5], v[204:207], v[188:191], v[2:5]
	s_barrier
	s_cmp_eq_u32 s52, 3
	v_mov_b32_e32 v144, v139
	s_cselect_b64 s[4:5], -1, 0
	s_cmp_lt_i32 s52, 5
	s_cbranch_scc1 .LBB0_295
	s_cmp_eq_u32 s52, 5
	s_cselect_b64 s[6:7], -1, 0
	s_movk_i32 s93, 0xf800
	s_cbranch_execz .LBB0_296
	s_branch .LBB0_297

.LBB0_455:
	s_setprio 0
	v_readlane_b32 s56, v255, 16
	v_readlane_b32 s54, v255, 22
	v_readlane_b32 s44, v255, 26
	v_readlane_b32 s72, v255, 7
	v_readlane_b32 s57, v255, 17
	v_readlane_b32 s55, v255, 23
	v_readlane_b32 s45, v255, 27
	s_movk_i32 s92, 0x4000
	s_barrier

.LBB0_475:
	s_add_u32 s49, s6, 0x10a00000
	s_addc_u32 s50, s7, 0
	s_add_u32 s51, s6, 0xb200000
	s_addc_u32 s52, s7, 0
	s_add_i32 s6, s40, s8
	v_ashrrev_i32_e32 v3, 31, v0
	s_ashr_i32 s7, s6, 31
	v_lshrrev_b32_e32 v3, 26, v3
	s_lshr_b32 s7, s7, 27
	v_lshlrev_b32_e32 v2, 4, v0
	v_add_u32_e32 v3, v0, v3
	v_bfe_i32 v0, v0, 27, 1
	s_add_i32 s7, s6, s7
	v_lshrrev_b32_e32 v0, 22, v0
	s_ashr_i32 s8, s7, 5
	s_and_b32 s7, s7, 0xffe0
	v_add_u32_e32 v0, v2, v0
	s_sub_i32 s6, s6, s7
	v_and_b32_e32 v0, 0xfffffc00, v0
	s_bfe_i32 s7, s6, 0x80000
	v_sub_u32_e32 v0, v2, v0
	s_bfe_u32 s7, s7, 0x2000d
	v_lshrrev_b32_e32 v2, 4, v0
	s_add_i32 s7, s6, s7
	v_bitop3_b32 v0, v2, v0, 32 bitop3:0x6c
	s_bfe_i32 s9, s7, 0x80000
	s_and_b32 s7, s7, 0xfc
	v_ashrrev_i32_e32 v6, 6, v3
	v_ashrrev_i32_e32 v3, 31, v0
	s_sub_i32 s6, s6, s7
	v_lshrrev_b32_e32 v3, 26, v3
	s_lshl_b32 s8, s8, 2
	s_sext_i32_i8 s6, s6
	s_ashr_i32 s10, s48, 6
	v_add_u32_e32 v3, v0, v3
	s_sext_i32_i16 s9, s9
	s_add_i32 s85, s8, s6
	s_ashr_i32 s11, s48, 8
	v_lshlrev_b32_e32 v2, 3, v6
	v_ashrrev_i32_e32 v7, 6, v3
	v_and_b32_e32 v3, 0xc0, v3
	s_lshl_b32 s53, s10, 10
	s_lshr_b32 s40, s9, 2
	s_mul_i32 s6, s85, 0x2c0000
	v_and_b32_e32 v2, 0x7ffff0, v2
	v_sub_u32_e32 v0, v0, v3
	v_mov_b32_e32 v3, 1
	s_mul_hi_i32 s7, s85, 0x2c0000
	s_add_u32 s6, s49, s6
	v_add_u32_e32 v2, v7, v2
	v_lshlrev_b32_e32 v4, 5, v6
	v_ashrrev_i16_sdwa v0, v3, sext(v0) dst_sel:DWORD dst_unused:UNUSED_PAD src0_sel:DWORD src1_sel:BYTE_0
	s_movk_i32 s0, 0x1600
	s_addc_u32 s7, s50, s7
	s_ashr_i32 s8, s9, 2
	v_and_b32_e32 v8, 32, v4
	v_bfe_i32 v9, v0, 0, 16
	v_mul_lo_u32 v0, v2, s0
	s_mul_hi_i32 s9, s8, 0x2c0000
	s_mul_i32 s8, s8, 0x2c0000
	v_or_b32_e32 v0, v0, v8
	s_add_u32 s8, s51, s8
	v_add_lshl_u32 v0, v0, v9, 1
	s_addc_u32 s9, s52, s9
	s_add_i32 s54, s53, 0
	v_lshl_add_u64 v[2:3], s[8:9], 0, v[0:1]
	s_add_i32 m0, s54, 0x10000
	v_lshl_add_u64 v[4:5], v[2:3], 0, s[26:27]
	global_load_lds_dwordx4 v0, s[8:9]
	s_add_i32 m0, s54, 0x12000
	s_add_i32 s55, s54, 0x2000
	global_load_lds_dwordx4 v[4:5], off
	v_lshl_add_u64 v[4:5], s[6:7], 0, v[0:1]
	s_mov_b32 m0, s54
	v_lshl_add_u64 v[12:13], v[4:5], 0, s[26:27]
	global_load_lds_dwordx4 v0, s[6:7]
	s_mov_b32 m0, s55
	s_add_i32 s56, s54, 0x4000
	global_load_lds_dwordx4 v[12:13], off
	v_lshl_add_u64 v[12:13], v[2:3], 0, s[28:29]
	s_add_i32 m0, s54, 0x14000
	s_add_i32 s57, s54, 0x6000
	global_load_lds_dwordx4 v[12:13], off
	v_lshl_add_u64 v[12:13], v[2:3], 0, s[30:31]
	s_add_i32 m0, s54, 0x16000
	s_mov_b64 s[92:93], s[58:59]
	global_load_lds_dwordx4 v[12:13], off
	v_lshl_add_u64 v[12:13], v[4:5], 0, s[28:29]
	s_mov_b32 m0, s56
	s_cmp_lg_u32 s11, 1
	global_load_lds_dwordx4 v[12:13], off
	v_lshl_add_u64 v[12:13], v[4:5], 0, s[30:31]
	s_mov_b32 m0, s57
	s_nop 0
	global_load_lds_dwordx4 v[12:13], off
	s_cbranch_scc1 .LBB0_477
	s_setprio 1
	s_barrier

.Lrot_enter_6:
	s_add_u32 s7, s46, 0xffea0080
	s_addc_u32 s78, s47, -1
	s_add_i32 s79, 0, 0x10000
	v_add_u32_e32 v132, s79, v135
	ds_read_b128 v[138:141], v132
	ds_read_b128 v[142:145], v132 offset:1024
	ds_read_b128 v[148:151], v132 offset:2048
	ds_read_b128 v[152:155], v132 offset:3072
	s_cmpk_eq_i32 s6, 0x54
	s_cselect_b32 s89, s43, s78
	s_cselect_b32 s88, s42, s7
	s_cselect_b32 s91, s45, s9
	s_cselect_b32 s90, s44, s8
	v_lshl_add_u64 v[132:133], s[46:47], 0, v[130:131]
	s_add_i32 m0, s54, 0xc000
	ds_read_b128 v[156:159], v136
	ds_read_b128 v[160:163], v136 offset:1024
	ds_read_b128 v[164:167], v136 offset:2048
	ds_read_b128 v[168:171], v136 offset:3072
	ds_read_b128 v[172:175], v136 offset:4096
	ds_read_b128 v[176:179], v136 offset:5120
	ds_read_b128 v[180:183], v136 offset:6144
	ds_read_b128 v[184:187], v136 offset:7168
	global_load_lds_dwordx4 v[132:133], off
	v_lshl_add_u64 v[132:133], v[132:133], 0, s[26:27]
	s_add_i32 m0, s54, 0xe000
	s_nop 0
	global_load_lds_dwordx4 v[132:133], off
	s_waitcnt lgkmcnt(8)
	s_barrier
	s_waitcnt lgkmcnt(0)
	v_mfma_f32_16x16x32_bf16 v[126:129], v[138:141], v[156:159], v[126:129]
	v_mfma_f32_16x16x32_bf16 v[122:125], v[148:151], v[156:159], v[122:125]
	v_mfma_f32_16x16x32_bf16 v[118:121], v[138:141], v[164:167], v[118:121]
	v_mfma_f32_16x16x32_bf16 v[110:113], v[148:151], v[164:167], v[110:113]
	v_mfma_f32_16x16x32_bf16 v[102:105], v[138:141], v[172:175], v[102:105]
	v_mfma_f32_16x16x32_bf16 v[94:97], v[148:151], v[172:175], v[94:97]
	v_mfma_f32_16x16x32_bf16 v[86:89], v[138:141], v[180:183], v[86:89]
	v_mfma_f32_16x16x32_bf16 v[78:81], v[148:151], v[180:183], v[78:81]
	v_mfma_f32_16x16x32_bf16 v[126:129], v[142:145], v[160:163], v[126:129]
	v_mfma_f32_16x16x32_bf16 v[122:125], v[152:155], v[160:163], v[122:125]
	v_mfma_f32_16x16x32_bf16 v[118:121], v[142:145], v[168:171], v[118:121]
	v_mfma_f32_16x16x32_bf16 v[110:113], v[152:155], v[168:171], v[110:113]
	v_mfma_f32_16x16x32_bf16 v[102:105], v[142:145], v[176:179], v[102:105]
	v_mfma_f32_16x16x32_bf16 v[94:97], v[152:155], v[176:179], v[94:97]
	v_mfma_f32_16x16x32_bf16 v[86:89], v[142:145], v[184:187], v[86:89]
	v_mfma_f32_16x16x32_bf16 v[78:81], v[152:155], v[184:187], v[78:81]
	s_barrier
	s_add_i32 s7, 0, 0x14000
	v_add_u32_e32 v132, s7, v135
	s_add_i32 s78, s79, s53
	ds_read_b128 v[188:191], v132
	ds_read_b128 v[192:195], v132 offset:1024
	ds_read_b128 v[196:199], v132 offset:2048
	ds_read_b128 v[200:203], v132 offset:3072
	v_lshl_add_u64 v[132:133], s[90:91], 0, v[0:1]
	s_mov_b32 m0, s78
	v_lshl_add_u64 v[204:205], v[132:133], 0, s[26:27]
	global_load_lds_dwordx4 v[132:133], off
	s_add_i32 m0, s78, 0x2000
	s_nop 0
	global_load_lds_dwordx4 v[204:205], off
	s_barrier
	s_waitcnt lgkmcnt(0)
	v_mfma_f32_16x16x32_bf16 v[114:117], v[188:191], v[156:159], v[114:117]
	v_mfma_f32_16x16x32_bf16 v[106:109], v[196:199], v[156:159], v[106:109]
	v_mfma_f32_16x16x32_bf16 v[98:101], v[188:191], v[164:167], v[98:101]
	v_mfma_f32_16x16x32_bf16 v[90:93], v[196:199], v[164:167], v[90:93]
	v_mfma_f32_16x16x32_bf16 v[82:85], v[188:191], v[172:175], v[82:85]
	v_mfma_f32_16x16x32_bf16 v[74:77], v[196:199], v[172:175], v[74:77]
	v_mfma_f32_16x16x32_bf16 v[70:73], v[188:191], v[180:183], v[70:73]
	v_mfma_f32_16x16x32_bf16 v[66:69], v[196:199], v[180:183], v[66:69]
	v_mfma_f32_16x16x32_bf16 v[114:117], v[192:195], v[160:163], v[114:117]
	v_mfma_f32_16x16x32_bf16 v[106:109], v[200:203], v[160:163], v[106:109]
	v_mfma_f32_16x16x32_bf16 v[98:101], v[192:195], v[168:171], v[98:101]
	v_mfma_f32_16x16x32_bf16 v[90:93], v[200:203], v[168:171], v[90:93]
	v_mfma_f32_16x16x32_bf16 v[82:85], v[192:195], v[176:179], v[82:85]
	v_mfma_f32_16x16x32_bf16 v[74:77], v[200:203], v[176:179], v[74:77]
	v_mfma_f32_16x16x32_bf16 v[70:73], v[192:195], v[184:187], v[70:73]
	v_mfma_f32_16x16x32_bf16 v[66:69], v[200:203], v[184:187], v[66:69]
	s_barrier
	s_mov_b32 m0, s54
	v_lshl_add_u64 v[204:205], s[88:89], 0, v[0:1]
	ds_read_b128 v[156:159], v136 offset:16384
	ds_read_b128 v[160:163], v136 offset:17408
	ds_read_b128 v[164:167], v136 offset:18432
	ds_read_b128 v[168:171], v136 offset:19456
	ds_read_b128 v[172:175], v136 offset:20480
	ds_read_b128 v[176:179], v136 offset:21504
	ds_read_b128 v[180:183], v136 offset:22528
	ds_read_b128 v[184:187], v136 offset:23552
	global_load_lds_dwordx4 v[204:205], off
	v_lshl_add_u64 v[206:207], v[204:205], 0, s[26:27]
	s_mov_b32 m0, s55
	s_nop 0
	global_load_lds_dwordx4 v[206:207], off
	s_barrier
	s_waitcnt lgkmcnt(0)
	v_mfma_f32_16x16x32_bf16 v[62:65], v[138:141], v[156:159], v[62:65]
	v_mfma_f32_16x16x32_bf16 v[58:61], v[148:151], v[156:159], v[58:61]
	v_mfma_f32_16x16x32_bf16 v[54:57], v[138:141], v[164:167], v[54:57]
	v_mfma_f32_16x16x32_bf16 v[46:49], v[148:151], v[164:167], v[46:49]
	v_mfma_f32_16x16x32_bf16 v[38:41], v[138:141], v[172:175], v[38:41]
	v_mfma_f32_16x16x32_bf16 v[30:33], v[148:151], v[172:175], v[30:33]
	v_mfma_f32_16x16x32_bf16 v[22:25], v[138:141], v[180:183], v[22:25]
	v_mfma_f32_16x16x32_bf16 v[14:17], v[148:151], v[180:183], v[14:17]
	v_mfma_f32_16x16x32_bf16 v[62:65], v[142:145], v[160:163], v[62:65]
	v_mfma_f32_16x16x32_bf16 v[58:61], v[152:155], v[160:163], v[58:61]
	v_mfma_f32_16x16x32_bf16 v[54:57], v[142:145], v[168:171], v[54:57]
	v_mfma_f32_16x16x32_bf16 v[46:49], v[152:155], v[168:171], v[46:49]
	v_mfma_f32_16x16x32_bf16 v[38:41], v[142:145], v[176:179], v[38:41]
	v_mfma_f32_16x16x32_bf16 v[30:33], v[152:155], v[176:179], v[30:33]
	v_mfma_f32_16x16x32_bf16 v[22:25], v[142:145], v[184:187], v[22:25]
	v_mfma_f32_16x16x32_bf16 v[14:17], v[152:155], v[184:187], v[14:17]
	s_barrier
	s_add_i32 s7, s7, s53
	v_lshl_add_u64 v[138:139], v[132:133], 0, s[28:29]
	s_mov_b32 m0, s7
	s_nop 0
	global_load_lds_dwordx4 v[138:139], off
	v_lshl_add_u64 v[138:139], v[132:133], 0, s[30:31]
	s_add_i32 m0, s7, 0x2000
	s_nop 0
	global_load_lds_dwordx4 v[138:139], off
	v_lshl_add_u64 v[230:231], v[204:205], 0, s[28:29]
	s_mov_b32 m0, s56
	s_nop 0
	global_load_lds_dwordx4 v[230:231], off
	v_lshl_add_u64 v[230:231], v[204:205], 0, s[30:31]
	s_mov_b32 m0, s57
	s_nop 0
	global_load_lds_dwordx4 v[230:231], off
	s_waitcnt vmcnt(8)
	s_barrier
	v_mfma_f32_16x16x32_bf16 v[50:53], v[188:191], v[156:159], v[50:53]
	v_mfma_f32_16x16x32_bf16 v[42:45], v[196:199], v[156:159], v[42:45]
	v_mfma_f32_16x16x32_bf16 v[34:37], v[188:191], v[164:167], v[34:37]
	v_mfma_f32_16x16x32_bf16 v[26:29], v[196:199], v[164:167], v[26:29]
	v_mfma_f32_16x16x32_bf16 v[18:21], v[188:191], v[172:175], v[18:21]
	v_mfma_f32_16x16x32_bf16 v[10:13], v[196:199], v[172:175], v[10:13]
	v_mfma_f32_16x16x32_bf16 v[6:9], v[188:191], v[180:183], v[6:9]
	v_mfma_f32_16x16x32_bf16 v[2:5], v[196:199], v[180:183], v[2:5]
	v_mfma_f32_16x16x32_bf16 v[50:53], v[192:195], v[160:163], v[50:53]
	v_mfma_f32_16x16x32_bf16 v[42:45], v[200:203], v[160:163], v[42:45]
	v_mfma_f32_16x16x32_bf16 v[34:37], v[192:195], v[168:171], v[34:37]
	v_mfma_f32_16x16x32_bf16 v[26:29], v[200:203], v[168:171], v[26:29]
	v_mfma_f32_16x16x32_bf16 v[18:21], v[192:195], v[176:179], v[18:21]
	v_mfma_f32_16x16x32_bf16 v[10:13], v[200:203], v[176:179], v[10:13]
	v_mfma_f32_16x16x32_bf16 v[6:9], v[192:195], v[184:187], v[6:9]
	v_mfma_f32_16x16x32_bf16 v[2:5], v[200:203], v[184:187], v[2:5]
	s_barrier
	s_add_i32 s7, 0, 0x18000
	v_add_u32_e32 v137, s7, v135
	ds_read_b128 v[138:141], v137
	ds_read_b128 v[142:145], v137 offset:1024
	ds_read_b128 v[148:151], v137 offset:2048
	ds_read_b128 v[152:155], v137 offset:3072
	ds_read_b128 v[156:159], v136 offset:32768
	ds_read_b128 v[160:163], v136 offset:33792
	ds_read_b128 v[164:167], v136 offset:34816
	ds_read_b128 v[168:171], v136 offset:35840
	ds_read_b128 v[172:175], v136 offset:36864
	ds_read_b128 v[176:179], v136 offset:37888
	ds_read_b128 v[180:183], v136 offset:38912
	ds_read_b128 v[184:187], v136 offset:39936
	s_waitcnt lgkmcnt(8)
	s_barrier
	s_waitcnt lgkmcnt(0)
	v_mfma_f32_16x16x32_bf16 v[126:129], v[138:141], v[156:159], v[126:129]
	v_mfma_f32_16x16x32_bf16 v[122:125], v[148:151], v[156:159], v[122:125]
	v_mfma_f32_16x16x32_bf16 v[118:121], v[138:141], v[164:167], v[118:121]
	v_mfma_f32_16x16x32_bf16 v[110:113], v[148:151], v[164:167], v[110:113]
	v_mfma_f32_16x16x32_bf16 v[102:105], v[138:141], v[172:175], v[102:105]
	v_mfma_f32_16x16x32_bf16 v[94:97], v[148:151], v[172:175], v[94:97]
	v_mfma_f32_16x16x32_bf16 v[86:89], v[138:141], v[180:183], v[86:89]
	v_mfma_f32_16x16x32_bf16 v[78:81], v[148:151], v[180:183], v[78:81]
	v_mfma_f32_16x16x32_bf16 v[126:129], v[142:145], v[160:163], v[126:129]
	v_mfma_f32_16x16x32_bf16 v[122:125], v[152:155], v[160:163], v[122:125]
	v_mfma_f32_16x16x32_bf16 v[118:121], v[142:145], v[168:171], v[118:121]
	v_mfma_f32_16x16x32_bf16 v[110:113], v[152:155], v[168:171], v[110:113]
	v_mfma_f32_16x16x32_bf16 v[102:105], v[142:145], v[176:179], v[102:105]
	v_mfma_f32_16x16x32_bf16 v[94:97], v[152:155], v[176:179], v[94:97]
	v_mfma_f32_16x16x32_bf16 v[86:89], v[142:145], v[184:187], v[86:89]
	v_mfma_f32_16x16x32_bf16 v[78:81], v[152:155], v[184:187], v[78:81]
	s_barrier
	s_add_i32 s78, 0, 0x1c000
	s_add_i32 s7, s7, s53
	v_add_u32_e32 v137, s78, v135
	v_lshl_add_u64 v[206:207], v[132:133], 0, s[34:35]
	s_mov_b32 m0, s7
	ds_read_b128 v[188:191], v137
	ds_read_b128 v[192:195], v137 offset:1024
	ds_read_b128 v[196:199], v137 offset:2048
	ds_read_b128 v[200:203], v137 offset:3072
	global_load_lds_dwordx4 v[206:207], off
	v_lshl_add_u64 v[206:207], v[132:133], 0, s[36:37]
	s_add_i32 m0, s7, 0x2000
	s_nop 0
	global_load_lds_dwordx4 v[206:207], off
	s_barrier
	s_waitcnt lgkmcnt(0)
	v_mfma_f32_16x16x32_bf16 v[114:117], v[188:191], v[156:159], v[114:117]
	v_mfma_f32_16x16x32_bf16 v[106:109], v[196:199], v[156:159], v[106:109]
	v_mfma_f32_16x16x32_bf16 v[98:101], v[188:191], v[164:167], v[98:101]
	v_mfma_f32_16x16x32_bf16 v[90:93], v[196:199], v[164:167], v[90:93]
	v_mfma_f32_16x16x32_bf16 v[82:85], v[188:191], v[172:175], v[82:85]
	v_mfma_f32_16x16x32_bf16 v[74:77], v[196:199], v[172:175], v[74:77]
	v_mfma_f32_16x16x32_bf16 v[70:73], v[188:191], v[180:183], v[70:73]
	v_mfma_f32_16x16x32_bf16 v[66:69], v[196:199], v[180:183], v[66:69]
	v_mfma_f32_16x16x32_bf16 v[114:117], v[192:195], v[160:163], v[114:117]
	v_mfma_f32_16x16x32_bf16 v[106:109], v[200:203], v[160:163], v[106:109]
	v_mfma_f32_16x16x32_bf16 v[98:101], v[192:195], v[168:171], v[98:101]
	v_mfma_f32_16x16x32_bf16 v[90:93], v[200:203], v[168:171], v[90:93]
	v_mfma_f32_16x16x32_bf16 v[82:85], v[192:195], v[176:179], v[82:85]
	v_mfma_f32_16x16x32_bf16 v[74:77], v[200:203], v[176:179], v[74:77]
	v_mfma_f32_16x16x32_bf16 v[70:73], v[192:195], v[184:187], v[70:73]
	v_mfma_f32_16x16x32_bf16 v[66:69], v[200:203], v[184:187], v[66:69]
	s_barrier
	s_mov_b32 m0, s62
	v_lshl_add_u64 v[206:207], v[204:205], 0, s[34:35]
	ds_read_b128 v[156:159], v136 offset:49152
	ds_read_b128 v[160:163], v136 offset:50176
	ds_read_b128 v[164:167], v136 offset:51200
	ds_read_b128 v[168:171], v136 offset:52224
	ds_read_b128 v[172:175], v136 offset:53248
	ds_read_b128 v[176:179], v136 offset:54272
	ds_read_b128 v[180:183], v136 offset:55296
	ds_read_b128 v[184:187], v136 offset:56320
	global_load_lds_dwordx4 v[206:207], off
	v_lshl_add_u64 v[204:205], v[204:205], 0, s[36:37]
	s_mov_b32 m0, s63
	s_nop 0
	global_load_lds_dwordx4 v[204:205], off
	s_barrier
	s_waitcnt lgkmcnt(0)
	v_mfma_f32_16x16x32_bf16 v[62:65], v[138:141], v[156:159], v[62:65]
	v_mfma_f32_16x16x32_bf16 v[58:61], v[148:151], v[156:159], v[58:61]
	v_mfma_f32_16x16x32_bf16 v[54:57], v[138:141], v[164:167], v[54:57]
	v_mfma_f32_16x16x32_bf16 v[46:49], v[148:151], v[164:167], v[46:49]
	v_mfma_f32_16x16x32_bf16 v[38:41], v[138:141], v[172:175], v[38:41]
	v_mfma_f32_16x16x32_bf16 v[30:33], v[148:151], v[172:175], v[30:33]
	v_mfma_f32_16x16x32_bf16 v[22:25], v[138:141], v[180:183], v[22:25]
	v_mfma_f32_16x16x32_bf16 v[14:17], v[148:151], v[180:183], v[14:17]
	v_mfma_f32_16x16x32_bf16 v[62:65], v[142:145], v[160:163], v[62:65]
	v_mfma_f32_16x16x32_bf16 v[58:61], v[152:155], v[160:163], v[58:61]
	v_mfma_f32_16x16x32_bf16 v[54:57], v[142:145], v[168:171], v[54:57]
	v_mfma_f32_16x16x32_bf16 v[46:49], v[152:155], v[168:171], v[46:49]
	v_mfma_f32_16x16x32_bf16 v[38:41], v[142:145], v[176:179], v[38:41]
	v_mfma_f32_16x16x32_bf16 v[30:33], v[152:155], v[176:179], v[30:33]
	v_mfma_f32_16x16x32_bf16 v[22:25], v[142:145], v[184:187], v[22:25]
	v_mfma_f32_16x16x32_bf16 v[14:17], v[152:155], v[184:187], v[14:17]
	s_barrier
	s_add_i32 s7, s78, s53
	v_lshl_add_u64 v[138:139], v[132:133], 0, s[18:19]
	s_mov_b32 m0, s7
	v_lshl_add_u64 v[132:133], v[132:133], 0, s[14:15]
	global_load_lds_dwordx4 v[138:139], off
	s_add_i32 m0, s7, 0x2000
	s_nop 0
	global_load_lds_dwordx4 v[132:133], off
	s_waitcnt vmcnt(6)
	s_add_i32 s6, s6, 2
	s_add_u32 s8, s8, 0x100
	s_addc_u32 s9, s9, 0
	s_add_u32 s46, s46, 0x100
	s_addc_u32 s47, s47, 0
	s_cmpk_gt_u32 s6, 0x55
	s_cbranch_scc0 .LBB0_485
	s_barrier
	v_mfma_f32_16x16x32_bf16 v[50:53], v[188:191], v[156:159], v[50:53]
	v_mfma_f32_16x16x32_bf16 v[42:45], v[196:199], v[156:159], v[42:45]
	v_mfma_f32_16x16x32_bf16 v[34:37], v[188:191], v[164:167], v[34:37]
	v_mfma_f32_16x16x32_bf16 v[26:29], v[196:199], v[164:167], v[26:29]
	v_mfma_f32_16x16x32_bf16 v[18:21], v[188:191], v[172:175], v[18:21]
	v_mfma_f32_16x16x32_bf16 v[10:13], v[196:199], v[172:175], v[10:13]
	v_mfma_f32_16x16x32_bf16 v[6:9], v[188:191], v[180:183], v[6:9]
	v_mfma_f32_16x16x32_bf16 v[2:5], v[196:199], v[180:183], v[2:5]
	v_mfma_f32_16x16x32_bf16 v[50:53], v[192:195], v[160:163], v[50:53]
	v_mfma_f32_16x16x32_bf16 v[42:45], v[200:203], v[160:163], v[42:45]
	v_mfma_f32_16x16x32_bf16 v[34:37], v[192:195], v[168:171], v[34:37]
	v_mfma_f32_16x16x32_bf16 v[26:29], v[200:203], v[168:171], v[26:29]
	v_mfma_f32_16x16x32_bf16 v[18:21], v[192:195], v[176:179], v[18:21]
	v_mfma_f32_16x16x32_bf16 v[10:13], v[200:203], v[176:179], v[10:13]
	v_mfma_f32_16x16x32_bf16 v[6:9], v[192:195], v[184:187], v[6:9]
	v_mfma_f32_16x16x32_bf16 v[2:5], v[200:203], v[184:187], v[2:5]
	s_barrier
	v_mov_b32_e32 v137, v134
	s_lshl_b32 s6, s86, 8
	v_ashrrev_i32_e32 v132, 2, v137
	s_or_b32 s6, s6, s59
	v_and_b32_e32 v132, -4, v132
	v_add_u32_e32 v132, s6, v132
	s_lshl_b32 s6, s85, 8
	s_add_i32 s6, s6, s58
	v_and_or_b32 v188, v137, 15, s6
	v_ashrrev_i32_e32 v189, 31, v188
	v_ashrrev_i32_e32 v133, 31, v132
	v_lshlrev_b64 v[206:207], 13, v[188:189]
	v_or_b32_e32 v156, 16, v188
	v_or_b32_e32 v172, 32, v188
	v_or_b32_e32 v188, 48, v188
	v_lshlrev_b64 v[132:133], 2, v[132:133]
	v_ashrrev_i32_e32 v157, 31, v156
	v_ashrrev_i32_e32 v173, 31, v172
	v_ashrrev_i32_e32 v189, 31, v188
	v_lshl_add_u64 v[204:205], s[4:5], 0, v[132:133]
	v_lshlrev_b64 v[208:209], 13, v[156:157]
	v_lshlrev_b64 v[210:211], 13, v[172:173]
	v_lshlrev_b64 v[212:213], 13, v[188:189]
	v_lshl_add_u64 v[152:153], v[204:205], 0, v[206:207]
	v_lshl_add_u64 v[168:169], v[204:205], 0, v[208:209]
	v_lshl_add_u64 v[184:185], v[204:205], 0, v[210:211]
	v_lshl_add_u64 v[200:201], v[204:205], 0, v[212:213]
	global_load_dwordx4 v[138:141], v[152:153], off
	global_load_dwordx4 v[142:145], v[152:153], off offset:64
	global_load_dwordx4 v[148:151], v[152:153], off offset:512
	s_nop 0
	global_load_dwordx4 v[152:155], v[152:153], off offset:576
	s_nop 0
	global_load_dwordx4 v[156:159], v[168:169], off
	global_load_dwordx4 v[160:163], v[168:169], off offset:64
	global_load_dwordx4 v[164:167], v[168:169], off offset:512
	s_nop 0
	global_load_dwordx4 v[168:171], v[168:169], off offset:576
	s_nop 0
	global_load_dwordx4 v[172:175], v[184:185], off
	global_load_dwordx4 v[176:179], v[184:185], off offset:64
	global_load_dwordx4 v[180:183], v[184:185], off offset:512
	s_nop 0
	global_load_dwordx4 v[184:187], v[184:185], off offset:576
	s_nop 0
	global_load_dwordx4 v[188:191], v[200:201], off
	global_load_dwordx4 v[192:195], v[200:201], off offset:64
	global_load_dwordx4 v[196:199], v[200:201], off offset:512
	s_nop 0
	global_load_dwordx4 v[200:203], v[200:201], off offset:576
	s_waitcnt vmcnt(0) lgkmcnt(0)
	v_pk_fma_f32 v[126:127], v[126:127], 0.5, v[138:139] op_sel_hi:[1,0,1]
	v_lshl_add_u64 v[138:139], s[4:5], 0, v[206:207]
	v_lshl_add_u64 v[138:139], v[138:139], 0, v[132:133]
	v_pk_fma_f32 v[116:117], v[116:117], 0.5, v[150:151] op_sel_hi:[1,0,1]
	v_pk_fma_f32 v[114:115], v[114:115], 0.5, v[148:149] op_sel_hi:[1,0,1]
	global_store_dwordx4 v[138:139], v[114:117], off offset:512
	v_pk_fma_f32 v[100:101], v[100:101], 0.5, v[166:167] op_sel_hi:[1,0,1]
	v_pk_fma_f32 v[98:99], v[98:99], 0.5, v[164:165] op_sel_hi:[1,0,1]
	v_lshl_add_u64 v[114:115], s[4:5], 0, v[208:209]
	v_lshl_add_u64 v[114:115], v[114:115], 0, v[132:133]
	global_store_dwordx4 v[114:115], v[98:101], off offset:512
	v_pk_fma_f32 v[84:85], v[84:85], 0.5, v[182:183] op_sel_hi:[1,0,1]
	v_pk_fma_f32 v[82:83], v[82:83], 0.5, v[180:181] op_sel_hi:[1,0,1]
	v_lshl_add_u64 v[98:99], s[4:5], 0, v[210:211]
	v_lshl_add_u64 v[98:99], v[98:99], 0, v[132:133]
	v_pk_fma_f32 v[108:109], v[108:109], 0.5, v[154:155] op_sel_hi:[1,0,1]
	v_pk_fma_f32 v[106:107], v[106:107], 0.5, v[152:153] op_sel_hi:[1,0,1]
	v_pk_fma_f32 v[92:93], v[92:93], 0.5, v[170:171] op_sel_hi:[1,0,1]
	v_pk_fma_f32 v[90:91], v[90:91], 0.5, v[168:169] op_sel_hi:[1,0,1]
	global_store_dwordx4 v[98:99], v[82:85], off offset:512
	v_pk_fma_f32 v[76:77], v[76:77], 0.5, v[186:187] op_sel_hi:[1,0,1]
	v_pk_fma_f32 v[74:75], v[74:75], 0.5, v[184:185] op_sel_hi:[1,0,1]
	v_lshl_add_u64 v[82:83], s[4:5], 0, v[212:213]
	global_store_dwordx4 v[138:139], v[106:109], off offset:576
	global_store_dwordx4 v[114:115], v[90:93], off offset:576
	global_store_dwordx4 v[98:99], v[74:77], off offset:576
	v_pk_fma_f32 v[108:109], v[120:121], 0.5, v[158:159] op_sel_hi:[1,0,1]
	v_pk_fma_f32 v[106:107], v[118:119], 0.5, v[156:157] op_sel_hi:[1,0,1]
	v_pk_fma_f32 v[92:93], v[104:105], 0.5, v[174:175] op_sel_hi:[1,0,1]
	v_pk_fma_f32 v[90:91], v[102:103], 0.5, v[172:173] op_sel_hi:[1,0,1]
	v_pk_fma_f32 v[76:77], v[88:89], 0.5, v[190:191] op_sel_hi:[1,0,1]
	v_pk_fma_f32 v[74:75], v[86:87], 0.5, v[188:189] op_sel_hi:[1,0,1]
	v_lshl_add_u64 v[82:83], v[82:83], 0, v[132:133]
	v_pk_fma_f32 v[128:129], v[128:129], 0.5, v[140:141] op_sel_hi:[1,0,1]
	v_pk_fma_f32 v[124:125], v[124:125], 0.5, v[144:145] op_sel_hi:[1,0,1]
	v_pk_fma_f32 v[122:123], v[122:123], 0.5, v[142:143] op_sel_hi:[1,0,1]
	global_store_dwordx4 v[114:115], v[106:109], off
	global_store_dwordx4 v[98:99], v[90:93], off
	global_store_dwordx4 v[82:83], v[74:77], off
	v_pk_fma_f32 v[108:109], v[112:113], 0.5, v[162:163] op_sel_hi:[1,0,1]
	v_pk_fma_f32 v[106:107], v[110:111], 0.5, v[160:161] op_sel_hi:[1,0,1]
	v_pk_fma_f32 v[92:93], v[96:97], 0.5, v[178:179] op_sel_hi:[1,0,1]
	v_pk_fma_f32 v[90:91], v[94:95], 0.5, v[176:177] op_sel_hi:[1,0,1]
	v_pk_fma_f32 v[76:77], v[80:81], 0.5, v[194:195] op_sel_hi:[1,0,1]
	v_pk_fma_f32 v[74:75], v[78:79], 0.5, v[192:193] op_sel_hi:[1,0,1]
	v_pk_fma_f32 v[72:73], v[72:73], 0.5, v[198:199] op_sel_hi:[1,0,1]
	v_pk_fma_f32 v[70:71], v[70:71], 0.5, v[196:197] op_sel_hi:[1,0,1]
	v_pk_fma_f32 v[68:69], v[68:69], 0.5, v[202:203] op_sel_hi:[1,0,1]
	v_pk_fma_f32 v[66:67], v[66:67], 0.5, v[200:201] op_sel_hi:[1,0,1]
	global_store_dwordx4 v[138:139], v[126:129], off
	global_store_dwordx4 v[138:139], v[122:125], off offset:64
	global_store_dwordx4 v[114:115], v[106:109], off offset:64
	global_store_dwordx4 v[98:99], v[90:93], off offset:64
	global_store_dwordx4 v[82:83], v[74:77], off offset:64
	global_store_dwordx4 v[82:83], v[70:73], off offset:512
	global_store_dwordx4 v[82:83], v[66:69], off offset:576
	s_mov_b64 s[6:7], 0x120000
	v_lshl_add_u64 v[140:141], v[206:207], 0, s[6:7]
	s_mov_b64 s[6:7], 0x140000
	v_lshl_add_u64 v[138:139], v[206:207], 0, s[0:1]
	v_lshl_add_u64 v[142:143], v[206:207], 0, s[6:7]
	v_lshl_add_u64 v[144:145], v[206:207], 0, s[28:29]
	v_lshl_add_u64 v[78:79], v[204:205], 0, v[138:139]
	v_lshl_add_u64 v[94:95], v[204:205], 0, v[140:141]
	v_lshl_add_u64 v[110:111], v[204:205], 0, v[142:143]
	v_lshl_add_u64 v[126:127], v[204:205], 0, v[144:145]
	global_load_dwordx4 v[66:69], v[78:79], off
	global_load_dwordx4 v[70:73], v[78:79], off offset:64
	global_load_dwordx4 v[74:77], v[78:79], off offset:512
	s_nop 0
	global_load_dwordx4 v[78:81], v[78:79], off offset:576
	s_nop 0
	global_load_dwordx4 v[82:85], v[94:95], off
	global_load_dwordx4 v[86:89], v[94:95], off offset:64
	global_load_dwordx4 v[90:93], v[94:95], off offset:512
	s_nop 0
	global_load_dwordx4 v[94:97], v[94:95], off offset:576
	s_nop 0
	global_load_dwordx4 v[98:101], v[110:111], off
	global_load_dwordx4 v[102:105], v[110:111], off offset:64
	global_load_dwordx4 v[106:109], v[110:111], off offset:512
	s_nop 0
	global_load_dwordx4 v[110:113], v[110:111], off offset:576
	s_nop 0
	global_load_dwordx4 v[114:117], v[126:127], off
	global_load_dwordx4 v[118:121], v[126:127], off offset:64
	global_load_dwordx4 v[122:125], v[126:127], off offset:512
	s_nop 0
	global_load_dwordx4 v[126:129], v[126:127], off offset:576
	s_waitcnt vmcnt(0) lgkmcnt(0)
	v_pk_fma_f32 v[62:63], v[62:63], 0.5, v[66:67] op_sel_hi:[1,0,1]
	v_lshl_add_u64 v[66:67], s[4:5], 0, v[138:139]
	v_lshl_add_u64 v[66:67], v[66:67], 0, v[132:133]
	v_pk_fma_f32 v[52:53], v[52:53], 0.5, v[76:77] op_sel_hi:[1,0,1]
	v_pk_fma_f32 v[50:51], v[50:51], 0.5, v[74:75] op_sel_hi:[1,0,1]
	global_store_dwordx4 v[66:67], v[50:53], off offset:512
	v_pk_fma_f32 v[36:37], v[36:37], 0.5, v[92:93] op_sel_hi:[1,0,1]
	v_pk_fma_f32 v[34:35], v[34:35], 0.5, v[90:91] op_sel_hi:[1,0,1]
	v_lshl_add_u64 v[50:51], s[4:5], 0, v[140:141]
	v_lshl_add_u64 v[50:51], v[50:51], 0, v[132:133]
	global_store_dwordx4 v[50:51], v[34:37], off offset:512
	v_pk_fma_f32 v[20:21], v[20:21], 0.5, v[108:109] op_sel_hi:[1,0,1]
	v_pk_fma_f32 v[18:19], v[18:19], 0.5, v[106:107] op_sel_hi:[1,0,1]
	v_lshl_add_u64 v[34:35], s[4:5], 0, v[142:143]
	v_lshl_add_u64 v[34:35], v[34:35], 0, v[132:133]
	v_pk_fma_f32 v[44:45], v[44:45], 0.5, v[80:81] op_sel_hi:[1,0,1]
	v_pk_fma_f32 v[42:43], v[42:43], 0.5, v[78:79] op_sel_hi:[1,0,1]
	v_pk_fma_f32 v[28:29], v[28:29], 0.5, v[96:97] op_sel_hi:[1,0,1]
	v_pk_fma_f32 v[26:27], v[26:27], 0.5, v[94:95] op_sel_hi:[1,0,1]
	global_store_dwordx4 v[34:35], v[18:21], off offset:512
	v_pk_fma_f32 v[12:13], v[12:13], 0.5, v[112:113] op_sel_hi:[1,0,1]
	v_pk_fma_f32 v[10:11], v[10:11], 0.5, v[110:111] op_sel_hi:[1,0,1]
	v_lshl_add_u64 v[18:19], s[4:5], 0, v[144:145]
	global_store_dwordx4 v[66:67], v[42:45], off offset:576
	global_store_dwordx4 v[50:51], v[26:29], off offset:576
	global_store_dwordx4 v[34:35], v[10:13], off offset:576
	v_pk_fma_f32 v[44:45], v[56:57], 0.5, v[84:85] op_sel_hi:[1,0,1]
	v_pk_fma_f32 v[42:43], v[54:55], 0.5, v[82:83] op_sel_hi:[1,0,1]
	v_pk_fma_f32 v[28:29], v[40:41], 0.5, v[100:101] op_sel_hi:[1,0,1]
	v_pk_fma_f32 v[26:27], v[38:39], 0.5, v[98:99] op_sel_hi:[1,0,1]
	v_pk_fma_f32 v[12:13], v[24:25], 0.5, v[116:117] op_sel_hi:[1,0,1]
	v_pk_fma_f32 v[10:11], v[22:23], 0.5, v[114:115] op_sel_hi:[1,0,1]
	v_lshl_add_u64 v[18:19], v[18:19], 0, v[132:133]
	v_pk_fma_f32 v[64:65], v[64:65], 0.5, v[68:69] op_sel_hi:[1,0,1]
	v_pk_fma_f32 v[60:61], v[60:61], 0.5, v[72:73] op_sel_hi:[1,0,1]
	v_pk_fma_f32 v[58:59], v[58:59], 0.5, v[70:71] op_sel_hi:[1,0,1]
	global_store_dwordx4 v[50:51], v[42:45], off
	global_store_dwordx4 v[34:35], v[26:29], off
	global_store_dwordx4 v[18:19], v[10:13], off
	v_pk_fma_f32 v[44:45], v[48:49], 0.5, v[88:89] op_sel_hi:[1,0,1]
	v_pk_fma_f32 v[42:43], v[46:47], 0.5, v[86:87] op_sel_hi:[1,0,1]
	v_pk_fma_f32 v[28:29], v[32:33], 0.5, v[104:105] op_sel_hi:[1,0,1]
	v_pk_fma_f32 v[26:27], v[30:31], 0.5, v[102:103] op_sel_hi:[1,0,1]
	v_pk_fma_f32 v[12:13], v[16:17], 0.5, v[120:121] op_sel_hi:[1,0,1]
	v_pk_fma_f32 v[10:11], v[14:15], 0.5, v[118:119] op_sel_hi:[1,0,1]
	v_pk_fma_f32 v[8:9], v[8:9], 0.5, v[124:125] op_sel_hi:[1,0,1]
	v_pk_fma_f32 v[6:7], v[6:7], 0.5, v[122:123] op_sel_hi:[1,0,1]
	v_pk_fma_f32 v[4:5], v[4:5], 0.5, v[128:129] op_sel_hi:[1,0,1]
	v_pk_fma_f32 v[2:3], v[2:3], 0.5, v[126:127] op_sel_hi:[1,0,1]
	global_store_dwordx4 v[66:67], v[62:65], off
	global_store_dwordx4 v[66:67], v[58:61], off offset:64
	global_store_dwordx4 v[50:51], v[42:45], off offset:64
	global_store_dwordx4 v[34:35], v[26:29], off offset:64
	global_store_dwordx4 v[18:19], v[10:13], off offset:64
	global_store_dwordx4 v[18:19], v[6:9], off offset:512
	global_store_dwordx4 v[18:19], v[2:5], off offset:576
	s_and_b64 vcc, exec, s[40:41]
	s_mov_b32 s85, s10
	s_mov_b32 s86, s11
	s_mov_b64 s[8:9], s[44:45]
	s_mov_b64 s[6:7], s[42:43]
	s_movk_i32 s89, 0x37ff
	s_mov_b32 s88, 0x16000
	s_movk_i32 s91, 0x60
	s_mov_b32 s78, 0x2a000000
	s_mov_b32 s79, 0x3fffe
	s_mov_b32 s90, 0xc0000
	s_cbranch_vccz .LBB0_478
	s_waitcnt vmcnt(0)
	s_cmpk_gt_u32 s48, 0xff
	s_cbranch_scc1 .LBB0_489
	s_barrier
.LBB0_489:
	s_setprio 0
	v_readlane_b32 s0, v255, 8
	v_readlane_b32 s62, v255, 10
	v_readlane_b32 s84, v255, 12
	v_readlane_b32 s86, v255, 14
	v_readlane_b32 s56, v255, 16
	v_readlane_b32 s52, v255, 18
	v_readlane_b32 s54, v255, 22
	v_readlane_b32 s44, v255, 26
	v_readlane_b32 s50, v255, 28
	v_readlane_b32 s72, v255, 7
	v_readlane_b32 s1, v255, 9
	s_mov_b64 s[58:59], s[92:93]
	v_readlane_b32 s63, v255, 11
	v_readlane_b32 s85, v255, 13
	v_readlane_b32 s87, v255, 15
	v_readlane_b32 s57, v255, 17
	v_readlane_b32 s53, v255, 19
	v_readlane_b32 s55, v255, 23
	v_readlane_b32 s45, v255, 27
	v_readlane_b32 s51, v255, 29
	s_movk_i32 s92, 0x4000
	s_movk_i32 s93, 0xf800
	s_barrier

.LBB0_491:
	s_andn2_b64 vcc, exec, s[4:5]
	s_cbranch_vccnz .LBB0_702
	s_cmp_lt_i32 s58, 5
	s_mov_b64 s[4:5], -1
	s_cbranch_scc1 .LBB0_558
	s_cmp_lt_i32 s58, 7
	s_cbranch_scc1 .LBB0_537
	s_cmp_lt_i32 s58, 8
	s_cbranch_scc1 .LBB0_515
	s_cmp_gt_i32 s58, 8
	s_cbranch_scc0 .LBB0_509
	s_mov_b32 s4, -1
	v_readlane_b32 s40, v255, 3
	v_mbcnt_lo_u32_b32 v0, s4, 0
	v_mbcnt_hi_u32_b32 v9, s4, v0
	v_readlane_b32 s4, v254, 4
	s_mov_b32 s11, s72
	v_readlane_b32 s41, v255, 4
	v_add_u32_e32 v0, s4, v9
	v_readlane_b32 s42, v255, 5
	v_readlane_b32 s43, v255, 6
	s_mov_b64 s[4:5], s[42:43]
	s_mov_b64 s[6:7], s[40:41]
	s_cmpk_gt_i32 s11, 0xaff
	v_readfirstlane_b32 s22, v0
	s_cbranch_scc1 .LBB0_508
	v_bfe_i32 v3, v0, 27, 1
	v_lshlrev_b32_e32 v2, 4, v0
	v_lshrrev_b32_e32 v3, 22, v3
	v_add_u32_e32 v3, v2, v3
	v_and_b32_e32 v3, 0xfffffc00, v3
	s_add_u32 s50, s4, 0x4600000
	v_sub_u32_e32 v2, v2, v3
	s_addc_u32 s51, s5, 0
	v_lshrrev_b32_e32 v3, 4, v2
	v_ashrrev_i32_e32 v4, 31, v0
	s_add_u32 s52, s4, 0x8600000
	v_bitop3_b32 v2, v3, v2, 32 bitop3:0x6c
	v_lshrrev_b32_e32 v4, 26, v4
	s_addc_u32 s53, s5, 0
	v_ashrrev_i32_e32 v3, 31, v2
	v_add_u32_e32 v0, v0, v4
	s_ashr_i32 s6, s11, 31
	v_lshrrev_b32_e32 v3, 26, v3
	v_ashrrev_i32_e32 v7, 6, v0
	s_lshr_b32 s6, s6, 29
	v_add_u32_e32 v3, v2, v3
	v_lshlrev_b32_e32 v0, 3, v7
	s_add_i32 s6, s11, s6
	s_ashr_i32 s40, s22, 6
	v_ashrrev_i32_e32 v6, 6, v3
	v_and_b32_e32 v0, -16, v0
	s_ashr_i32 s7, s6, 3
	s_and_b32 s6, s6, -8
	s_ashr_i32 s41, s22, 8
	s_lshl_b32 s54, s40, 10
	v_add_u32_e32 v4, v6, v0
	v_and_b32_e32 v0, 3, v6
	s_mov_b32 s0, 0xfffe0
	s_sub_i32 s6, s11, s6
	v_and_or_b32 v0, v4, s0, v0
	s_cmp_lt_i32 s6, 0
	s_movk_i32 s0, 0x161
	s_cselect_b32 s8, s0, 0x160
	s_mul_i32 s6, s8, s6
	s_add_i32 s6, s6, s7
	s_mul_hi_i32 s7, s6, 0x2e8ba2e9
	s_lshr_b32 s8, s7, 31
	s_ashr_i32 s7, s7, 6
	s_add_i32 s7, s7, s8
	s_lshl_b32 s8, s7, 3
	s_mulk_i32 s7, 0x160
	s_sub_i32 s6, s6, s7
	s_bfe_u32 s7, s6, 0x3001c
	s_add_i32 s7, s6, s7
	s_sext_i32_i16 s9, s7
	s_and_b32 s7, s7, 0xfff8
	s_sub_i32 s6, s6, s7
	s_sext_i32_i16 s6, s6
	s_add_i32 s48, s8, s6
	s_ashr_i32 s49, s48, 31
	v_lshrrev_b32_e32 v5, 2, v4
	v_lshlrev_b32_e32 v8, 1, v4
	v_and_b32_e32 v3, 0xc0, v3
	s_lshr_b32 s10, s9, 3
	s_lshl_b64 s[6:7], s[48:49], 20
	v_and_b32_e32 v5, 4, v5
	v_and_b32_e32 v8, 24, v8
	v_sub_u32_e32 v2, v2, v3
	v_mov_b32_e32 v3, 1
	s_add_u32 s6, s50, s6
	v_or3_b32 v0, v0, v5, v8
	v_lshlrev_b32_e32 v5, 5, v7
	v_ashrrev_i16_sdwa v2, v3, sext(v2) dst_sel:DWORD dst_unused:UNUSED_PAD src0_sel:DWORD src1_sel:BYTE_0
	s_addc_u32 s7, s51, s7
	s_bfe_i64 s[8:9], s[10:11], 0x100000
	v_and_b32_e32 v5, 32, v5
	v_bfe_i32 v8, v2, 0, 16
	s_lshl_b64 s[8:9], s[8:9], 20
	v_add_lshl_u32 v2, v5, v8, 1
	s_add_u32 s8, s52, s8
	v_lshl_add_u32 v0, v0, 12, v2
	s_addc_u32 s9, s53, s9
	s_add_i32 s49, s54, 0
	v_lshl_add_u32 v130, v4, 12, v2
	v_lshl_add_u64 v[2:3], s[8:9], 0, v[0:1]
	s_add_i32 m0, s49, 0x10000
	v_lshl_add_u64 v[4:5], v[2:3], 0, s[60:61]
	global_load_lds_dwordx4 v0, s[8:9]
	s_add_i32 m0, s49, 0x12000
	v_mov_b32_e32 v131, v1
	global_load_lds_dwordx4 v[4:5], off
	v_lshl_add_u64 v[4:5], s[6:7], 0, v[130:131]
	s_mov_b32 m0, s49
	s_add_i32 s55, s49, 0x2000
	global_load_lds_dwordx4 v130, s[6:7]
	v_lshl_add_u64 v[10:11], v[4:5], 0, s[60:61]
	s_mov_b32 m0, s55
	s_add_i32 s56, s49, 0x4000
	global_load_lds_dwordx4 v[10:11], off
	v_lshl_add_u64 v[10:11], v[2:3], 0, s[20:21]
	s_add_i32 m0, s49, 0x14000
	s_add_i32 s57, s49, 0x6000
	global_load_lds_dwordx4 v[10:11], off
	v_lshl_add_u64 v[10:11], v[2:3], 0, s[64:65]
	s_add_i32 m0, s49, 0x16000
	s_mov_b64 s[92:93], s[58:59]
	global_load_lds_dwordx4 v[10:11], off
	v_lshl_add_u64 v[10:11], v[4:5], 0, s[20:21]
	s_mov_b32 m0, s56
	s_cmp_lg_u32 s41, 1
	global_load_lds_dwordx4 v[10:11], off
	v_lshl_add_u64 v[10:11], v[4:5], 0, s[64:65]
	s_mov_b32 m0, s57
	s_nop 0
	global_load_lds_dwordx4 v[10:11], off
	s_cbranch_scc1 .LBB0_499
	s_setprio 1
	s_barrier

.Lrot_enter_5:
	s_add_u32 s8, s6, 0x100
	s_addc_u32 s9, s7, 0
	s_add_i32 s78, 0, 0x10000
	v_add_u32_e32 v134, s78, v137
	ds_read_b128 v[140:143], v134
	ds_read_b128 v[148:151], v134 offset:1024
	ds_read_b128 v[152:155], v134 offset:2048
	ds_read_b128 v[156:159], v134 offset:3072
	s_cmp_eq_u32 s87, 28
	s_cselect_b32 s89, s43, s9
	s_cselect_b32 s88, s42, s8
	s_cselect_b32 s91, s47, s86
	s_cselect_b32 s90, s46, s41
	v_lshl_add_u64 v[134:135], s[6:7], 0, v[132:133]
	v_lshl_add_u64 v[144:145], v[134:135], 0, s[16:17]
	s_add_i32 m0, s49, 0xc000
	ds_read_b128 v[160:163], v138
	ds_read_b128 v[164:167], v138 offset:1024
	ds_read_b128 v[168:171], v138 offset:2048
	ds_read_b128 v[172:175], v138 offset:3072
	ds_read_b128 v[176:179], v138 offset:4096
	ds_read_b128 v[180:183], v138 offset:5120
	ds_read_b128 v[184:187], v138 offset:6144
	ds_read_b128 v[188:191], v138 offset:7168
	global_load_lds_dwordx4 v[144:145], off
	v_lshl_add_u64 v[134:135], v[134:135], 0, s[80:81]
	s_add_i32 m0, s49, 0xe000
	s_nop 0
	global_load_lds_dwordx4 v[134:135], off
	s_waitcnt lgkmcnt(8)
	s_barrier
	s_waitcnt lgkmcnt(0)
	v_mfma_f32_16x16x32_bf16 v[126:129], v[140:143], v[160:163], v[126:129]
	v_mfma_f32_16x16x32_bf16 v[118:121], v[152:155], v[160:163], v[118:121]
	v_mfma_f32_16x16x32_bf16 v[110:113], v[140:143], v[168:171], v[110:113]
	v_mfma_f32_16x16x32_bf16 v[102:105], v[152:155], v[168:171], v[102:105]
	v_mfma_f32_16x16x32_bf16 v[94:97], v[140:143], v[176:179], v[94:97]
	v_mfma_f32_16x16x32_bf16 v[86:89], v[152:155], v[176:179], v[86:89]
	v_mfma_f32_16x16x32_bf16 v[78:81], v[140:143], v[184:187], v[78:81]
	v_mfma_f32_16x16x32_bf16 v[70:73], v[152:155], v[184:187], v[70:73]
	v_mfma_f32_16x16x32_bf16 v[126:129], v[148:151], v[164:167], v[126:129]
	v_mfma_f32_16x16x32_bf16 v[118:121], v[156:159], v[164:167], v[118:121]
	v_mfma_f32_16x16x32_bf16 v[110:113], v[148:151], v[172:175], v[110:113]
	v_mfma_f32_16x16x32_bf16 v[102:105], v[156:159], v[172:175], v[102:105]
	v_mfma_f32_16x16x32_bf16 v[94:97], v[148:151], v[180:183], v[94:97]
	v_mfma_f32_16x16x32_bf16 v[86:89], v[156:159], v[180:183], v[86:89]
	v_mfma_f32_16x16x32_bf16 v[78:81], v[148:151], v[188:191], v[78:81]
	v_mfma_f32_16x16x32_bf16 v[70:73], v[156:159], v[188:191], v[70:73]
	s_barrier
	s_add_i32 s6, 0, 0x14000
	v_add_u32_e32 v134, s6, v137
	s_add_i32 s7, s78, s54
	ds_read_b128 v[192:195], v134
	ds_read_b128 v[196:199], v134 offset:1024
	ds_read_b128 v[200:203], v134 offset:2048
	ds_read_b128 v[204:207], v134 offset:3072
	v_lshl_add_u64 v[134:135], s[90:91], 0, v[0:1]
	s_mov_b32 m0, s7
	v_lshl_add_u64 v[144:145], v[134:135], 0, s[60:61]
	global_load_lds_dwordx4 v[134:135], off
	s_add_i32 m0, s7, 0x2000
	s_nop 0
	global_load_lds_dwordx4 v[144:145], off
	s_barrier
	s_waitcnt lgkmcnt(0)
	v_mfma_f32_16x16x32_bf16 v[122:125], v[192:195], v[160:163], v[122:125]
	v_mfma_f32_16x16x32_bf16 v[114:117], v[200:203], v[160:163], v[114:117]
	v_mfma_f32_16x16x32_bf16 v[106:109], v[192:195], v[168:171], v[106:109]
	v_mfma_f32_16x16x32_bf16 v[98:101], v[200:203], v[168:171], v[98:101]
	v_mfma_f32_16x16x32_bf16 v[90:93], v[192:195], v[176:179], v[90:93]
	v_mfma_f32_16x16x32_bf16 v[82:85], v[200:203], v[176:179], v[82:85]
	v_mfma_f32_16x16x32_bf16 v[74:77], v[192:195], v[184:187], v[74:77]
	v_mfma_f32_16x16x32_bf16 v[66:69], v[200:203], v[184:187], v[66:69]
	v_mfma_f32_16x16x32_bf16 v[122:125], v[196:199], v[164:167], v[122:125]
	v_mfma_f32_16x16x32_bf16 v[114:117], v[204:207], v[164:167], v[114:117]
	v_mfma_f32_16x16x32_bf16 v[106:109], v[196:199], v[172:175], v[106:109]
	v_mfma_f32_16x16x32_bf16 v[98:101], v[204:207], v[172:175], v[98:101]
	v_mfma_f32_16x16x32_bf16 v[90:93], v[196:199], v[180:183], v[90:93]
	v_mfma_f32_16x16x32_bf16 v[82:85], v[204:207], v[180:183], v[82:85]
	v_mfma_f32_16x16x32_bf16 v[74:77], v[196:199], v[188:191], v[74:77]
	v_mfma_f32_16x16x32_bf16 v[66:69], v[204:207], v[188:191], v[66:69]
	s_barrier
	s_mov_b32 m0, s49
	v_lshl_add_u64 v[144:145], s[88:89], 0, v[130:131]
	ds_read_b128 v[160:163], v138 offset:16384
	ds_read_b128 v[164:167], v138 offset:17408
	ds_read_b128 v[168:171], v138 offset:18432
	ds_read_b128 v[172:175], v138 offset:19456
	ds_read_b128 v[176:179], v138 offset:20480
	ds_read_b128 v[180:183], v138 offset:21504
	ds_read_b128 v[184:187], v138 offset:22528
	ds_read_b128 v[188:191], v138 offset:23552
	global_load_lds_dwordx4 v[144:145], off
	v_lshl_add_u64 v[208:209], v[144:145], 0, s[60:61]
	s_mov_b32 m0, s55
	s_nop 0
	global_load_lds_dwordx4 v[208:209], off
	s_barrier
	s_waitcnt lgkmcnt(0)
	v_mfma_f32_16x16x32_bf16 v[62:65], v[140:143], v[160:163], v[62:65]
	v_mfma_f32_16x16x32_bf16 v[54:57], v[152:155], v[160:163], v[54:57]
	v_mfma_f32_16x16x32_bf16 v[46:49], v[140:143], v[168:171], v[46:49]
	v_mfma_f32_16x16x32_bf16 v[38:41], v[152:155], v[168:171], v[38:41]
	v_mfma_f32_16x16x32_bf16 v[30:33], v[140:143], v[176:179], v[30:33]
	v_mfma_f32_16x16x32_bf16 v[22:25], v[152:155], v[176:179], v[22:25]
	v_mfma_f32_16x16x32_bf16 v[14:17], v[140:143], v[184:187], v[14:17]
	v_mfma_f32_16x16x32_bf16 v[6:9], v[152:155], v[184:187], v[6:9]
	v_mfma_f32_16x16x32_bf16 v[62:65], v[148:151], v[164:167], v[62:65]
	v_mfma_f32_16x16x32_bf16 v[54:57], v[156:159], v[164:167], v[54:57]
	v_mfma_f32_16x16x32_bf16 v[46:49], v[148:151], v[172:175], v[46:49]
	v_mfma_f32_16x16x32_bf16 v[38:41], v[156:159], v[172:175], v[38:41]
	v_mfma_f32_16x16x32_bf16 v[30:33], v[148:151], v[180:183], v[30:33]
	v_mfma_f32_16x16x32_bf16 v[22:25], v[156:159], v[180:183], v[22:25]
	v_mfma_f32_16x16x32_bf16 v[14:17], v[148:151], v[188:191], v[14:17]
	v_mfma_f32_16x16x32_bf16 v[6:9], v[156:159], v[188:191], v[6:9]
	s_barrier
	s_add_i32 s6, s6, s54
	v_lshl_add_u64 v[140:141], v[134:135], 0, s[20:21]
	s_mov_b32 m0, s6
	s_nop 0
	global_load_lds_dwordx4 v[140:141], off
	v_lshl_add_u64 v[140:141], v[134:135], 0, s[64:65]
	s_add_i32 m0, s6, 0x2000
	s_nop 0
	global_load_lds_dwordx4 v[140:141], off
	v_lshl_add_u64 v[230:231], v[144:145], 0, s[20:21]
	s_mov_b32 m0, s56
	s_nop 0
	global_load_lds_dwordx4 v[230:231], off
	v_lshl_add_u64 v[230:231], v[144:145], 0, s[64:65]
	s_mov_b32 m0, s57
	s_nop 0
	global_load_lds_dwordx4 v[230:231], off
	s_waitcnt vmcnt(8)
	s_barrier
	v_mfma_f32_16x16x32_bf16 v[58:61], v[192:195], v[160:163], v[58:61]
	v_mfma_f32_16x16x32_bf16 v[50:53], v[200:203], v[160:163], v[50:53]
	v_mfma_f32_16x16x32_bf16 v[42:45], v[192:195], v[168:171], v[42:45]
	v_mfma_f32_16x16x32_bf16 v[34:37], v[200:203], v[168:171], v[34:37]
	v_mfma_f32_16x16x32_bf16 v[26:29], v[192:195], v[176:179], v[26:29]
	v_mfma_f32_16x16x32_bf16 v[18:21], v[200:203], v[176:179], v[18:21]
	v_mfma_f32_16x16x32_bf16 v[10:13], v[192:195], v[184:187], v[10:13]
	v_mfma_f32_16x16x32_bf16 v[2:5], v[200:203], v[184:187], v[2:5]
	v_mfma_f32_16x16x32_bf16 v[58:61], v[196:199], v[164:167], v[58:61]
	v_mfma_f32_16x16x32_bf16 v[50:53], v[204:207], v[164:167], v[50:53]
	v_mfma_f32_16x16x32_bf16 v[42:45], v[196:199], v[172:175], v[42:45]
	v_mfma_f32_16x16x32_bf16 v[34:37], v[204:207], v[172:175], v[34:37]
	v_mfma_f32_16x16x32_bf16 v[26:29], v[196:199], v[180:183], v[26:29]
	v_mfma_f32_16x16x32_bf16 v[18:21], v[204:207], v[180:183], v[18:21]
	v_mfma_f32_16x16x32_bf16 v[10:13], v[196:199], v[188:191], v[10:13]
	v_mfma_f32_16x16x32_bf16 v[2:5], v[204:207], v[188:191], v[2:5]
	s_barrier
	s_add_i32 s6, 0, 0x18000
	v_add_u32_e32 v139, s6, v137
	ds_read_b128 v[140:143], v139
	ds_read_b128 v[148:151], v139 offset:1024
	ds_read_b128 v[152:155], v139 offset:2048
	ds_read_b128 v[156:159], v139 offset:3072
	ds_read_b128 v[160:163], v138 offset:32768
	ds_read_b128 v[164:167], v138 offset:33792
	ds_read_b128 v[168:171], v138 offset:34816
	ds_read_b128 v[172:175], v138 offset:35840
	ds_read_b128 v[176:179], v138 offset:36864
	ds_read_b128 v[180:183], v138 offset:37888
	ds_read_b128 v[184:187], v138 offset:38912
	ds_read_b128 v[188:191], v138 offset:39936
	s_waitcnt lgkmcnt(8)
	s_barrier
	s_waitcnt lgkmcnt(0)
	v_mfma_f32_16x16x32_bf16 v[126:129], v[140:143], v[160:163], v[126:129]
	v_mfma_f32_16x16x32_bf16 v[118:121], v[152:155], v[160:163], v[118:121]
	v_mfma_f32_16x16x32_bf16 v[110:113], v[140:143], v[168:171], v[110:113]
	v_mfma_f32_16x16x32_bf16 v[102:105], v[152:155], v[168:171], v[102:105]
	v_mfma_f32_16x16x32_bf16 v[94:97], v[140:143], v[176:179], v[94:97]
	v_mfma_f32_16x16x32_bf16 v[86:89], v[152:155], v[176:179], v[86:89]
	v_mfma_f32_16x16x32_bf16 v[78:81], v[140:143], v[184:187], v[78:81]
	v_mfma_f32_16x16x32_bf16 v[70:73], v[152:155], v[184:187], v[70:73]
	v_mfma_f32_16x16x32_bf16 v[126:129], v[148:151], v[164:167], v[126:129]
	v_mfma_f32_16x16x32_bf16 v[118:121], v[156:159], v[164:167], v[118:121]
	v_mfma_f32_16x16x32_bf16 v[110:113], v[148:151], v[172:175], v[110:113]
	v_mfma_f32_16x16x32_bf16 v[102:105], v[156:159], v[172:175], v[102:105]
	v_mfma_f32_16x16x32_bf16 v[94:97], v[148:151], v[180:183], v[94:97]
	v_mfma_f32_16x16x32_bf16 v[86:89], v[156:159], v[180:183], v[86:89]
	v_mfma_f32_16x16x32_bf16 v[78:81], v[148:151], v[188:191], v[78:81]
	v_mfma_f32_16x16x32_bf16 v[70:73], v[156:159], v[188:191], v[70:73]
	s_barrier
	s_add_i32 s7, 0, 0x1c000
	s_add_i32 s6, s6, s54
	v_add_u32_e32 v139, s7, v137
	v_lshl_add_u64 v[208:209], v[134:135], 0, s[34:35]
	s_mov_b32 m0, s6
	ds_read_b128 v[192:195], v139
	ds_read_b128 v[196:199], v139 offset:1024
	ds_read_b128 v[200:203], v139 offset:2048
	ds_read_b128 v[204:207], v139 offset:3072
	global_load_lds_dwordx4 v[208:209], off
	v_lshl_add_u64 v[208:209], v[134:135], 0, s[66:67]
	s_add_i32 m0, s6, 0x2000
	s_nop 0
	global_load_lds_dwordx4 v[208:209], off
	s_barrier
	s_waitcnt lgkmcnt(0)
	v_mfma_f32_16x16x32_bf16 v[122:125], v[192:195], v[160:163], v[122:125]
	v_mfma_f32_16x16x32_bf16 v[114:117], v[200:203], v[160:163], v[114:117]
	v_mfma_f32_16x16x32_bf16 v[106:109], v[192:195], v[168:171], v[106:109]
	v_mfma_f32_16x16x32_bf16 v[98:101], v[200:203], v[168:171], v[98:101]
	v_mfma_f32_16x16x32_bf16 v[90:93], v[192:195], v[176:179], v[90:93]
	v_mfma_f32_16x16x32_bf16 v[82:85], v[200:203], v[176:179], v[82:85]
	v_mfma_f32_16x16x32_bf16 v[74:77], v[192:195], v[184:187], v[74:77]
	v_mfma_f32_16x16x32_bf16 v[66:69], v[200:203], v[184:187], v[66:69]
	v_mfma_f32_16x16x32_bf16 v[122:125], v[196:199], v[164:167], v[122:125]
	v_mfma_f32_16x16x32_bf16 v[114:117], v[204:207], v[164:167], v[114:117]
	v_mfma_f32_16x16x32_bf16 v[106:109], v[196:199], v[172:175], v[106:109]
	v_mfma_f32_16x16x32_bf16 v[98:101], v[204:207], v[172:175], v[98:101]
	v_mfma_f32_16x16x32_bf16 v[90:93], v[196:199], v[180:183], v[90:93]
	v_mfma_f32_16x16x32_bf16 v[82:85], v[204:207], v[180:183], v[82:85]
	v_mfma_f32_16x16x32_bf16 v[74:77], v[196:199], v[188:191], v[74:77]
	v_mfma_f32_16x16x32_bf16 v[66:69], v[204:207], v[188:191], v[66:69]
	s_barrier
	s_mov_b32 m0, s59
	v_lshl_add_u64 v[208:209], v[144:145], 0, s[34:35]
	ds_read_b128 v[160:163], v138 offset:49152
	ds_read_b128 v[164:167], v138 offset:50176
	ds_read_b128 v[168:171], v138 offset:51200
	ds_read_b128 v[172:175], v138 offset:52224
	ds_read_b128 v[176:179], v138 offset:53248
	ds_read_b128 v[180:183], v138 offset:54272
	ds_read_b128 v[184:187], v138 offset:55296
	ds_read_b128 v[188:191], v138 offset:56320
	global_load_lds_dwordx4 v[208:209], off
	v_lshl_add_u64 v[144:145], v[144:145], 0, s[66:67]
	s_mov_b32 m0, s62
	s_nop 0
	global_load_lds_dwordx4 v[144:145], off
	s_barrier
	s_waitcnt lgkmcnt(0)
	v_mfma_f32_16x16x32_bf16 v[62:65], v[140:143], v[160:163], v[62:65]
	v_mfma_f32_16x16x32_bf16 v[54:57], v[152:155], v[160:163], v[54:57]
	v_mfma_f32_16x16x32_bf16 v[46:49], v[140:143], v[168:171], v[46:49]
	v_mfma_f32_16x16x32_bf16 v[38:41], v[152:155], v[168:171], v[38:41]
	v_mfma_f32_16x16x32_bf16 v[30:33], v[140:143], v[176:179], v[30:33]
	v_mfma_f32_16x16x32_bf16 v[22:25], v[152:155], v[176:179], v[22:25]
	v_mfma_f32_16x16x32_bf16 v[14:17], v[140:143], v[184:187], v[14:17]
	v_mfma_f32_16x16x32_bf16 v[6:9], v[152:155], v[184:187], v[6:9]
	v_mfma_f32_16x16x32_bf16 v[62:65], v[148:151], v[164:167], v[62:65]
	v_mfma_f32_16x16x32_bf16 v[54:57], v[156:159], v[164:167], v[54:57]
	v_mfma_f32_16x16x32_bf16 v[46:49], v[148:151], v[172:175], v[46:49]
	v_mfma_f32_16x16x32_bf16 v[38:41], v[156:159], v[172:175], v[38:41]
	v_mfma_f32_16x16x32_bf16 v[30:33], v[148:151], v[180:183], v[30:33]
	v_mfma_f32_16x16x32_bf16 v[22:25], v[156:159], v[180:183], v[22:25]
	v_mfma_f32_16x16x32_bf16 v[14:17], v[148:151], v[188:191], v[14:17]
	v_mfma_f32_16x16x32_bf16 v[6:9], v[156:159], v[188:191], v[6:9]
	s_barrier
	s_add_i32 s6, s7, s54
	v_lshl_add_u64 v[140:141], v[134:135], 0, s[16:17]
	s_mov_b32 m0, s6
	v_lshl_add_u64 v[134:135], v[134:135], 0, s[80:81]
	global_load_lds_dwordx4 v[140:141], off
	s_add_i32 m0, s6, 0x2000
	s_nop 0
	global_load_lds_dwordx4 v[134:135], off
	s_waitcnt vmcnt(6)
	s_add_i32 s87, s87, 2
	s_add_u32 s41, s41, 0x100
	s_addc_u32 s86, s86, 0
	s_cmp_gt_u32 s87, 29
	s_mov_b64 s[6:7], s[8:9]
	s_cbranch_scc0 .LBB0_503
	s_barrier
	v_mfma_f32_16x16x32_bf16 v[58:61], v[192:195], v[160:163], v[58:61]
	v_mfma_f32_16x16x32_bf16 v[50:53], v[200:203], v[160:163], v[50:53]
	v_mfma_f32_16x16x32_bf16 v[42:45], v[192:195], v[168:171], v[42:45]
	v_mfma_f32_16x16x32_bf16 v[34:37], v[200:203], v[168:171], v[34:37]
	v_mfma_f32_16x16x32_bf16 v[26:29], v[192:195], v[176:179], v[26:29]
	v_mfma_f32_16x16x32_bf16 v[18:21], v[200:203], v[176:179], v[18:21]
	v_mfma_f32_16x16x32_bf16 v[10:13], v[192:195], v[184:187], v[10:13]
	v_mfma_f32_16x16x32_bf16 v[2:5], v[200:203], v[184:187], v[2:5]
	v_mfma_f32_16x16x32_bf16 v[58:61], v[196:199], v[164:167], v[58:61]
	v_mfma_f32_16x16x32_bf16 v[50:53], v[204:207], v[164:167], v[50:53]
	v_mfma_f32_16x16x32_bf16 v[42:45], v[196:199], v[172:175], v[42:45]
	v_mfma_f32_16x16x32_bf16 v[34:37], v[204:207], v[172:175], v[34:37]
	v_mfma_f32_16x16x32_bf16 v[26:29], v[196:199], v[180:183], v[26:29]
	v_mfma_f32_16x16x32_bf16 v[18:21], v[204:207], v[180:183], v[18:21]
	v_mfma_f32_16x16x32_bf16 v[10:13], v[196:199], v[188:191], v[10:13]
	v_mfma_f32_16x16x32_bf16 v[2:5], v[204:207], v[188:191], v[2:5]
	s_barrier
	v_mul_f32_e32 v144, 0xbfb8aa3b, v126
	v_exp_f32_e32 v144, v144
	v_mov_b32_e32 v134, v136
	s_lshl_b32 s6, s48, 8
	v_add_f32_e32 v144, 1.0, v144
	v_rcp_f32_e32 v144, v144
	s_add_i32 s6, s6, s10
	v_and_or_b32 v139, v134, 15, s6
	s_lshl_b32 s6, s85, 7
	v_mul_f32_e32 v126, v126, v144
	v_mul_f32_e32 v122, v126, v122
	v_mul_f32_e32 v126, 0xbfb8aa3b, v127
	v_exp_f32_e32 v126, v126
	v_ashrrev_i32_e32 v134, 1, v134
	s_or_b32 s6, s6, s58
	v_and_b32_e32 v134, -8, v134
	v_add_f32_e32 v126, 1.0, v126
	v_rcp_f32_e32 v126, v126
	v_add_u32_e32 v140, s6, v134
	v_ashrrev_i32_e32 v141, 31, v140
	v_mov_b64_e32 v[134:135], s[4:5]
	v_mul_f32_e32 v126, v127, v126
	v_mul_f32_e32 v123, v126, v123
	v_mul_f32_e32 v126, 0xbfb8aa3b, v128
	v_exp_f32_e32 v126, v126
	v_mad_i64_i32 v[142:143], s[6:7], v139, s74, v[134:135]
	s_and_b64 vcc, exec, s[44:45]
	v_add_f32_e32 v126, 1.0, v126
	v_rcp_f32_e32 v126, v126
	s_mov_b32 s48, s40
	s_mov_b32 s85, s84
	s_mov_b64 s[8:9], s[46:47]
	v_mul_f32_e32 v126, v128, v126
	v_mul_f32_e32 v124, v126, v124
	v_mul_f32_e32 v126, 0xbfb8aa3b, v129
	v_exp_f32_e32 v126, v126
	s_nop 0
	v_add_f32_e32 v126, 1.0, v126
	v_rcp_f32_e32 v126, v126
	s_nop 0
	v_mul_f32_e32 v126, v129, v126
	v_mul_f32_e32 v125, v126, v125
	v_mul_f32_e32 v126, 0xbfb8aa3b, v118
	v_exp_f32_e32 v126, v126
	s_nop 0
	v_add_f32_e32 v126, 1.0, v126
	v_rcp_f32_e32 v126, v126
	s_nop 0
	v_mul_f32_e32 v118, v118, v126
	v_mul_f32_e32 v118, v118, v114
	v_mul_f32_e32 v114, 0xbfb8aa3b, v119
	v_exp_f32_e32 v114, v114
	s_nop 0
	v_add_f32_e32 v114, 1.0, v114
	v_rcp_f32_e32 v114, v114
	s_nop 0
	v_mul_f32_e32 v114, v119, v114
	v_mul_f32_e32 v119, v114, v115
	v_mul_f32_e32 v114, 0xbfb8aa3b, v120
	v_exp_f32_e32 v114, v114
	s_nop 0
	v_add_f32_e32 v114, 1.0, v114
	v_rcp_f32_e32 v114, v114
	s_nop 0
	v_mul_f32_e32 v114, v120, v114
	v_mul_f32_e32 v126, v114, v116
	v_mul_f32_e32 v114, 0xbfb8aa3b, v121
	v_exp_f32_e32 v114, v114
	v_cvt_pk_bf16_f32 v116, v122, v123
	s_nop 0
	v_add_f32_e32 v114, 1.0, v114
	v_rcp_f32_e32 v114, v114
	s_nop 0
	v_mul_f32_e32 v114, v121, v114
	v_mul_f32_e32 v127, v114, v117
	v_lshlrev_b64 v[114:115], 1, v[140:141]
	v_lshl_add_u64 v[120:121], v[142:143], 0, v[114:115]
	v_cvt_pk_bf16_f32 v117, v124, v125
	v_cvt_pk_bf16_f32 v118, v118, v119
	v_cvt_pk_bf16_f32 v119, v126, v127
	global_store_dwordx4 v[120:121], v[116:119], off
	s_nop 1
	v_mul_f32_e32 v118, 0xbfb8aa3b, v110
	v_exp_f32_e32 v118, v118
	v_or_b32_e32 v116, 16, v139
	v_mad_i64_i32 v[116:117], s[6:7], v116, s74, v[134:135]
	v_add_f32_e32 v118, 1.0, v118
	v_rcp_f32_e32 v118, v118
	s_nop 0
	v_mul_f32_e32 v110, v110, v118
	v_mul_f32_e32 v106, v110, v106
	v_mul_f32_e32 v110, 0xbfb8aa3b, v111
	v_exp_f32_e32 v110, v110
	s_nop 0
	v_add_f32_e32 v110, 1.0, v110
	v_rcp_f32_e32 v110, v110
	s_nop 0
	v_mul_f32_e32 v110, v111, v110
	v_mul_f32_e32 v107, v110, v107
	v_mul_f32_e32 v110, 0xbfb8aa3b, v112
	v_exp_f32_e32 v110, v110
	s_nop 0
	v_add_f32_e32 v110, 1.0, v110
	v_rcp_f32_e32 v110, v110
	s_nop 0
	v_mul_f32_e32 v110, v112, v110
	v_mul_f32_e32 v108, v110, v108
	v_mul_f32_e32 v110, 0xbfb8aa3b, v113
	v_exp_f32_e32 v110, v110
	s_nop 0
	v_add_f32_e32 v110, 1.0, v110
	v_rcp_f32_e32 v110, v110
	s_nop 0
	v_mul_f32_e32 v110, v113, v110
	v_mul_f32_e32 v109, v110, v109
	v_mul_f32_e32 v110, 0xbfb8aa3b, v102
	v_exp_f32_e32 v110, v110
	s_nop 0
	v_add_f32_e32 v110, 1.0, v110
	v_rcp_f32_e32 v110, v110
	s_nop 0
	v_mul_f32_e32 v102, v102, v110
	v_mul_f32_e32 v110, v102, v98
	v_mul_f32_e32 v98, 0xbfb8aa3b, v103
	v_exp_f32_e32 v98, v98
	s_nop 0
	v_add_f32_e32 v98, 1.0, v98
	v_rcp_f32_e32 v98, v98
	s_nop 0
	v_mul_f32_e32 v98, v103, v98
	v_mul_f32_e32 v111, v98, v99
	v_mul_f32_e32 v98, 0xbfb8aa3b, v104
	v_exp_f32_e32 v98, v98
	v_lshl_add_u64 v[102:103], v[116:117], 0, v[114:115]
	v_add_f32_e32 v98, 1.0, v98
	v_rcp_f32_e32 v98, v98
	s_nop 0
	v_mul_f32_e32 v98, v104, v98
	v_mul_f32_e32 v104, v98, v100
	v_mul_f32_e32 v98, 0xbfb8aa3b, v105
	v_exp_f32_e32 v98, v98
	s_nop 0
	v_add_f32_e32 v98, 1.0, v98
	v_rcp_f32_e32 v98, v98
	s_nop 0
	v_mul_f32_e32 v98, v105, v98
	v_mul_f32_e32 v101, v98, v101
	v_cvt_pk_bf16_f32 v98, v106, v107
	v_cvt_pk_bf16_f32 v99, v108, v109
	v_cvt_pk_bf16_f32 v100, v110, v111
	v_cvt_pk_bf16_f32 v101, v104, v101
	global_store_dwordx4 v[102:103], v[98:101], off
	s_nop 1
	v_mul_f32_e32 v100, 0xbfb8aa3b, v94
	v_exp_f32_e32 v100, v100
	v_or_b32_e32 v98, 32, v139
	v_mad_i64_i32 v[98:99], s[6:7], v98, s74, v[134:135]
	v_add_f32_e32 v100, 1.0, v100
	v_rcp_f32_e32 v100, v100
	s_nop 0
	v_mul_f32_e32 v94, v94, v100
	v_mul_f32_e32 v90, v94, v90
	v_mul_f32_e32 v94, 0xbfb8aa3b, v95
	v_exp_f32_e32 v94, v94
	s_nop 0
	v_add_f32_e32 v94, 1.0, v94
	v_rcp_f32_e32 v94, v94
	s_nop 0
	v_mul_f32_e32 v94, v95, v94
	v_mul_f32_e32 v91, v94, v91
	v_mul_f32_e32 v94, 0xbfb8aa3b, v96
	v_exp_f32_e32 v94, v94
	s_nop 0
	v_add_f32_e32 v94, 1.0, v94
	v_rcp_f32_e32 v94, v94
	s_nop 0
	v_mul_f32_e32 v94, v96, v94
	v_mul_f32_e32 v92, v94, v92
	v_mul_f32_e32 v94, 0xbfb8aa3b, v97
	v_exp_f32_e32 v94, v94
	s_nop 0
	v_add_f32_e32 v94, 1.0, v94
	v_rcp_f32_e32 v94, v94
	s_nop 0
	v_mul_f32_e32 v94, v97, v94
	v_mul_f32_e32 v93, v94, v93
	v_mul_f32_e32 v94, 0xbfb8aa3b, v86
	v_exp_f32_e32 v94, v94
	s_nop 0
	v_add_f32_e32 v94, 1.0, v94
	v_rcp_f32_e32 v94, v94
	s_nop 0
	v_mul_f32_e32 v86, v86, v94
	v_mul_f32_e32 v94, v86, v82
	v_mul_f32_e32 v82, 0xbfb8aa3b, v87
	v_exp_f32_e32 v82, v82
	s_nop 0
	v_add_f32_e32 v82, 1.0, v82
	v_rcp_f32_e32 v82, v82
	s_nop 0
	v_mul_f32_e32 v82, v87, v82
	v_mul_f32_e32 v95, v82, v83
	v_mul_f32_e32 v82, 0xbfb8aa3b, v88
	v_exp_f32_e32 v82, v82
	v_lshl_add_u64 v[86:87], v[98:99], 0, v[114:115]
	v_add_f32_e32 v82, 1.0, v82
	v_rcp_f32_e32 v82, v82
	s_nop 0
	v_mul_f32_e32 v82, v88, v82
	v_mul_f32_e32 v88, v82, v84
	v_mul_f32_e32 v82, 0xbfb8aa3b, v89
	v_exp_f32_e32 v82, v82
	s_nop 0
	v_add_f32_e32 v82, 1.0, v82
	v_rcp_f32_e32 v82, v82
	s_nop 0
	v_mul_f32_e32 v82, v89, v82
	v_mul_f32_e32 v85, v82, v85
	v_cvt_pk_bf16_f32 v82, v90, v91
	v_cvt_pk_bf16_f32 v83, v92, v93
	v_cvt_pk_bf16_f32 v84, v94, v95
	v_cvt_pk_bf16_f32 v85, v88, v85
	global_store_dwordx4 v[86:87], v[82:85], off
	s_nop 1
	v_mul_f32_e32 v84, 0xbfb8aa3b, v78
	v_exp_f32_e32 v84, v84
	v_or_b32_e32 v82, 48, v139
	v_mad_i64_i32 v[82:83], s[6:7], v82, s74, v[134:135]
	v_add_f32_e32 v84, 1.0, v84
	v_rcp_f32_e32 v84, v84
	s_nop 0
	v_mul_f32_e32 v78, v78, v84
	v_mul_f32_e32 v74, v78, v74
	v_mul_f32_e32 v78, 0xbfb8aa3b, v79
	v_exp_f32_e32 v78, v78
	s_nop 0
	v_add_f32_e32 v78, 1.0, v78
	v_rcp_f32_e32 v78, v78
	s_nop 0
	v_mul_f32_e32 v78, v79, v78
	v_mul_f32_e32 v75, v78, v75
	v_mul_f32_e32 v78, 0xbfb8aa3b, v80
	v_exp_f32_e32 v78, v78
	s_nop 0
	v_add_f32_e32 v78, 1.0, v78
	v_rcp_f32_e32 v78, v78
	s_nop 0
	v_mul_f32_e32 v78, v80, v78
	v_mul_f32_e32 v76, v78, v76
	v_mul_f32_e32 v78, 0xbfb8aa3b, v81
	v_exp_f32_e32 v78, v78
	s_nop 0
	v_add_f32_e32 v78, 1.0, v78
	v_rcp_f32_e32 v78, v78
	s_nop 0
	v_mul_f32_e32 v78, v81, v78
	v_mul_f32_e32 v77, v78, v77
	v_mul_f32_e32 v78, 0xbfb8aa3b, v70
	v_exp_f32_e32 v78, v78
	s_nop 0
	v_add_f32_e32 v78, 1.0, v78
	v_rcp_f32_e32 v78, v78
	s_nop 0
	v_mul_f32_e32 v70, v70, v78
	v_mul_f32_e32 v78, v70, v66
	v_mul_f32_e32 v66, 0xbfb8aa3b, v71
	v_exp_f32_e32 v66, v66
	s_nop 0
	v_add_f32_e32 v66, 1.0, v66
	v_rcp_f32_e32 v66, v66
	s_nop 0
	v_mul_f32_e32 v66, v71, v66
	v_mul_f32_e32 v79, v66, v67
	v_mul_f32_e32 v66, 0xbfb8aa3b, v72
	v_exp_f32_e32 v66, v66
	v_lshl_add_u64 v[70:71], v[82:83], 0, v[114:115]
	v_add_f32_e32 v66, 1.0, v66
	v_rcp_f32_e32 v66, v66
	s_nop 0
	v_mul_f32_e32 v66, v72, v66
	v_mul_f32_e32 v72, v66, v68
	v_mul_f32_e32 v66, 0xbfb8aa3b, v73
	v_exp_f32_e32 v66, v66
	s_nop 0
	v_add_f32_e32 v66, 1.0, v66
	v_rcp_f32_e32 v66, v66
	s_nop 0
	v_mul_f32_e32 v66, v73, v66
	v_mul_f32_e32 v69, v66, v69
	v_cvt_pk_bf16_f32 v66, v74, v75
	v_cvt_pk_bf16_f32 v67, v76, v77
	v_cvt_pk_bf16_f32 v68, v78, v79
	v_cvt_pk_bf16_f32 v69, v72, v69
	global_store_dwordx4 v[70:71], v[66:69], off
	s_nop 1
	v_mul_f32_e32 v68, 0xbfb8aa3b, v62
	v_exp_f32_e32 v68, v68
	v_add_u32_e32 v66, 0x80, v139
	v_mad_i64_i32 v[66:67], s[6:7], v66, s74, v[134:135]
	v_add_f32_e32 v68, 1.0, v68
	v_rcp_f32_e32 v68, v68
	s_nop 0
	v_mul_f32_e32 v62, v62, v68
	v_mul_f32_e32 v58, v62, v58
	v_mul_f32_e32 v62, 0xbfb8aa3b, v63
	v_exp_f32_e32 v62, v62
	s_nop 0
	v_add_f32_e32 v62, 1.0, v62
	v_rcp_f32_e32 v62, v62
	s_nop 0
	v_mul_f32_e32 v62, v63, v62
	v_mul_f32_e32 v59, v62, v59
	v_mul_f32_e32 v62, 0xbfb8aa3b, v64
	v_exp_f32_e32 v62, v62
	s_nop 0
	v_add_f32_e32 v62, 1.0, v62
	v_rcp_f32_e32 v62, v62
	s_nop 0
	v_mul_f32_e32 v62, v64, v62
	v_mul_f32_e32 v60, v62, v60
	v_mul_f32_e32 v62, 0xbfb8aa3b, v65
	v_exp_f32_e32 v62, v62
	s_nop 0
	v_add_f32_e32 v62, 1.0, v62
	v_rcp_f32_e32 v62, v62
	s_nop 0
	v_mul_f32_e32 v62, v65, v62
	v_mul_f32_e32 v61, v62, v61
	v_mul_f32_e32 v62, 0xbfb8aa3b, v54
	v_exp_f32_e32 v62, v62
	s_nop 0
	v_add_f32_e32 v62, 1.0, v62
	v_rcp_f32_e32 v62, v62
	s_nop 0
	v_mul_f32_e32 v54, v54, v62
	v_mul_f32_e32 v62, v54, v50
	v_mul_f32_e32 v50, 0xbfb8aa3b, v55
	v_exp_f32_e32 v50, v50
	s_nop 0
	v_add_f32_e32 v50, 1.0, v50
	v_rcp_f32_e32 v50, v50
	s_nop 0
	v_mul_f32_e32 v50, v55, v50
	v_mul_f32_e32 v63, v50, v51
	v_mul_f32_e32 v50, 0xbfb8aa3b, v56
	v_exp_f32_e32 v50, v50
	v_lshl_add_u64 v[54:55], v[66:67], 0, v[114:115]
	v_add_f32_e32 v50, 1.0, v50
	v_rcp_f32_e32 v50, v50
	s_nop 0
	v_mul_f32_e32 v50, v56, v50
	v_mul_f32_e32 v56, v50, v52
	v_mul_f32_e32 v50, 0xbfb8aa3b, v57
	v_exp_f32_e32 v50, v50
	s_nop 0
	v_add_f32_e32 v50, 1.0, v50
	v_rcp_f32_e32 v50, v50
	s_nop 0
	v_mul_f32_e32 v50, v57, v50
	v_mul_f32_e32 v53, v50, v53
	v_cvt_pk_bf16_f32 v50, v58, v59
	v_cvt_pk_bf16_f32 v51, v60, v61
	v_cvt_pk_bf16_f32 v52, v62, v63
	v_cvt_pk_bf16_f32 v53, v56, v53
	global_store_dwordx4 v[54:55], v[50:53], off
	s_nop 1
	v_mul_f32_e32 v52, 0xbfb8aa3b, v46
	v_exp_f32_e32 v52, v52
	v_add_u32_e32 v50, 0x90, v139
	v_mad_i64_i32 v[50:51], s[6:7], v50, s74, v[134:135]
	v_add_f32_e32 v52, 1.0, v52
	v_rcp_f32_e32 v52, v52
	s_nop 0
	v_mul_f32_e32 v46, v46, v52
	v_mul_f32_e32 v42, v46, v42
	v_mul_f32_e32 v46, 0xbfb8aa3b, v47
	v_exp_f32_e32 v46, v46
	s_nop 0
	v_add_f32_e32 v46, 1.0, v46
	v_rcp_f32_e32 v46, v46
	s_nop 0
	v_mul_f32_e32 v46, v47, v46
	v_mul_f32_e32 v43, v46, v43
	v_mul_f32_e32 v46, 0xbfb8aa3b, v48
	v_exp_f32_e32 v46, v46
	s_nop 0
	v_add_f32_e32 v46, 1.0, v46
	v_rcp_f32_e32 v46, v46
	s_nop 0
	v_mul_f32_e32 v46, v48, v46
	v_mul_f32_e32 v44, v46, v44
	v_mul_f32_e32 v46, 0xbfb8aa3b, v49
	v_exp_f32_e32 v46, v46
	s_nop 0
	v_add_f32_e32 v46, 1.0, v46
	v_rcp_f32_e32 v46, v46
	s_nop 0
	v_mul_f32_e32 v46, v49, v46
	v_mul_f32_e32 v45, v46, v45
	v_mul_f32_e32 v46, 0xbfb8aa3b, v38
	v_exp_f32_e32 v46, v46
	s_nop 0
	v_add_f32_e32 v46, 1.0, v46
	v_rcp_f32_e32 v46, v46
	s_nop 0
	v_mul_f32_e32 v38, v38, v46
	v_mul_f32_e32 v46, v38, v34
	v_mul_f32_e32 v34, 0xbfb8aa3b, v39
	v_exp_f32_e32 v34, v34
	s_nop 0
	v_add_f32_e32 v34, 1.0, v34
	v_rcp_f32_e32 v34, v34
	s_nop 0
	v_mul_f32_e32 v34, v39, v34
	v_mul_f32_e32 v47, v34, v35
	v_mul_f32_e32 v34, 0xbfb8aa3b, v40
	v_exp_f32_e32 v34, v34
	v_lshl_add_u64 v[38:39], v[50:51], 0, v[114:115]
	v_add_f32_e32 v34, 1.0, v34
	v_rcp_f32_e32 v34, v34
	s_nop 0
	v_mul_f32_e32 v34, v40, v34
	v_mul_f32_e32 v40, v34, v36
	v_mul_f32_e32 v34, 0xbfb8aa3b, v41
	v_exp_f32_e32 v34, v34
	s_nop 0
	v_add_f32_e32 v34, 1.0, v34
	v_rcp_f32_e32 v34, v34
	s_nop 0
	v_mul_f32_e32 v34, v41, v34
	v_mul_f32_e32 v37, v34, v37
	v_cvt_pk_bf16_f32 v34, v42, v43
	v_cvt_pk_bf16_f32 v35, v44, v45
	v_cvt_pk_bf16_f32 v36, v46, v47
	v_cvt_pk_bf16_f32 v37, v40, v37
	global_store_dwordx4 v[38:39], v[34:37], off
	s_nop 1
	v_mul_f32_e32 v36, 0xbfb8aa3b, v30
	v_exp_f32_e32 v36, v36
	v_add_u32_e32 v34, 0xa0, v139
	v_mad_i64_i32 v[34:35], s[6:7], v34, s74, v[134:135]
	v_add_f32_e32 v36, 1.0, v36
	v_rcp_f32_e32 v36, v36
	s_nop 0
	v_mul_f32_e32 v30, v30, v36
	v_mul_f32_e32 v26, v30, v26
	v_mul_f32_e32 v30, 0xbfb8aa3b, v31
	v_exp_f32_e32 v30, v30
	s_nop 0
	v_add_f32_e32 v30, 1.0, v30
	v_rcp_f32_e32 v30, v30
	s_nop 0
	v_mul_f32_e32 v30, v31, v30
	v_mul_f32_e32 v27, v30, v27
	v_mul_f32_e32 v30, 0xbfb8aa3b, v32
	v_exp_f32_e32 v30, v30
	s_nop 0
	v_add_f32_e32 v30, 1.0, v30
	v_rcp_f32_e32 v30, v30
	s_nop 0
	v_mul_f32_e32 v30, v32, v30
	v_mul_f32_e32 v28, v30, v28
	v_mul_f32_e32 v30, 0xbfb8aa3b, v33
	v_exp_f32_e32 v30, v30
	s_nop 0
	v_add_f32_e32 v30, 1.0, v30
	v_rcp_f32_e32 v30, v30
	s_nop 0
	v_mul_f32_e32 v30, v33, v30
	v_mul_f32_e32 v29, v30, v29
	v_mul_f32_e32 v30, 0xbfb8aa3b, v22
	v_exp_f32_e32 v30, v30
	s_nop 0
	v_add_f32_e32 v30, 1.0, v30
	v_rcp_f32_e32 v30, v30
	s_nop 0
	v_mul_f32_e32 v22, v22, v30
	v_mul_f32_e32 v30, v22, v18
	v_mul_f32_e32 v18, 0xbfb8aa3b, v23
	v_exp_f32_e32 v18, v18
	s_nop 0
	v_add_f32_e32 v18, 1.0, v18
	v_rcp_f32_e32 v18, v18
	s_nop 0
	v_mul_f32_e32 v18, v23, v18
	v_mul_f32_e32 v31, v18, v19
	v_mul_f32_e32 v18, 0xbfb8aa3b, v24
	v_exp_f32_e32 v18, v18
	v_lshl_add_u64 v[22:23], v[34:35], 0, v[114:115]
	v_add_f32_e32 v18, 1.0, v18
	v_rcp_f32_e32 v18, v18
	s_nop 0
	v_mul_f32_e32 v18, v24, v18
	v_mul_f32_e32 v24, v18, v20
	v_mul_f32_e32 v18, 0xbfb8aa3b, v25
	v_exp_f32_e32 v18, v18
	s_nop 0
	v_add_f32_e32 v18, 1.0, v18
	v_rcp_f32_e32 v18, v18
	s_nop 0
	v_mul_f32_e32 v18, v25, v18
	v_mul_f32_e32 v21, v18, v21
	v_cvt_pk_bf16_f32 v18, v26, v27
	v_cvt_pk_bf16_f32 v19, v28, v29
	v_cvt_pk_bf16_f32 v20, v30, v31
	v_cvt_pk_bf16_f32 v21, v24, v21
	global_store_dwordx4 v[22:23], v[18:21], off
	s_nop 1
	v_mul_f32_e32 v20, 0xbfb8aa3b, v14
	v_exp_f32_e32 v20, v20
	v_add_u32_e32 v18, 0xb0, v139
	v_mad_i64_i32 v[18:19], s[6:7], v18, s74, v[134:135]
	v_add_f32_e32 v20, 1.0, v20
	v_rcp_f32_e32 v20, v20
	s_mov_b64 s[6:7], s[42:43]
	v_mul_f32_e32 v14, v14, v20
	v_mul_f32_e32 v10, v14, v10
	v_mul_f32_e32 v14, 0xbfb8aa3b, v15
	v_exp_f32_e32 v14, v14
	s_nop 0
	v_add_f32_e32 v14, 1.0, v14
	v_rcp_f32_e32 v14, v14
	s_nop 0
	v_mul_f32_e32 v14, v15, v14
	v_mul_f32_e32 v11, v14, v11
	v_mul_f32_e32 v14, 0xbfb8aa3b, v16
	v_exp_f32_e32 v14, v14
	s_nop 0
	v_add_f32_e32 v14, 1.0, v14
	v_rcp_f32_e32 v14, v14
	s_nop 0
	v_mul_f32_e32 v14, v16, v14
	v_mul_f32_e32 v12, v14, v12
	v_mul_f32_e32 v14, 0xbfb8aa3b, v17
	v_exp_f32_e32 v14, v14
	s_nop 0
	v_add_f32_e32 v14, 1.0, v14
	v_rcp_f32_e32 v14, v14
	s_nop 0
	v_mul_f32_e32 v14, v17, v14
	v_mul_f32_e32 v13, v14, v13
	v_mul_f32_e32 v14, 0xbfb8aa3b, v6
	v_exp_f32_e32 v14, v14
	s_nop 0
	v_add_f32_e32 v14, 1.0, v14
	v_rcp_f32_e32 v14, v14
	s_nop 0
	v_mul_f32_e32 v6, v6, v14
	v_mul_f32_e32 v14, v6, v2
	v_mul_f32_e32 v2, 0xbfb8aa3b, v7
	v_exp_f32_e32 v2, v2
	s_nop 0
	v_add_f32_e32 v2, 1.0, v2
	v_rcp_f32_e32 v2, v2
	s_nop 0
	v_mul_f32_e32 v2, v7, v2
	v_mul_f32_e32 v15, v2, v3
	v_mul_f32_e32 v2, 0xbfb8aa3b, v8
	v_exp_f32_e32 v2, v2
	v_lshl_add_u64 v[6:7], v[18:19], 0, v[114:115]
	v_add_f32_e32 v2, 1.0, v2
	v_rcp_f32_e32 v2, v2
	s_nop 0
	v_mul_f32_e32 v2, v8, v2
	v_mul_f32_e32 v8, v2, v4
	v_mul_f32_e32 v2, 0xbfb8aa3b, v9
	v_exp_f32_e32 v2, v2
	s_nop 0
	v_add_f32_e32 v2, 1.0, v2
	v_rcp_f32_e32 v2, v2
	s_nop 0
	v_mul_f32_e32 v2, v9, v2
	v_mul_f32_e32 v5, v2, v5
	v_cvt_pk_bf16_f32 v2, v10, v11
	v_cvt_pk_bf16_f32 v3, v12, v13
	v_cvt_pk_bf16_f32 v4, v14, v15
	v_cvt_pk_bf16_f32 v5, v8, v5
	global_store_dwordx4 v[6:7], v[2:5], off
	s_cbranch_vccz .LBB0_500
	s_waitcnt vmcnt(0)
	v_readlane_b32 s0, v255, 8
	v_readlane_b32 s62, v255, 10
	v_readlane_b32 s84, v255, 12
	s_cmpk_gt_u32 s22, 0xff
	v_readlane_b32 s1, v255, 9
	s_mov_b64 s[58:59], s[92:93]
	v_readlane_b32 s63, v255, 11
	v_readlane_b32 s85, v255, 13
	s_cbranch_scc1 .LBB0_507
	s_barrier
.LBB0_507:
	s_setprio 0
	v_readlane_b32 s86, v255, 14
	v_readlane_b32 s56, v255, 16
	v_readlane_b32 s52, v255, 18
	v_readlane_b32 s54, v255, 22
	v_readlane_b32 s44, v255, 26
	v_readlane_b32 s50, v255, 28
	v_readlane_b32 s72, v255, 7
	v_readlane_b32 s87, v255, 15
	v_readlane_b32 s57, v255, 17
	v_readlane_b32 s53, v255, 19
	v_readlane_b32 s55, v255, 23
	v_readlane_b32 s45, v255, 27
	v_readlane_b32 s51, v255, 29
	s_movk_i32 s92, 0x4000
	s_movk_i32 s93, 0xf800
	s_movk_i32 s89, 0x37ff
	s_mov_b32 s88, 0x16000
	s_movk_i32 s91, 0x60
	s_mov_b32 s78, 0x2a000000
	s_mov_b32 s79, 0x3fffe
	s_mov_b32 s90, 0xc0000
	s_barrier

.LBB0_521:
	s_add_u32 s49, s6, 0x10a00000
	s_addc_u32 s50, s7, 0
	s_add_u32 s51, s6, 0xf400000
	s_addc_u32 s52, s7, 0
	s_add_i32 s6, s40, s8
	v_ashrrev_i32_e32 v3, 31, v0
	s_ashr_i32 s7, s6, 31
	v_lshrrev_b32_e32 v3, 26, v3
	s_lshr_b32 s7, s7, 27
	v_lshlrev_b32_e32 v2, 4, v0
	v_add_u32_e32 v3, v0, v3
	v_bfe_i32 v0, v0, 27, 1
	s_add_i32 s7, s6, s7
	v_lshrrev_b32_e32 v0, 22, v0
	s_ashr_i32 s8, s7, 5
	s_and_b32 s7, s7, 0xffe0
	v_add_u32_e32 v0, v2, v0
	s_sub_i32 s6, s6, s7
	v_and_b32_e32 v0, 0xfffffc00, v0
	s_bfe_i32 s7, s6, 0x80000
	v_sub_u32_e32 v0, v2, v0
	s_bfe_u32 s7, s7, 0x2000d
	v_lshrrev_b32_e32 v2, 4, v0
	s_add_i32 s7, s6, s7
	v_bitop3_b32 v0, v2, v0, 32 bitop3:0x6c
	s_bfe_i32 s9, s7, 0x80000
	s_and_b32 s7, s7, 0xfc
	v_ashrrev_i32_e32 v6, 6, v3
	v_ashrrev_i32_e32 v3, 31, v0
	s_sub_i32 s6, s6, s7
	v_lshrrev_b32_e32 v3, 26, v3
	s_lshl_b32 s8, s8, 2
	s_sext_i32_i8 s6, s6
	s_ashr_i32 s10, s48, 6
	v_add_u32_e32 v3, v0, v3
	s_sext_i32_i16 s9, s9
	s_add_i32 s85, s8, s6
	s_ashr_i32 s11, s48, 8
	v_lshlrev_b32_e32 v2, 3, v6
	v_ashrrev_i32_e32 v7, 6, v3
	v_and_b32_e32 v3, 0xc0, v3
	s_lshl_b32 s53, s10, 10
	s_lshr_b32 s40, s9, 2
	s_mul_i32 s6, s85, 0x2c0000
	v_and_b32_e32 v2, 0x7ffff0, v2
	v_sub_u32_e32 v0, v0, v3
	v_mov_b32_e32 v3, 1
	s_mul_hi_i32 s7, s85, 0x2c0000
	s_add_u32 s6, s49, s6
	v_add_u32_e32 v2, v7, v2
	v_lshlrev_b32_e32 v4, 5, v6
	v_ashrrev_i16_sdwa v0, v3, sext(v0) dst_sel:DWORD dst_unused:UNUSED_PAD src0_sel:DWORD src1_sel:BYTE_0
	s_movk_i32 s0, 0x1600
	s_addc_u32 s7, s50, s7
	s_ashr_i32 s8, s9, 2
	v_and_b32_e32 v8, 32, v4
	v_bfe_i32 v9, v0, 0, 16
	v_mul_lo_u32 v0, v2, s0
	s_mul_hi_i32 s9, s8, 0x2c0000
	s_mul_i32 s8, s8, 0x2c0000
	v_or_b32_e32 v0, v0, v8
	s_add_u32 s8, s51, s8
	v_add_lshl_u32 v0, v0, v9, 1
	s_addc_u32 s9, s52, s9
	s_add_i32 s54, s53, 0
	v_lshl_add_u64 v[2:3], s[8:9], 0, v[0:1]
	s_add_i32 m0, s54, 0x10000
	v_lshl_add_u64 v[4:5], v[2:3], 0, s[26:27]
	global_load_lds_dwordx4 v0, s[8:9]
	s_add_i32 m0, s54, 0x12000
	s_add_i32 s55, s54, 0x2000
	global_load_lds_dwordx4 v[4:5], off
	v_lshl_add_u64 v[4:5], s[6:7], 0, v[0:1]
	s_mov_b32 m0, s54
	v_lshl_add_u64 v[12:13], v[4:5], 0, s[26:27]
	global_load_lds_dwordx4 v0, s[6:7]
	s_mov_b32 m0, s55
	s_add_i32 s56, s54, 0x4000
	global_load_lds_dwordx4 v[12:13], off
	v_lshl_add_u64 v[12:13], v[2:3], 0, s[28:29]
	s_add_i32 m0, s54, 0x14000
	s_add_i32 s57, s54, 0x6000
	global_load_lds_dwordx4 v[12:13], off
	v_lshl_add_u64 v[12:13], v[2:3], 0, s[30:31]
	s_add_i32 m0, s54, 0x16000
	s_mov_b64 s[92:93], s[58:59]
	global_load_lds_dwordx4 v[12:13], off
	v_lshl_add_u64 v[12:13], v[4:5], 0, s[28:29]
	s_mov_b32 m0, s56
	s_cmp_lg_u32 s11, 1
	global_load_lds_dwordx4 v[12:13], off
	v_lshl_add_u64 v[12:13], v[4:5], 0, s[30:31]
	s_mov_b32 m0, s57
	s_nop 0
	global_load_lds_dwordx4 v[12:13], off
	s_cbranch_scc1 .LBB0_523
	s_setprio 1
	s_barrier

.LBB0_537:
	s_andn2_b64 vcc, exec, s[4:5]
	s_cbranch_vccnz .LBB0_557
	s_cmp_gt_i32 s58, 5
	s_mov_b64 s[4:5], -1
	s_cbranch_scc0 .LBB0_552
	s_mov_b32 s4, -1
	v_readlane_b32 s40, v255, 3
	v_mbcnt_lo_u32_b32 v0, s4, 0
	v_mbcnt_hi_u32_b32 v9, s4, v0
	v_readlane_b32 s4, v254, 4
	s_mov_b32 s11, s72
	v_readlane_b32 s41, v255, 4
	v_add_u32_e32 v0, s4, v9
	v_readlane_b32 s42, v255, 5
	v_readlane_b32 s43, v255, 6
	s_mov_b64 s[4:5], s[42:43]
	s_mov_b64 s[6:7], s[40:41]
	s_cmpk_gt_i32 s11, 0xaff
	v_readfirstlane_b32 s22, v0
	s_cbranch_scc1 .LBB0_551
	v_bfe_i32 v3, v0, 27, 1
	v_lshlrev_b32_e32 v2, 4, v0
	v_lshrrev_b32_e32 v3, 22, v3
	v_add_u32_e32 v3, v2, v3
	v_and_b32_e32 v3, 0xfffffc00, v3
	s_add_u32 s50, s4, 0x4600000
	v_sub_u32_e32 v2, v2, v3
	s_addc_u32 s51, s5, 0
	v_lshrrev_b32_e32 v3, 4, v2
	v_ashrrev_i32_e32 v4, 31, v0
	s_add_u32 s52, s4, 0xc800000
	v_bitop3_b32 v2, v3, v2, 32 bitop3:0x6c
	v_lshrrev_b32_e32 v4, 26, v4
	s_addc_u32 s53, s5, 0
	v_ashrrev_i32_e32 v3, 31, v2
	v_add_u32_e32 v0, v0, v4
	s_ashr_i32 s6, s11, 31
	v_lshrrev_b32_e32 v3, 26, v3
	v_ashrrev_i32_e32 v7, 6, v0
	s_lshr_b32 s6, s6, 29
	v_add_u32_e32 v3, v2, v3
	v_lshlrev_b32_e32 v0, 3, v7
	s_add_i32 s6, s11, s6
	s_ashr_i32 s40, s22, 6
	v_ashrrev_i32_e32 v6, 6, v3
	v_and_b32_e32 v0, -16, v0
	s_ashr_i32 s7, s6, 3
	s_and_b32 s6, s6, -8
	s_ashr_i32 s41, s22, 8
	s_lshl_b32 s54, s40, 10
	v_add_u32_e32 v4, v6, v0
	v_and_b32_e32 v0, 3, v6
	s_mov_b32 s0, 0xfffe0
	s_sub_i32 s6, s11, s6
	v_and_or_b32 v0, v4, s0, v0
	s_cmp_lt_i32 s6, 0
	s_movk_i32 s0, 0x161
	s_cselect_b32 s8, s0, 0x160
	s_mul_i32 s6, s8, s6
	s_add_i32 s6, s6, s7
	s_mul_hi_i32 s7, s6, 0x2e8ba2e9
	s_lshr_b32 s8, s7, 31
	s_ashr_i32 s7, s7, 6
	s_add_i32 s7, s7, s8
	s_lshl_b32 s8, s7, 3
	s_mulk_i32 s7, 0x160
	s_sub_i32 s6, s6, s7
	s_bfe_u32 s7, s6, 0x3001c
	s_add_i32 s7, s6, s7
	s_sext_i32_i16 s9, s7
	s_and_b32 s7, s7, 0xfff8
	s_sub_i32 s6, s6, s7
	s_sext_i32_i16 s6, s6
	s_add_i32 s48, s8, s6
	s_ashr_i32 s49, s48, 31
	v_lshrrev_b32_e32 v5, 2, v4
	v_lshlrev_b32_e32 v8, 1, v4
	v_and_b32_e32 v3, 0xc0, v3
	s_lshr_b32 s10, s9, 3
	s_lshl_b64 s[6:7], s[48:49], 20
	v_and_b32_e32 v5, 4, v5
	v_and_b32_e32 v8, 24, v8
	v_sub_u32_e32 v2, v2, v3
	v_mov_b32_e32 v3, 1
	s_add_u32 s6, s50, s6
	v_or3_b32 v0, v0, v5, v8
	v_lshlrev_b32_e32 v5, 5, v7
	v_ashrrev_i16_sdwa v2, v3, sext(v2) dst_sel:DWORD dst_unused:UNUSED_PAD src0_sel:DWORD src1_sel:BYTE_0
	s_addc_u32 s7, s51, s7
	s_bfe_i64 s[8:9], s[10:11], 0x100000
	v_and_b32_e32 v5, 32, v5
	v_bfe_i32 v8, v2, 0, 16
	s_lshl_b64 s[8:9], s[8:9], 20
	v_add_lshl_u32 v2, v5, v8, 1
	s_add_u32 s8, s52, s8
	v_lshl_add_u32 v0, v0, 12, v2
	s_addc_u32 s9, s53, s9
	s_add_i32 s49, s54, 0
	v_lshl_add_u32 v130, v4, 12, v2
	v_lshl_add_u64 v[2:3], s[8:9], 0, v[0:1]
	s_add_i32 m0, s49, 0x10000
	v_lshl_add_u64 v[4:5], v[2:3], 0, s[60:61]
	global_load_lds_dwordx4 v0, s[8:9]
	s_add_i32 m0, s49, 0x12000
	v_mov_b32_e32 v131, v1
	global_load_lds_dwordx4 v[4:5], off
	v_lshl_add_u64 v[4:5], s[6:7], 0, v[130:131]
	s_mov_b32 m0, s49
	s_add_i32 s55, s49, 0x2000
	global_load_lds_dwordx4 v130, s[6:7]
	v_lshl_add_u64 v[10:11], v[4:5], 0, s[60:61]
	s_mov_b32 m0, s55
	s_add_i32 s56, s49, 0x4000
	global_load_lds_dwordx4 v[10:11], off
	v_lshl_add_u64 v[10:11], v[2:3], 0, s[20:21]
	s_add_i32 m0, s49, 0x14000
	s_add_i32 s57, s49, 0x6000
	global_load_lds_dwordx4 v[10:11], off
	v_lshl_add_u64 v[10:11], v[2:3], 0, s[64:65]
	s_add_i32 m0, s49, 0x16000
	s_mov_b64 s[92:93], s[58:59]
	global_load_lds_dwordx4 v[10:11], off
	v_lshl_add_u64 v[10:11], v[4:5], 0, s[20:21]
	s_mov_b32 m0, s56
	s_cmp_lg_u32 s41, 1
	global_load_lds_dwordx4 v[10:11], off
	v_lshl_add_u64 v[10:11], v[4:5], 0, s[64:65]
	s_mov_b32 m0, s57
	s_nop 0
	global_load_lds_dwordx4 v[10:11], off
	s_cbranch_scc1 .LBB0_542
	s_setprio 1
	s_barrier

.LBB0_567:
	v_ashrrev_i32_e32 v3, 31, v0
	v_lshrrev_b32_e32 v3, 26, v3
	v_lshlrev_b32_e32 v2, 4, v0
	v_add_u32_e32 v3, v0, v3
	v_bfe_i32 v0, v0, 27, 1
	v_lshrrev_b32_e32 v0, 22, v0
	v_add_u32_e32 v0, v2, v0
	v_and_b32_e32 v0, 0xfffffc00, v0
	v_sub_u32_e32 v0, v2, v0
	v_lshrrev_b32_e32 v2, 4, v0
	v_bitop3_b32 v0, v2, v0, 32 bitop3:0x6c
	v_ashrrev_i32_e32 v6, 6, v3
	v_ashrrev_i32_e32 v3, 31, v0
	v_lshrrev_b32_e32 v3, 26, v3
	v_add_u32_e32 v3, v0, v3
	v_ashrrev_i32_e32 v7, 6, v3
	v_and_b32_e32 v3, 0xc0, v3
	v_lshlrev_b32_e32 v2, 3, v6
	v_sub_u32_e32 v0, v0, v3
	v_mov_b32_e32 v3, 1
	v_and_b32_e32 v2, -16, v2
	v_lshlrev_b32_e32 v4, 5, v6
	v_ashrrev_i16_sdwa v0, v3, sext(v0) dst_sel:DWORD dst_unused:UNUSED_PAD src0_sel:DWORD src1_sel:BYTE_0
	s_add_u32 s83, s6, 0x4600000
	v_add_u32_e32 v2, v7, v2
	v_and_b32_e32 v4, 32, v4
	v_bfe_i32 v8, v0, 0, 16
	s_addc_u32 s58, s7, 0
	v_add_u32_e32 v0, v4, v8
	v_lshlrev_b32_e32 v3, 12, v2
	s_add_u32 s59, s6, 0x2800000
	v_lshl_add_u32 v148, v0, 1, v3
	s_movk_i32 s0, 0xf400
	s_addc_u32 s62, s7, 0
	v_mad_u64_u32 v[4:5], s[6:7], v2, s0, v[148:149]
	s_add_i32 s6, s40, s41
	s_ashr_i32 s7, s6, 31
	s_lshr_b32 s7, s7, 27
	s_add_i32 s7, s6, s7
	s_load_dwordx2 s[42:43], s[8:9], 0x0
	s_ashr_i32 s8, s7, 5
	s_and_b32 s7, s7, 0xffe0
	s_sub_i32 s6, s6, s7
	s_bfe_i32 s7, s6, 0x80000
	s_bfe_u32 s7, s7, 0x2000d
	s_add_i32 s7, s6, s7
	s_lshl_b32 s9, s8, 2
	s_bfe_i32 s8, s7, 0x80000
	s_and_b32 s7, s7, 0xfc
	s_sub_i32 s6, s6, s7
	s_sext_i32_i8 s6, s6
	s_add_i32 s54, s9, s6
	s_ashr_i32 s10, s2, 6
	s_sext_i32_i16 s40, s8
	s_ashr_i32 s55, s54, 31
	s_ashr_i32 s11, s2, 8
	s_lshl_b32 s63, s10, 10
	s_lshr_b32 s8, s40, 2
	s_lshl_b64 s[6:7], s[54:55], 20
	s_add_u32 s9, s83, s6
	s_addc_u32 s41, s58, s7
	s_ashr_i32 s6, s40, 3
	s_ashr_i32 s7, s6, 31
	s_lshl_b64 s[6:7], s[6:7], 10
	s_add_u32 s6, s9, s6
	s_addc_u32 s7, s41, s7
	s_bfe_i64 s[8:9], s[8:9], 0x100000
	s_lshl_b64 s[8:9], s[8:9], 18
	s_add_u32 s8, s59, s8
	s_addc_u32 s9, s62, s9
	v_mov_b32_e32 v0, v4
	s_add_i32 s55, s63, 0
	v_lshl_add_u64 v[2:3], s[8:9], 0, v[0:1]
	s_add_i32 m0, s55, 0x10000
	v_mov_b32_e32 v149, v1
	global_load_lds_dwordx4 v4, s[8:9]
	v_lshl_add_u64 v[4:5], v[2:3], 0, s[38:39]
	s_add_i32 m0, s55, 0x12000
	s_add_i32 s84, s55, 0x2000
	global_load_lds_dwordx4 v[4:5], off
	v_lshl_add_u64 v[4:5], s[6:7], 0, v[148:149]
	s_mov_b32 m0, s55
	v_lshl_add_u64 v[10:11], v[4:5], 0, s[60:61]
	global_load_lds_dwordx4 v148, s[6:7]
	s_mov_b32 m0, s84
	s_mov_b64 s[0:1], 0x20000
	global_load_lds_dwordx4 v[10:11], off
	v_lshl_add_u64 v[10:11], v[2:3], 0, s[0:1]
	s_add_i32 m0, s55, 0x14000
	s_add_i32 s85, s55, 0x4000
	global_load_lds_dwordx4 v[10:11], off
	v_lshl_add_u64 v[10:11], v[2:3], 0, s[44:45]
	s_add_i32 m0, s55, 0x16000
	s_add_i32 s86, s55, 0x6000
	global_load_lds_dwordx4 v[10:11], off
	v_lshl_add_u64 v[10:11], v[4:5], 0, s[20:21]
	s_mov_b32 m0, s85
	s_cmp_lg_u32 s11, 1
	global_load_lds_dwordx4 v[10:11], off
	v_lshl_add_u64 v[10:11], v[4:5], 0, s[64:65]
	s_mov_b32 m0, s86
	s_nop 0
	global_load_lds_dwordx4 v[10:11], off
	s_cbranch_scc1 .LBB0_569
	s_setprio 1
	s_barrier

.LBB0_578:
	s_barrier
	v_mfma_f32_16x16x32_bf16 v[50:53], v[188:191], v[152:155], v[50:53]
	v_mfma_f32_16x16x32_bf16 v[42:45], v[196:199], v[152:155], v[42:45]
	v_mfma_f32_16x16x32_bf16 v[34:37], v[188:191], v[164:167], v[34:37]
	v_mfma_f32_16x16x32_bf16 v[26:29], v[196:199], v[164:167], v[26:29]
	v_mfma_f32_16x16x32_bf16 v[18:21], v[188:191], v[172:175], v[18:21]
	v_mfma_f32_16x16x32_bf16 v[10:13], v[196:199], v[172:175], v[10:13]
	v_mfma_f32_16x16x32_bf16 v[6:9], v[188:191], v[180:183], v[6:9]
	v_mfma_f32_16x16x32_bf16 v[2:5], v[196:199], v[180:183], v[2:5]
	v_mfma_f32_16x16x32_bf16 v[50:53], v[192:195], v[160:163], v[50:53]
	v_mfma_f32_16x16x32_bf16 v[42:45], v[200:203], v[160:163], v[42:45]
	v_mfma_f32_16x16x32_bf16 v[34:37], v[192:195], v[168:171], v[34:37]
	v_mfma_f32_16x16x32_bf16 v[26:29], v[200:203], v[168:171], v[26:29]
	v_mfma_f32_16x16x32_bf16 v[18:21], v[192:195], v[176:179], v[18:21]
	v_mfma_f32_16x16x32_bf16 v[10:13], v[200:203], v[176:179], v[10:13]
	v_mfma_f32_16x16x32_bf16 v[6:9], v[192:195], v[184:187], v[6:9]
	v_mfma_f32_16x16x32_bf16 v[2:5], v[200:203], v[184:187], v[2:5]
	s_barrier
.Lrot_enter_2:
	s_add_u32 s7, s40, 0xfff80080
	s_addc_u32 s11, s41, -1
	s_add_i32 s49, 0, 0x10000
	v_add_u32_e32 v142, s49, v158
	ds_read_b128 v[130:133], v142
	ds_read_b128 v[134:137], v142 offset:1024
	ds_read_b128 v[138:141], v142 offset:2048
	ds_read_b128 v[142:145], v142 offset:3072
	s_cmp_eq_u32 s6, 4
	s_cselect_b32 s95, s51, s11
	s_cselect_b32 s94, s50, s7
	s_cselect_b32 s97, s53, s9
	s_cselect_b32 s96, s52, s8
	v_lshl_add_u64 v[156:157], s[40:41], 0, v[150:151]
	s_add_i32 m0, s55, 0xc000
	ds_read_b128 v[152:155], v159
	ds_read_b128 v[160:163], v159 offset:1024
	ds_read_b128 v[164:167], v159 offset:2048
	ds_read_b128 v[168:171], v159 offset:3072
	ds_read_b128 v[172:175], v159 offset:4096
	ds_read_b128 v[176:179], v159 offset:5120
	ds_read_b128 v[180:183], v159 offset:6144
	ds_read_b128 v[184:187], v159 offset:7168
	global_load_lds_dwordx4 v[156:157], off
	v_lshl_add_u64 v[156:157], v[156:157], 0, s[60:61]
	s_add_i32 m0, s55, 0xe000
	s_nop 0
	global_load_lds_dwordx4 v[156:157], off
	s_waitcnt lgkmcnt(8)
	s_barrier
	s_waitcnt lgkmcnt(0)
	v_mfma_f32_16x16x32_bf16 v[126:129], v[130:133], v[152:155], v[126:129]
	v_mfma_f32_16x16x32_bf16 v[122:125], v[138:141], v[152:155], v[122:125]
	v_mfma_f32_16x16x32_bf16 v[114:117], v[130:133], v[164:167], v[114:117]
	v_mfma_f32_16x16x32_bf16 v[110:113], v[138:141], v[164:167], v[110:113]
	v_mfma_f32_16x16x32_bf16 v[102:105], v[130:133], v[172:175], v[102:105]
	v_mfma_f32_16x16x32_bf16 v[94:97], v[138:141], v[172:175], v[94:97]
	v_mfma_f32_16x16x32_bf16 v[86:89], v[130:133], v[180:183], v[86:89]
	v_mfma_f32_16x16x32_bf16 v[78:81], v[138:141], v[180:183], v[78:81]
	v_mfma_f32_16x16x32_bf16 v[126:129], v[134:137], v[160:163], v[126:129]
	v_mfma_f32_16x16x32_bf16 v[122:125], v[142:145], v[160:163], v[122:125]
	v_mfma_f32_16x16x32_bf16 v[114:117], v[134:137], v[168:171], v[114:117]
	v_mfma_f32_16x16x32_bf16 v[110:113], v[142:145], v[168:171], v[110:113]
	v_mfma_f32_16x16x32_bf16 v[102:105], v[134:137], v[176:179], v[102:105]
	v_mfma_f32_16x16x32_bf16 v[94:97], v[142:145], v[176:179], v[94:97]
	v_mfma_f32_16x16x32_bf16 v[86:89], v[134:137], v[184:187], v[86:89]
	v_mfma_f32_16x16x32_bf16 v[78:81], v[142:145], v[184:187], v[78:81]
	s_barrier
	s_add_i32 s7, 0, 0x14000
	v_add_u32_e32 v156, s7, v158
	s_add_i32 s11, s49, s63
	ds_read_b128 v[188:191], v156
	ds_read_b128 v[192:195], v156 offset:1024
	ds_read_b128 v[196:199], v156 offset:2048
	ds_read_b128 v[200:203], v156 offset:3072
	v_lshl_add_u64 v[156:157], s[96:97], 0, v[0:1]
	s_mov_b32 m0, s11
	v_lshl_add_u64 v[204:205], v[156:157], 0, s[68:69]
	global_load_lds_dwordx4 v[156:157], off
	s_add_i32 m0, s11, 0x2000
	s_nop 0
	global_load_lds_dwordx4 v[204:205], off
	s_barrier
	s_waitcnt lgkmcnt(0)
	v_mfma_f32_16x16x32_bf16 v[118:121], v[188:191], v[152:155], v[118:121]
	v_mfma_f32_16x16x32_bf16 v[106:109], v[196:199], v[152:155], v[106:109]
	v_mfma_f32_16x16x32_bf16 v[98:101], v[188:191], v[164:167], v[98:101]
	v_mfma_f32_16x16x32_bf16 v[90:93], v[196:199], v[164:167], v[90:93]
	v_mfma_f32_16x16x32_bf16 v[82:85], v[188:191], v[172:175], v[82:85]
	v_mfma_f32_16x16x32_bf16 v[74:77], v[196:199], v[172:175], v[74:77]
	v_mfma_f32_16x16x32_bf16 v[70:73], v[188:191], v[180:183], v[70:73]
	v_mfma_f32_16x16x32_bf16 v[66:69], v[196:199], v[180:183], v[66:69]
	v_mfma_f32_16x16x32_bf16 v[118:121], v[192:195], v[160:163], v[118:121]
	v_mfma_f32_16x16x32_bf16 v[106:109], v[200:203], v[160:163], v[106:109]
	v_mfma_f32_16x16x32_bf16 v[98:101], v[192:195], v[168:171], v[98:101]
	v_mfma_f32_16x16x32_bf16 v[90:93], v[200:203], v[168:171], v[90:93]
	v_mfma_f32_16x16x32_bf16 v[82:85], v[192:195], v[176:179], v[82:85]
	v_mfma_f32_16x16x32_bf16 v[74:77], v[200:203], v[176:179], v[74:77]
	v_mfma_f32_16x16x32_bf16 v[70:73], v[192:195], v[184:187], v[70:73]
	v_mfma_f32_16x16x32_bf16 v[66:69], v[200:203], v[184:187], v[66:69]
	s_barrier
	s_mov_b32 m0, s55
	v_lshl_add_u64 v[204:205], s[94:95], 0, v[148:149]
	ds_read_b128 v[152:155], v159 offset:16384
	ds_read_b128 v[160:163], v159 offset:17408
	ds_read_b128 v[164:167], v159 offset:18432
	ds_read_b128 v[168:171], v159 offset:19456
	ds_read_b128 v[172:175], v159 offset:20480
	ds_read_b128 v[176:179], v159 offset:21504
	ds_read_b128 v[180:183], v159 offset:22528
	ds_read_b128 v[184:187], v159 offset:23552
	global_load_lds_dwordx4 v[204:205], off
	v_lshl_add_u64 v[206:207], v[204:205], 0, s[60:61]
	s_mov_b32 m0, s84
	s_nop 0
	global_load_lds_dwordx4 v[206:207], off
	s_barrier
	s_waitcnt lgkmcnt(0)
	v_mfma_f32_16x16x32_bf16 v[62:65], v[130:133], v[152:155], v[62:65]
	v_mfma_f32_16x16x32_bf16 v[58:61], v[138:141], v[152:155], v[58:61]
	v_mfma_f32_16x16x32_bf16 v[54:57], v[130:133], v[164:167], v[54:57]
	v_mfma_f32_16x16x32_bf16 v[46:49], v[138:141], v[164:167], v[46:49]
	v_mfma_f32_16x16x32_bf16 v[38:41], v[130:133], v[172:175], v[38:41]
	v_mfma_f32_16x16x32_bf16 v[30:33], v[138:141], v[172:175], v[30:33]
	v_mfma_f32_16x16x32_bf16 v[22:25], v[130:133], v[180:183], v[22:25]
	v_mfma_f32_16x16x32_bf16 v[14:17], v[138:141], v[180:183], v[14:17]
	v_mfma_f32_16x16x32_bf16 v[62:65], v[134:137], v[160:163], v[62:65]
	v_mfma_f32_16x16x32_bf16 v[58:61], v[142:145], v[160:163], v[58:61]
	v_mfma_f32_16x16x32_bf16 v[54:57], v[134:137], v[168:171], v[54:57]
	v_mfma_f32_16x16x32_bf16 v[46:49], v[142:145], v[168:171], v[46:49]
	v_mfma_f32_16x16x32_bf16 v[38:41], v[134:137], v[176:179], v[38:41]
	v_mfma_f32_16x16x32_bf16 v[30:33], v[142:145], v[176:179], v[30:33]
	v_mfma_f32_16x16x32_bf16 v[22:25], v[134:137], v[184:187], v[22:25]
	v_mfma_f32_16x16x32_bf16 v[14:17], v[142:145], v[184:187], v[14:17]
	s_barrier
	s_add_i32 s7, s7, s63
	v_lshl_add_u64 v[130:131], v[156:157], 0, vcc
	s_mov_b32 m0, s7
	s_nop 0
	global_load_lds_dwordx4 v[130:131], off
	v_lshl_add_u64 v[130:131], v[156:157], 0, s[78:79]
	s_add_i32 m0, s7, 0x2000
	s_nop 0
	global_load_lds_dwordx4 v[130:131], off
	v_lshl_add_u64 v[230:231], v[204:205], 0, s[20:21]
	s_mov_b32 m0, s85
	s_nop 0
	global_load_lds_dwordx4 v[230:231], off
	v_lshl_add_u64 v[230:231], v[204:205], 0, s[64:65]
	s_mov_b32 m0, s86
	s_nop 0
	global_load_lds_dwordx4 v[230:231], off
	s_waitcnt vmcnt(8)
	s_barrier
	v_mfma_f32_16x16x32_bf16 v[50:53], v[188:191], v[152:155], v[50:53]
	v_mfma_f32_16x16x32_bf16 v[42:45], v[196:199], v[152:155], v[42:45]
	v_mfma_f32_16x16x32_bf16 v[34:37], v[188:191], v[164:167], v[34:37]
	v_mfma_f32_16x16x32_bf16 v[26:29], v[196:199], v[164:167], v[26:29]
	v_mfma_f32_16x16x32_bf16 v[18:21], v[188:191], v[172:175], v[18:21]
	v_mfma_f32_16x16x32_bf16 v[10:13], v[196:199], v[172:175], v[10:13]
	v_mfma_f32_16x16x32_bf16 v[6:9], v[188:191], v[180:183], v[6:9]
	v_mfma_f32_16x16x32_bf16 v[2:5], v[196:199], v[180:183], v[2:5]
	v_mfma_f32_16x16x32_bf16 v[50:53], v[192:195], v[160:163], v[50:53]
	v_mfma_f32_16x16x32_bf16 v[42:45], v[200:203], v[160:163], v[42:45]
	v_mfma_f32_16x16x32_bf16 v[34:37], v[192:195], v[168:171], v[34:37]
	v_mfma_f32_16x16x32_bf16 v[26:29], v[200:203], v[168:171], v[26:29]
	v_mfma_f32_16x16x32_bf16 v[18:21], v[192:195], v[176:179], v[18:21]
	v_mfma_f32_16x16x32_bf16 v[10:13], v[200:203], v[176:179], v[10:13]
	v_mfma_f32_16x16x32_bf16 v[6:9], v[192:195], v[184:187], v[6:9]
	v_mfma_f32_16x16x32_bf16 v[2:5], v[200:203], v[184:187], v[2:5]
	s_barrier
	s_add_i32 s7, 0, 0x18000
	v_add_u32_e32 v142, s7, v158
	ds_read_b128 v[130:133], v142
	ds_read_b128 v[134:137], v142 offset:1024
	ds_read_b128 v[138:141], v142 offset:2048
	ds_read_b128 v[142:145], v142 offset:3072
	ds_read_b128 v[152:155], v159 offset:32768
	ds_read_b128 v[160:163], v159 offset:33792
	ds_read_b128 v[164:167], v159 offset:34816
	ds_read_b128 v[168:171], v159 offset:35840
	ds_read_b128 v[172:175], v159 offset:36864
	ds_read_b128 v[176:179], v159 offset:37888
	ds_read_b128 v[180:183], v159 offset:38912
	ds_read_b128 v[184:187], v159 offset:39936
	s_waitcnt lgkmcnt(8)
	s_barrier
	s_waitcnt lgkmcnt(0)
	v_mfma_f32_16x16x32_bf16 v[126:129], v[130:133], v[152:155], v[126:129]
	v_mfma_f32_16x16x32_bf16 v[122:125], v[138:141], v[152:155], v[122:125]
	v_mfma_f32_16x16x32_bf16 v[114:117], v[130:133], v[164:167], v[114:117]
	v_mfma_f32_16x16x32_bf16 v[110:113], v[138:141], v[164:167], v[110:113]
	v_mfma_f32_16x16x32_bf16 v[102:105], v[130:133], v[172:175], v[102:105]
	v_mfma_f32_16x16x32_bf16 v[94:97], v[138:141], v[172:175], v[94:97]
	v_mfma_f32_16x16x32_bf16 v[86:89], v[130:133], v[180:183], v[86:89]
	v_mfma_f32_16x16x32_bf16 v[78:81], v[138:141], v[180:183], v[78:81]
	v_mfma_f32_16x16x32_bf16 v[126:129], v[134:137], v[160:163], v[126:129]
	v_mfma_f32_16x16x32_bf16 v[122:125], v[142:145], v[160:163], v[122:125]
	v_mfma_f32_16x16x32_bf16 v[114:117], v[134:137], v[168:171], v[114:117]
	v_mfma_f32_16x16x32_bf16 v[110:113], v[142:145], v[168:171], v[110:113]
	v_mfma_f32_16x16x32_bf16 v[102:105], v[134:137], v[176:179], v[102:105]
	v_mfma_f32_16x16x32_bf16 v[94:97], v[142:145], v[176:179], v[94:97]
	v_mfma_f32_16x16x32_bf16 v[86:89], v[134:137], v[184:187], v[86:89]
	v_mfma_f32_16x16x32_bf16 v[78:81], v[142:145], v[184:187], v[78:81]
	s_barrier
	s_add_i32 s11, 0, 0x1c000
	s_add_i32 s7, s7, s63
	v_add_u32_e32 v200, s11, v158
	v_lshl_add_u64 v[206:207], v[156:157], 0, s[34:35]
	s_mov_b32 m0, s7
	ds_read_b128 v[188:191], v200
	ds_read_b128 v[192:195], v200 offset:1024
	ds_read_b128 v[196:199], v200 offset:2048
	ds_read_b128 v[200:203], v200 offset:3072
	global_load_lds_dwordx4 v[206:207], off
	v_lshl_add_u64 v[206:207], v[156:157], 0, s[38:39]
	s_add_i32 m0, s7, 0x2000
	s_nop 0
	global_load_lds_dwordx4 v[206:207], off
	s_barrier
	s_waitcnt lgkmcnt(0)
	v_mfma_f32_16x16x32_bf16 v[118:121], v[188:191], v[152:155], v[118:121]
	v_mfma_f32_16x16x32_bf16 v[106:109], v[196:199], v[152:155], v[106:109]
	v_mfma_f32_16x16x32_bf16 v[98:101], v[188:191], v[164:167], v[98:101]
	v_mfma_f32_16x16x32_bf16 v[90:93], v[196:199], v[164:167], v[90:93]
	v_mfma_f32_16x16x32_bf16 v[82:85], v[188:191], v[172:175], v[82:85]
	v_mfma_f32_16x16x32_bf16 v[74:77], v[196:199], v[172:175], v[74:77]
	v_mfma_f32_16x16x32_bf16 v[70:73], v[188:191], v[180:183], v[70:73]
	v_mfma_f32_16x16x32_bf16 v[66:69], v[196:199], v[180:183], v[66:69]
	v_mfma_f32_16x16x32_bf16 v[118:121], v[192:195], v[160:163], v[118:121]
	v_mfma_f32_16x16x32_bf16 v[106:109], v[200:203], v[160:163], v[106:109]
	v_mfma_f32_16x16x32_bf16 v[98:101], v[192:195], v[168:171], v[98:101]
	v_mfma_f32_16x16x32_bf16 v[90:93], v[200:203], v[168:171], v[90:93]
	v_mfma_f32_16x16x32_bf16 v[82:85], v[192:195], v[176:179], v[82:85]
	v_mfma_f32_16x16x32_bf16 v[74:77], v[200:203], v[176:179], v[74:77]
	v_mfma_f32_16x16x32_bf16 v[70:73], v[192:195], v[184:187], v[70:73]
	v_mfma_f32_16x16x32_bf16 v[66:69], v[200:203], v[184:187], v[66:69]
	s_barrier
	s_mov_b32 m0, s89
	v_lshl_add_u64 v[206:207], v[204:205], 0, s[34:35]
	ds_read_b128 v[152:155], v159 offset:49152
	ds_read_b128 v[160:163], v159 offset:50176
	ds_read_b128 v[164:167], v159 offset:51200
	ds_read_b128 v[168:171], v159 offset:52224
	ds_read_b128 v[172:175], v159 offset:53248
	ds_read_b128 v[176:179], v159 offset:54272
	ds_read_b128 v[180:183], v159 offset:55296
	ds_read_b128 v[184:187], v159 offset:56320
	global_load_lds_dwordx4 v[206:207], off
	v_lshl_add_u64 v[204:205], v[204:205], 0, s[66:67]
	s_mov_b32 m0, s90
	s_nop 0
	global_load_lds_dwordx4 v[204:205], off
	s_barrier
	s_waitcnt lgkmcnt(0)
	v_mfma_f32_16x16x32_bf16 v[62:65], v[130:133], v[152:155], v[62:65]
	v_mfma_f32_16x16x32_bf16 v[58:61], v[138:141], v[152:155], v[58:61]
	v_mfma_f32_16x16x32_bf16 v[54:57], v[130:133], v[164:167], v[54:57]
	v_mfma_f32_16x16x32_bf16 v[46:49], v[138:141], v[164:167], v[46:49]
	v_mfma_f32_16x16x32_bf16 v[38:41], v[130:133], v[172:175], v[38:41]
	v_mfma_f32_16x16x32_bf16 v[30:33], v[138:141], v[172:175], v[30:33]
	v_mfma_f32_16x16x32_bf16 v[22:25], v[130:133], v[180:183], v[22:25]
	v_mfma_f32_16x16x32_bf16 v[14:17], v[138:141], v[180:183], v[14:17]
	v_mfma_f32_16x16x32_bf16 v[62:65], v[134:137], v[160:163], v[62:65]
	v_mfma_f32_16x16x32_bf16 v[58:61], v[142:145], v[160:163], v[58:61]
	v_mfma_f32_16x16x32_bf16 v[54:57], v[134:137], v[168:171], v[54:57]
	v_mfma_f32_16x16x32_bf16 v[46:49], v[142:145], v[168:171], v[46:49]
	v_mfma_f32_16x16x32_bf16 v[38:41], v[134:137], v[176:179], v[38:41]
	v_mfma_f32_16x16x32_bf16 v[30:33], v[142:145], v[176:179], v[30:33]
	v_mfma_f32_16x16x32_bf16 v[22:25], v[134:137], v[184:187], v[22:25]
	v_mfma_f32_16x16x32_bf16 v[14:17], v[142:145], v[184:187], v[14:17]
	s_barrier
	s_add_i32 s7, s11, s63
	v_lshl_add_u64 v[130:131], v[156:157], 0, s[72:73]
	s_mov_b32 m0, s7
	s_nop 0
	global_load_lds_dwordx4 v[130:131], off
	v_lshl_add_u64 v[130:131], v[156:157], 0, s[56:57]
	s_add_i32 m0, s7, 0x2000
	s_nop 0
	global_load_lds_dwordx4 v[130:131], off
	s_waitcnt vmcnt(6)
	s_add_i32 s6, s6, 2
	s_add_u32 s8, s8, 0x100
	s_addc_u32 s9, s9, 0
	s_add_u32 s40, s40, 0x100
	s_addc_u32 s41, s41, 0
	s_cmp_gt_u32 s6, 5
	s_cbranch_scc0 .LBB0_578
	s_barrier
	v_mfma_f32_16x16x32_bf16 v[50:53], v[188:191], v[152:155], v[50:53]
	v_mfma_f32_16x16x32_bf16 v[42:45], v[196:199], v[152:155], v[42:45]
	v_mfma_f32_16x16x32_bf16 v[34:37], v[188:191], v[164:167], v[34:37]
	v_mfma_f32_16x16x32_bf16 v[26:29], v[196:199], v[164:167], v[26:29]
	v_mfma_f32_16x16x32_bf16 v[18:21], v[188:191], v[172:175], v[18:21]
	v_mfma_f32_16x16x32_bf16 v[10:13], v[196:199], v[172:175], v[10:13]
	v_mfma_f32_16x16x32_bf16 v[6:9], v[188:191], v[180:183], v[6:9]
	v_mfma_f32_16x16x32_bf16 v[2:5], v[196:199], v[180:183], v[2:5]
	v_mfma_f32_16x16x32_bf16 v[50:53], v[192:195], v[160:163], v[50:53]
	v_mfma_f32_16x16x32_bf16 v[42:45], v[200:203], v[160:163], v[42:45]
	v_mfma_f32_16x16x32_bf16 v[34:37], v[192:195], v[168:171], v[34:37]
	v_mfma_f32_16x16x32_bf16 v[26:29], v[200:203], v[168:171], v[26:29]
	v_mfma_f32_16x16x32_bf16 v[18:21], v[192:195], v[176:179], v[18:21]
	v_mfma_f32_16x16x32_bf16 v[10:13], v[200:203], v[176:179], v[10:13]
	v_mfma_f32_16x16x32_bf16 v[6:9], v[192:195], v[184:187], v[6:9]
	v_mfma_f32_16x16x32_bf16 v[2:5], v[200:203], v[184:187], v[2:5]
	s_barrier
	v_mov_b32_e32 v156, v146
	s_lshl_b32 s6, s92, 8
	v_ashrrev_i32_e32 v130, 2, v156
	s_or_b32 s6, s6, s88
	v_and_b32_e32 v130, -4, v130
	v_add_u32_e32 v152, s6, v130
	v_ashrrev_i32_e32 v153, 31, v152
	v_cndmask_b32_e64 v131, 0, 1, s[44:45]
	v_lshl_add_u64 v[154:155], v[152:153], 2, s[42:43]
	v_mov_b32_e32 v130, 1.0
	v_cmp_ne_u32_e64 s[40:41], 1, v131
	s_andn2_b64 vcc, exec, s[44:45]
	v_mov_b32_e32 v134, 1.0
	v_mov_b32_e32 v135, 1.0
	v_mov_b32_e32 v136, 1.0
	v_mov_b32_e32 v137, 1.0
	s_cbranch_vccnz .LBB0_581
	global_load_dwordx4 v[134:137], v[154:155], off

.LBB0_589:
	s_setprio 0
	v_readlane_b32 s0, v255, 8
	v_readlane_b32 s58, v255, 30
	v_readlane_b32 s62, v255, 10
	v_readlane_b32 s84, v255, 12
	v_readlane_b32 s86, v255, 14
	v_readlane_b32 s52, v255, 18
	v_readlane_b32 s54, v255, 22
	v_readlane_b32 s44, v255, 26
	v_readlane_b32 s72, v255, 7
	v_readlane_b32 s1, v255, 9
	v_readlane_b32 s59, v255, 31
	v_readlane_b32 s63, v255, 11
	v_readlane_b32 s85, v255, 13
	v_readlane_b32 s87, v255, 15
	v_readlane_b32 s53, v255, 19
	v_readlane_b32 s55, v255, 23
	v_readlane_b32 s45, v255, 27
	s_movk_i32 s92, 0x4000
	s_movk_i32 s89, 0x37ff
	s_mov_b32 s88, 0x16000
	s_movk_i32 s91, 0x60
	s_mov_b32 s78, 0x2a000000
	s_mov_b32 s79, 0x3fffe
	s_mov_b32 s90, 0xc0000
	s_mov_b64 s[48:49], 0x2000
	s_barrier

.LBB0_669:
	s_add_u32 s51, s6, 0x10a00000
	s_addc_u32 s52, s7, 0
	s_add_u32 s53, s6, 0xb200000
	s_addc_u32 s54, s7, 0
	s_add_i32 s6, s42, s43
	v_ashrrev_i32_e32 v3, 31, v0
	s_ashr_i32 s7, s6, 31
	v_lshrrev_b32_e32 v3, 26, v3
	s_lshr_b32 s7, s7, 27
	v_lshlrev_b32_e32 v2, 4, v0
	v_add_u32_e32 v3, v0, v3
	v_bfe_i32 v0, v0, 27, 1
	s_add_i32 s7, s6, s7
	s_load_dwordx2 s[40:41], s[8:9], 0x0
	v_lshrrev_b32_e32 v0, 22, v0
	s_ashr_i32 s8, s7, 5
	s_and_b32 s7, s7, 0xffe0
	v_add_u32_e32 v0, v2, v0
	s_sub_i32 s6, s6, s7
	v_and_b32_e32 v0, 0xfffffc00, v0
	s_bfe_i32 s7, s6, 0x80000
	v_sub_u32_e32 v0, v2, v0
	s_bfe_u32 s7, s7, 0x2000d
	v_lshrrev_b32_e32 v2, 4, v0
	s_add_i32 s7, s6, s7
	v_bitop3_b32 v0, v2, v0, 32 bitop3:0x6c
	s_bfe_i32 s9, s7, 0x80000
	s_and_b32 s7, s7, 0xfc
	v_ashrrev_i32_e32 v6, 6, v3
	v_ashrrev_i32_e32 v3, 31, v0
	s_sub_i32 s6, s6, s7
	v_lshrrev_b32_e32 v3, 26, v3
	s_lshl_b32 s8, s8, 2
	s_sext_i32_i8 s6, s6
	s_ashr_i32 s10, s50, 6
	v_add_u32_e32 v3, v0, v3
	s_sext_i32_i16 s9, s9
	s_add_i32 s87, s8, s6
	s_ashr_i32 s11, s50, 8
	v_lshlrev_b32_e32 v2, 3, v6
	v_ashrrev_i32_e32 v7, 6, v3
	v_and_b32_e32 v3, 0xc0, v3
	s_lshl_b32 s55, s10, 10
	s_lshr_b32 s42, s9, 2
	s_mul_i32 s6, s87, 0x2c0000
	v_and_b32_e32 v2, 0x7ffff0, v2
	v_sub_u32_e32 v0, v0, v3
	v_mov_b32_e32 v3, 1
	s_mul_hi_i32 s7, s87, 0x2c0000
	s_add_u32 s6, s51, s6
	v_add_u32_e32 v2, v7, v2
	v_lshlrev_b32_e32 v4, 5, v6
	v_ashrrev_i16_sdwa v0, v3, sext(v0) dst_sel:DWORD dst_unused:UNUSED_PAD src0_sel:DWORD src1_sel:BYTE_0
	s_movk_i32 s0, 0x1600
	s_addc_u32 s7, s52, s7
	s_ashr_i32 s8, s9, 2
	v_and_b32_e32 v8, 32, v4
	v_bfe_i32 v9, v0, 0, 16
	v_mul_lo_u32 v0, v2, s0
	s_mul_hi_i32 s9, s8, 0x2c0000
	s_mul_i32 s8, s8, 0x2c0000
	v_or_b32_e32 v0, v0, v8
	s_add_u32 s8, s53, s8
	v_add_lshl_u32 v0, v0, v9, 1
	s_addc_u32 s9, s54, s9
	s_add_i32 s56, s55, 0
	v_lshl_add_u64 v[2:3], s[8:9], 0, v[0:1]
	s_add_i32 m0, s56, 0x10000
	v_lshl_add_u64 v[4:5], v[2:3], 0, s[26:27]
	global_load_lds_dwordx4 v0, s[8:9]
	s_add_i32 m0, s56, 0x12000
	s_add_i32 s57, s56, 0x2000
	global_load_lds_dwordx4 v[4:5], off
	v_lshl_add_u64 v[4:5], s[6:7], 0, v[0:1]
	s_mov_b32 m0, s56
	v_lshl_add_u64 v[12:13], v[4:5], 0, s[26:27]
	global_load_lds_dwordx4 v0, s[6:7]
	s_mov_b32 m0, s57
	s_add_i32 s58, s56, 0x4000
	global_load_lds_dwordx4 v[12:13], off
	v_lshl_add_u64 v[12:13], v[2:3], 0, s[28:29]
	s_add_i32 m0, s56, 0x14000
	s_add_i32 s59, s56, 0x6000
	global_load_lds_dwordx4 v[12:13], off
	v_lshl_add_u64 v[12:13], v[2:3], 0, s[30:31]
	s_add_i32 m0, s56, 0x16000
	s_mov_b32 s1, 0x16000
	global_load_lds_dwordx4 v[12:13], off
	v_lshl_add_u64 v[12:13], v[4:5], 0, s[28:29]
	s_mov_b32 m0, s58
	s_cmp_lg_u32 s11, 1
	global_load_lds_dwordx4 v[12:13], off
	v_lshl_add_u64 v[12:13], v[4:5], 0, s[30:31]
	s_mov_b32 m0, s59
	s_nop 0
	global_load_lds_dwordx4 v[12:13], off
	s_cbranch_scc1 .LBB0_671
	s_setprio 1
	s_barrier

.Lrot_enter_1:
	s_add_u32 s7, s48, 0xffea0080
	s_addc_u32 s78, s49, -1
	s_add_i32 s79, 0, 0x10000
	v_add_u32_e32 v132, s79, v135
	ds_read_b128 v[138:141], v132
	ds_read_b128 v[142:145], v132 offset:1024
	ds_read_b128 v[148:151], v132 offset:2048
	ds_read_b128 v[152:155], v132 offset:3072
	s_cmpk_eq_i32 s6, 0x54
	s_cselect_b32 s91, s45, s78
	s_cselect_b32 s90, s44, s7
	s_cselect_b32 s93, s47, s9
	s_cselect_b32 s92, s46, s8
	v_lshl_add_u64 v[132:133], s[48:49], 0, v[130:131]
	s_add_i32 m0, s56, 0xc000
	ds_read_b128 v[156:159], v136
	ds_read_b128 v[160:163], v136 offset:1024
	ds_read_b128 v[164:167], v136 offset:2048
	ds_read_b128 v[168:171], v136 offset:3072
	ds_read_b128 v[172:175], v136 offset:4096
	ds_read_b128 v[176:179], v136 offset:5120
	ds_read_b128 v[180:183], v136 offset:6144
	ds_read_b128 v[184:187], v136 offset:7168
	global_load_lds_dwordx4 v[132:133], off
	v_lshl_add_u64 v[132:133], v[132:133], 0, s[26:27]
	s_add_i32 m0, s56, 0xe000
	s_nop 0
	global_load_lds_dwordx4 v[132:133], off
	s_waitcnt lgkmcnt(8)
	s_barrier
	s_waitcnt lgkmcnt(0)
	v_mfma_f32_16x16x32_bf16 v[126:129], v[138:141], v[156:159], v[126:129]
	v_mfma_f32_16x16x32_bf16 v[122:125], v[148:151], v[156:159], v[122:125]
	v_mfma_f32_16x16x32_bf16 v[118:121], v[138:141], v[164:167], v[118:121]
	v_mfma_f32_16x16x32_bf16 v[110:113], v[148:151], v[164:167], v[110:113]
	v_mfma_f32_16x16x32_bf16 v[102:105], v[138:141], v[172:175], v[102:105]
	v_mfma_f32_16x16x32_bf16 v[94:97], v[148:151], v[172:175], v[94:97]
	v_mfma_f32_16x16x32_bf16 v[86:89], v[138:141], v[180:183], v[86:89]
	v_mfma_f32_16x16x32_bf16 v[78:81], v[148:151], v[180:183], v[78:81]
	v_mfma_f32_16x16x32_bf16 v[126:129], v[142:145], v[160:163], v[126:129]
	v_mfma_f32_16x16x32_bf16 v[122:125], v[152:155], v[160:163], v[122:125]
	v_mfma_f32_16x16x32_bf16 v[118:121], v[142:145], v[168:171], v[118:121]
	v_mfma_f32_16x16x32_bf16 v[110:113], v[152:155], v[168:171], v[110:113]
	v_mfma_f32_16x16x32_bf16 v[102:105], v[142:145], v[176:179], v[102:105]
	v_mfma_f32_16x16x32_bf16 v[94:97], v[152:155], v[176:179], v[94:97]
	v_mfma_f32_16x16x32_bf16 v[86:89], v[142:145], v[184:187], v[86:89]
	v_mfma_f32_16x16x32_bf16 v[78:81], v[152:155], v[184:187], v[78:81]
	s_barrier
	s_add_i32 s7, 0, 0x14000
	v_add_u32_e32 v132, s7, v135
	s_add_i32 s78, s79, s55
	ds_read_b128 v[188:191], v132
	ds_read_b128 v[192:195], v132 offset:1024
	ds_read_b128 v[196:199], v132 offset:2048
	ds_read_b128 v[200:203], v132 offset:3072
	v_lshl_add_u64 v[132:133], s[92:93], 0, v[0:1]
	s_mov_b32 m0, s78
	v_lshl_add_u64 v[204:205], v[132:133], 0, s[26:27]
	global_load_lds_dwordx4 v[132:133], off
	s_add_i32 m0, s78, 0x2000
	s_nop 0
	global_load_lds_dwordx4 v[204:205], off
	s_barrier
	s_waitcnt lgkmcnt(0)
	v_mfma_f32_16x16x32_bf16 v[114:117], v[188:191], v[156:159], v[114:117]
	v_mfma_f32_16x16x32_bf16 v[106:109], v[196:199], v[156:159], v[106:109]
	v_mfma_f32_16x16x32_bf16 v[98:101], v[188:191], v[164:167], v[98:101]
	v_mfma_f32_16x16x32_bf16 v[90:93], v[196:199], v[164:167], v[90:93]
	v_mfma_f32_16x16x32_bf16 v[82:85], v[188:191], v[172:175], v[82:85]
	v_mfma_f32_16x16x32_bf16 v[74:77], v[196:199], v[172:175], v[74:77]
	v_mfma_f32_16x16x32_bf16 v[70:73], v[188:191], v[180:183], v[70:73]
	v_mfma_f32_16x16x32_bf16 v[66:69], v[196:199], v[180:183], v[66:69]
	v_mfma_f32_16x16x32_bf16 v[114:117], v[192:195], v[160:163], v[114:117]
	v_mfma_f32_16x16x32_bf16 v[106:109], v[200:203], v[160:163], v[106:109]
	v_mfma_f32_16x16x32_bf16 v[98:101], v[192:195], v[168:171], v[98:101]
	v_mfma_f32_16x16x32_bf16 v[90:93], v[200:203], v[168:171], v[90:93]
	v_mfma_f32_16x16x32_bf16 v[82:85], v[192:195], v[176:179], v[82:85]
	v_mfma_f32_16x16x32_bf16 v[74:77], v[200:203], v[176:179], v[74:77]
	v_mfma_f32_16x16x32_bf16 v[70:73], v[192:195], v[184:187], v[70:73]
	v_mfma_f32_16x16x32_bf16 v[66:69], v[200:203], v[184:187], v[66:69]
	s_barrier
	s_mov_b32 m0, s56
	v_lshl_add_u64 v[204:205], s[90:91], 0, v[0:1]
	ds_read_b128 v[156:159], v136 offset:16384
	ds_read_b128 v[160:163], v136 offset:17408
	ds_read_b128 v[164:167], v136 offset:18432
	ds_read_b128 v[168:171], v136 offset:19456
	ds_read_b128 v[172:175], v136 offset:20480
	ds_read_b128 v[176:179], v136 offset:21504
	ds_read_b128 v[180:183], v136 offset:22528
	ds_read_b128 v[184:187], v136 offset:23552
	global_load_lds_dwordx4 v[204:205], off
	v_lshl_add_u64 v[206:207], v[204:205], 0, s[26:27]
	s_mov_b32 m0, s57
	s_nop 0
	global_load_lds_dwordx4 v[206:207], off
	s_barrier
	s_waitcnt lgkmcnt(0)
	v_mfma_f32_16x16x32_bf16 v[62:65], v[138:141], v[156:159], v[62:65]
	v_mfma_f32_16x16x32_bf16 v[58:61], v[148:151], v[156:159], v[58:61]
	v_mfma_f32_16x16x32_bf16 v[54:57], v[138:141], v[164:167], v[54:57]
	v_mfma_f32_16x16x32_bf16 v[46:49], v[148:151], v[164:167], v[46:49]
	v_mfma_f32_16x16x32_bf16 v[38:41], v[138:141], v[172:175], v[38:41]
	v_mfma_f32_16x16x32_bf16 v[30:33], v[148:151], v[172:175], v[30:33]
	v_mfma_f32_16x16x32_bf16 v[22:25], v[138:141], v[180:183], v[22:25]
	v_mfma_f32_16x16x32_bf16 v[14:17], v[148:151], v[180:183], v[14:17]
	v_mfma_f32_16x16x32_bf16 v[62:65], v[142:145], v[160:163], v[62:65]
	v_mfma_f32_16x16x32_bf16 v[58:61], v[152:155], v[160:163], v[58:61]
	v_mfma_f32_16x16x32_bf16 v[54:57], v[142:145], v[168:171], v[54:57]
	v_mfma_f32_16x16x32_bf16 v[46:49], v[152:155], v[168:171], v[46:49]
	v_mfma_f32_16x16x32_bf16 v[38:41], v[142:145], v[176:179], v[38:41]
	v_mfma_f32_16x16x32_bf16 v[30:33], v[152:155], v[176:179], v[30:33]
	v_mfma_f32_16x16x32_bf16 v[22:25], v[142:145], v[184:187], v[22:25]
	v_mfma_f32_16x16x32_bf16 v[14:17], v[152:155], v[184:187], v[14:17]
	s_barrier
	s_add_i32 s7, s7, s55
	v_lshl_add_u64 v[138:139], v[132:133], 0, s[28:29]
	s_mov_b32 m0, s7
	s_nop 0
	global_load_lds_dwordx4 v[138:139], off
	v_lshl_add_u64 v[138:139], v[132:133], 0, s[30:31]
	s_add_i32 m0, s7, 0x2000
	s_nop 0
	global_load_lds_dwordx4 v[138:139], off
	v_lshl_add_u64 v[230:231], v[204:205], 0, s[28:29]
	s_mov_b32 m0, s58
	s_nop 0
	global_load_lds_dwordx4 v[230:231], off
	v_lshl_add_u64 v[230:231], v[204:205], 0, s[30:31]
	s_mov_b32 m0, s59
	s_nop 0
	global_load_lds_dwordx4 v[230:231], off
	s_waitcnt vmcnt(8)
	s_barrier
	v_mfma_f32_16x16x32_bf16 v[50:53], v[188:191], v[156:159], v[50:53]
	v_mfma_f32_16x16x32_bf16 v[42:45], v[196:199], v[156:159], v[42:45]
	v_mfma_f32_16x16x32_bf16 v[34:37], v[188:191], v[164:167], v[34:37]
	v_mfma_f32_16x16x32_bf16 v[26:29], v[196:199], v[164:167], v[26:29]
	v_mfma_f32_16x16x32_bf16 v[18:21], v[188:191], v[172:175], v[18:21]
	v_mfma_f32_16x16x32_bf16 v[10:13], v[196:199], v[172:175], v[10:13]
	v_mfma_f32_16x16x32_bf16 v[6:9], v[188:191], v[180:183], v[6:9]
	v_mfma_f32_16x16x32_bf16 v[2:5], v[196:199], v[180:183], v[2:5]
	v_mfma_f32_16x16x32_bf16 v[50:53], v[192:195], v[160:163], v[50:53]
	v_mfma_f32_16x16x32_bf16 v[42:45], v[200:203], v[160:163], v[42:45]
	v_mfma_f32_16x16x32_bf16 v[34:37], v[192:195], v[168:171], v[34:37]
	v_mfma_f32_16x16x32_bf16 v[26:29], v[200:203], v[168:171], v[26:29]
	v_mfma_f32_16x16x32_bf16 v[18:21], v[192:195], v[176:179], v[18:21]
	v_mfma_f32_16x16x32_bf16 v[10:13], v[200:203], v[176:179], v[10:13]
	v_mfma_f32_16x16x32_bf16 v[6:9], v[192:195], v[184:187], v[6:9]
	v_mfma_f32_16x16x32_bf16 v[2:5], v[200:203], v[184:187], v[2:5]
	s_barrier
	s_add_i32 s7, 0, 0x18000
	v_add_u32_e32 v137, s7, v135
	ds_read_b128 v[138:141], v137
	ds_read_b128 v[142:145], v137 offset:1024
	ds_read_b128 v[148:151], v137 offset:2048
	ds_read_b128 v[152:155], v137 offset:3072
	ds_read_b128 v[156:159], v136 offset:32768
	ds_read_b128 v[160:163], v136 offset:33792
	ds_read_b128 v[164:167], v136 offset:34816
	ds_read_b128 v[168:171], v136 offset:35840
	ds_read_b128 v[172:175], v136 offset:36864
	ds_read_b128 v[176:179], v136 offset:37888
	ds_read_b128 v[180:183], v136 offset:38912
	ds_read_b128 v[184:187], v136 offset:39936
	s_waitcnt lgkmcnt(8)
	s_barrier
	s_waitcnt lgkmcnt(0)
	v_mfma_f32_16x16x32_bf16 v[126:129], v[138:141], v[156:159], v[126:129]
	v_mfma_f32_16x16x32_bf16 v[122:125], v[148:151], v[156:159], v[122:125]
	v_mfma_f32_16x16x32_bf16 v[118:121], v[138:141], v[164:167], v[118:121]
	v_mfma_f32_16x16x32_bf16 v[110:113], v[148:151], v[164:167], v[110:113]
	v_mfma_f32_16x16x32_bf16 v[102:105], v[138:141], v[172:175], v[102:105]
	v_mfma_f32_16x16x32_bf16 v[94:97], v[148:151], v[172:175], v[94:97]
	v_mfma_f32_16x16x32_bf16 v[86:89], v[138:141], v[180:183], v[86:89]
	v_mfma_f32_16x16x32_bf16 v[78:81], v[148:151], v[180:183], v[78:81]
	v_mfma_f32_16x16x32_bf16 v[126:129], v[142:145], v[160:163], v[126:129]
	v_mfma_f32_16x16x32_bf16 v[122:125], v[152:155], v[160:163], v[122:125]
	v_mfma_f32_16x16x32_bf16 v[118:121], v[142:145], v[168:171], v[118:121]
	v_mfma_f32_16x16x32_bf16 v[110:113], v[152:155], v[168:171], v[110:113]
	v_mfma_f32_16x16x32_bf16 v[102:105], v[142:145], v[176:179], v[102:105]
	v_mfma_f32_16x16x32_bf16 v[94:97], v[152:155], v[176:179], v[94:97]
	v_mfma_f32_16x16x32_bf16 v[86:89], v[142:145], v[184:187], v[86:89]
	v_mfma_f32_16x16x32_bf16 v[78:81], v[152:155], v[184:187], v[78:81]
	s_barrier
	s_add_i32 s78, 0, 0x1c000
	s_add_i32 s7, s7, s55
	v_add_u32_e32 v137, s78, v135
	v_lshl_add_u64 v[206:207], v[132:133], 0, s[34:35]
	s_mov_b32 m0, s7
	ds_read_b128 v[188:191], v137
	ds_read_b128 v[192:195], v137 offset:1024
	ds_read_b128 v[196:199], v137 offset:2048
	ds_read_b128 v[200:203], v137 offset:3072
	global_load_lds_dwordx4 v[206:207], off
	v_lshl_add_u64 v[206:207], v[132:133], 0, s[36:37]
	s_add_i32 m0, s7, 0x2000
	s_nop 0
	global_load_lds_dwordx4 v[206:207], off
	s_barrier
	s_waitcnt lgkmcnt(0)
	v_mfma_f32_16x16x32_bf16 v[114:117], v[188:191], v[156:159], v[114:117]
	v_mfma_f32_16x16x32_bf16 v[106:109], v[196:199], v[156:159], v[106:109]
	v_mfma_f32_16x16x32_bf16 v[98:101], v[188:191], v[164:167], v[98:101]
	v_mfma_f32_16x16x32_bf16 v[90:93], v[196:199], v[164:167], v[90:93]
	v_mfma_f32_16x16x32_bf16 v[82:85], v[188:191], v[172:175], v[82:85]
	v_mfma_f32_16x16x32_bf16 v[74:77], v[196:199], v[172:175], v[74:77]
	v_mfma_f32_16x16x32_bf16 v[70:73], v[188:191], v[180:183], v[70:73]
	v_mfma_f32_16x16x32_bf16 v[66:69], v[196:199], v[180:183], v[66:69]
	v_mfma_f32_16x16x32_bf16 v[114:117], v[192:195], v[160:163], v[114:117]
	v_mfma_f32_16x16x32_bf16 v[106:109], v[200:203], v[160:163], v[106:109]
	v_mfma_f32_16x16x32_bf16 v[98:101], v[192:195], v[168:171], v[98:101]
	v_mfma_f32_16x16x32_bf16 v[90:93], v[200:203], v[168:171], v[90:93]
	v_mfma_f32_16x16x32_bf16 v[82:85], v[192:195], v[176:179], v[82:85]
	v_mfma_f32_16x16x32_bf16 v[74:77], v[200:203], v[176:179], v[74:77]
	v_mfma_f32_16x16x32_bf16 v[70:73], v[192:195], v[184:187], v[70:73]
	v_mfma_f32_16x16x32_bf16 v[66:69], v[200:203], v[184:187], v[66:69]
	s_barrier
	s_mov_b32 m0, s84
	v_lshl_add_u64 v[206:207], v[204:205], 0, s[34:35]
	ds_read_b128 v[156:159], v136 offset:49152
	ds_read_b128 v[160:163], v136 offset:50176
	ds_read_b128 v[164:167], v136 offset:51200
	ds_read_b128 v[168:171], v136 offset:52224
	ds_read_b128 v[172:175], v136 offset:53248
	ds_read_b128 v[176:179], v136 offset:54272
	ds_read_b128 v[180:183], v136 offset:55296
	ds_read_b128 v[184:187], v136 offset:56320
	global_load_lds_dwordx4 v[206:207], off
	v_lshl_add_u64 v[204:205], v[204:205], 0, s[36:37]
	s_mov_b32 m0, s85
	s_nop 0
	global_load_lds_dwordx4 v[204:205], off
	s_barrier
	s_waitcnt lgkmcnt(0)
	v_mfma_f32_16x16x32_bf16 v[62:65], v[138:141], v[156:159], v[62:65]
	v_mfma_f32_16x16x32_bf16 v[58:61], v[148:151], v[156:159], v[58:61]
	v_mfma_f32_16x16x32_bf16 v[54:57], v[138:141], v[164:167], v[54:57]
	v_mfma_f32_16x16x32_bf16 v[46:49], v[148:151], v[164:167], v[46:49]
	v_mfma_f32_16x16x32_bf16 v[38:41], v[138:141], v[172:175], v[38:41]
	v_mfma_f32_16x16x32_bf16 v[30:33], v[148:151], v[172:175], v[30:33]
	v_mfma_f32_16x16x32_bf16 v[22:25], v[138:141], v[180:183], v[22:25]
	v_mfma_f32_16x16x32_bf16 v[14:17], v[148:151], v[180:183], v[14:17]
	v_mfma_f32_16x16x32_bf16 v[62:65], v[142:145], v[160:163], v[62:65]
	v_mfma_f32_16x16x32_bf16 v[58:61], v[152:155], v[160:163], v[58:61]
	v_mfma_f32_16x16x32_bf16 v[54:57], v[142:145], v[168:171], v[54:57]
	v_mfma_f32_16x16x32_bf16 v[46:49], v[152:155], v[168:171], v[46:49]
	v_mfma_f32_16x16x32_bf16 v[38:41], v[142:145], v[176:179], v[38:41]
	v_mfma_f32_16x16x32_bf16 v[30:33], v[152:155], v[176:179], v[30:33]
	v_mfma_f32_16x16x32_bf16 v[22:25], v[142:145], v[184:187], v[22:25]
	v_mfma_f32_16x16x32_bf16 v[14:17], v[152:155], v[184:187], v[14:17]
	s_barrier
	s_add_i32 s7, s78, s55
	v_lshl_add_u64 v[138:139], v[132:133], 0, s[18:19]
	s_mov_b32 m0, s7
	v_lshl_add_u64 v[132:133], v[132:133], 0, s[14:15]
	global_load_lds_dwordx4 v[138:139], off
	s_add_i32 m0, s7, 0x2000
	s_nop 0
	global_load_lds_dwordx4 v[132:133], off
	s_waitcnt vmcnt(6)
	s_add_i32 s6, s6, 2
	s_add_u32 s8, s8, 0x100
	s_addc_u32 s9, s9, 0
	s_add_u32 s48, s48, 0x100
	s_addc_u32 s49, s49, 0
	s_cmpk_gt_u32 s6, 0x55
	s_cbranch_scc0 .LBB0_679
	s_barrier
	v_mfma_f32_16x16x32_bf16 v[50:53], v[188:191], v[156:159], v[50:53]
	v_mfma_f32_16x16x32_bf16 v[42:45], v[196:199], v[156:159], v[42:45]
	v_mfma_f32_16x16x32_bf16 v[34:37], v[188:191], v[164:167], v[34:37]
	v_mfma_f32_16x16x32_bf16 v[26:29], v[196:199], v[164:167], v[26:29]
	v_mfma_f32_16x16x32_bf16 v[18:21], v[188:191], v[172:175], v[18:21]
	v_mfma_f32_16x16x32_bf16 v[10:13], v[196:199], v[172:175], v[10:13]
	v_mfma_f32_16x16x32_bf16 v[6:9], v[188:191], v[180:183], v[6:9]
	v_mfma_f32_16x16x32_bf16 v[2:5], v[196:199], v[180:183], v[2:5]
	v_mfma_f32_16x16x32_bf16 v[50:53], v[192:195], v[160:163], v[50:53]
	v_mfma_f32_16x16x32_bf16 v[42:45], v[200:203], v[160:163], v[42:45]
	v_mfma_f32_16x16x32_bf16 v[34:37], v[192:195], v[168:171], v[34:37]
	v_mfma_f32_16x16x32_bf16 v[26:29], v[200:203], v[168:171], v[26:29]
	v_mfma_f32_16x16x32_bf16 v[18:21], v[192:195], v[176:179], v[18:21]
	v_mfma_f32_16x16x32_bf16 v[10:13], v[200:203], v[176:179], v[10:13]
	v_mfma_f32_16x16x32_bf16 v[6:9], v[192:195], v[184:187], v[6:9]
	v_mfma_f32_16x16x32_bf16 v[2:5], v[200:203], v[184:187], v[2:5]
	s_barrier
	v_mov_b32_e32 v137, v134
	s_lshl_b32 s6, s88, 8
	v_ashrrev_i32_e32 v132, 2, v137
	s_or_b32 s6, s6, s63
	v_and_b32_e32 v132, -4, v132
	v_add_u32_e32 v132, s6, v132
	s_lshl_b32 s6, s87, 8
	s_add_i32 s6, s6, s62
	v_and_or_b32 v188, v137, 15, s6
	v_ashrrev_i32_e32 v189, 31, v188
	v_ashrrev_i32_e32 v133, 31, v132
	v_lshlrev_b64 v[206:207], 13, v[188:189]
	v_or_b32_e32 v156, 16, v188
	v_or_b32_e32 v172, 32, v188
	v_or_b32_e32 v188, 48, v188
	v_lshlrev_b64 v[132:133], 2, v[132:133]
	v_ashrrev_i32_e32 v157, 31, v156
	v_ashrrev_i32_e32 v173, 31, v172
	v_ashrrev_i32_e32 v189, 31, v188
	v_lshl_add_u64 v[204:205], s[40:41], 0, v[132:133]
	v_lshlrev_b64 v[208:209], 13, v[156:157]
	v_lshlrev_b64 v[210:211], 13, v[172:173]
	v_lshlrev_b64 v[212:213], 13, v[188:189]
	v_lshl_add_u64 v[152:153], v[204:205], 0, v[206:207]
	v_lshl_add_u64 v[168:169], v[204:205], 0, v[208:209]
	v_lshl_add_u64 v[184:185], v[204:205], 0, v[210:211]
	v_lshl_add_u64 v[200:201], v[204:205], 0, v[212:213]
	global_load_dwordx4 v[138:141], v[152:153], off
	global_load_dwordx4 v[142:145], v[152:153], off offset:64
	global_load_dwordx4 v[148:151], v[152:153], off offset:512
	s_nop 0
	global_load_dwordx4 v[152:155], v[152:153], off offset:576
	s_nop 0
	global_load_dwordx4 v[156:159], v[168:169], off
	global_load_dwordx4 v[160:163], v[168:169], off offset:64
	global_load_dwordx4 v[164:167], v[168:169], off offset:512
	s_nop 0
	global_load_dwordx4 v[168:171], v[168:169], off offset:576
	s_nop 0
	global_load_dwordx4 v[172:175], v[184:185], off
	global_load_dwordx4 v[176:179], v[184:185], off offset:64
	global_load_dwordx4 v[180:183], v[184:185], off offset:512
	s_nop 0
	global_load_dwordx4 v[184:187], v[184:185], off offset:576
	s_nop 0
	global_load_dwordx4 v[188:191], v[200:201], off
	global_load_dwordx4 v[192:195], v[200:201], off offset:64
	global_load_dwordx4 v[196:199], v[200:201], off offset:512
	s_nop 0
	global_load_dwordx4 v[200:203], v[200:201], off offset:576
	s_waitcnt vmcnt(0)
	v_pk_fma_f32 v[126:127], v[126:127], 0.5, v[138:139] op_sel_hi:[1,0,1]
	v_lshl_add_u64 v[138:139], s[4:5], 0, v[206:207]
	v_lshl_add_u64 v[138:139], v[138:139], 0, v[132:133]
	v_pk_fma_f32 v[116:117], v[116:117], 0.5, v[150:151] op_sel_hi:[1,0,1]
	v_pk_fma_f32 v[114:115], v[114:115], 0.5, v[148:149] op_sel_hi:[1,0,1]
	global_store_dwordx4 v[138:139], v[114:117], off offset:512
	v_pk_fma_f32 v[100:101], v[100:101], 0.5, v[166:167] op_sel_hi:[1,0,1]
	v_pk_fma_f32 v[98:99], v[98:99], 0.5, v[164:165] op_sel_hi:[1,0,1]
	v_lshl_add_u64 v[114:115], s[4:5], 0, v[208:209]
	v_lshl_add_u64 v[114:115], v[114:115], 0, v[132:133]
	global_store_dwordx4 v[114:115], v[98:101], off offset:512
	v_pk_fma_f32 v[84:85], v[84:85], 0.5, v[182:183] op_sel_hi:[1,0,1]
	v_pk_fma_f32 v[82:83], v[82:83], 0.5, v[180:181] op_sel_hi:[1,0,1]
	v_lshl_add_u64 v[98:99], s[4:5], 0, v[210:211]
	v_lshl_add_u64 v[98:99], v[98:99], 0, v[132:133]
	v_pk_fma_f32 v[108:109], v[108:109], 0.5, v[154:155] op_sel_hi:[1,0,1]
	v_pk_fma_f32 v[106:107], v[106:107], 0.5, v[152:153] op_sel_hi:[1,0,1]
	v_pk_fma_f32 v[92:93], v[92:93], 0.5, v[170:171] op_sel_hi:[1,0,1]
	v_pk_fma_f32 v[90:91], v[90:91], 0.5, v[168:169] op_sel_hi:[1,0,1]
	global_store_dwordx4 v[98:99], v[82:85], off offset:512
	v_pk_fma_f32 v[76:77], v[76:77], 0.5, v[186:187] op_sel_hi:[1,0,1]
	v_pk_fma_f32 v[74:75], v[74:75], 0.5, v[184:185] op_sel_hi:[1,0,1]
	v_lshl_add_u64 v[82:83], s[4:5], 0, v[212:213]
	global_store_dwordx4 v[138:139], v[106:109], off offset:576
	global_store_dwordx4 v[114:115], v[90:93], off offset:576
	global_store_dwordx4 v[98:99], v[74:77], off offset:576
	v_pk_fma_f32 v[108:109], v[120:121], 0.5, v[158:159] op_sel_hi:[1,0,1]
	v_pk_fma_f32 v[106:107], v[118:119], 0.5, v[156:157] op_sel_hi:[1,0,1]
	v_pk_fma_f32 v[92:93], v[104:105], 0.5, v[174:175] op_sel_hi:[1,0,1]
	v_pk_fma_f32 v[90:91], v[102:103], 0.5, v[172:173] op_sel_hi:[1,0,1]
	v_pk_fma_f32 v[76:77], v[88:89], 0.5, v[190:191] op_sel_hi:[1,0,1]
	v_pk_fma_f32 v[74:75], v[86:87], 0.5, v[188:189] op_sel_hi:[1,0,1]
	v_lshl_add_u64 v[82:83], v[82:83], 0, v[132:133]
	v_pk_fma_f32 v[128:129], v[128:129], 0.5, v[140:141] op_sel_hi:[1,0,1]
	v_pk_fma_f32 v[124:125], v[124:125], 0.5, v[144:145] op_sel_hi:[1,0,1]
	v_pk_fma_f32 v[122:123], v[122:123], 0.5, v[142:143] op_sel_hi:[1,0,1]
	global_store_dwordx4 v[114:115], v[106:109], off
	global_store_dwordx4 v[98:99], v[90:93], off
	global_store_dwordx4 v[82:83], v[74:77], off
	v_pk_fma_f32 v[108:109], v[112:113], 0.5, v[162:163] op_sel_hi:[1,0,1]
	v_pk_fma_f32 v[106:107], v[110:111], 0.5, v[160:161] op_sel_hi:[1,0,1]
	v_pk_fma_f32 v[92:93], v[96:97], 0.5, v[178:179] op_sel_hi:[1,0,1]
	v_pk_fma_f32 v[90:91], v[94:95], 0.5, v[176:177] op_sel_hi:[1,0,1]
	v_pk_fma_f32 v[76:77], v[80:81], 0.5, v[194:195] op_sel_hi:[1,0,1]
	v_pk_fma_f32 v[74:75], v[78:79], 0.5, v[192:193] op_sel_hi:[1,0,1]
	v_pk_fma_f32 v[72:73], v[72:73], 0.5, v[198:199] op_sel_hi:[1,0,1]
	v_pk_fma_f32 v[70:71], v[70:71], 0.5, v[196:197] op_sel_hi:[1,0,1]
	v_pk_fma_f32 v[68:69], v[68:69], 0.5, v[202:203] op_sel_hi:[1,0,1]
	v_pk_fma_f32 v[66:67], v[66:67], 0.5, v[200:201] op_sel_hi:[1,0,1]
	global_store_dwordx4 v[138:139], v[126:129], off
	global_store_dwordx4 v[138:139], v[122:125], off offset:64
	global_store_dwordx4 v[114:115], v[106:109], off offset:64
	global_store_dwordx4 v[98:99], v[90:93], off offset:64
	global_store_dwordx4 v[82:83], v[74:77], off offset:64
	global_store_dwordx4 v[82:83], v[70:73], off offset:512
	global_store_dwordx4 v[82:83], v[66:69], off offset:576
	s_mov_b64 s[6:7], 0x120000
	v_lshl_add_u64 v[140:141], v[206:207], 0, s[6:7]
	s_mov_b64 s[6:7], 0x140000
	v_lshl_add_u64 v[138:139], v[206:207], 0, s[0:1]
	v_lshl_add_u64 v[142:143], v[206:207], 0, s[6:7]
	v_lshl_add_u64 v[144:145], v[206:207], 0, s[28:29]
	v_lshl_add_u64 v[78:79], v[204:205], 0, v[138:139]
	v_lshl_add_u64 v[94:95], v[204:205], 0, v[140:141]
	v_lshl_add_u64 v[110:111], v[204:205], 0, v[142:143]
	v_lshl_add_u64 v[126:127], v[204:205], 0, v[144:145]
	global_load_dwordx4 v[66:69], v[78:79], off
	global_load_dwordx4 v[70:73], v[78:79], off offset:64
	global_load_dwordx4 v[74:77], v[78:79], off offset:512
	s_nop 0
	global_load_dwordx4 v[78:81], v[78:79], off offset:576
	s_nop 0
	global_load_dwordx4 v[82:85], v[94:95], off
	global_load_dwordx4 v[86:89], v[94:95], off offset:64
	global_load_dwordx4 v[90:93], v[94:95], off offset:512
	s_nop 0
	global_load_dwordx4 v[94:97], v[94:95], off offset:576
	s_nop 0
	global_load_dwordx4 v[98:101], v[110:111], off
	global_load_dwordx4 v[102:105], v[110:111], off offset:64
	global_load_dwordx4 v[106:109], v[110:111], off offset:512
	s_nop 0
	global_load_dwordx4 v[110:113], v[110:111], off offset:576
	s_nop 0
	global_load_dwordx4 v[114:117], v[126:127], off
	global_load_dwordx4 v[118:121], v[126:127], off offset:64
	global_load_dwordx4 v[122:125], v[126:127], off offset:512
	s_nop 0
	global_load_dwordx4 v[126:129], v[126:127], off offset:576
	s_waitcnt vmcnt(0)
	v_pk_fma_f32 v[62:63], v[62:63], 0.5, v[66:67] op_sel_hi:[1,0,1]
	v_lshl_add_u64 v[66:67], s[4:5], 0, v[138:139]
	v_lshl_add_u64 v[66:67], v[66:67], 0, v[132:133]
	v_pk_fma_f32 v[52:53], v[52:53], 0.5, v[76:77] op_sel_hi:[1,0,1]
	v_pk_fma_f32 v[50:51], v[50:51], 0.5, v[74:75] op_sel_hi:[1,0,1]
	global_store_dwordx4 v[66:67], v[50:53], off offset:512
	v_pk_fma_f32 v[36:37], v[36:37], 0.5, v[92:93] op_sel_hi:[1,0,1]
	v_pk_fma_f32 v[34:35], v[34:35], 0.5, v[90:91] op_sel_hi:[1,0,1]
	v_lshl_add_u64 v[50:51], s[4:5], 0, v[140:141]
	v_lshl_add_u64 v[50:51], v[50:51], 0, v[132:133]
	global_store_dwordx4 v[50:51], v[34:37], off offset:512
	v_pk_fma_f32 v[20:21], v[20:21], 0.5, v[108:109] op_sel_hi:[1,0,1]
	v_pk_fma_f32 v[18:19], v[18:19], 0.5, v[106:107] op_sel_hi:[1,0,1]
	v_lshl_add_u64 v[34:35], s[4:5], 0, v[142:143]
	v_lshl_add_u64 v[34:35], v[34:35], 0, v[132:133]
	v_pk_fma_f32 v[44:45], v[44:45], 0.5, v[80:81] op_sel_hi:[1,0,1]
	v_pk_fma_f32 v[42:43], v[42:43], 0.5, v[78:79] op_sel_hi:[1,0,1]
	v_pk_fma_f32 v[28:29], v[28:29], 0.5, v[96:97] op_sel_hi:[1,0,1]
	v_pk_fma_f32 v[26:27], v[26:27], 0.5, v[94:95] op_sel_hi:[1,0,1]
	global_store_dwordx4 v[34:35], v[18:21], off offset:512
	v_pk_fma_f32 v[12:13], v[12:13], 0.5, v[112:113] op_sel_hi:[1,0,1]
	v_pk_fma_f32 v[10:11], v[10:11], 0.5, v[110:111] op_sel_hi:[1,0,1]
	v_lshl_add_u64 v[18:19], s[4:5], 0, v[144:145]
	global_store_dwordx4 v[66:67], v[42:45], off offset:576
	global_store_dwordx4 v[50:51], v[26:29], off offset:576
	global_store_dwordx4 v[34:35], v[10:13], off offset:576
	v_pk_fma_f32 v[44:45], v[56:57], 0.5, v[84:85] op_sel_hi:[1,0,1]
	v_pk_fma_f32 v[42:43], v[54:55], 0.5, v[82:83] op_sel_hi:[1,0,1]
	v_pk_fma_f32 v[28:29], v[40:41], 0.5, v[100:101] op_sel_hi:[1,0,1]
	v_pk_fma_f32 v[26:27], v[38:39], 0.5, v[98:99] op_sel_hi:[1,0,1]
	v_pk_fma_f32 v[12:13], v[24:25], 0.5, v[116:117] op_sel_hi:[1,0,1]
	v_pk_fma_f32 v[10:11], v[22:23], 0.5, v[114:115] op_sel_hi:[1,0,1]
	v_lshl_add_u64 v[18:19], v[18:19], 0, v[132:133]
	v_pk_fma_f32 v[64:65], v[64:65], 0.5, v[68:69] op_sel_hi:[1,0,1]
	v_pk_fma_f32 v[60:61], v[60:61], 0.5, v[72:73] op_sel_hi:[1,0,1]
	v_pk_fma_f32 v[58:59], v[58:59], 0.5, v[70:71] op_sel_hi:[1,0,1]
	global_store_dwordx4 v[50:51], v[42:45], off
	global_store_dwordx4 v[34:35], v[26:29], off
	global_store_dwordx4 v[18:19], v[10:13], off
	v_pk_fma_f32 v[44:45], v[48:49], 0.5, v[88:89] op_sel_hi:[1,0,1]
	v_pk_fma_f32 v[42:43], v[46:47], 0.5, v[86:87] op_sel_hi:[1,0,1]
	v_pk_fma_f32 v[28:29], v[32:33], 0.5, v[104:105] op_sel_hi:[1,0,1]
	v_pk_fma_f32 v[26:27], v[30:31], 0.5, v[102:103] op_sel_hi:[1,0,1]
	v_pk_fma_f32 v[12:13], v[16:17], 0.5, v[120:121] op_sel_hi:[1,0,1]
	v_pk_fma_f32 v[10:11], v[14:15], 0.5, v[118:119] op_sel_hi:[1,0,1]
	v_pk_fma_f32 v[8:9], v[8:9], 0.5, v[124:125] op_sel_hi:[1,0,1]
	v_pk_fma_f32 v[6:7], v[6:7], 0.5, v[122:123] op_sel_hi:[1,0,1]
	v_pk_fma_f32 v[4:5], v[4:5], 0.5, v[128:129] op_sel_hi:[1,0,1]
	v_pk_fma_f32 v[2:3], v[2:3], 0.5, v[126:127] op_sel_hi:[1,0,1]
	global_store_dwordx4 v[66:67], v[62:65], off
	global_store_dwordx4 v[66:67], v[58:61], off offset:64
	global_store_dwordx4 v[50:51], v[42:45], off offset:64
	global_store_dwordx4 v[34:35], v[26:29], off offset:64
	global_store_dwordx4 v[18:19], v[10:13], off offset:64
	global_store_dwordx4 v[18:19], v[6:9], off offset:512
	global_store_dwordx4 v[18:19], v[2:5], off offset:576
	s_and_b64 vcc, exec, s[42:43]
	s_mov_b32 s87, s10
	s_mov_b32 s88, s11
	s_mov_b64 s[8:9], s[46:47]
	s_mov_b64 s[6:7], s[44:45]
	s_movk_i32 s92, 0x4000
	s_movk_i32 s93, 0xf800
	s_movk_i32 s91, 0x60
	s_mov_b32 s78, 0x2a000000
	s_mov_b32 s79, 0x3fffe
	s_mov_b32 s90, 0xc0000
	s_cbranch_vccz .LBB0_672
	s_waitcnt vmcnt(0)
	s_cmpk_gt_u32 s50, 0xff
	s_cbranch_scc1 .LBB0_683
	s_barrier
.LBB0_683:
	s_setprio 0
	v_readlane_b32 s0, v255, 8
	s_mov_b64 s[58:59], s[94:95]
	v_readlane_b32 s62, v255, 10
	v_readlane_b32 s84, v255, 12
	v_readlane_b32 s86, v255, 14
	v_readlane_b32 s56, v255, 16
	v_readlane_b32 s52, v255, 18
	v_readlane_b32 s54, v255, 22
	v_readlane_b32 s94, v255, 24
	v_readlane_b32 s44, v255, 26
	v_readlane_b32 s72, v255, 7
	v_readlane_b32 s1, v255, 9
	v_readlane_b32 s63, v255, 11
	v_readlane_b32 s85, v255, 13
	v_readlane_b32 s87, v255, 15
	v_readlane_b32 s57, v255, 17
	v_readlane_b32 s53, v255, 19
	v_readlane_b32 s55, v255, 23
	v_readlane_b32 s95, v255, 25
	v_readlane_b32 s45, v255, 27
	s_mov_b32 s88, 0x16000
	s_barrier

.LBB0_685:
	s_andn2_b64 vcc, exec, s[4:5]
	s_cbranch_vccnz .LBB0_702
	s_cmp_gt_i32 s58, 0
	s_mov_b64 s[4:5], -1
	s_cbranch_scc0 .LBB0_700
	s_mov_b32 s4, -1
	v_readlane_b32 s40, v255, 3
	v_mbcnt_lo_u32_b32 v0, s4, 0
	v_mbcnt_hi_u32_b32 v6, s4, v0
	v_readlane_b32 s4, v254, 4
	s_mov_b32 s11, s72
	v_readlane_b32 s41, v255, 4
	v_add_u32_e32 v0, s4, v6
	v_readlane_b32 s42, v255, 5
	v_readlane_b32 s43, v255, 6
	s_mov_b64 s[4:5], s[42:43]
	s_mov_b64 s[6:7], s[40:41]
	s_cmpk_gt_i32 s11, 0xaff
	v_readfirstlane_b32 s22, v0
	s_cbranch_scc1 .LBB0_699
	v_bfe_i32 v3, v0, 27, 1
	v_lshlrev_b32_e32 v2, 4, v0
	v_lshrrev_b32_e32 v3, 22, v3
	v_add_u32_e32 v3, v2, v3
	v_and_b32_e32 v3, 0xfffffc00, v3
	s_add_u32 s50, s4, 0x4600000
	v_sub_u32_e32 v2, v2, v3
	s_addc_u32 s51, s5, 0
	v_lshrrev_b32_e32 v3, 4, v2
	v_ashrrev_i32_e32 v4, 31, v0
	s_add_u32 s52, s4, 0x8600000
	v_bitop3_b32 v2, v3, v2, 32 bitop3:0x6c
	v_lshrrev_b32_e32 v4, 26, v4
	s_addc_u32 s53, s5, 0
	v_ashrrev_i32_e32 v3, 31, v2
	v_add_u32_e32 v0, v0, v4
	s_ashr_i32 s6, s11, 31
	v_lshrrev_b32_e32 v3, 26, v3
	v_ashrrev_i32_e32 v8, 6, v0
	s_lshr_b32 s6, s6, 29
	v_add_u32_e32 v3, v2, v3
	v_lshlrev_b32_e32 v0, 3, v8
	s_add_i32 s6, s11, s6
	s_ashr_i32 s40, s22, 6
	v_ashrrev_i32_e32 v7, 6, v3
	v_and_b32_e32 v0, -16, v0
	s_ashr_i32 s7, s6, 3
	s_and_b32 s6, s6, -8
	s_ashr_i32 s41, s22, 8
	s_lshl_b32 s54, s40, 10
	v_add_u32_e32 v4, v7, v0
	v_and_b32_e32 v0, 3, v7
	s_mov_b32 s0, 0xfffe0
	s_sub_i32 s6, s11, s6
	v_and_or_b32 v0, v4, s0, v0
	s_cmp_lt_i32 s6, 0
	s_movk_i32 s0, 0x161
	s_cselect_b32 s8, s0, 0x160
	s_mul_i32 s6, s8, s6
	s_add_i32 s6, s6, s7
	s_mul_hi_i32 s7, s6, 0x2e8ba2e9
	s_lshr_b32 s8, s7, 31
	s_ashr_i32 s7, s7, 6
	s_add_i32 s7, s7, s8
	s_lshl_b32 s8, s7, 3
	s_mulk_i32 s7, 0x160
	s_sub_i32 s6, s6, s7
	s_bfe_u32 s7, s6, 0x3001c
	s_add_i32 s7, s6, s7
	s_sext_i32_i16 s9, s7
	s_and_b32 s7, s7, 0xfff8
	s_sub_i32 s6, s6, s7
	s_sext_i32_i16 s6, s6
	s_add_i32 s48, s8, s6
	s_ashr_i32 s49, s48, 31
	v_lshrrev_b32_e32 v5, 2, v4
	v_lshlrev_b32_e32 v9, 1, v4
	v_and_b32_e32 v3, 0xc0, v3
	s_lshr_b32 s10, s9, 3
	s_lshl_b64 s[6:7], s[48:49], 20
	v_and_b32_e32 v5, 4, v5
	v_and_b32_e32 v9, 24, v9
	v_sub_u32_e32 v2, v2, v3
	v_mov_b32_e32 v3, 1
	s_add_u32 s6, s50, s6
	v_or3_b32 v0, v0, v5, v9
	v_lshlrev_b32_e32 v5, 5, v8
	v_ashrrev_i16_sdwa v2, v3, sext(v2) dst_sel:DWORD dst_unused:UNUSED_PAD src0_sel:DWORD src1_sel:BYTE_0
	s_addc_u32 s7, s51, s7
	s_bfe_i64 s[8:9], s[10:11], 0x100000
	v_and_b32_e32 v5, 32, v5
	v_bfe_i32 v9, v2, 0, 16
	s_lshl_b64 s[8:9], s[8:9], 20
	v_add_lshl_u32 v2, v5, v9, 1
	s_add_u32 s8, s52, s8
	v_lshl_add_u32 v0, v0, 12, v2
	s_addc_u32 s9, s53, s9
	s_add_i32 s49, s54, 0
	v_lshl_add_u32 v130, v4, 12, v2
	v_lshl_add_u64 v[2:3], s[8:9], 0, v[0:1]
	s_add_i32 m0, s49, 0x10000
	v_lshl_add_u64 v[4:5], v[2:3], 0, s[60:61]
	global_load_lds_dwordx4 v0, s[8:9]
	s_add_i32 m0, s49, 0x12000
	v_mov_b32_e32 v131, v1
	global_load_lds_dwordx4 v[4:5], off
	v_lshl_add_u64 v[4:5], s[6:7], 0, v[130:131]
	s_mov_b32 m0, s49
	s_add_i32 s55, s49, 0x2000
	global_load_lds_dwordx4 v130, s[6:7]
	v_lshl_add_u64 v[10:11], v[4:5], 0, s[60:61]
	s_mov_b32 m0, s55
	s_add_i32 s56, s49, 0x4000
	global_load_lds_dwordx4 v[10:11], off
	v_lshl_add_u64 v[10:11], v[2:3], 0, s[20:21]
	s_add_i32 m0, s49, 0x14000
	s_add_i32 s57, s49, 0x6000
	global_load_lds_dwordx4 v[10:11], off
	v_lshl_add_u64 v[10:11], v[2:3], 0, s[64:65]
	s_add_i32 m0, s49, 0x16000
	s_mov_b64 s[92:93], s[58:59]
	global_load_lds_dwordx4 v[10:11], off
	v_lshl_add_u64 v[10:11], v[4:5], 0, s[20:21]
	s_mov_b32 m0, s56
	s_cmp_lg_u32 s41, 1
	global_load_lds_dwordx4 v[10:11], off
	v_lshl_add_u64 v[10:11], v[4:5], 0, s[64:65]
	s_mov_b32 m0, s57
	s_nop 0
	global_load_lds_dwordx4 v[10:11], off
	s_cbranch_scc1 .LBB0_690
	s_setprio 1
	s_barrier

.Lrot_enter_0:
	s_add_u32 s8, s6, 0x100
	s_addc_u32 s9, s7, 0
	s_add_i32 s78, 0, 0x10000
	v_add_u32_e32 v134, s78, v137
	ds_read_b128 v[140:143], v134
	ds_read_b128 v[148:151], v134 offset:1024
	ds_read_b128 v[152:155], v134 offset:2048
	ds_read_b128 v[156:159], v134 offset:3072
	s_cmp_eq_u32 s87, 28
	s_cselect_b32 s89, s45, s9
	s_cselect_b32 s88, s44, s8
	s_cselect_b32 s91, s47, s86
	s_cselect_b32 s90, s46, s41
	v_lshl_add_u64 v[134:135], s[6:7], 0, v[132:133]
	v_lshl_add_u64 v[144:145], v[134:135], 0, s[16:17]
	s_add_i32 m0, s49, 0xc000
	ds_read_b128 v[160:163], v138
	ds_read_b128 v[164:167], v138 offset:1024
	ds_read_b128 v[168:171], v138 offset:2048
	ds_read_b128 v[172:175], v138 offset:3072
	ds_read_b128 v[176:179], v138 offset:4096
	ds_read_b128 v[180:183], v138 offset:5120
	ds_read_b128 v[184:187], v138 offset:6144
	ds_read_b128 v[188:191], v138 offset:7168
	global_load_lds_dwordx4 v[144:145], off
	v_lshl_add_u64 v[134:135], v[134:135], 0, s[80:81]
	s_add_i32 m0, s49, 0xe000
	s_nop 0
	global_load_lds_dwordx4 v[134:135], off
	s_waitcnt lgkmcnt(8)
	s_barrier
	s_waitcnt lgkmcnt(0)
	v_mfma_f32_16x16x32_bf16 v[126:129], v[140:143], v[160:163], v[126:129]
	v_mfma_f32_16x16x32_bf16 v[122:125], v[152:155], v[160:163], v[122:125]
	v_mfma_f32_16x16x32_bf16 v[110:113], v[140:143], v[168:171], v[110:113]
	v_mfma_f32_16x16x32_bf16 v[106:109], v[152:155], v[168:171], v[106:109]
	v_mfma_f32_16x16x32_bf16 v[94:97], v[140:143], v[176:179], v[94:97]
	v_mfma_f32_16x16x32_bf16 v[90:93], v[152:155], v[176:179], v[90:93]
	v_mfma_f32_16x16x32_bf16 v[78:81], v[140:143], v[184:187], v[78:81]
	v_mfma_f32_16x16x32_bf16 v[74:77], v[152:155], v[184:187], v[74:77]
	v_mfma_f32_16x16x32_bf16 v[126:129], v[148:151], v[164:167], v[126:129]
	v_mfma_f32_16x16x32_bf16 v[122:125], v[156:159], v[164:167], v[122:125]
	v_mfma_f32_16x16x32_bf16 v[110:113], v[148:151], v[172:175], v[110:113]
	v_mfma_f32_16x16x32_bf16 v[106:109], v[156:159], v[172:175], v[106:109]
	v_mfma_f32_16x16x32_bf16 v[94:97], v[148:151], v[180:183], v[94:97]
	v_mfma_f32_16x16x32_bf16 v[90:93], v[156:159], v[180:183], v[90:93]
	v_mfma_f32_16x16x32_bf16 v[78:81], v[148:151], v[188:191], v[78:81]
	v_mfma_f32_16x16x32_bf16 v[74:77], v[156:159], v[188:191], v[74:77]
	s_barrier
	s_add_i32 s6, 0, 0x14000
	v_add_u32_e32 v134, s6, v137
	s_add_i32 s7, s78, s54
	ds_read_b128 v[192:195], v134
	ds_read_b128 v[196:199], v134 offset:1024
	ds_read_b128 v[200:203], v134 offset:2048
	ds_read_b128 v[204:207], v134 offset:3072
	v_lshl_add_u64 v[134:135], s[90:91], 0, v[0:1]
	s_mov_b32 m0, s7
	v_lshl_add_u64 v[144:145], v[134:135], 0, s[60:61]
	global_load_lds_dwordx4 v[134:135], off
	s_add_i32 m0, s7, 0x2000
	s_nop 0
	global_load_lds_dwordx4 v[144:145], off
	s_barrier
	s_waitcnt lgkmcnt(0)
	v_mfma_f32_16x16x32_bf16 v[118:121], v[192:195], v[160:163], v[118:121]
	v_mfma_f32_16x16x32_bf16 v[114:117], v[200:203], v[160:163], v[114:117]
	v_mfma_f32_16x16x32_bf16 v[102:105], v[192:195], v[168:171], v[102:105]
	v_mfma_f32_16x16x32_bf16 v[98:101], v[200:203], v[168:171], v[98:101]
	v_mfma_f32_16x16x32_bf16 v[86:89], v[192:195], v[176:179], v[86:89]
	v_mfma_f32_16x16x32_bf16 v[82:85], v[200:203], v[176:179], v[82:85]
	v_mfma_f32_16x16x32_bf16 v[70:73], v[192:195], v[184:187], v[70:73]
	v_mfma_f32_16x16x32_bf16 v[66:69], v[200:203], v[184:187], v[66:69]
	v_mfma_f32_16x16x32_bf16 v[118:121], v[196:199], v[164:167], v[118:121]
	v_mfma_f32_16x16x32_bf16 v[114:117], v[204:207], v[164:167], v[114:117]
	v_mfma_f32_16x16x32_bf16 v[102:105], v[196:199], v[172:175], v[102:105]
	v_mfma_f32_16x16x32_bf16 v[98:101], v[204:207], v[172:175], v[98:101]
	v_mfma_f32_16x16x32_bf16 v[86:89], v[196:199], v[180:183], v[86:89]
	v_mfma_f32_16x16x32_bf16 v[82:85], v[204:207], v[180:183], v[82:85]
	v_mfma_f32_16x16x32_bf16 v[70:73], v[196:199], v[188:191], v[70:73]
	v_mfma_f32_16x16x32_bf16 v[66:69], v[204:207], v[188:191], v[66:69]
	s_barrier
	s_mov_b32 m0, s49
	v_lshl_add_u64 v[144:145], s[88:89], 0, v[130:131]
	ds_read_b128 v[160:163], v138 offset:16384
	ds_read_b128 v[164:167], v138 offset:17408
	ds_read_b128 v[168:171], v138 offset:18432
	ds_read_b128 v[172:175], v138 offset:19456
	ds_read_b128 v[176:179], v138 offset:20480
	ds_read_b128 v[180:183], v138 offset:21504
	ds_read_b128 v[184:187], v138 offset:22528
	ds_read_b128 v[188:191], v138 offset:23552
	global_load_lds_dwordx4 v[144:145], off
	v_lshl_add_u64 v[208:209], v[144:145], 0, s[60:61]
	s_mov_b32 m0, s55
	s_nop 0
	global_load_lds_dwordx4 v[208:209], off
	s_barrier
	s_waitcnt lgkmcnt(0)
	v_mfma_f32_16x16x32_bf16 v[62:65], v[140:143], v[160:163], v[62:65]
	v_mfma_f32_16x16x32_bf16 v[58:61], v[152:155], v[160:163], v[58:61]
	v_mfma_f32_16x16x32_bf16 v[46:49], v[140:143], v[168:171], v[46:49]
	v_mfma_f32_16x16x32_bf16 v[42:45], v[152:155], v[168:171], v[42:45]
	v_mfma_f32_16x16x32_bf16 v[30:33], v[140:143], v[176:179], v[30:33]
	v_mfma_f32_16x16x32_bf16 v[26:29], v[152:155], v[176:179], v[26:29]
	v_mfma_f32_16x16x32_bf16 v[14:17], v[140:143], v[184:187], v[14:17]
	v_mfma_f32_16x16x32_bf16 v[10:13], v[152:155], v[184:187], v[10:13]
	v_mfma_f32_16x16x32_bf16 v[62:65], v[148:151], v[164:167], v[62:65]
	v_mfma_f32_16x16x32_bf16 v[58:61], v[156:159], v[164:167], v[58:61]
	v_mfma_f32_16x16x32_bf16 v[46:49], v[148:151], v[172:175], v[46:49]
	v_mfma_f32_16x16x32_bf16 v[42:45], v[156:159], v[172:175], v[42:45]
	v_mfma_f32_16x16x32_bf16 v[30:33], v[148:151], v[180:183], v[30:33]
	v_mfma_f32_16x16x32_bf16 v[26:29], v[156:159], v[180:183], v[26:29]
	v_mfma_f32_16x16x32_bf16 v[14:17], v[148:151], v[188:191], v[14:17]
	v_mfma_f32_16x16x32_bf16 v[10:13], v[156:159], v[188:191], v[10:13]
	s_barrier
	s_add_i32 s6, s6, s54
	v_lshl_add_u64 v[140:141], v[134:135], 0, s[20:21]
	s_mov_b32 m0, s6
	s_nop 0
	global_load_lds_dwordx4 v[140:141], off
	v_lshl_add_u64 v[140:141], v[134:135], 0, s[64:65]
	s_add_i32 m0, s6, 0x2000
	s_nop 0
	global_load_lds_dwordx4 v[140:141], off
	v_lshl_add_u64 v[230:231], v[144:145], 0, s[20:21]
	s_mov_b32 m0, s56
	s_nop 0
	global_load_lds_dwordx4 v[230:231], off
	v_lshl_add_u64 v[230:231], v[144:145], 0, s[64:65]
	s_mov_b32 m0, s57
	s_nop 0
	global_load_lds_dwordx4 v[230:231], off
	s_waitcnt vmcnt(8)
	s_barrier
	v_mfma_f32_16x16x32_bf16 v[54:57], v[192:195], v[160:163], v[54:57]
	v_mfma_f32_16x16x32_bf16 v[50:53], v[200:203], v[160:163], v[50:53]
	v_mfma_f32_16x16x32_bf16 v[38:41], v[192:195], v[168:171], v[38:41]
	v_mfma_f32_16x16x32_bf16 v[34:37], v[200:203], v[168:171], v[34:37]
	v_mfma_f32_16x16x32_bf16 v[22:25], v[192:195], v[176:179], v[22:25]
	v_mfma_f32_16x16x32_bf16 v[18:21], v[200:203], v[176:179], v[18:21]
	v_mfma_f32_16x16x32_bf16 v[6:9], v[192:195], v[184:187], v[6:9]
	v_mfma_f32_16x16x32_bf16 v[2:5], v[200:203], v[184:187], v[2:5]
	v_mfma_f32_16x16x32_bf16 v[54:57], v[196:199], v[164:167], v[54:57]
	v_mfma_f32_16x16x32_bf16 v[50:53], v[204:207], v[164:167], v[50:53]
	v_mfma_f32_16x16x32_bf16 v[38:41], v[196:199], v[172:175], v[38:41]
	v_mfma_f32_16x16x32_bf16 v[34:37], v[204:207], v[172:175], v[34:37]
	v_mfma_f32_16x16x32_bf16 v[22:25], v[196:199], v[180:183], v[22:25]
	v_mfma_f32_16x16x32_bf16 v[18:21], v[204:207], v[180:183], v[18:21]
	v_mfma_f32_16x16x32_bf16 v[6:9], v[196:199], v[188:191], v[6:9]
	v_mfma_f32_16x16x32_bf16 v[2:5], v[204:207], v[188:191], v[2:5]
	s_barrier
	s_add_i32 s6, 0, 0x18000
	v_add_u32_e32 v139, s6, v137
	ds_read_b128 v[140:143], v139
	ds_read_b128 v[148:151], v139 offset:1024
	ds_read_b128 v[152:155], v139 offset:2048
	ds_read_b128 v[156:159], v139 offset:3072
	ds_read_b128 v[160:163], v138 offset:32768
	ds_read_b128 v[164:167], v138 offset:33792
	ds_read_b128 v[168:171], v138 offset:34816
	ds_read_b128 v[172:175], v138 offset:35840
	ds_read_b128 v[176:179], v138 offset:36864
	ds_read_b128 v[180:183], v138 offset:37888
	ds_read_b128 v[184:187], v138 offset:38912
	ds_read_b128 v[188:191], v138 offset:39936
	s_waitcnt lgkmcnt(8)
	s_barrier
	s_waitcnt lgkmcnt(0)
	v_mfma_f32_16x16x32_bf16 v[126:129], v[140:143], v[160:163], v[126:129]
	v_mfma_f32_16x16x32_bf16 v[122:125], v[152:155], v[160:163], v[122:125]
	v_mfma_f32_16x16x32_bf16 v[110:113], v[140:143], v[168:171], v[110:113]
	v_mfma_f32_16x16x32_bf16 v[106:109], v[152:155], v[168:171], v[106:109]
	v_mfma_f32_16x16x32_bf16 v[94:97], v[140:143], v[176:179], v[94:97]
	v_mfma_f32_16x16x32_bf16 v[90:93], v[152:155], v[176:179], v[90:93]
	v_mfma_f32_16x16x32_bf16 v[78:81], v[140:143], v[184:187], v[78:81]
	v_mfma_f32_16x16x32_bf16 v[74:77], v[152:155], v[184:187], v[74:77]
	v_mfma_f32_16x16x32_bf16 v[126:129], v[148:151], v[164:167], v[126:129]
	v_mfma_f32_16x16x32_bf16 v[122:125], v[156:159], v[164:167], v[122:125]
	v_mfma_f32_16x16x32_bf16 v[110:113], v[148:151], v[172:175], v[110:113]
	v_mfma_f32_16x16x32_bf16 v[106:109], v[156:159], v[172:175], v[106:109]
	v_mfma_f32_16x16x32_bf16 v[94:97], v[148:151], v[180:183], v[94:97]
	v_mfma_f32_16x16x32_bf16 v[90:93], v[156:159], v[180:183], v[90:93]
	v_mfma_f32_16x16x32_bf16 v[78:81], v[148:151], v[188:191], v[78:81]
	v_mfma_f32_16x16x32_bf16 v[74:77], v[156:159], v[188:191], v[74:77]
	s_barrier
	s_add_i32 s7, 0, 0x1c000
	s_add_i32 s6, s6, s54
	v_add_u32_e32 v139, s7, v137
	v_lshl_add_u64 v[208:209], v[134:135], 0, s[34:35]
	s_mov_b32 m0, s6
	ds_read_b128 v[192:195], v139
	ds_read_b128 v[196:199], v139 offset:1024
	ds_read_b128 v[200:203], v139 offset:2048
	ds_read_b128 v[204:207], v139 offset:3072
	global_load_lds_dwordx4 v[208:209], off
	v_lshl_add_u64 v[208:209], v[134:135], 0, s[66:67]
	s_add_i32 m0, s6, 0x2000
	s_nop 0
	global_load_lds_dwordx4 v[208:209], off
	s_barrier
	s_waitcnt lgkmcnt(0)
	v_mfma_f32_16x16x32_bf16 v[118:121], v[192:195], v[160:163], v[118:121]
	v_mfma_f32_16x16x32_bf16 v[114:117], v[200:203], v[160:163], v[114:117]
	v_mfma_f32_16x16x32_bf16 v[102:105], v[192:195], v[168:171], v[102:105]
	v_mfma_f32_16x16x32_bf16 v[98:101], v[200:203], v[168:171], v[98:101]
	v_mfma_f32_16x16x32_bf16 v[86:89], v[192:195], v[176:179], v[86:89]
	v_mfma_f32_16x16x32_bf16 v[82:85], v[200:203], v[176:179], v[82:85]
	v_mfma_f32_16x16x32_bf16 v[70:73], v[192:195], v[184:187], v[70:73]
	v_mfma_f32_16x16x32_bf16 v[66:69], v[200:203], v[184:187], v[66:69]
	v_mfma_f32_16x16x32_bf16 v[118:121], v[196:199], v[164:167], v[118:121]
	v_mfma_f32_16x16x32_bf16 v[114:117], v[204:207], v[164:167], v[114:117]
	v_mfma_f32_16x16x32_bf16 v[102:105], v[196:199], v[172:175], v[102:105]
	v_mfma_f32_16x16x32_bf16 v[98:101], v[204:207], v[172:175], v[98:101]
	v_mfma_f32_16x16x32_bf16 v[86:89], v[196:199], v[180:183], v[86:89]
	v_mfma_f32_16x16x32_bf16 v[82:85], v[204:207], v[180:183], v[82:85]
	v_mfma_f32_16x16x32_bf16 v[70:73], v[196:199], v[188:191], v[70:73]
	v_mfma_f32_16x16x32_bf16 v[66:69], v[204:207], v[188:191], v[66:69]
	s_barrier
	s_mov_b32 m0, s58
	v_lshl_add_u64 v[208:209], v[144:145], 0, s[34:35]
	ds_read_b128 v[160:163], v138 offset:49152
	ds_read_b128 v[164:167], v138 offset:50176
	ds_read_b128 v[168:171], v138 offset:51200
	ds_read_b128 v[172:175], v138 offset:52224
	ds_read_b128 v[176:179], v138 offset:53248
	ds_read_b128 v[180:183], v138 offset:54272
	ds_read_b128 v[184:187], v138 offset:55296
	ds_read_b128 v[188:191], v138 offset:56320
	global_load_lds_dwordx4 v[208:209], off
	v_lshl_add_u64 v[144:145], v[144:145], 0, s[66:67]
	s_mov_b32 m0, s59
	s_nop 0
	global_load_lds_dwordx4 v[144:145], off
	s_barrier
	s_waitcnt lgkmcnt(0)
	v_mfma_f32_16x16x32_bf16 v[62:65], v[140:143], v[160:163], v[62:65]
	v_mfma_f32_16x16x32_bf16 v[58:61], v[152:155], v[160:163], v[58:61]
	v_mfma_f32_16x16x32_bf16 v[46:49], v[140:143], v[168:171], v[46:49]
	v_mfma_f32_16x16x32_bf16 v[42:45], v[152:155], v[168:171], v[42:45]
	v_mfma_f32_16x16x32_bf16 v[30:33], v[140:143], v[176:179], v[30:33]
	v_mfma_f32_16x16x32_bf16 v[26:29], v[152:155], v[176:179], v[26:29]
	v_mfma_f32_16x16x32_bf16 v[14:17], v[140:143], v[184:187], v[14:17]
	v_mfma_f32_16x16x32_bf16 v[10:13], v[152:155], v[184:187], v[10:13]
	v_mfma_f32_16x16x32_bf16 v[62:65], v[148:151], v[164:167], v[62:65]
	v_mfma_f32_16x16x32_bf16 v[58:61], v[156:159], v[164:167], v[58:61]
	v_mfma_f32_16x16x32_bf16 v[46:49], v[148:151], v[172:175], v[46:49]
	v_mfma_f32_16x16x32_bf16 v[42:45], v[156:159], v[172:175], v[42:45]
	v_mfma_f32_16x16x32_bf16 v[30:33], v[148:151], v[180:183], v[30:33]
	v_mfma_f32_16x16x32_bf16 v[26:29], v[156:159], v[180:183], v[26:29]
	v_mfma_f32_16x16x32_bf16 v[14:17], v[148:151], v[188:191], v[14:17]
	v_mfma_f32_16x16x32_bf16 v[10:13], v[156:159], v[188:191], v[10:13]
	s_barrier
	s_add_i32 s6, s7, s54
	v_lshl_add_u64 v[140:141], v[134:135], 0, s[16:17]
	s_mov_b32 m0, s6
	v_lshl_add_u64 v[134:135], v[134:135], 0, s[80:81]
	global_load_lds_dwordx4 v[140:141], off
	s_add_i32 m0, s6, 0x2000
	s_nop 0
	global_load_lds_dwordx4 v[134:135], off
	s_waitcnt vmcnt(6)
	s_add_i32 s87, s87, 2
	s_add_u32 s41, s41, 0x100
	s_addc_u32 s86, s86, 0
	s_cmp_gt_u32 s87, 29
	s_mov_b64 s[6:7], s[8:9]
	s_cbranch_scc0 .LBB0_694
	s_barrier
	v_mfma_f32_16x16x32_bf16 v[54:57], v[192:195], v[160:163], v[54:57]
	v_mfma_f32_16x16x32_bf16 v[50:53], v[200:203], v[160:163], v[50:53]
	v_mfma_f32_16x16x32_bf16 v[38:41], v[192:195], v[168:171], v[38:41]
	v_mfma_f32_16x16x32_bf16 v[34:37], v[200:203], v[168:171], v[34:37]
	v_mfma_f32_16x16x32_bf16 v[22:25], v[192:195], v[176:179], v[22:25]
	v_mfma_f32_16x16x32_bf16 v[18:21], v[200:203], v[176:179], v[18:21]
	v_mfma_f32_16x16x32_bf16 v[6:9], v[192:195], v[184:187], v[6:9]
	v_mfma_f32_16x16x32_bf16 v[2:5], v[200:203], v[184:187], v[2:5]
	v_mfma_f32_16x16x32_bf16 v[54:57], v[196:199], v[164:167], v[54:57]
	v_mfma_f32_16x16x32_bf16 v[50:53], v[204:207], v[164:167], v[50:53]
	v_mfma_f32_16x16x32_bf16 v[38:41], v[196:199], v[172:175], v[38:41]
	v_mfma_f32_16x16x32_bf16 v[34:37], v[204:207], v[172:175], v[34:37]
	v_mfma_f32_16x16x32_bf16 v[22:25], v[196:199], v[180:183], v[22:25]
	v_mfma_f32_16x16x32_bf16 v[18:21], v[204:207], v[180:183], v[18:21]
	v_mfma_f32_16x16x32_bf16 v[6:9], v[196:199], v[188:191], v[6:9]
	v_mfma_f32_16x16x32_bf16 v[2:5], v[204:207], v[188:191], v[2:5]
	s_barrier
	v_mov_b32_e32 v134, v136
	s_lshl_b32 s6, s48, 8
	s_add_i32 s6, s6, s10
	v_and_or_b32 v139, v134, 15, s6
	s_lshl_b32 s6, s85, 7
	v_ashrrev_i32_e32 v134, 1, v134
	s_or_b32 s6, s6, s62
	v_and_b32_e32 v134, -8, v134
	v_add_u32_e32 v140, s6, v134
	v_mul_f32_e32 v134, 0xbfb8aa3b, v126
	v_exp_f32_e32 v142, v134
	v_mul_f32_e32 v134, 0xbfb8aa3b, v127
	v_exp_f32_e32 v143, v134
	v_ashrrev_i32_e32 v141, 31, v140
	v_add_f32_e32 v142, 1.0, v142
	v_rcp_f32_e32 v144, v142
	v_add_f32_e32 v142, 1.0, v143
	v_rcp_f32_e32 v145, v142
	v_mov_b64_e32 v[134:135], s[4:5]
	v_mul_f32_e32 v126, v126, v144
	v_mul_f32_e32 v118, v126, v118
	v_mul_f32_e32 v126, v127, v145
	v_mul_f32_e32 v127, 0xbfb8aa3b, v128
	v_exp_f32_e32 v127, v127
	v_mul_f32_e32 v144, 0xbfb8aa3b, v129
	v_exp_f32_e32 v144, v144
	v_mul_f32_e32 v119, v126, v119
	v_add_f32_e32 v126, 1.0, v127
	v_rcp_f32_e32 v126, v126
	v_add_f32_e32 v127, 1.0, v144
	v_mul_f32_e32 v144, 0xbfb8aa3b, v122
	v_rcp_f32_e32 v127, v127
	v_exp_f32_e32 v144, v144
	v_mul_f32_e32 v126, v128, v126
	v_mul_f32_e32 v126, v126, v120
	v_mul_f32_e32 v120, v129, v127
	v_add_f32_e32 v127, 1.0, v144
	v_rcp_f32_e32 v127, v127
	v_mul_f32_e32 v128, 0xbfb8aa3b, v123
	v_mul_f32_e32 v129, v120, v121
	v_exp_f32_e32 v128, v128
	v_mul_f32_e32 v120, v122, v127
	v_mul_f32_e32 v122, v120, v114
	v_mul_f32_e32 v120, 0xbfb8aa3b, v124
	v_exp_f32_e32 v120, v120
	v_mul_f32_e32 v121, 0xbfb8aa3b, v125
	v_exp_f32_e32 v121, v121
	v_add_f32_e32 v114, 1.0, v128
	v_rcp_f32_e32 v114, v114
	v_add_f32_e32 v120, 1.0, v120
	v_rcp_f32_e32 v120, v120
	v_add_f32_e32 v121, 1.0, v121
	v_rcp_f32_e32 v121, v121
	v_mul_f32_e32 v114, v123, v114
	v_mul_f32_e32 v123, v114, v115
	v_mul_f32_e32 v114, v124, v120
	v_mul_f32_e32 v124, v114, v116
	v_mul_f32_e32 v114, v125, v121
	v_mad_i64_i32 v[142:143], s[6:7], v139, s74, v[134:135]
	v_mul_f32_e32 v125, v114, v117
	v_lshlrev_b64 v[114:115], 1, v[140:141]
	v_lshl_add_u64 v[120:121], v[142:143], 0, v[114:115]
	v_cvt_pk_bf16_f32 v116, v118, v119
	v_cvt_pk_bf16_f32 v117, v126, v129
	v_cvt_pk_bf16_f32 v118, v122, v123
	v_cvt_pk_bf16_f32 v119, v124, v125
	global_store_dwordx4 v[120:121], v[116:119], off
	s_and_b64 vcc, exec, s[42:43]
	s_mov_b32 s48, s40
	v_mul_f32_e32 v116, 0xbfb8aa3b, v110
	v_exp_f32_e32 v116, v116
	v_mul_f32_e32 v117, 0xbfb8aa3b, v111
	v_exp_f32_e32 v117, v117
	v_or_b32_e32 v118, 16, v139
	v_add_f32_e32 v116, 1.0, v116
	v_rcp_f32_e32 v119, v116
	v_add_f32_e32 v116, 1.0, v117
	v_rcp_f32_e32 v120, v116
	v_mad_i64_i32 v[116:117], s[6:7], v118, s74, v[134:135]
	v_mul_f32_e32 v110, v110, v119
	v_mul_f32_e32 v110, v110, v102
	v_mul_f32_e32 v102, v111, v120
	v_mul_f32_e32 v111, 0xbfb8aa3b, v112
	v_exp_f32_e32 v111, v111
	v_mul_f32_e32 v118, 0xbfb8aa3b, v113
	v_exp_f32_e32 v118, v118
	v_mul_f32_e32 v119, v102, v103
	v_add_f32_e32 v102, 1.0, v111
	v_rcp_f32_e32 v102, v102
	v_add_f32_e32 v103, 1.0, v118
	v_mul_f32_e32 v111, 0xbfb8aa3b, v106
	v_rcp_f32_e32 v103, v103
	v_exp_f32_e32 v111, v111
	v_mul_f32_e32 v102, v112, v102
	v_mul_f32_e32 v104, v102, v104
	v_mul_f32_e32 v102, v113, v103
	v_add_f32_e32 v103, 1.0, v111
	v_rcp_f32_e32 v103, v103
	v_mul_f32_e32 v111, 0xbfb8aa3b, v107
	v_mul_f32_e32 v105, v102, v105
	v_exp_f32_e32 v111, v111
	v_mul_f32_e32 v102, v106, v103
	v_mul_f32_e32 v106, v102, v98
	v_mul_f32_e32 v102, 0xbfb8aa3b, v108
	v_exp_f32_e32 v102, v102
	v_mul_f32_e32 v103, 0xbfb8aa3b, v109
	v_exp_f32_e32 v103, v103
	v_add_f32_e32 v98, 1.0, v111
	v_rcp_f32_e32 v98, v98
	v_add_f32_e32 v102, 1.0, v102
	v_rcp_f32_e32 v102, v102
	v_add_f32_e32 v103, 1.0, v103
	v_rcp_f32_e32 v103, v103
	v_mul_f32_e32 v98, v107, v98
	v_mul_f32_e32 v107, v98, v99
	v_mul_f32_e32 v98, v108, v102
	v_mul_f32_e32 v108, v98, v100
	v_mul_f32_e32 v98, v109, v103
	v_mul_f32_e32 v101, v98, v101
	v_lshl_add_u64 v[102:103], v[116:117], 0, v[114:115]
	v_cvt_pk_bf16_f32 v98, v110, v119
	v_cvt_pk_bf16_f32 v99, v104, v105
	v_cvt_pk_bf16_f32 v100, v106, v107
	v_cvt_pk_bf16_f32 v101, v108, v101
	global_store_dwordx4 v[102:103], v[98:101], off
	s_mov_b32 s85, s84
	s_mov_b64 s[8:9], s[46:47]
	v_mul_f32_e32 v98, 0xbfb8aa3b, v94
	v_exp_f32_e32 v98, v98
	v_mul_f32_e32 v99, 0xbfb8aa3b, v95
	v_exp_f32_e32 v99, v99
	v_or_b32_e32 v100, 32, v139
	v_add_f32_e32 v98, 1.0, v98
	v_rcp_f32_e32 v101, v98
	v_add_f32_e32 v98, 1.0, v99
	v_rcp_f32_e32 v102, v98
	v_mad_i64_i32 v[98:99], s[6:7], v100, s74, v[134:135]
	v_mul_f32_e32 v94, v94, v101
	v_mul_f32_e32 v94, v94, v86
	v_mul_f32_e32 v86, v95, v102
	v_mul_f32_e32 v95, 0xbfb8aa3b, v96
	v_exp_f32_e32 v95, v95
	v_mul_f32_e32 v100, 0xbfb8aa3b, v97
	v_exp_f32_e32 v100, v100
	v_mul_f32_e32 v101, v86, v87
	v_add_f32_e32 v86, 1.0, v95
	v_rcp_f32_e32 v86, v86
	v_add_f32_e32 v87, 1.0, v100
	v_mul_f32_e32 v95, 0xbfb8aa3b, v90
	v_rcp_f32_e32 v87, v87
	v_exp_f32_e32 v95, v95
	v_mul_f32_e32 v86, v96, v86
	v_mul_f32_e32 v88, v86, v88
	v_mul_f32_e32 v86, v97, v87
	v_add_f32_e32 v87, 1.0, v95
	v_rcp_f32_e32 v87, v87
	v_mul_f32_e32 v95, 0xbfb8aa3b, v91
	v_mul_f32_e32 v89, v86, v89
	v_exp_f32_e32 v95, v95
	v_mul_f32_e32 v86, v90, v87
	v_mul_f32_e32 v90, v86, v82
	v_mul_f32_e32 v86, 0xbfb8aa3b, v92
	v_exp_f32_e32 v86, v86
	v_mul_f32_e32 v87, 0xbfb8aa3b, v93
	v_exp_f32_e32 v87, v87
	v_add_f32_e32 v82, 1.0, v95
	v_rcp_f32_e32 v82, v82
	v_add_f32_e32 v86, 1.0, v86
	v_rcp_f32_e32 v86, v86
	v_add_f32_e32 v87, 1.0, v87
	v_rcp_f32_e32 v87, v87
	v_mul_f32_e32 v82, v91, v82
	v_mul_f32_e32 v91, v82, v83
	v_mul_f32_e32 v82, v92, v86
	v_mul_f32_e32 v92, v82, v84
	v_mul_f32_e32 v82, v93, v87
	v_mul_f32_e32 v85, v82, v85
	v_lshl_add_u64 v[86:87], v[98:99], 0, v[114:115]
	v_cvt_pk_bf16_f32 v82, v94, v101
	v_cvt_pk_bf16_f32 v83, v88, v89
	v_cvt_pk_bf16_f32 v84, v90, v91
	v_cvt_pk_bf16_f32 v85, v92, v85
	global_store_dwordx4 v[86:87], v[82:85], off
	s_nop 1
	v_mul_f32_e32 v82, 0xbfb8aa3b, v78
	v_exp_f32_e32 v82, v82
	v_mul_f32_e32 v83, 0xbfb8aa3b, v79
	v_exp_f32_e32 v83, v83
	v_or_b32_e32 v84, 48, v139
	v_add_f32_e32 v82, 1.0, v82
	v_rcp_f32_e32 v85, v82
	v_add_f32_e32 v82, 1.0, v83
	v_rcp_f32_e32 v86, v82
	v_mad_i64_i32 v[82:83], s[6:7], v84, s74, v[134:135]
	v_mul_f32_e32 v78, v78, v85
	v_mul_f32_e32 v78, v78, v70
	v_mul_f32_e32 v70, v79, v86
	v_mul_f32_e32 v79, 0xbfb8aa3b, v80
	v_exp_f32_e32 v79, v79
	v_mul_f32_e32 v84, 0xbfb8aa3b, v81
	v_exp_f32_e32 v84, v84
	v_mul_f32_e32 v85, v70, v71
	v_add_f32_e32 v70, 1.0, v79
	v_rcp_f32_e32 v70, v70
	v_add_f32_e32 v71, 1.0, v84
	v_mul_f32_e32 v79, 0xbfb8aa3b, v74
	v_rcp_f32_e32 v71, v71
	v_exp_f32_e32 v79, v79
	v_mul_f32_e32 v70, v80, v70
	v_mul_f32_e32 v72, v70, v72
	v_mul_f32_e32 v70, v81, v71
	v_add_f32_e32 v71, 1.0, v79
	v_rcp_f32_e32 v71, v71
	v_mul_f32_e32 v79, 0xbfb8aa3b, v75
	v_mul_f32_e32 v73, v70, v73
	v_exp_f32_e32 v79, v79
	v_mul_f32_e32 v70, v74, v71
	v_mul_f32_e32 v74, v70, v66
	v_mul_f32_e32 v70, 0xbfb8aa3b, v76
	v_exp_f32_e32 v70, v70
	v_mul_f32_e32 v71, 0xbfb8aa3b, v77
	v_exp_f32_e32 v71, v71
	v_add_f32_e32 v66, 1.0, v79
	v_rcp_f32_e32 v66, v66
	v_add_f32_e32 v70, 1.0, v70
	v_rcp_f32_e32 v70, v70
	v_add_f32_e32 v71, 1.0, v71
	v_rcp_f32_e32 v71, v71
	v_mul_f32_e32 v66, v75, v66
	v_mul_f32_e32 v75, v66, v67
	v_mul_f32_e32 v66, v76, v70
	v_mul_f32_e32 v76, v66, v68
	v_mul_f32_e32 v66, v77, v71
	v_mul_f32_e32 v69, v66, v69
	v_lshl_add_u64 v[70:71], v[82:83], 0, v[114:115]
	v_cvt_pk_bf16_f32 v66, v78, v85
	v_cvt_pk_bf16_f32 v67, v72, v73
	v_cvt_pk_bf16_f32 v68, v74, v75
	v_cvt_pk_bf16_f32 v69, v76, v69
	global_store_dwordx4 v[70:71], v[66:69], off
	s_nop 1
	v_mul_f32_e32 v66, 0xbfb8aa3b, v62
	v_exp_f32_e32 v66, v66
	v_mul_f32_e32 v67, 0xbfb8aa3b, v63
	v_exp_f32_e32 v67, v67
	v_add_u32_e32 v68, 0x80, v139
	v_add_f32_e32 v66, 1.0, v66
	v_rcp_f32_e32 v69, v66
	v_add_f32_e32 v66, 1.0, v67
	v_rcp_f32_e32 v70, v66
	v_mad_i64_i32 v[66:67], s[6:7], v68, s74, v[134:135]
	v_mul_f32_e32 v62, v62, v69
	v_mul_f32_e32 v62, v62, v54
	v_mul_f32_e32 v54, v63, v70
	v_mul_f32_e32 v63, 0xbfb8aa3b, v64
	v_exp_f32_e32 v63, v63
	v_mul_f32_e32 v68, 0xbfb8aa3b, v65
	v_exp_f32_e32 v68, v68
	v_mul_f32_e32 v69, v54, v55
	v_add_f32_e32 v54, 1.0, v63
	v_rcp_f32_e32 v54, v54
	v_add_f32_e32 v55, 1.0, v68
	v_mul_f32_e32 v63, 0xbfb8aa3b, v58
	v_rcp_f32_e32 v55, v55
	v_exp_f32_e32 v63, v63
	v_mul_f32_e32 v54, v64, v54
	v_mul_f32_e32 v56, v54, v56
	v_mul_f32_e32 v54, v65, v55
	v_add_f32_e32 v55, 1.0, v63
	v_rcp_f32_e32 v55, v55
	v_mul_f32_e32 v63, 0xbfb8aa3b, v59
	v_mul_f32_e32 v57, v54, v57
	v_exp_f32_e32 v63, v63
	v_mul_f32_e32 v54, v58, v55
	v_mul_f32_e32 v58, v54, v50
	v_mul_f32_e32 v54, 0xbfb8aa3b, v60
	v_exp_f32_e32 v54, v54
	v_mul_f32_e32 v55, 0xbfb8aa3b, v61
	v_exp_f32_e32 v55, v55
	v_add_f32_e32 v50, 1.0, v63
	v_rcp_f32_e32 v50, v50
	v_add_f32_e32 v54, 1.0, v54
	v_rcp_f32_e32 v54, v54
	v_add_f32_e32 v55, 1.0, v55
	v_rcp_f32_e32 v55, v55
	v_mul_f32_e32 v50, v59, v50
	v_mul_f32_e32 v59, v50, v51
	v_mul_f32_e32 v50, v60, v54
	v_mul_f32_e32 v60, v50, v52
	v_mul_f32_e32 v50, v61, v55
	v_mul_f32_e32 v53, v50, v53
	v_lshl_add_u64 v[54:55], v[66:67], 0, v[114:115]
	v_cvt_pk_bf16_f32 v50, v62, v69
	v_cvt_pk_bf16_f32 v51, v56, v57
	v_cvt_pk_bf16_f32 v52, v58, v59
	v_cvt_pk_bf16_f32 v53, v60, v53
	global_store_dwordx4 v[54:55], v[50:53], off
	s_nop 1
	v_mul_f32_e32 v50, 0xbfb8aa3b, v46
	v_exp_f32_e32 v50, v50
	v_mul_f32_e32 v51, 0xbfb8aa3b, v47
	v_exp_f32_e32 v51, v51
	v_add_u32_e32 v52, 0x90, v139
	v_add_f32_e32 v50, 1.0, v50
	v_rcp_f32_e32 v53, v50
	v_add_f32_e32 v50, 1.0, v51
	v_rcp_f32_e32 v54, v50
	v_mad_i64_i32 v[50:51], s[6:7], v52, s74, v[134:135]
	v_mul_f32_e32 v46, v46, v53
	v_mul_f32_e32 v46, v46, v38
	v_mul_f32_e32 v38, v47, v54
	v_mul_f32_e32 v47, 0xbfb8aa3b, v48
	v_exp_f32_e32 v47, v47
	v_mul_f32_e32 v52, 0xbfb8aa3b, v49
	v_exp_f32_e32 v52, v52
	v_mul_f32_e32 v53, v38, v39
	v_add_f32_e32 v38, 1.0, v47
	v_rcp_f32_e32 v38, v38
	v_add_f32_e32 v39, 1.0, v52
	v_mul_f32_e32 v47, 0xbfb8aa3b, v42
	v_rcp_f32_e32 v39, v39
	v_exp_f32_e32 v47, v47
	v_mul_f32_e32 v38, v48, v38
	v_mul_f32_e32 v40, v38, v40
	v_mul_f32_e32 v38, v49, v39
	v_add_f32_e32 v39, 1.0, v47
	v_rcp_f32_e32 v39, v39
	v_mul_f32_e32 v47, 0xbfb8aa3b, v43
	v_mul_f32_e32 v41, v38, v41
	v_exp_f32_e32 v47, v47
	v_mul_f32_e32 v38, v42, v39
	v_mul_f32_e32 v42, v38, v34
	v_mul_f32_e32 v38, 0xbfb8aa3b, v44
	v_exp_f32_e32 v38, v38
	v_mul_f32_e32 v39, 0xbfb8aa3b, v45
	v_exp_f32_e32 v39, v39
	v_add_f32_e32 v34, 1.0, v47
	v_rcp_f32_e32 v34, v34
	v_add_f32_e32 v38, 1.0, v38
	v_rcp_f32_e32 v38, v38
	v_add_f32_e32 v39, 1.0, v39
	v_rcp_f32_e32 v39, v39
	v_mul_f32_e32 v34, v43, v34
	v_mul_f32_e32 v43, v34, v35
	v_mul_f32_e32 v34, v44, v38
	v_mul_f32_e32 v44, v34, v36
	v_mul_f32_e32 v34, v45, v39
	v_mul_f32_e32 v37, v34, v37
	v_lshl_add_u64 v[38:39], v[50:51], 0, v[114:115]
	v_cvt_pk_bf16_f32 v34, v46, v53
	v_cvt_pk_bf16_f32 v35, v40, v41
	v_cvt_pk_bf16_f32 v36, v42, v43
	v_cvt_pk_bf16_f32 v37, v44, v37
	global_store_dwordx4 v[38:39], v[34:37], off
	s_nop 1
	v_mul_f32_e32 v34, 0xbfb8aa3b, v30
	v_exp_f32_e32 v34, v34
	v_mul_f32_e32 v35, 0xbfb8aa3b, v31
	v_exp_f32_e32 v35, v35
	v_add_u32_e32 v36, 0xa0, v139
	v_add_f32_e32 v34, 1.0, v34
	v_rcp_f32_e32 v37, v34
	v_add_f32_e32 v34, 1.0, v35
	v_rcp_f32_e32 v38, v34
	v_mad_i64_i32 v[34:35], s[6:7], v36, s74, v[134:135]
	v_mul_f32_e32 v30, v30, v37
	v_mul_f32_e32 v30, v30, v22
	v_mul_f32_e32 v22, v31, v38
	v_mul_f32_e32 v31, 0xbfb8aa3b, v32
	v_exp_f32_e32 v31, v31
	v_mul_f32_e32 v36, 0xbfb8aa3b, v33
	v_exp_f32_e32 v36, v36
	v_mul_f32_e32 v37, v22, v23
	v_add_f32_e32 v22, 1.0, v31
	v_rcp_f32_e32 v22, v22
	v_add_f32_e32 v23, 1.0, v36
	v_mul_f32_e32 v31, 0xbfb8aa3b, v26
	v_rcp_f32_e32 v23, v23
	v_exp_f32_e32 v31, v31
	v_mul_f32_e32 v22, v32, v22
	v_mul_f32_e32 v24, v22, v24
	v_mul_f32_e32 v22, v33, v23
	v_add_f32_e32 v23, 1.0, v31
	v_rcp_f32_e32 v23, v23
	v_mul_f32_e32 v31, 0xbfb8aa3b, v27
	v_mul_f32_e32 v25, v22, v25
	v_exp_f32_e32 v31, v31
	v_mul_f32_e32 v22, v26, v23
	v_mul_f32_e32 v26, v22, v18
	v_mul_f32_e32 v22, 0xbfb8aa3b, v28
	v_exp_f32_e32 v22, v22
	v_mul_f32_e32 v23, 0xbfb8aa3b, v29
	v_exp_f32_e32 v23, v23
	v_add_f32_e32 v18, 1.0, v31
	v_rcp_f32_e32 v18, v18
	v_add_f32_e32 v22, 1.0, v22
	v_rcp_f32_e32 v22, v22
	v_add_f32_e32 v23, 1.0, v23
	v_rcp_f32_e32 v23, v23
	v_mul_f32_e32 v18, v27, v18
	v_mul_f32_e32 v27, v18, v19
	v_mul_f32_e32 v18, v28, v22
	v_mul_f32_e32 v28, v18, v20
	v_mul_f32_e32 v18, v29, v23
	v_mul_f32_e32 v21, v18, v21
	v_lshl_add_u64 v[22:23], v[34:35], 0, v[114:115]
	v_cvt_pk_bf16_f32 v18, v30, v37
	v_cvt_pk_bf16_f32 v19, v24, v25
	v_cvt_pk_bf16_f32 v20, v26, v27
	v_cvt_pk_bf16_f32 v21, v28, v21
	global_store_dwordx4 v[22:23], v[18:21], off
	s_nop 1
	v_mul_f32_e32 v18, 0xbfb8aa3b, v14
	v_exp_f32_e32 v18, v18
	v_mul_f32_e32 v19, 0xbfb8aa3b, v15
	v_exp_f32_e32 v19, v19
	v_add_u32_e32 v20, 0xb0, v139
	v_add_f32_e32 v18, 1.0, v18
	v_rcp_f32_e32 v21, v18
	v_add_f32_e32 v18, 1.0, v19
	v_rcp_f32_e32 v22, v18
	v_mad_i64_i32 v[18:19], s[6:7], v20, s74, v[134:135]
	v_mul_f32_e32 v14, v14, v21
	v_mul_f32_e32 v14, v14, v6
	v_mul_f32_e32 v6, v15, v22
	v_mul_f32_e32 v15, 0xbfb8aa3b, v16
	v_exp_f32_e32 v15, v15
	v_mul_f32_e32 v20, 0xbfb8aa3b, v17
	v_exp_f32_e32 v20, v20
	v_mul_f32_e32 v21, v6, v7
	v_add_f32_e32 v6, 1.0, v15
	v_rcp_f32_e32 v6, v6
	v_add_f32_e32 v7, 1.0, v20
	v_mul_f32_e32 v15, 0xbfb8aa3b, v10
	v_rcp_f32_e32 v7, v7
	v_exp_f32_e32 v15, v15
	v_mul_f32_e32 v6, v16, v6
	v_mul_f32_e32 v8, v6, v8
	v_mul_f32_e32 v6, v17, v7
	v_add_f32_e32 v7, 1.0, v15
	v_rcp_f32_e32 v7, v7
	v_mul_f32_e32 v15, 0xbfb8aa3b, v11
	v_mul_f32_e32 v9, v6, v9
	v_exp_f32_e32 v15, v15
	v_mul_f32_e32 v6, v10, v7
	v_mul_f32_e32 v10, v6, v2
	v_mul_f32_e32 v6, 0xbfb8aa3b, v12
	v_exp_f32_e32 v6, v6
	v_mul_f32_e32 v7, 0xbfb8aa3b, v13
	v_exp_f32_e32 v7, v7
	v_add_f32_e32 v2, 1.0, v15
	v_rcp_f32_e32 v2, v2
	v_add_f32_e32 v6, 1.0, v6
	v_rcp_f32_e32 v6, v6
	v_add_f32_e32 v7, 1.0, v7
	v_rcp_f32_e32 v7, v7
	v_mul_f32_e32 v2, v11, v2
	v_mul_f32_e32 v11, v2, v3
	v_mul_f32_e32 v2, v12, v6
	v_mul_f32_e32 v12, v2, v4
	v_mul_f32_e32 v2, v13, v7
	v_mul_f32_e32 v5, v2, v5
	v_lshl_add_u64 v[6:7], v[18:19], 0, v[114:115]
	s_mov_b64 s[6:7], s[44:45]
	v_cvt_pk_bf16_f32 v2, v14, v21
	v_cvt_pk_bf16_f32 v3, v8, v9
	v_cvt_pk_bf16_f32 v4, v10, v11
	v_cvt_pk_bf16_f32 v5, v12, v5
	global_store_dwordx4 v[6:7], v[2:5], off
	s_cbranch_vccz .LBB0_691
	s_waitcnt vmcnt(0)
	v_readlane_b32 s0, v255, 8
	v_readlane_b32 s62, v255, 10
	v_readlane_b32 s84, v255, 12
	v_readlane_b32 s44, v255, 26
	s_cmpk_gt_u32 s22, 0xff
	v_readlane_b32 s1, v255, 9
	s_mov_b64 s[58:59], s[92:93]
	v_readlane_b32 s63, v255, 11
	v_readlane_b32 s85, v255, 13
	v_readlane_b32 s45, v255, 27
	s_cbranch_scc1 .LBB0_698
	s_barrier
.LBB0_698:
	s_setprio 0
	v_readlane_b32 s86, v255, 14
	v_readlane_b32 s56, v255, 16
	v_readlane_b32 s52, v255, 18
	v_readlane_b32 s54, v255, 22
	v_readlane_b32 s50, v255, 28
	v_readlane_b32 s72, v255, 7
	v_readlane_b32 s87, v255, 15
	v_readlane_b32 s57, v255, 17
	v_readlane_b32 s53, v255, 19
	v_readlane_b32 s55, v255, 23
	v_readlane_b32 s51, v255, 29
	s_movk_i32 s92, 0x4000
	s_movk_i32 s93, 0xf800
	s_movk_i32 s89, 0x37ff
	s_mov_b32 s88, 0x16000
	s_movk_i32 s91, 0x60
	s_mov_b32 s78, 0x2a000000
	s_mov_b32 s79, 0x3fffe
	s_mov_b32 s90, 0xc0000
	s_barrier
